# v40 minus the mid-burst s_setprio 0/1 pairs (post-barrier wait kept)
# baseline (speedup 1.0000x reference)
.LBB0_379:
	v_add_u32_e32 v14, s56, v140
	v_add_u32_e32 v30, s57, v140
	ds_read_b128 v[2:5], v14
	ds_read_b128 v[6:9], v14 offset:1024
	ds_read_b128 v[10:13], v14 offset:2048
	ds_read_b128 v[14:17], v14 offset:3072
	ds_read_b128 v[18:21], v30
	ds_read_b128 v[22:25], v30 offset:1024
	ds_read_b128 v[26:29], v30 offset:2048
	ds_read_b128 v[30:33], v30 offset:3072
	v_add_u32_e32 v141, 0, v1
	ds_read_b128 v[34:37], v141
	ds_read_b128 v[38:41], v141 offset:1024
	ds_read_b128 v[42:45], v141 offset:2048
	ds_read_b128 v[46:49], v141 offset:3072
	ds_read_b128 v[50:53], v141 offset:4096
	ds_read_b128 v[54:57], v141 offset:5120
	ds_read_b128 v[58:61], v141 offset:6144
	ds_read_b128 v[62:65], v141 offset:7168
	s_waitcnt vmcnt(8)
	s_waitcnt lgkmcnt(0)
	s_barrier
	s_setprio 1
	s_waitcnt lgkmcnt(0)
	v_mfma_f32_16x16x32_bf16 v[66:69], v[2:5], v[34:37], 0
	v_mfma_f32_16x16x32_bf16 v[66:69], v[6:9], v[38:41], v[66:69]
	v_mfma_f32_16x16x32_bf16 v[70:73], v[10:13], v[34:37], 0
	v_mfma_f32_16x16x32_bf16 v[70:73], v[14:17], v[38:41], v[70:73]
	v_mfma_f32_16x16x32_bf16 v[78:81], v[10:13], v[42:45], 0
	v_mfma_f32_16x16x32_bf16 v[78:81], v[14:17], v[46:49], v[78:81]
	v_mfma_f32_16x16x32_bf16 v[74:77], v[2:5], v[42:45], 0
	v_mfma_f32_16x16x32_bf16 v[74:77], v[6:9], v[46:49], v[74:77]
	v_mfma_f32_16x16x32_bf16 v[82:85], v[2:5], v[50:53], 0
	v_mfma_f32_16x16x32_bf16 v[82:85], v[6:9], v[54:57], v[82:85]
	v_mfma_f32_16x16x32_bf16 v[86:89], v[10:13], v[50:53], 0
	v_mfma_f32_16x16x32_bf16 v[86:89], v[14:17], v[54:57], v[86:89]
	v_mfma_f32_16x16x32_bf16 v[94:97], v[10:13], v[58:61], 0
	v_mfma_f32_16x16x32_bf16 v[94:97], v[14:17], v[62:65], v[94:97]
	v_mfma_f32_16x16x32_bf16 v[90:93], v[2:5], v[58:61], 0
	v_mfma_f32_16x16x32_bf16 v[90:93], v[6:9], v[62:65], v[90:93]
	v_mfma_f32_16x16x32_bf16 v[98:101], v[18:21], v[34:37], 0
	v_mfma_f32_16x16x32_bf16 v[34:37], v[26:29], v[34:37], 0
	v_mfma_f32_16x16x32_bf16 v[102:105], v[18:21], v[42:45], 0
	v_mfma_f32_16x16x32_bf16 v[42:45], v[26:29], v[42:45], 0
	v_mfma_f32_16x16x32_bf16 v[106:109], v[18:21], v[50:53], 0
	v_mfma_f32_16x16x32_bf16 v[50:53], v[26:29], v[50:53], 0
	v_mfma_f32_16x16x32_bf16 v[110:113], v[18:21], v[58:61], 0
	v_mfma_f32_16x16x32_bf16 v[58:61], v[26:29], v[58:61], 0
	v_mfma_f32_16x16x32_bf16 v[98:101], v[22:25], v[38:41], v[98:101]
	v_mfma_f32_16x16x32_bf16 v[38:41], v[30:33], v[38:41], v[34:37]
	v_mfma_f32_16x16x32_bf16 v[102:105], v[22:25], v[46:49], v[102:105]
	v_mfma_f32_16x16x32_bf16 v[46:49], v[30:33], v[46:49], v[42:45]
	v_mfma_f32_16x16x32_bf16 v[106:109], v[22:25], v[54:57], v[106:109]
	v_mfma_f32_16x16x32_bf16 v[54:57], v[30:33], v[54:57], v[50:53]
	s_setprio 2
	s_barrier
	v_mfma_f32_16x16x32_bf16 v[110:113], v[22:25], v[62:65], v[110:113]
	v_mfma_f32_16x16x32_bf16 v[62:65], v[30:33], v[62:65], v[58:61]
	s_setprio 0
	v_lshl_add_u64 v[136:137], s[38:39], 0, v[130:131]
	s_add_i32 s60, s56, s21
	v_mov_b32_e32 v135, v131
	v_lshl_add_u64 v[142:143], v[136:137], 0, s[10:11]
	s_mov_b32 m0, s60
	v_lshl_add_u64 v[244:245], s[38:39], 0, v[134:135]
	ds_read_b128 v[34:37], v141 offset:16384
	ds_read_b128 v[42:45], v141 offset:17408
	ds_read_b128 v[50:53], v141 offset:18432
	ds_read_b128 v[58:61], v141 offset:19456
	ds_read_b128 v[114:117], v141 offset:20480
	ds_read_b128 v[118:121], v141 offset:21504
	ds_read_b128 v[122:125], v141 offset:22528
	ds_read_b128 v[126:129], v141 offset:23552
	global_load_lds_dwordx4 v[142:143], off
	v_lshl_add_u64 v[142:143], v[244:245], 0, s[10:11]
	s_add_i32 m0, s60, 0x2000
	s_add_i32 s60, s57, s21
	global_load_lds_dwordx4 v[142:143], off
	s_mov_b32 m0, s60
	v_mov_b32_e32 v139, v131
	global_load_lds_dwordx4 v130, s[40:41]
	s_add_i32 m0, s60, 0x2000
	v_lshl_add_u64 v[246:247], s[36:37], 0, v[138:139]
	v_mov_b32_e32 v133, v131
	global_load_lds_dwordx4 v134, s[40:41]
	v_lshl_add_u64 v[142:143], v[246:247], 0, s[10:11]
	s_mov_b32 m0, s33
	v_lshl_add_u64 v[248:249], s[36:37], 0, v[132:133]
	global_load_lds_dwordx4 v[142:143], off
	v_lshl_add_u64 v[142:143], v[248:249], 0, s[10:11]
	s_mov_b32 m0, s46
	s_nop 0
	global_load_lds_dwordx4 v[142:143], off
	s_waitcnt vmcnt(8)
	s_waitcnt lgkmcnt(0)
	s_barrier
	s_setprio 1
	s_waitcnt lgkmcnt(0)
	v_mfma_f32_16x16x32_bf16 v[142:145], v[2:5], v[34:37], 0
	v_mfma_f32_16x16x32_bf16 v[148:151], v[10:13], v[34:37], 0
	v_mfma_f32_16x16x32_bf16 v[152:155], v[2:5], v[50:53], 0
	v_mfma_f32_16x16x32_bf16 v[156:159], v[10:13], v[50:53], 0
	v_mfma_f32_16x16x32_bf16 v[160:163], v[2:5], v[114:117], 0
	v_mfma_f32_16x16x32_bf16 v[164:167], v[10:13], v[114:117], 0
	v_mfma_f32_16x16x32_bf16 v[2:5], v[2:5], v[122:125], 0
	v_mfma_f32_16x16x32_bf16 v[10:13], v[10:13], v[122:125], 0
	v_mfma_f32_16x16x32_bf16 v[142:145], v[6:9], v[42:45], v[142:145]
	v_mfma_f32_16x16x32_bf16 v[148:151], v[14:17], v[42:45], v[148:151]
	v_mfma_f32_16x16x32_bf16 v[152:155], v[6:9], v[58:61], v[152:155]
	v_mfma_f32_16x16x32_bf16 v[156:159], v[14:17], v[58:61], v[156:159]
	v_mfma_f32_16x16x32_bf16 v[160:163], v[6:9], v[118:121], v[160:163]
	v_mfma_f32_16x16x32_bf16 v[164:167], v[14:17], v[118:121], v[164:167]
	v_mfma_f32_16x16x32_bf16 v[168:171], v[6:9], v[126:129], v[2:5]
	v_mfma_f32_16x16x32_bf16 v[172:175], v[14:17], v[126:129], v[10:13]
	v_mfma_f32_16x16x32_bf16 v[2:5], v[18:21], v[34:37], 0
	v_mfma_f32_16x16x32_bf16 v[6:9], v[26:29], v[34:37], 0
	v_mfma_f32_16x16x32_bf16 v[10:13], v[18:21], v[50:53], 0
	v_mfma_f32_16x16x32_bf16 v[14:17], v[26:29], v[50:53], 0
	v_mfma_f32_16x16x32_bf16 v[34:37], v[18:21], v[114:117], 0
	v_mfma_f32_16x16x32_bf16 v[50:53], v[26:29], v[114:117], 0
	v_mfma_f32_16x16x32_bf16 v[18:21], v[18:21], v[122:125], 0
	v_mfma_f32_16x16x32_bf16 v[26:29], v[26:29], v[122:125], 0
	v_mfma_f32_16x16x32_bf16 v[114:117], v[22:25], v[42:45], v[2:5]
	v_mfma_f32_16x16x32_bf16 v[188:191], v[22:25], v[118:121], v[34:37]
	v_mfma_f32_16x16x32_bf16 v[118:121], v[30:33], v[118:121], v[50:53]
	v_mfma_f32_16x16x32_bf16 v[176:179], v[30:33], v[42:45], v[6:9]
	v_mfma_f32_16x16x32_bf16 v[180:183], v[22:25], v[58:61], v[10:13]
	v_mfma_f32_16x16x32_bf16 v[184:187], v[30:33], v[58:61], v[14:17]
	s_setprio 2
	s_barrier
	v_mfma_f32_16x16x32_bf16 v[192:195], v[22:25], v[126:129], v[18:21]
	v_mfma_f32_16x16x32_bf16 v[196:199], v[30:33], v[126:129], v[26:29]
	s_setprio 0
	s_add_i32 s60, 0, 0x18000
	v_add_u32_e32 v2, s60, v140
	s_add_i32 s61, 0, 0x1c000
	ds_read_b128 v[200:203], v2
	ds_read_b128 v[204:207], v2 offset:1024
	ds_read_b128 v[208:211], v2 offset:2048
	ds_read_b128 v[212:215], v2 offset:3072
	v_add_u32_e32 v2, s61, v140
	ds_read_b128 v[216:219], v2
	ds_read_b128 v[220:223], v2 offset:1024
	ds_read_b128 v[224:227], v2 offset:2048
	ds_read_b128 v[228:231], v2 offset:3072
	s_mov_b32 m0, s47
	ds_read_b128 v[42:45], v141 offset:32768
	ds_read_b128 v[50:53], v141 offset:33792
	ds_read_b128 v[58:61], v141 offset:34816
	ds_read_b128 v[122:125], v141 offset:35840
	ds_read_b128 v[126:129], v141 offset:36864
	ds_read_b128 v[232:235], v141 offset:37888
	ds_read_b128 v[236:239], v141 offset:38912
	ds_read_b128 v[240:243], v141 offset:39936
	global_load_lds_dwordx4 v138, s[42:43]
	s_mov_b32 m0, s48
	s_nop 0
	global_load_lds_dwordx4 v132, s[42:43]
	s_waitcnt vmcnt(8)
	s_waitcnt lgkmcnt(0)
	s_barrier
	s_setprio 1
	s_waitcnt lgkmcnt(0)
	v_mfma_f32_16x16x32_bf16 v[2:5], v[200:203], v[42:45], v[66:69]
	v_mfma_f32_16x16x32_bf16 v[6:9], v[208:211], v[42:45], v[70:73]
	v_mfma_f32_16x16x32_bf16 v[10:13], v[200:203], v[58:61], v[74:77]
	v_mfma_f32_16x16x32_bf16 v[14:17], v[208:211], v[58:61], v[78:81]
	v_mfma_f32_16x16x32_bf16 v[18:21], v[200:203], v[126:129], v[82:85]
	v_mfma_f32_16x16x32_bf16 v[22:25], v[208:211], v[126:129], v[86:89]
	v_mfma_f32_16x16x32_bf16 v[26:29], v[200:203], v[236:239], v[90:93]
	v_mfma_f32_16x16x32_bf16 v[30:33], v[208:211], v[236:239], v[94:97]
	v_mfma_f32_16x16x32_bf16 v[2:5], v[204:207], v[50:53], v[2:5]
	v_mfma_f32_16x16x32_bf16 v[6:9], v[212:215], v[50:53], v[6:9]
	v_mfma_f32_16x16x32_bf16 v[10:13], v[204:207], v[122:125], v[10:13]
	v_mfma_f32_16x16x32_bf16 v[14:17], v[212:215], v[122:125], v[14:17]
	v_mfma_f32_16x16x32_bf16 v[18:21], v[204:207], v[232:235], v[18:21]
	v_mfma_f32_16x16x32_bf16 v[22:25], v[212:215], v[232:235], v[22:25]
	v_mfma_f32_16x16x32_bf16 v[26:29], v[204:207], v[240:243], v[26:29]
	v_mfma_f32_16x16x32_bf16 v[30:33], v[212:215], v[240:243], v[30:33]
	v_mfma_f32_16x16x32_bf16 v[34:37], v[216:219], v[42:45], v[98:101]
	v_mfma_f32_16x16x32_bf16 v[38:41], v[224:227], v[42:45], v[38:41]
	v_mfma_f32_16x16x32_bf16 v[34:37], v[220:223], v[50:53], v[34:37]
	v_mfma_f32_16x16x32_bf16 v[38:41], v[228:231], v[50:53], v[38:41]
	v_mfma_f32_16x16x32_bf16 v[42:45], v[216:219], v[58:61], v[102:105]
	v_mfma_f32_16x16x32_bf16 v[46:49], v[224:227], v[58:61], v[46:49]
	v_mfma_f32_16x16x32_bf16 v[50:53], v[216:219], v[126:129], v[106:109]
	v_mfma_f32_16x16x32_bf16 v[54:57], v[224:227], v[126:129], v[54:57]
	v_mfma_f32_16x16x32_bf16 v[58:61], v[216:219], v[236:239], v[110:113]
	v_mfma_f32_16x16x32_bf16 v[62:65], v[224:227], v[236:239], v[62:65]
	v_mfma_f32_16x16x32_bf16 v[42:45], v[220:223], v[122:125], v[42:45]
	v_mfma_f32_16x16x32_bf16 v[46:49], v[228:231], v[122:125], v[46:49]
	v_mfma_f32_16x16x32_bf16 v[50:53], v[220:223], v[232:235], v[50:53]
	v_mfma_f32_16x16x32_bf16 v[54:57], v[228:231], v[232:235], v[54:57]
	s_setprio 2
	s_barrier
	v_mfma_f32_16x16x32_bf16 v[58:61], v[220:223], v[240:243], v[58:61]
	v_mfma_f32_16x16x32_bf16 v[62:65], v[228:231], v[240:243], v[62:65]
	s_setprio 0
	s_add_i32 s60, s60, s21
	v_lshl_add_u64 v[66:67], v[136:137], 0, s[12:13]
	s_mov_b32 m0, s60
	ds_read_b128 v[94:97], v141 offset:49152
	ds_read_b128 v[98:101], v141 offset:50176
	ds_read_b128 v[102:105], v141 offset:51200
	ds_read_b128 v[106:109], v141 offset:52224
	ds_read_b128 v[110:113], v141 offset:53248
	ds_read_b128 v[232:235], v141 offset:54272
	ds_read_b128 v[236:239], v141 offset:55296
	ds_read_b128 v[240:243], v141 offset:56320
	global_load_lds_dwordx4 v[66:67], off
	v_lshl_add_u64 v[66:67], v[244:245], 0, s[12:13]
	s_add_i32 m0, s60, 0x2000
	s_add_i32 s60, s61, s21
	global_load_lds_dwordx4 v[66:67], off
	s_mov_b32 m0, s60
	v_lshl_add_u64 v[66:67], v[246:247], 0, s[12:13]
	global_load_lds_dwordx4 v130, s[44:45]
	s_add_i32 m0, s60, 0x2000
	s_nop 0
	global_load_lds_dwordx4 v134, s[44:45]
	s_mov_b32 m0, s52
	s_nop 0
	global_load_lds_dwordx4 v[66:67], off
	v_lshl_add_u64 v[66:67], v[248:249], 0, s[12:13]
	s_mov_b32 m0, s53
	s_nop 0
	global_load_lds_dwordx4 v[66:67], off
	s_waitcnt vmcnt(8)
	s_waitcnt lgkmcnt(0)
	s_barrier
	s_setprio 1
	s_waitcnt lgkmcnt(0)
	v_mfma_f32_16x16x32_bf16 v[66:69], v[200:203], v[94:97], v[142:145]
	v_mfma_f32_16x16x32_bf16 v[122:125], v[204:207], v[98:101], v[66:69]
	v_mfma_f32_16x16x32_bf16 v[66:69], v[208:211], v[94:97], v[148:151]
	v_mfma_f32_16x16x32_bf16 v[126:129], v[212:215], v[98:101], v[66:69]
	v_mfma_f32_16x16x32_bf16 v[66:69], v[200:203], v[102:105], v[152:155]
	v_mfma_f32_16x16x32_bf16 v[70:73], v[208:211], v[102:105], v[156:159]
	v_mfma_f32_16x16x32_bf16 v[74:77], v[200:203], v[110:113], v[160:163]
	v_mfma_f32_16x16x32_bf16 v[78:81], v[208:211], v[110:113], v[164:167]
	v_mfma_f32_16x16x32_bf16 v[82:85], v[200:203], v[236:239], v[168:171]
	v_mfma_f32_16x16x32_bf16 v[86:89], v[208:211], v[236:239], v[172:175]
	v_mfma_f32_16x16x32_bf16 v[66:69], v[204:207], v[106:109], v[66:69]
	v_mfma_f32_16x16x32_bf16 v[70:73], v[212:215], v[106:109], v[70:73]
	v_mfma_f32_16x16x32_bf16 v[74:77], v[204:207], v[232:235], v[74:77]
	v_mfma_f32_16x16x32_bf16 v[78:81], v[212:215], v[232:235], v[78:81]
	v_mfma_f32_16x16x32_bf16 v[82:85], v[204:207], v[240:243], v[82:85]
	v_mfma_f32_16x16x32_bf16 v[86:89], v[212:215], v[240:243], v[86:89]
	v_mfma_f32_16x16x32_bf16 v[90:93], v[216:219], v[94:97], v[114:117]
	v_mfma_f32_16x16x32_bf16 v[94:97], v[224:227], v[94:97], v[176:179]
	v_mfma_f32_16x16x32_bf16 v[90:93], v[220:223], v[98:101], v[90:93]
	v_mfma_f32_16x16x32_bf16 v[94:97], v[228:231], v[98:101], v[94:97]
	v_mfma_f32_16x16x32_bf16 v[98:101], v[216:219], v[102:105], v[180:183]
	v_mfma_f32_16x16x32_bf16 v[102:105], v[224:227], v[102:105], v[184:187]
	v_mfma_f32_16x16x32_bf16 v[98:101], v[220:223], v[106:109], v[98:101]
	v_mfma_f32_16x16x32_bf16 v[102:105], v[228:231], v[106:109], v[102:105]
	v_mfma_f32_16x16x32_bf16 v[106:109], v[216:219], v[110:113], v[188:191]
	v_mfma_f32_16x16x32_bf16 v[110:113], v[224:227], v[110:113], v[118:121]
	v_mfma_f32_16x16x32_bf16 v[114:117], v[216:219], v[236:239], v[192:195]
	v_mfma_f32_16x16x32_bf16 v[118:121], v[224:227], v[236:239], v[196:199]
	v_mfma_f32_16x16x32_bf16 v[106:109], v[220:223], v[232:235], v[106:109]
	v_mfma_f32_16x16x32_bf16 v[110:113], v[228:231], v[232:235], v[110:113]
	s_setprio 2
	s_barrier
	v_mfma_f32_16x16x32_bf16 v[114:117], v[220:223], v[240:243], v[114:117]
	v_mfma_f32_16x16x32_bf16 v[118:121], v[228:231], v[240:243], v[118:121]
	s_setprio 0
	s_add_i32 s59, s59, 2
	s_cmp_ge_i32 s59, s15
	s_cbranch_scc0 .LBB0_379
	v_mov_b32_e32 v136, v130
	s_branch .LBB0_382

.LBB0_383:
	v_add_u32_e32 v133, s56, v140
	ds_read_b128 v[142:145], v133
	ds_read_b128 v[148:151], v133 offset:1024
	ds_read_b128 v[152:155], v133 offset:2048
	ds_read_b128 v[156:159], v133 offset:3072
	v_add_u32_e32 v133, s57, v140
	ds_read_b128 v[160:163], v133
	ds_read_b128 v[164:167], v133 offset:1024
	ds_read_b128 v[168:171], v133 offset:2048
	ds_read_b128 v[172:175], v133 offset:3072
	s_add_u32 s38, s36, 0xfff80080
	s_addc_u32 s39, s37, -1
	s_cmp_eq_u32 s43, 28
	s_cselect_b32 s41, s31, s39
	s_cselect_b32 s40, s30, s38
	s_cselect_b32 s39, s35, s42
	s_cselect_b32 s38, s34, s15
	s_mov_b32 m0, s54
	v_add_u32_e32 v141, 0, v1
	ds_read_b128 v[176:179], v141
	ds_read_b128 v[180:183], v141 offset:1024
	ds_read_b128 v[184:187], v141 offset:2048
	ds_read_b128 v[188:191], v141 offset:3072
	ds_read_b128 v[192:195], v141 offset:4096
	ds_read_b128 v[196:199], v141 offset:5120
	ds_read_b128 v[200:203], v141 offset:6144
	ds_read_b128 v[204:207], v141 offset:7168
	global_load_lds_dwordx4 v130, s[36:37]
	s_mov_b32 m0, s55
	v_mov_b32_e32 v133, v131
	global_load_lds_dwordx4 v132, s[36:37]
	s_waitcnt vmcnt(8)
	s_waitcnt lgkmcnt(0)
	s_barrier
	s_setprio 1
	s_waitcnt lgkmcnt(0)
	v_mfma_f32_16x16x32_bf16 v[2:5], v[142:145], v[176:179], v[2:5]
	v_mfma_f32_16x16x32_bf16 v[2:5], v[148:151], v[180:183], v[2:5]
	v_mfma_f32_16x16x32_bf16 v[6:9], v[156:159], v[180:183], v[6:9]
	v_mfma_f32_16x16x32_bf16 v[6:9], v[152:155], v[176:179], v[6:9]
	v_mfma_f32_16x16x32_bf16 v[14:17], v[152:155], v[184:187], v[14:17]
	v_mfma_f32_16x16x32_bf16 v[14:17], v[156:159], v[188:191], v[14:17]
	v_mfma_f32_16x16x32_bf16 v[10:13], v[148:151], v[188:191], v[10:13]
	v_mfma_f32_16x16x32_bf16 v[10:13], v[142:145], v[184:187], v[10:13]
	v_mfma_f32_16x16x32_bf16 v[18:21], v[142:145], v[192:195], v[18:21]
	v_mfma_f32_16x16x32_bf16 v[18:21], v[148:151], v[196:199], v[18:21]
	v_mfma_f32_16x16x32_bf16 v[22:25], v[156:159], v[196:199], v[22:25]
	v_mfma_f32_16x16x32_bf16 v[22:25], v[152:155], v[192:195], v[22:25]
	v_mfma_f32_16x16x32_bf16 v[30:33], v[152:155], v[200:203], v[30:33]
	v_mfma_f32_16x16x32_bf16 v[30:33], v[156:159], v[204:207], v[30:33]
	v_mfma_f32_16x16x32_bf16 v[26:29], v[148:151], v[204:207], v[26:29]
	v_mfma_f32_16x16x32_bf16 v[26:29], v[142:145], v[200:203], v[26:29]
	v_mfma_f32_16x16x32_bf16 v[34:37], v[160:163], v[176:179], v[34:37]
	v_mfma_f32_16x16x32_bf16 v[34:37], v[164:167], v[180:183], v[34:37]
	v_mfma_f32_16x16x32_bf16 v[38:41], v[172:175], v[180:183], v[38:41]
	v_mfma_f32_16x16x32_bf16 v[38:41], v[168:171], v[176:179], v[38:41]
	v_mfma_f32_16x16x32_bf16 v[46:49], v[168:171], v[184:187], v[46:49]
	v_mfma_f32_16x16x32_bf16 v[46:49], v[172:175], v[188:191], v[46:49]
	v_mfma_f32_16x16x32_bf16 v[42:45], v[164:167], v[188:191], v[42:45]
	v_mfma_f32_16x16x32_bf16 v[42:45], v[160:163], v[184:187], v[42:45]
	v_mfma_f32_16x16x32_bf16 v[50:53], v[160:163], v[192:195], v[50:53]
	v_mfma_f32_16x16x32_bf16 v[50:53], v[164:167], v[196:199], v[50:53]
	v_mfma_f32_16x16x32_bf16 v[54:57], v[172:175], v[196:199], v[54:57]
	v_mfma_f32_16x16x32_bf16 v[54:57], v[168:171], v[192:195], v[54:57]
	v_mfma_f32_16x16x32_bf16 v[62:65], v[168:171], v[200:203], v[62:65]
	v_mfma_f32_16x16x32_bf16 v[62:65], v[172:175], v[204:207], v[62:65]
	s_setprio 2
	s_barrier
	v_mfma_f32_16x16x32_bf16 v[58:61], v[164:167], v[204:207], v[58:61]
	v_mfma_f32_16x16x32_bf16 v[58:61], v[160:163], v[200:203], v[58:61]
	s_setprio 0
	s_add_i32 s44, s56, s21
	s_mov_b32 m0, s44
	ds_read_b128 v[176:179], v141 offset:16384
	ds_read_b128 v[180:183], v141 offset:17408
	ds_read_b128 v[184:187], v141 offset:18432
	ds_read_b128 v[188:191], v141 offset:19456
	ds_read_b128 v[192:195], v141 offset:20480
	ds_read_b128 v[196:199], v141 offset:21504
	ds_read_b128 v[200:203], v141 offset:22528
	ds_read_b128 v[204:207], v141 offset:23552
	global_load_lds_dwordx4 v136, s[38:39]
	s_add_i32 m0, s44, 0x2000
	s_add_u32 s44, s38, 0x80000
	s_addc_u32 s45, s39, 0
	s_add_i32 s59, s57, s21
	global_load_lds_dwordx4 v134, s[38:39]
	s_mov_b32 m0, s59
	v_mov_b32_e32 v137, v131
	global_load_lds_dwordx4 v136, s[44:45]
	s_add_i32 m0, s59, 0x2000
	v_mov_b32_e32 v135, v131
	global_load_lds_dwordx4 v134, s[44:45]
	s_mov_b32 m0, s33
	v_lshl_add_u64 v[138:139], s[38:39], 0, v[136:137]
	global_load_lds_dwordx4 v130, s[40:41]
	s_mov_b32 m0, s46
	v_lshl_add_u64 v[208:209], s[38:39], 0, v[134:135]
	global_load_lds_dwordx4 v132, s[40:41]
	s_waitcnt vmcnt(8)
	s_waitcnt lgkmcnt(0)
	v_lshl_add_u64 v[210:211], s[40:41], 0, v[130:131]
	v_lshl_add_u64 v[212:213], s[40:41], 0, v[132:133]
	s_barrier
	s_setprio 1
	s_waitcnt lgkmcnt(0)
	v_mfma_f32_16x16x32_bf16 v[122:125], v[142:145], v[176:179], v[122:125]
	v_mfma_f32_16x16x32_bf16 v[122:125], v[148:151], v[180:183], v[122:125]
	v_mfma_f32_16x16x32_bf16 v[126:129], v[156:159], v[180:183], v[126:129]
	v_mfma_f32_16x16x32_bf16 v[126:129], v[152:155], v[176:179], v[126:129]
	v_mfma_f32_16x16x32_bf16 v[70:73], v[152:155], v[184:187], v[70:73]
	v_mfma_f32_16x16x32_bf16 v[70:73], v[156:159], v[188:191], v[70:73]
	v_mfma_f32_16x16x32_bf16 v[66:69], v[148:151], v[188:191], v[66:69]
	v_mfma_f32_16x16x32_bf16 v[66:69], v[142:145], v[184:187], v[66:69]
	v_mfma_f32_16x16x32_bf16 v[74:77], v[142:145], v[192:195], v[74:77]
	v_mfma_f32_16x16x32_bf16 v[74:77], v[148:151], v[196:199], v[74:77]
	v_mfma_f32_16x16x32_bf16 v[78:81], v[156:159], v[196:199], v[78:81]
	v_mfma_f32_16x16x32_bf16 v[78:81], v[152:155], v[192:195], v[78:81]
	v_mfma_f32_16x16x32_bf16 v[86:89], v[152:155], v[200:203], v[86:89]
	v_mfma_f32_16x16x32_bf16 v[86:89], v[156:159], v[204:207], v[86:89]
	v_mfma_f32_16x16x32_bf16 v[82:85], v[148:151], v[204:207], v[82:85]
	v_mfma_f32_16x16x32_bf16 v[82:85], v[142:145], v[200:203], v[82:85]
	v_mfma_f32_16x16x32_bf16 v[90:93], v[160:163], v[176:179], v[90:93]
	v_mfma_f32_16x16x32_bf16 v[90:93], v[164:167], v[180:183], v[90:93]
	v_mfma_f32_16x16x32_bf16 v[94:97], v[172:175], v[180:183], v[94:97]
	v_mfma_f32_16x16x32_bf16 v[94:97], v[168:171], v[176:179], v[94:97]
	v_mfma_f32_16x16x32_bf16 v[102:105], v[168:171], v[184:187], v[102:105]
	v_mfma_f32_16x16x32_bf16 v[102:105], v[172:175], v[188:191], v[102:105]
	v_mfma_f32_16x16x32_bf16 v[98:101], v[164:167], v[188:191], v[98:101]
	v_mfma_f32_16x16x32_bf16 v[98:101], v[160:163], v[184:187], v[98:101]
	v_mfma_f32_16x16x32_bf16 v[106:109], v[160:163], v[192:195], v[106:109]
	v_mfma_f32_16x16x32_bf16 v[106:109], v[164:167], v[196:199], v[106:109]
	v_mfma_f32_16x16x32_bf16 v[110:113], v[172:175], v[196:199], v[110:113]
	v_mfma_f32_16x16x32_bf16 v[110:113], v[168:171], v[192:195], v[110:113]
	v_mfma_f32_16x16x32_bf16 v[118:121], v[168:171], v[200:203], v[118:121]
	v_mfma_f32_16x16x32_bf16 v[118:121], v[172:175], v[204:207], v[118:121]
	s_setprio 2
	s_barrier
	v_mfma_f32_16x16x32_bf16 v[114:117], v[164:167], v[204:207], v[114:117]
	v_mfma_f32_16x16x32_bf16 v[114:117], v[160:163], v[200:203], v[114:117]
	s_setprio 0
	s_add_i32 s44, 0, 0x18000
	v_add_u32_e32 v135, s44, v140
	s_add_i32 s45, 0, 0x1c000
	ds_read_b128 v[142:145], v135
	ds_read_b128 v[148:151], v135 offset:1024
	ds_read_b128 v[152:155], v135 offset:2048
	ds_read_b128 v[156:159], v135 offset:3072
	v_add_u32_e32 v135, s45, v140
	ds_read_b128 v[160:163], v135
	ds_read_b128 v[164:167], v135 offset:1024
	ds_read_b128 v[168:171], v135 offset:2048
	ds_read_b128 v[172:175], v135 offset:3072
	s_add_u32 s40, s40, 0x80000
	s_addc_u32 s41, s41, 0
	s_mov_b32 m0, s47
	ds_read_b128 v[176:179], v141 offset:32768
	ds_read_b128 v[180:183], v141 offset:33792
	ds_read_b128 v[184:187], v141 offset:34816
	ds_read_b128 v[188:191], v141 offset:35840
	ds_read_b128 v[192:195], v141 offset:36864
	ds_read_b128 v[196:199], v141 offset:37888
	ds_read_b128 v[200:203], v141 offset:38912
	ds_read_b128 v[204:207], v141 offset:39936
	global_load_lds_dwordx4 v130, s[40:41]
	s_mov_b32 m0, s48
	s_nop 0
	global_load_lds_dwordx4 v132, s[40:41]
	s_waitcnt vmcnt(8)
	s_waitcnt lgkmcnt(0)
	s_barrier
	s_setprio 1
	s_waitcnt lgkmcnt(0)
	v_mfma_f32_16x16x32_bf16 v[2:5], v[142:145], v[176:179], v[2:5]
	v_mfma_f32_16x16x32_bf16 v[2:5], v[148:151], v[180:183], v[2:5]
	v_mfma_f32_16x16x32_bf16 v[6:9], v[156:159], v[180:183], v[6:9]
	v_mfma_f32_16x16x32_bf16 v[6:9], v[152:155], v[176:179], v[6:9]
	v_mfma_f32_16x16x32_bf16 v[14:17], v[152:155], v[184:187], v[14:17]
	v_mfma_f32_16x16x32_bf16 v[14:17], v[156:159], v[188:191], v[14:17]
	v_mfma_f32_16x16x32_bf16 v[10:13], v[148:151], v[188:191], v[10:13]
	v_mfma_f32_16x16x32_bf16 v[10:13], v[142:145], v[184:187], v[10:13]
	v_mfma_f32_16x16x32_bf16 v[18:21], v[142:145], v[192:195], v[18:21]
	v_mfma_f32_16x16x32_bf16 v[18:21], v[148:151], v[196:199], v[18:21]
	v_mfma_f32_16x16x32_bf16 v[22:25], v[156:159], v[196:199], v[22:25]
	v_mfma_f32_16x16x32_bf16 v[22:25], v[152:155], v[192:195], v[22:25]
	v_mfma_f32_16x16x32_bf16 v[30:33], v[152:155], v[200:203], v[30:33]
	v_mfma_f32_16x16x32_bf16 v[30:33], v[156:159], v[204:207], v[30:33]
	v_mfma_f32_16x16x32_bf16 v[26:29], v[148:151], v[204:207], v[26:29]
	v_mfma_f32_16x16x32_bf16 v[26:29], v[142:145], v[200:203], v[26:29]
	v_mfma_f32_16x16x32_bf16 v[34:37], v[160:163], v[176:179], v[34:37]
	v_mfma_f32_16x16x32_bf16 v[34:37], v[164:167], v[180:183], v[34:37]
	v_mfma_f32_16x16x32_bf16 v[38:41], v[172:175], v[180:183], v[38:41]
	v_mfma_f32_16x16x32_bf16 v[38:41], v[168:171], v[176:179], v[38:41]
	v_mfma_f32_16x16x32_bf16 v[46:49], v[168:171], v[184:187], v[46:49]
	v_mfma_f32_16x16x32_bf16 v[46:49], v[172:175], v[188:191], v[46:49]
	v_mfma_f32_16x16x32_bf16 v[42:45], v[164:167], v[188:191], v[42:45]
	v_mfma_f32_16x16x32_bf16 v[42:45], v[160:163], v[184:187], v[42:45]
	v_mfma_f32_16x16x32_bf16 v[50:53], v[160:163], v[192:195], v[50:53]
	v_mfma_f32_16x16x32_bf16 v[50:53], v[164:167], v[196:199], v[50:53]
	v_mfma_f32_16x16x32_bf16 v[54:57], v[172:175], v[196:199], v[54:57]
	v_mfma_f32_16x16x32_bf16 v[54:57], v[168:171], v[192:195], v[54:57]
	v_mfma_f32_16x16x32_bf16 v[62:65], v[168:171], v[200:203], v[62:65]
	v_mfma_f32_16x16x32_bf16 v[62:65], v[172:175], v[204:207], v[62:65]
	s_setprio 2
	s_barrier
	v_mfma_f32_16x16x32_bf16 v[58:61], v[164:167], v[204:207], v[58:61]
	v_mfma_f32_16x16x32_bf16 v[58:61], v[160:163], v[200:203], v[58:61]
	s_setprio 0
	s_add_i32 s40, s44, s21
	v_lshl_add_u64 v[138:139], v[138:139], 0, s[6:7]
	s_mov_b32 m0, s40
	ds_read_b128 v[176:179], v141 offset:49152
	ds_read_b128 v[180:183], v141 offset:50176
	ds_read_b128 v[184:187], v141 offset:51200
	ds_read_b128 v[188:191], v141 offset:52224
	ds_read_b128 v[192:195], v141 offset:53248
	ds_read_b128 v[196:199], v141 offset:54272
	ds_read_b128 v[200:203], v141 offset:55296
	ds_read_b128 v[204:207], v141 offset:56320
	global_load_lds_dwordx4 v[138:139], off
	s_add_i32 m0, s40, 0x2000
	s_add_u32 s38, s38, 0x80080
	v_lshl_add_u64 v[138:139], v[208:209], 0, s[6:7]
	s_addc_u32 s39, s39, 0
	s_add_i32 s40, s45, s21
	global_load_lds_dwordx4 v[138:139], off
	s_mov_b32 m0, s40
	v_lshl_add_u64 v[138:139], v[210:211], 0, s[6:7]
	global_load_lds_dwordx4 v136, s[38:39]
	s_add_i32 m0, s40, 0x2000
	s_nop 0
	global_load_lds_dwordx4 v134, s[38:39]
	s_mov_b32 m0, s52
	s_nop 0
	global_load_lds_dwordx4 v[138:139], off
	v_lshl_add_u64 v[138:139], v[212:213], 0, s[6:7]
	s_mov_b32 m0, s53
	s_nop 0
	global_load_lds_dwordx4 v[138:139], off
	s_waitcnt vmcnt(8)
	s_waitcnt lgkmcnt(0)
	s_barrier
	s_setprio 1
	s_waitcnt lgkmcnt(0)
	v_mfma_f32_16x16x32_bf16 v[122:125], v[142:145], v[176:179], v[122:125]
	v_mfma_f32_16x16x32_bf16 v[122:125], v[148:151], v[180:183], v[122:125]
	v_mfma_f32_16x16x32_bf16 v[126:129], v[156:159], v[180:183], v[126:129]
	v_mfma_f32_16x16x32_bf16 v[126:129], v[152:155], v[176:179], v[126:129]
	v_mfma_f32_16x16x32_bf16 v[70:73], v[152:155], v[184:187], v[70:73]
	v_mfma_f32_16x16x32_bf16 v[70:73], v[156:159], v[188:191], v[70:73]
	v_mfma_f32_16x16x32_bf16 v[66:69], v[148:151], v[188:191], v[66:69]
	v_mfma_f32_16x16x32_bf16 v[66:69], v[142:145], v[184:187], v[66:69]
	v_mfma_f32_16x16x32_bf16 v[74:77], v[142:145], v[192:195], v[74:77]
	v_mfma_f32_16x16x32_bf16 v[74:77], v[148:151], v[196:199], v[74:77]
	v_mfma_f32_16x16x32_bf16 v[78:81], v[156:159], v[196:199], v[78:81]
	v_mfma_f32_16x16x32_bf16 v[78:81], v[152:155], v[192:195], v[78:81]
	v_mfma_f32_16x16x32_bf16 v[86:89], v[152:155], v[200:203], v[86:89]
	v_mfma_f32_16x16x32_bf16 v[86:89], v[156:159], v[204:207], v[86:89]
	v_mfma_f32_16x16x32_bf16 v[82:85], v[148:151], v[204:207], v[82:85]
	v_mfma_f32_16x16x32_bf16 v[82:85], v[142:145], v[200:203], v[82:85]
	v_mfma_f32_16x16x32_bf16 v[90:93], v[160:163], v[176:179], v[90:93]
	v_mfma_f32_16x16x32_bf16 v[90:93], v[164:167], v[180:183], v[90:93]
	v_mfma_f32_16x16x32_bf16 v[94:97], v[172:175], v[180:183], v[94:97]
	v_mfma_f32_16x16x32_bf16 v[94:97], v[168:171], v[176:179], v[94:97]
	v_mfma_f32_16x16x32_bf16 v[102:105], v[168:171], v[184:187], v[102:105]
	v_mfma_f32_16x16x32_bf16 v[102:105], v[172:175], v[188:191], v[102:105]
	v_mfma_f32_16x16x32_bf16 v[98:101], v[164:167], v[188:191], v[98:101]
	v_mfma_f32_16x16x32_bf16 v[98:101], v[160:163], v[184:187], v[98:101]
	v_mfma_f32_16x16x32_bf16 v[106:109], v[160:163], v[192:195], v[106:109]
	v_mfma_f32_16x16x32_bf16 v[106:109], v[164:167], v[196:199], v[106:109]
	v_mfma_f32_16x16x32_bf16 v[110:113], v[172:175], v[196:199], v[110:113]
	v_mfma_f32_16x16x32_bf16 v[110:113], v[168:171], v[192:195], v[110:113]
	v_mfma_f32_16x16x32_bf16 v[118:121], v[168:171], v[200:203], v[118:121]
	v_mfma_f32_16x16x32_bf16 v[118:121], v[172:175], v[204:207], v[118:121]
	s_setprio 2
	s_barrier
	v_mfma_f32_16x16x32_bf16 v[114:117], v[164:167], v[204:207], v[114:117]
	v_mfma_f32_16x16x32_bf16 v[114:117], v[160:163], v[200:203], v[114:117]
	s_setprio 0
	s_add_i32 s43, s43, 2
	s_add_u32 s36, s36, 0x100
	s_addc_u32 s37, s37, 0
	s_add_u32 s15, s15, 0x100
	s_addc_u32 s42, s42, 0
	s_cmp_gt_u32 s43, 29
	s_cbranch_scc0 .LBB0_383
	s_and_b64 vcc, exec, s[8:9]
	s_cbranch_vccz .LBB0_386
	s_barrier

.LBB0_462:
	v_add_u32_e32 v14, s54, v140
	v_add_u32_e32 v30, s55, v140
	ds_read_b128 v[2:5], v14
	ds_read_b128 v[6:9], v14 offset:1024
	ds_read_b128 v[10:13], v14 offset:2048
	ds_read_b128 v[14:17], v14 offset:3072
	ds_read_b128 v[18:21], v30
	ds_read_b128 v[22:25], v30 offset:1024
	ds_read_b128 v[26:29], v30 offset:2048
	ds_read_b128 v[30:33], v30 offset:3072
	v_add_u32_e32 v141, 0, v1
	ds_read_b128 v[34:37], v141
	ds_read_b128 v[38:41], v141 offset:1024
	ds_read_b128 v[42:45], v141 offset:2048
	ds_read_b128 v[46:49], v141 offset:3072
	ds_read_b128 v[50:53], v141 offset:4096
	ds_read_b128 v[54:57], v141 offset:5120
	ds_read_b128 v[58:61], v141 offset:6144
	ds_read_b128 v[62:65], v141 offset:7168
	s_waitcnt vmcnt(8)
	s_waitcnt lgkmcnt(0)
	s_barrier
	s_setprio 1
	s_waitcnt lgkmcnt(0)
	v_mfma_f32_16x16x32_bf16 v[66:69], v[2:5], v[34:37], 0
	v_mfma_f32_16x16x32_bf16 v[66:69], v[6:9], v[38:41], v[66:69]
	v_mfma_f32_16x16x32_bf16 v[70:73], v[10:13], v[34:37], 0
	v_mfma_f32_16x16x32_bf16 v[70:73], v[14:17], v[38:41], v[70:73]
	v_mfma_f32_16x16x32_bf16 v[78:81], v[10:13], v[42:45], 0
	v_mfma_f32_16x16x32_bf16 v[78:81], v[14:17], v[46:49], v[78:81]
	v_mfma_f32_16x16x32_bf16 v[74:77], v[2:5], v[42:45], 0
	v_mfma_f32_16x16x32_bf16 v[74:77], v[6:9], v[46:49], v[74:77]
	v_mfma_f32_16x16x32_bf16 v[82:85], v[2:5], v[50:53], 0
	v_mfma_f32_16x16x32_bf16 v[82:85], v[6:9], v[54:57], v[82:85]
	v_mfma_f32_16x16x32_bf16 v[86:89], v[10:13], v[50:53], 0
	v_mfma_f32_16x16x32_bf16 v[86:89], v[14:17], v[54:57], v[86:89]
	v_mfma_f32_16x16x32_bf16 v[94:97], v[10:13], v[58:61], 0
	v_mfma_f32_16x16x32_bf16 v[94:97], v[14:17], v[62:65], v[94:97]
	v_mfma_f32_16x16x32_bf16 v[90:93], v[2:5], v[58:61], 0
	v_mfma_f32_16x16x32_bf16 v[90:93], v[6:9], v[62:65], v[90:93]
	v_mfma_f32_16x16x32_bf16 v[98:101], v[18:21], v[34:37], 0
	v_mfma_f32_16x16x32_bf16 v[34:37], v[26:29], v[34:37], 0
	v_mfma_f32_16x16x32_bf16 v[102:105], v[18:21], v[42:45], 0
	v_mfma_f32_16x16x32_bf16 v[42:45], v[26:29], v[42:45], 0
	v_mfma_f32_16x16x32_bf16 v[106:109], v[18:21], v[50:53], 0
	v_mfma_f32_16x16x32_bf16 v[50:53], v[26:29], v[50:53], 0
	v_mfma_f32_16x16x32_bf16 v[110:113], v[18:21], v[58:61], 0
	v_mfma_f32_16x16x32_bf16 v[58:61], v[26:29], v[58:61], 0
	v_mfma_f32_16x16x32_bf16 v[98:101], v[22:25], v[38:41], v[98:101]
	v_mfma_f32_16x16x32_bf16 v[38:41], v[30:33], v[38:41], v[34:37]
	v_mfma_f32_16x16x32_bf16 v[102:105], v[22:25], v[46:49], v[102:105]
	v_mfma_f32_16x16x32_bf16 v[46:49], v[30:33], v[46:49], v[42:45]
	v_mfma_f32_16x16x32_bf16 v[106:109], v[22:25], v[54:57], v[106:109]
	v_mfma_f32_16x16x32_bf16 v[54:57], v[30:33], v[54:57], v[50:53]
	s_setprio 2
	s_barrier
	v_mfma_f32_16x16x32_bf16 v[110:113], v[22:25], v[62:65], v[110:113]
	v_mfma_f32_16x16x32_bf16 v[62:65], v[30:33], v[62:65], v[58:61]
	s_setprio 0
	v_lshl_add_u64 v[136:137], s[36:37], 0, v[130:131]
	s_add_i32 s62, s54, s21
	v_mov_b32_e32 v135, v131
	v_lshl_add_u64 v[142:143], v[136:137], 0, s[12:13]
	s_mov_b32 m0, s62
	v_lshl_add_u64 v[244:245], s[36:37], 0, v[134:135]
	ds_read_b128 v[34:37], v141 offset:16384
	ds_read_b128 v[42:45], v141 offset:17408
	ds_read_b128 v[50:53], v141 offset:18432
	ds_read_b128 v[58:61], v141 offset:19456
	ds_read_b128 v[114:117], v141 offset:20480
	ds_read_b128 v[118:121], v141 offset:21504
	ds_read_b128 v[122:125], v141 offset:22528
	ds_read_b128 v[126:129], v141 offset:23552
	global_load_lds_dwordx4 v[142:143], off
	v_lshl_add_u64 v[142:143], v[244:245], 0, s[12:13]
	s_add_i32 m0, s62, 0x2000
	s_add_i32 s62, s55, s21
	global_load_lds_dwordx4 v[142:143], off
	s_mov_b32 m0, s62
	v_mov_b32_e32 v139, v131
	global_load_lds_dwordx4 v130, s[38:39]
	s_add_i32 m0, s62, 0x2000
	v_lshl_add_u64 v[246:247], s[34:35], 0, v[138:139]
	v_mov_b32_e32 v133, v131
	global_load_lds_dwordx4 v134, s[38:39]
	v_lshl_add_u64 v[142:143], v[246:247], 0, s[12:13]
	s_mov_b32 m0, s33
	v_lshl_add_u64 v[248:249], s[34:35], 0, v[132:133]
	global_load_lds_dwordx4 v[142:143], off
	v_lshl_add_u64 v[142:143], v[248:249], 0, s[12:13]
	s_mov_b32 m0, s44
	s_nop 0
	global_load_lds_dwordx4 v[142:143], off
	s_waitcnt vmcnt(8)
	s_waitcnt lgkmcnt(0)
	s_barrier
	s_setprio 1
	s_waitcnt lgkmcnt(0)
	v_mfma_f32_16x16x32_bf16 v[142:145], v[2:5], v[34:37], 0
	v_mfma_f32_16x16x32_bf16 v[148:151], v[10:13], v[34:37], 0
	v_mfma_f32_16x16x32_bf16 v[152:155], v[2:5], v[50:53], 0
	v_mfma_f32_16x16x32_bf16 v[156:159], v[10:13], v[50:53], 0
	v_mfma_f32_16x16x32_bf16 v[160:163], v[2:5], v[114:117], 0
	v_mfma_f32_16x16x32_bf16 v[164:167], v[10:13], v[114:117], 0
	v_mfma_f32_16x16x32_bf16 v[2:5], v[2:5], v[122:125], 0
	v_mfma_f32_16x16x32_bf16 v[10:13], v[10:13], v[122:125], 0
	v_mfma_f32_16x16x32_bf16 v[142:145], v[6:9], v[42:45], v[142:145]
	v_mfma_f32_16x16x32_bf16 v[148:151], v[14:17], v[42:45], v[148:151]
	v_mfma_f32_16x16x32_bf16 v[152:155], v[6:9], v[58:61], v[152:155]
	v_mfma_f32_16x16x32_bf16 v[156:159], v[14:17], v[58:61], v[156:159]
	v_mfma_f32_16x16x32_bf16 v[160:163], v[6:9], v[118:121], v[160:163]
	v_mfma_f32_16x16x32_bf16 v[164:167], v[14:17], v[118:121], v[164:167]
	v_mfma_f32_16x16x32_bf16 v[168:171], v[6:9], v[126:129], v[2:5]
	v_mfma_f32_16x16x32_bf16 v[172:175], v[14:17], v[126:129], v[10:13]
	v_mfma_f32_16x16x32_bf16 v[2:5], v[18:21], v[34:37], 0
	v_mfma_f32_16x16x32_bf16 v[6:9], v[26:29], v[34:37], 0
	v_mfma_f32_16x16x32_bf16 v[10:13], v[18:21], v[50:53], 0
	v_mfma_f32_16x16x32_bf16 v[14:17], v[26:29], v[50:53], 0
	v_mfma_f32_16x16x32_bf16 v[34:37], v[18:21], v[114:117], 0
	v_mfma_f32_16x16x32_bf16 v[50:53], v[26:29], v[114:117], 0
	v_mfma_f32_16x16x32_bf16 v[18:21], v[18:21], v[122:125], 0
	v_mfma_f32_16x16x32_bf16 v[26:29], v[26:29], v[122:125], 0
	v_mfma_f32_16x16x32_bf16 v[114:117], v[22:25], v[42:45], v[2:5]
	v_mfma_f32_16x16x32_bf16 v[122:125], v[30:33], v[42:45], v[6:9]
	v_mfma_f32_16x16x32_bf16 v[184:187], v[22:25], v[118:121], v[34:37]
	v_mfma_f32_16x16x32_bf16 v[118:121], v[30:33], v[118:121], v[50:53]
	v_mfma_f32_16x16x32_bf16 v[188:191], v[22:25], v[126:129], v[18:21]
	v_mfma_f32_16x16x32_bf16 v[126:129], v[30:33], v[126:129], v[26:29]
	s_setprio 2
	s_barrier
	v_mfma_f32_16x16x32_bf16 v[176:179], v[22:25], v[58:61], v[10:13]
	v_mfma_f32_16x16x32_bf16 v[180:183], v[30:33], v[58:61], v[14:17]
	s_setprio 0
	s_add_i32 s62, 0, 0x18000
	v_add_u32_e32 v2, s62, v140
	s_add_i32 s63, 0, 0x1c000
	ds_read_b128 v[192:195], v2
	ds_read_b128 v[196:199], v2 offset:1024
	ds_read_b128 v[200:203], v2 offset:2048
	ds_read_b128 v[204:207], v2 offset:3072
	v_add_u32_e32 v2, s63, v140
	ds_read_b128 v[208:211], v2
	ds_read_b128 v[212:215], v2 offset:1024
	ds_read_b128 v[216:219], v2 offset:2048
	ds_read_b128 v[220:223], v2 offset:3072
	s_mov_b32 m0, s45
	ds_read_b128 v[42:45], v141 offset:32768
	ds_read_b128 v[50:53], v141 offset:33792
	ds_read_b128 v[58:61], v141 offset:34816
	ds_read_b128 v[224:227], v141 offset:35840
	ds_read_b128 v[228:231], v141 offset:36864
	ds_read_b128 v[232:235], v141 offset:37888
	ds_read_b128 v[236:239], v141 offset:38912
	ds_read_b128 v[240:243], v141 offset:39936
	global_load_lds_dwordx4 v138, s[40:41]
	s_mov_b32 m0, s46
	s_nop 0
	global_load_lds_dwordx4 v132, s[40:41]
	s_waitcnt vmcnt(8)
	s_waitcnt lgkmcnt(0)
	s_barrier
	s_setprio 1
	s_waitcnt lgkmcnt(0)
	v_mfma_f32_16x16x32_bf16 v[2:5], v[192:195], v[42:45], v[66:69]
	v_mfma_f32_16x16x32_bf16 v[6:9], v[200:203], v[42:45], v[70:73]
	v_mfma_f32_16x16x32_bf16 v[10:13], v[192:195], v[58:61], v[74:77]
	v_mfma_f32_16x16x32_bf16 v[14:17], v[200:203], v[58:61], v[78:81]
	v_mfma_f32_16x16x32_bf16 v[18:21], v[192:195], v[228:231], v[82:85]
	v_mfma_f32_16x16x32_bf16 v[22:25], v[200:203], v[228:231], v[86:89]
	v_mfma_f32_16x16x32_bf16 v[26:29], v[192:195], v[236:239], v[90:93]
	v_mfma_f32_16x16x32_bf16 v[30:33], v[200:203], v[236:239], v[94:97]
	v_mfma_f32_16x16x32_bf16 v[2:5], v[196:199], v[50:53], v[2:5]
	v_mfma_f32_16x16x32_bf16 v[6:9], v[204:207], v[50:53], v[6:9]
	v_mfma_f32_16x16x32_bf16 v[10:13], v[196:199], v[224:227], v[10:13]
	v_mfma_f32_16x16x32_bf16 v[14:17], v[204:207], v[224:227], v[14:17]
	v_mfma_f32_16x16x32_bf16 v[18:21], v[196:199], v[232:235], v[18:21]
	v_mfma_f32_16x16x32_bf16 v[22:25], v[204:207], v[232:235], v[22:25]
	v_mfma_f32_16x16x32_bf16 v[26:29], v[196:199], v[240:243], v[26:29]
	v_mfma_f32_16x16x32_bf16 v[30:33], v[204:207], v[240:243], v[30:33]
	v_mfma_f32_16x16x32_bf16 v[34:37], v[208:211], v[42:45], v[98:101]
	v_mfma_f32_16x16x32_bf16 v[38:41], v[216:219], v[42:45], v[38:41]
	v_mfma_f32_16x16x32_bf16 v[34:37], v[212:215], v[50:53], v[34:37]
	v_mfma_f32_16x16x32_bf16 v[38:41], v[220:223], v[50:53], v[38:41]
	v_mfma_f32_16x16x32_bf16 v[42:45], v[208:211], v[58:61], v[102:105]
	v_mfma_f32_16x16x32_bf16 v[46:49], v[216:219], v[58:61], v[46:49]
	v_mfma_f32_16x16x32_bf16 v[50:53], v[208:211], v[228:231], v[106:109]
	v_mfma_f32_16x16x32_bf16 v[54:57], v[216:219], v[228:231], v[54:57]
	v_mfma_f32_16x16x32_bf16 v[58:61], v[208:211], v[236:239], v[110:113]
	v_mfma_f32_16x16x32_bf16 v[62:65], v[216:219], v[236:239], v[62:65]
	v_mfma_f32_16x16x32_bf16 v[42:45], v[212:215], v[224:227], v[42:45]
	v_mfma_f32_16x16x32_bf16 v[46:49], v[220:223], v[224:227], v[46:49]
	v_mfma_f32_16x16x32_bf16 v[50:53], v[212:215], v[232:235], v[50:53]
	v_mfma_f32_16x16x32_bf16 v[54:57], v[220:223], v[232:235], v[54:57]
	s_setprio 2
	s_barrier
	v_mfma_f32_16x16x32_bf16 v[58:61], v[212:215], v[240:243], v[58:61]
	v_mfma_f32_16x16x32_bf16 v[62:65], v[220:223], v[240:243], v[62:65]
	s_setprio 0
	s_add_i32 s62, s62, s21
	v_lshl_add_u64 v[66:67], v[136:137], 0, s[14:15]
	s_mov_b32 m0, s62
	ds_read_b128 v[102:105], v141 offset:49152
	ds_read_b128 v[106:109], v141 offset:50176
	ds_read_b128 v[110:113], v141 offset:51200
	ds_read_b128 v[224:227], v141 offset:52224
	ds_read_b128 v[228:231], v141 offset:53248
	ds_read_b128 v[232:235], v141 offset:54272
	ds_read_b128 v[236:239], v141 offset:55296
	ds_read_b128 v[240:243], v141 offset:56320
	global_load_lds_dwordx4 v[66:67], off
	v_lshl_add_u64 v[66:67], v[244:245], 0, s[14:15]
	s_add_i32 m0, s62, 0x2000
	s_add_i32 s62, s63, s21
	global_load_lds_dwordx4 v[66:67], off
	s_mov_b32 m0, s62
	v_lshl_add_u64 v[66:67], v[246:247], 0, s[14:15]
	global_load_lds_dwordx4 v130, s[42:43]
	s_add_i32 m0, s62, 0x2000
	s_nop 0
	global_load_lds_dwordx4 v134, s[42:43]
	s_mov_b32 m0, s50
	s_nop 0
	global_load_lds_dwordx4 v[66:67], off
	v_lshl_add_u64 v[66:67], v[248:249], 0, s[14:15]
	s_mov_b32 m0, s51
	s_nop 0
	global_load_lds_dwordx4 v[66:67], off
	s_waitcnt vmcnt(8)
	s_waitcnt lgkmcnt(0)
	s_barrier
	s_setprio 1
	s_waitcnt lgkmcnt(0)
	v_mfma_f32_16x16x32_bf16 v[66:69], v[192:195], v[102:105], v[142:145]
	v_mfma_f32_16x16x32_bf16 v[70:73], v[200:203], v[102:105], v[148:151]
	v_mfma_f32_16x16x32_bf16 v[74:77], v[192:195], v[110:113], v[152:155]
	v_mfma_f32_16x16x32_bf16 v[78:81], v[200:203], v[110:113], v[156:159]
	v_mfma_f32_16x16x32_bf16 v[82:85], v[192:195], v[228:231], v[160:163]
	v_mfma_f32_16x16x32_bf16 v[86:89], v[200:203], v[228:231], v[164:167]
	v_mfma_f32_16x16x32_bf16 v[90:93], v[192:195], v[236:239], v[168:171]
	v_mfma_f32_16x16x32_bf16 v[94:97], v[200:203], v[236:239], v[172:175]
	v_mfma_f32_16x16x32_bf16 v[66:69], v[196:199], v[106:109], v[66:69]
	v_mfma_f32_16x16x32_bf16 v[70:73], v[204:207], v[106:109], v[70:73]
	v_mfma_f32_16x16x32_bf16 v[74:77], v[196:199], v[224:227], v[74:77]
	v_mfma_f32_16x16x32_bf16 v[78:81], v[204:207], v[224:227], v[78:81]
	v_mfma_f32_16x16x32_bf16 v[82:85], v[196:199], v[232:235], v[82:85]
	v_mfma_f32_16x16x32_bf16 v[86:89], v[204:207], v[232:235], v[86:89]
	v_mfma_f32_16x16x32_bf16 v[90:93], v[196:199], v[240:243], v[90:93]
	v_mfma_f32_16x16x32_bf16 v[94:97], v[204:207], v[240:243], v[94:97]
	v_mfma_f32_16x16x32_bf16 v[98:101], v[208:211], v[102:105], v[114:117]
	v_mfma_f32_16x16x32_bf16 v[102:105], v[216:219], v[102:105], v[122:125]
	v_mfma_f32_16x16x32_bf16 v[98:101], v[212:215], v[106:109], v[98:101]
	v_mfma_f32_16x16x32_bf16 v[102:105], v[220:223], v[106:109], v[102:105]
	v_mfma_f32_16x16x32_bf16 v[106:109], v[208:211], v[110:113], v[176:179]
	v_mfma_f32_16x16x32_bf16 v[110:113], v[216:219], v[110:113], v[180:183]
	v_mfma_f32_16x16x32_bf16 v[114:117], v[208:211], v[228:231], v[184:187]
	v_mfma_f32_16x16x32_bf16 v[118:121], v[216:219], v[228:231], v[118:121]
	v_mfma_f32_16x16x32_bf16 v[122:125], v[208:211], v[236:239], v[188:191]
	v_mfma_f32_16x16x32_bf16 v[126:129], v[216:219], v[236:239], v[126:129]
	v_mfma_f32_16x16x32_bf16 v[106:109], v[212:215], v[224:227], v[106:109]
	v_mfma_f32_16x16x32_bf16 v[110:113], v[220:223], v[224:227], v[110:113]
	v_mfma_f32_16x16x32_bf16 v[114:117], v[212:215], v[232:235], v[114:117]
	v_mfma_f32_16x16x32_bf16 v[118:121], v[220:223], v[232:235], v[118:121]
	s_setprio 2
	s_barrier
	v_mfma_f32_16x16x32_bf16 v[122:125], v[212:215], v[240:243], v[122:125]
	v_mfma_f32_16x16x32_bf16 v[126:129], v[220:223], v[240:243], v[126:129]
	s_setprio 0
	s_add_i32 s61, s61, 2
	s_cmp_ge_i32 s61, s60
	s_cbranch_scc0 .LBB0_462
	v_mov_b32_e32 v136, v130
	s_branch .LBB0_465

.LBB0_466:
	v_add_u32_e32 v133, s54, v140
	ds_read_b128 v[142:145], v133
	ds_read_b128 v[148:151], v133 offset:1024
	ds_read_b128 v[152:155], v133 offset:2048
	ds_read_b128 v[156:159], v133 offset:3072
	v_add_u32_e32 v133, s55, v140
	ds_read_b128 v[160:163], v133
	ds_read_b128 v[164:167], v133 offset:1024
	ds_read_b128 v[168:171], v133 offset:2048
	ds_read_b128 v[172:175], v133 offset:3072
	s_add_u32 s36, s34, 0xffc00080
	s_addc_u32 s37, s35, -1
	s_cmp_eq_u32 s42, 4
	s_cselect_b32 s39, s29, s37
	s_cselect_b32 s38, s28, s36
	s_cselect_b32 s37, s31, s41
	s_cselect_b32 s36, s30, s40
	s_mov_b32 m0, s52
	v_add_u32_e32 v141, 0, v1
	ds_read_b128 v[176:179], v141
	ds_read_b128 v[180:183], v141 offset:1024
	ds_read_b128 v[184:187], v141 offset:2048
	ds_read_b128 v[188:191], v141 offset:3072
	ds_read_b128 v[192:195], v141 offset:4096
	ds_read_b128 v[196:199], v141 offset:5120
	ds_read_b128 v[200:203], v141 offset:6144
	ds_read_b128 v[204:207], v141 offset:7168
	global_load_lds_dwordx4 v130, s[34:35]
	s_mov_b32 m0, s53
	v_mov_b32_e32 v133, v131
	global_load_lds_dwordx4 v132, s[34:35]
	s_waitcnt vmcnt(8)
	s_waitcnt lgkmcnt(0)
	s_barrier
	s_setprio 1
	s_waitcnt lgkmcnt(0)
	v_mfma_f32_16x16x32_bf16 v[2:5], v[142:145], v[176:179], v[2:5]
	v_mfma_f32_16x16x32_bf16 v[2:5], v[148:151], v[180:183], v[2:5]
	v_mfma_f32_16x16x32_bf16 v[6:9], v[156:159], v[180:183], v[6:9]
	v_mfma_f32_16x16x32_bf16 v[6:9], v[152:155], v[176:179], v[6:9]
	v_mfma_f32_16x16x32_bf16 v[14:17], v[152:155], v[184:187], v[14:17]
	v_mfma_f32_16x16x32_bf16 v[14:17], v[156:159], v[188:191], v[14:17]
	v_mfma_f32_16x16x32_bf16 v[10:13], v[148:151], v[188:191], v[10:13]
	v_mfma_f32_16x16x32_bf16 v[10:13], v[142:145], v[184:187], v[10:13]
	v_mfma_f32_16x16x32_bf16 v[18:21], v[142:145], v[192:195], v[18:21]
	v_mfma_f32_16x16x32_bf16 v[18:21], v[148:151], v[196:199], v[18:21]
	v_mfma_f32_16x16x32_bf16 v[22:25], v[156:159], v[196:199], v[22:25]
	v_mfma_f32_16x16x32_bf16 v[22:25], v[152:155], v[192:195], v[22:25]
	v_mfma_f32_16x16x32_bf16 v[30:33], v[152:155], v[200:203], v[30:33]
	v_mfma_f32_16x16x32_bf16 v[30:33], v[156:159], v[204:207], v[30:33]
	v_mfma_f32_16x16x32_bf16 v[26:29], v[148:151], v[204:207], v[26:29]
	v_mfma_f32_16x16x32_bf16 v[26:29], v[142:145], v[200:203], v[26:29]
	v_mfma_f32_16x16x32_bf16 v[34:37], v[160:163], v[176:179], v[34:37]
	v_mfma_f32_16x16x32_bf16 v[34:37], v[164:167], v[180:183], v[34:37]
	v_mfma_f32_16x16x32_bf16 v[38:41], v[172:175], v[180:183], v[38:41]
	v_mfma_f32_16x16x32_bf16 v[38:41], v[168:171], v[176:179], v[38:41]
	v_mfma_f32_16x16x32_bf16 v[46:49], v[168:171], v[184:187], v[46:49]
	v_mfma_f32_16x16x32_bf16 v[46:49], v[172:175], v[188:191], v[46:49]
	v_mfma_f32_16x16x32_bf16 v[42:45], v[164:167], v[188:191], v[42:45]
	v_mfma_f32_16x16x32_bf16 v[42:45], v[160:163], v[184:187], v[42:45]
	v_mfma_f32_16x16x32_bf16 v[50:53], v[160:163], v[192:195], v[50:53]
	v_mfma_f32_16x16x32_bf16 v[50:53], v[164:167], v[196:199], v[50:53]
	v_mfma_f32_16x16x32_bf16 v[54:57], v[172:175], v[196:199], v[54:57]
	v_mfma_f32_16x16x32_bf16 v[54:57], v[168:171], v[192:195], v[54:57]
	v_mfma_f32_16x16x32_bf16 v[62:65], v[168:171], v[200:203], v[62:65]
	v_mfma_f32_16x16x32_bf16 v[62:65], v[172:175], v[204:207], v[62:65]
	s_setprio 2
	s_barrier
	v_mfma_f32_16x16x32_bf16 v[58:61], v[164:167], v[204:207], v[58:61]
	v_mfma_f32_16x16x32_bf16 v[58:61], v[160:163], v[200:203], v[58:61]
	s_setprio 0
	s_add_i32 s43, s54, s21
	s_mov_b32 m0, s43
	ds_read_b128 v[176:179], v141 offset:16384
	ds_read_b128 v[180:183], v141 offset:17408
	ds_read_b128 v[184:187], v141 offset:18432
	ds_read_b128 v[188:191], v141 offset:19456
	ds_read_b128 v[192:195], v141 offset:20480
	ds_read_b128 v[196:199], v141 offset:21504
	ds_read_b128 v[200:203], v141 offset:22528
	ds_read_b128 v[204:207], v141 offset:23552
	global_load_lds_dwordx4 v136, s[36:37]
	s_add_i32 m0, s43, 0x2000
	s_add_u32 s60, s36, 0x80000
	s_addc_u32 s61, s37, 0
	s_add_i32 s43, s55, s21
	global_load_lds_dwordx4 v134, s[36:37]
	s_mov_b32 m0, s43
	v_mov_b32_e32 v137, v131
	global_load_lds_dwordx4 v136, s[60:61]
	s_add_i32 m0, s43, 0x2000
	v_mov_b32_e32 v135, v131
	global_load_lds_dwordx4 v134, s[60:61]
	s_mov_b32 m0, s33
	v_lshl_add_u64 v[138:139], s[36:37], 0, v[136:137]
	global_load_lds_dwordx4 v130, s[38:39]
	s_mov_b32 m0, s44
	v_lshl_add_u64 v[208:209], s[36:37], 0, v[134:135]
	global_load_lds_dwordx4 v132, s[38:39]
	s_waitcnt vmcnt(8)
	s_waitcnt lgkmcnt(0)
	v_lshl_add_u64 v[210:211], s[38:39], 0, v[130:131]
	v_lshl_add_u64 v[212:213], s[38:39], 0, v[132:133]
	s_barrier
	s_setprio 1
	s_waitcnt lgkmcnt(0)
	v_mfma_f32_16x16x32_bf16 v[66:69], v[142:145], v[176:179], v[66:69]
	v_mfma_f32_16x16x32_bf16 v[66:69], v[148:151], v[180:183], v[66:69]
	v_mfma_f32_16x16x32_bf16 v[70:73], v[156:159], v[180:183], v[70:73]
	v_mfma_f32_16x16x32_bf16 v[70:73], v[152:155], v[176:179], v[70:73]
	v_mfma_f32_16x16x32_bf16 v[78:81], v[152:155], v[184:187], v[78:81]
	v_mfma_f32_16x16x32_bf16 v[78:81], v[156:159], v[188:191], v[78:81]
	v_mfma_f32_16x16x32_bf16 v[74:77], v[148:151], v[188:191], v[74:77]
	v_mfma_f32_16x16x32_bf16 v[74:77], v[142:145], v[184:187], v[74:77]
	v_mfma_f32_16x16x32_bf16 v[82:85], v[142:145], v[192:195], v[82:85]
	v_mfma_f32_16x16x32_bf16 v[82:85], v[148:151], v[196:199], v[82:85]
	v_mfma_f32_16x16x32_bf16 v[86:89], v[156:159], v[196:199], v[86:89]
	v_mfma_f32_16x16x32_bf16 v[86:89], v[152:155], v[192:195], v[86:89]
	v_mfma_f32_16x16x32_bf16 v[94:97], v[152:155], v[200:203], v[94:97]
	v_mfma_f32_16x16x32_bf16 v[94:97], v[156:159], v[204:207], v[94:97]
	v_mfma_f32_16x16x32_bf16 v[90:93], v[148:151], v[204:207], v[90:93]
	v_mfma_f32_16x16x32_bf16 v[90:93], v[142:145], v[200:203], v[90:93]
	v_mfma_f32_16x16x32_bf16 v[98:101], v[160:163], v[176:179], v[98:101]
	v_mfma_f32_16x16x32_bf16 v[98:101], v[164:167], v[180:183], v[98:101]
	v_mfma_f32_16x16x32_bf16 v[102:105], v[172:175], v[180:183], v[102:105]
	v_mfma_f32_16x16x32_bf16 v[102:105], v[168:171], v[176:179], v[102:105]
	v_mfma_f32_16x16x32_bf16 v[110:113], v[168:171], v[184:187], v[110:113]
	v_mfma_f32_16x16x32_bf16 v[110:113], v[172:175], v[188:191], v[110:113]
	v_mfma_f32_16x16x32_bf16 v[106:109], v[164:167], v[188:191], v[106:109]
	v_mfma_f32_16x16x32_bf16 v[106:109], v[160:163], v[184:187], v[106:109]
	v_mfma_f32_16x16x32_bf16 v[114:117], v[160:163], v[192:195], v[114:117]
	v_mfma_f32_16x16x32_bf16 v[114:117], v[164:167], v[196:199], v[114:117]
	v_mfma_f32_16x16x32_bf16 v[118:121], v[172:175], v[196:199], v[118:121]
	v_mfma_f32_16x16x32_bf16 v[118:121], v[168:171], v[192:195], v[118:121]
	v_mfma_f32_16x16x32_bf16 v[126:129], v[168:171], v[200:203], v[126:129]
	v_mfma_f32_16x16x32_bf16 v[126:129], v[172:175], v[204:207], v[126:129]
	s_setprio 2
	s_barrier
	v_mfma_f32_16x16x32_bf16 v[122:125], v[164:167], v[204:207], v[122:125]
	v_mfma_f32_16x16x32_bf16 v[122:125], v[160:163], v[200:203], v[122:125]
	s_setprio 0
	s_add_i32 s43, 0, 0x18000
	v_add_u32_e32 v135, s43, v140
	s_add_i32 s60, 0, 0x1c000
	ds_read_b128 v[142:145], v135
	ds_read_b128 v[148:151], v135 offset:1024
	ds_read_b128 v[152:155], v135 offset:2048
	ds_read_b128 v[156:159], v135 offset:3072
	v_add_u32_e32 v135, s60, v140
	ds_read_b128 v[160:163], v135
	ds_read_b128 v[164:167], v135 offset:1024
	ds_read_b128 v[168:171], v135 offset:2048
	ds_read_b128 v[172:175], v135 offset:3072
	s_add_u32 s38, s38, 0x400000
	s_addc_u32 s39, s39, 0
	s_mov_b32 m0, s45
	ds_read_b128 v[176:179], v141 offset:32768
	ds_read_b128 v[180:183], v141 offset:33792
	ds_read_b128 v[184:187], v141 offset:34816
	ds_read_b128 v[188:191], v141 offset:35840
	ds_read_b128 v[192:195], v141 offset:36864
	ds_read_b128 v[196:199], v141 offset:37888
	ds_read_b128 v[200:203], v141 offset:38912
	ds_read_b128 v[204:207], v141 offset:39936
	global_load_lds_dwordx4 v130, s[38:39]
	s_mov_b32 m0, s46
	s_nop 0
	global_load_lds_dwordx4 v132, s[38:39]
	s_waitcnt vmcnt(8)
	s_waitcnt lgkmcnt(0)
	s_barrier
	s_setprio 1
	s_waitcnt lgkmcnt(0)
	v_mfma_f32_16x16x32_bf16 v[2:5], v[142:145], v[176:179], v[2:5]
	v_mfma_f32_16x16x32_bf16 v[2:5], v[148:151], v[180:183], v[2:5]
	v_mfma_f32_16x16x32_bf16 v[6:9], v[156:159], v[180:183], v[6:9]
	v_mfma_f32_16x16x32_bf16 v[6:9], v[152:155], v[176:179], v[6:9]
	v_mfma_f32_16x16x32_bf16 v[14:17], v[152:155], v[184:187], v[14:17]
	v_mfma_f32_16x16x32_bf16 v[14:17], v[156:159], v[188:191], v[14:17]
	v_mfma_f32_16x16x32_bf16 v[10:13], v[148:151], v[188:191], v[10:13]
	v_mfma_f32_16x16x32_bf16 v[10:13], v[142:145], v[184:187], v[10:13]
	v_mfma_f32_16x16x32_bf16 v[18:21], v[142:145], v[192:195], v[18:21]
	v_mfma_f32_16x16x32_bf16 v[18:21], v[148:151], v[196:199], v[18:21]
	v_mfma_f32_16x16x32_bf16 v[22:25], v[156:159], v[196:199], v[22:25]
	v_mfma_f32_16x16x32_bf16 v[22:25], v[152:155], v[192:195], v[22:25]
	v_mfma_f32_16x16x32_bf16 v[30:33], v[152:155], v[200:203], v[30:33]
	v_mfma_f32_16x16x32_bf16 v[30:33], v[156:159], v[204:207], v[30:33]
	v_mfma_f32_16x16x32_bf16 v[26:29], v[148:151], v[204:207], v[26:29]
	v_mfma_f32_16x16x32_bf16 v[26:29], v[142:145], v[200:203], v[26:29]
	v_mfma_f32_16x16x32_bf16 v[34:37], v[160:163], v[176:179], v[34:37]
	v_mfma_f32_16x16x32_bf16 v[34:37], v[164:167], v[180:183], v[34:37]
	v_mfma_f32_16x16x32_bf16 v[38:41], v[172:175], v[180:183], v[38:41]
	v_mfma_f32_16x16x32_bf16 v[38:41], v[168:171], v[176:179], v[38:41]
	v_mfma_f32_16x16x32_bf16 v[46:49], v[168:171], v[184:187], v[46:49]
	v_mfma_f32_16x16x32_bf16 v[46:49], v[172:175], v[188:191], v[46:49]
	v_mfma_f32_16x16x32_bf16 v[42:45], v[164:167], v[188:191], v[42:45]
	v_mfma_f32_16x16x32_bf16 v[42:45], v[160:163], v[184:187], v[42:45]
	v_mfma_f32_16x16x32_bf16 v[50:53], v[160:163], v[192:195], v[50:53]
	v_mfma_f32_16x16x32_bf16 v[50:53], v[164:167], v[196:199], v[50:53]
	v_mfma_f32_16x16x32_bf16 v[54:57], v[172:175], v[196:199], v[54:57]
	v_mfma_f32_16x16x32_bf16 v[54:57], v[168:171], v[192:195], v[54:57]
	v_mfma_f32_16x16x32_bf16 v[62:65], v[168:171], v[200:203], v[62:65]
	v_mfma_f32_16x16x32_bf16 v[62:65], v[172:175], v[204:207], v[62:65]
	s_setprio 2
	s_barrier
	v_mfma_f32_16x16x32_bf16 v[58:61], v[164:167], v[204:207], v[58:61]
	v_mfma_f32_16x16x32_bf16 v[58:61], v[160:163], v[200:203], v[58:61]
	s_setprio 0
	s_add_i32 s38, s43, s21
	v_lshl_add_u64 v[138:139], v[138:139], 0, s[8:9]
	s_mov_b32 m0, s38
	ds_read_b128 v[176:179], v141 offset:49152
	ds_read_b128 v[180:183], v141 offset:50176
	ds_read_b128 v[184:187], v141 offset:51200
	ds_read_b128 v[188:191], v141 offset:52224
	ds_read_b128 v[192:195], v141 offset:53248
	ds_read_b128 v[196:199], v141 offset:54272
	ds_read_b128 v[200:203], v141 offset:55296
	ds_read_b128 v[204:207], v141 offset:56320
	global_load_lds_dwordx4 v[138:139], off
	s_add_i32 m0, s38, 0x2000
	s_add_u32 s36, s36, 0x80080
	v_lshl_add_u64 v[138:139], v[208:209], 0, s[8:9]
	s_addc_u32 s37, s37, 0
	s_add_i32 s38, s60, s21
	global_load_lds_dwordx4 v[138:139], off
	s_mov_b32 m0, s38
	v_lshl_add_u64 v[138:139], v[210:211], 0, s[8:9]
	global_load_lds_dwordx4 v136, s[36:37]
	s_add_i32 m0, s38, 0x2000
	s_nop 0
	global_load_lds_dwordx4 v134, s[36:37]
	s_mov_b32 m0, s50
	s_nop 0
	global_load_lds_dwordx4 v[138:139], off
	v_lshl_add_u64 v[138:139], v[212:213], 0, s[8:9]
	s_mov_b32 m0, s51
	s_nop 0
	global_load_lds_dwordx4 v[138:139], off
	s_waitcnt vmcnt(8)
	s_waitcnt lgkmcnt(0)
	s_barrier
	s_setprio 1
	s_waitcnt lgkmcnt(0)
	v_mfma_f32_16x16x32_bf16 v[66:69], v[142:145], v[176:179], v[66:69]
	v_mfma_f32_16x16x32_bf16 v[66:69], v[148:151], v[180:183], v[66:69]
	v_mfma_f32_16x16x32_bf16 v[70:73], v[156:159], v[180:183], v[70:73]
	v_mfma_f32_16x16x32_bf16 v[70:73], v[152:155], v[176:179], v[70:73]
	v_mfma_f32_16x16x32_bf16 v[78:81], v[152:155], v[184:187], v[78:81]
	v_mfma_f32_16x16x32_bf16 v[78:81], v[156:159], v[188:191], v[78:81]
	v_mfma_f32_16x16x32_bf16 v[74:77], v[148:151], v[188:191], v[74:77]
	v_mfma_f32_16x16x32_bf16 v[74:77], v[142:145], v[184:187], v[74:77]
	v_mfma_f32_16x16x32_bf16 v[82:85], v[142:145], v[192:195], v[82:85]
	v_mfma_f32_16x16x32_bf16 v[82:85], v[148:151], v[196:199], v[82:85]
	v_mfma_f32_16x16x32_bf16 v[86:89], v[156:159], v[196:199], v[86:89]
	v_mfma_f32_16x16x32_bf16 v[86:89], v[152:155], v[192:195], v[86:89]
	v_mfma_f32_16x16x32_bf16 v[94:97], v[152:155], v[200:203], v[94:97]
	v_mfma_f32_16x16x32_bf16 v[94:97], v[156:159], v[204:207], v[94:97]
	v_mfma_f32_16x16x32_bf16 v[90:93], v[148:151], v[204:207], v[90:93]
	v_mfma_f32_16x16x32_bf16 v[90:93], v[142:145], v[200:203], v[90:93]
	v_mfma_f32_16x16x32_bf16 v[98:101], v[160:163], v[176:179], v[98:101]
	v_mfma_f32_16x16x32_bf16 v[98:101], v[164:167], v[180:183], v[98:101]
	v_mfma_f32_16x16x32_bf16 v[102:105], v[172:175], v[180:183], v[102:105]
	v_mfma_f32_16x16x32_bf16 v[102:105], v[168:171], v[176:179], v[102:105]
	v_mfma_f32_16x16x32_bf16 v[110:113], v[168:171], v[184:187], v[110:113]
	v_mfma_f32_16x16x32_bf16 v[110:113], v[172:175], v[188:191], v[110:113]
	v_mfma_f32_16x16x32_bf16 v[106:109], v[164:167], v[188:191], v[106:109]
	v_mfma_f32_16x16x32_bf16 v[106:109], v[160:163], v[184:187], v[106:109]
	v_mfma_f32_16x16x32_bf16 v[114:117], v[160:163], v[192:195], v[114:117]
	v_mfma_f32_16x16x32_bf16 v[114:117], v[164:167], v[196:199], v[114:117]
	v_mfma_f32_16x16x32_bf16 v[118:121], v[172:175], v[196:199], v[118:121]
	v_mfma_f32_16x16x32_bf16 v[118:121], v[168:171], v[192:195], v[118:121]
	v_mfma_f32_16x16x32_bf16 v[126:129], v[168:171], v[200:203], v[126:129]
	v_mfma_f32_16x16x32_bf16 v[126:129], v[172:175], v[204:207], v[126:129]
	s_setprio 2
	s_barrier
	v_mfma_f32_16x16x32_bf16 v[122:125], v[164:167], v[204:207], v[122:125]
	v_mfma_f32_16x16x32_bf16 v[122:125], v[160:163], v[200:203], v[122:125]
	s_setprio 0
	s_add_i32 s42, s42, 2
	s_add_u32 s34, s34, 0x100
	s_addc_u32 s35, s35, 0
	s_add_u32 s40, s40, 0x100
	s_addc_u32 s41, s41, 0
	s_cmp_gt_u32 s42, 5
	s_cbranch_scc0 .LBB0_466
	s_and_b64 vcc, exec, s[10:11]
	s_cbranch_vccz .LBB0_469
	s_barrier

.LBB0_495:
	v_add_u32_e32 v14, s58, v140
	v_add_u32_e32 v30, s59, v140
	ds_read_b128 v[2:5], v14
	ds_read_b128 v[6:9], v14 offset:1024
	ds_read_b128 v[10:13], v14 offset:2048
	ds_read_b128 v[14:17], v14 offset:3072
	ds_read_b128 v[18:21], v30
	ds_read_b128 v[22:25], v30 offset:1024
	ds_read_b128 v[26:29], v30 offset:2048
	ds_read_b128 v[30:33], v30 offset:3072
	v_add_u32_e32 v141, 0, v1
	ds_read_b128 v[34:37], v141
	ds_read_b128 v[38:41], v141 offset:1024
	ds_read_b128 v[42:45], v141 offset:2048
	ds_read_b128 v[46:49], v141 offset:3072
	ds_read_b128 v[50:53], v141 offset:4096
	ds_read_b128 v[54:57], v141 offset:5120
	ds_read_b128 v[58:61], v141 offset:6144
	ds_read_b128 v[62:65], v141 offset:7168
	s_waitcnt vmcnt(8)
	s_waitcnt lgkmcnt(0)
	s_barrier
	s_setprio 1
	s_waitcnt lgkmcnt(0)
	v_mfma_f32_16x16x32_bf16 v[66:69], v[2:5], v[34:37], 0
	v_mfma_f32_16x16x32_bf16 v[66:69], v[6:9], v[38:41], v[66:69]
	v_mfma_f32_16x16x32_bf16 v[70:73], v[10:13], v[34:37], 0
	v_mfma_f32_16x16x32_bf16 v[70:73], v[14:17], v[38:41], v[70:73]
	v_mfma_f32_16x16x32_bf16 v[78:81], v[10:13], v[42:45], 0
	v_mfma_f32_16x16x32_bf16 v[78:81], v[14:17], v[46:49], v[78:81]
	v_mfma_f32_16x16x32_bf16 v[74:77], v[2:5], v[42:45], 0
	v_mfma_f32_16x16x32_bf16 v[74:77], v[6:9], v[46:49], v[74:77]
	v_mfma_f32_16x16x32_bf16 v[82:85], v[2:5], v[50:53], 0
	v_mfma_f32_16x16x32_bf16 v[82:85], v[6:9], v[54:57], v[82:85]
	v_mfma_f32_16x16x32_bf16 v[86:89], v[10:13], v[50:53], 0
	v_mfma_f32_16x16x32_bf16 v[86:89], v[14:17], v[54:57], v[86:89]
	v_mfma_f32_16x16x32_bf16 v[94:97], v[10:13], v[58:61], 0
	v_mfma_f32_16x16x32_bf16 v[94:97], v[14:17], v[62:65], v[94:97]
	v_mfma_f32_16x16x32_bf16 v[90:93], v[2:5], v[58:61], 0
	v_mfma_f32_16x16x32_bf16 v[90:93], v[6:9], v[62:65], v[90:93]
	v_mfma_f32_16x16x32_bf16 v[98:101], v[18:21], v[34:37], 0
	v_mfma_f32_16x16x32_bf16 v[34:37], v[26:29], v[34:37], 0
	v_mfma_f32_16x16x32_bf16 v[102:105], v[18:21], v[42:45], 0
	v_mfma_f32_16x16x32_bf16 v[42:45], v[26:29], v[42:45], 0
	v_mfma_f32_16x16x32_bf16 v[106:109], v[18:21], v[50:53], 0
	v_mfma_f32_16x16x32_bf16 v[50:53], v[26:29], v[50:53], 0
	v_mfma_f32_16x16x32_bf16 v[110:113], v[18:21], v[58:61], 0
	v_mfma_f32_16x16x32_bf16 v[58:61], v[26:29], v[58:61], 0
	v_mfma_f32_16x16x32_bf16 v[98:101], v[22:25], v[38:41], v[98:101]
	v_mfma_f32_16x16x32_bf16 v[38:41], v[30:33], v[38:41], v[34:37]
	v_mfma_f32_16x16x32_bf16 v[102:105], v[22:25], v[46:49], v[102:105]
	v_mfma_f32_16x16x32_bf16 v[46:49], v[30:33], v[46:49], v[42:45]
	v_mfma_f32_16x16x32_bf16 v[106:109], v[22:25], v[54:57], v[106:109]
	v_mfma_f32_16x16x32_bf16 v[54:57], v[30:33], v[54:57], v[50:53]
	s_setprio 2
	s_barrier
	v_mfma_f32_16x16x32_bf16 v[110:113], v[22:25], v[62:65], v[110:113]
	v_mfma_f32_16x16x32_bf16 v[62:65], v[30:33], v[62:65], v[58:61]
	s_setprio 0
	v_lshl_add_u64 v[136:137], s[38:39], 0, v[130:131]
	s_add_i32 s62, s58, s46
	v_mov_b32_e32 v135, v131
	v_lshl_add_u64 v[142:143], v[136:137], 0, s[10:11]
	s_mov_b32 m0, s62
	v_lshl_add_u64 v[244:245], s[38:39], 0, v[134:135]
	ds_read_b128 v[34:37], v141 offset:16384
	ds_read_b128 v[42:45], v141 offset:17408
	ds_read_b128 v[50:53], v141 offset:18432
	ds_read_b128 v[58:61], v141 offset:19456
	ds_read_b128 v[114:117], v141 offset:20480
	ds_read_b128 v[118:121], v141 offset:21504
	ds_read_b128 v[122:125], v141 offset:22528
	ds_read_b128 v[126:129], v141 offset:23552
	global_load_lds_dwordx4 v[142:143], off
	v_lshl_add_u64 v[142:143], v[244:245], 0, s[10:11]
	s_add_i32 m0, s62, 0x2000
	s_add_i32 s62, s59, s46
	global_load_lds_dwordx4 v[142:143], off
	s_mov_b32 m0, s62
	v_mov_b32_e32 v139, v131
	global_load_lds_dwordx4 v130, s[40:41]
	s_add_i32 m0, s62, 0x2000
	v_lshl_add_u64 v[246:247], s[36:37], 0, v[138:139]
	v_mov_b32_e32 v133, v131
	global_load_lds_dwordx4 v134, s[40:41]
	v_lshl_add_u64 v[142:143], v[246:247], 0, s[10:11]
	s_mov_b32 m0, s47
	v_lshl_add_u64 v[248:249], s[36:37], 0, v[132:133]
	global_load_lds_dwordx4 v[142:143], off
	v_lshl_add_u64 v[142:143], v[248:249], 0, s[10:11]
	s_mov_b32 m0, s48
	s_nop 0
	global_load_lds_dwordx4 v[142:143], off
	s_waitcnt vmcnt(8)
	s_waitcnt lgkmcnt(0)
	s_barrier
	s_setprio 1
	s_waitcnt lgkmcnt(0)
	v_mfma_f32_16x16x32_bf16 v[142:145], v[2:5], v[34:37], 0
	v_mfma_f32_16x16x32_bf16 v[148:151], v[10:13], v[34:37], 0
	v_mfma_f32_16x16x32_bf16 v[152:155], v[2:5], v[50:53], 0
	v_mfma_f32_16x16x32_bf16 v[156:159], v[10:13], v[50:53], 0
	v_mfma_f32_16x16x32_bf16 v[160:163], v[2:5], v[114:117], 0
	v_mfma_f32_16x16x32_bf16 v[164:167], v[10:13], v[114:117], 0
	v_mfma_f32_16x16x32_bf16 v[2:5], v[2:5], v[122:125], 0
	v_mfma_f32_16x16x32_bf16 v[10:13], v[10:13], v[122:125], 0
	v_mfma_f32_16x16x32_bf16 v[142:145], v[6:9], v[42:45], v[142:145]
	v_mfma_f32_16x16x32_bf16 v[148:151], v[14:17], v[42:45], v[148:151]
	v_mfma_f32_16x16x32_bf16 v[152:155], v[6:9], v[58:61], v[152:155]
	v_mfma_f32_16x16x32_bf16 v[156:159], v[14:17], v[58:61], v[156:159]
	v_mfma_f32_16x16x32_bf16 v[160:163], v[6:9], v[118:121], v[160:163]
	v_mfma_f32_16x16x32_bf16 v[164:167], v[14:17], v[118:121], v[164:167]
	v_mfma_f32_16x16x32_bf16 v[168:171], v[6:9], v[126:129], v[2:5]
	v_mfma_f32_16x16x32_bf16 v[172:175], v[14:17], v[126:129], v[10:13]
	v_mfma_f32_16x16x32_bf16 v[2:5], v[18:21], v[34:37], 0
	v_mfma_f32_16x16x32_bf16 v[6:9], v[26:29], v[34:37], 0
	v_mfma_f32_16x16x32_bf16 v[10:13], v[18:21], v[50:53], 0
	v_mfma_f32_16x16x32_bf16 v[14:17], v[26:29], v[50:53], 0
	v_mfma_f32_16x16x32_bf16 v[34:37], v[18:21], v[114:117], 0
	v_mfma_f32_16x16x32_bf16 v[50:53], v[26:29], v[114:117], 0
	v_mfma_f32_16x16x32_bf16 v[18:21], v[18:21], v[122:125], 0
	v_mfma_f32_16x16x32_bf16 v[26:29], v[26:29], v[122:125], 0
	v_mfma_f32_16x16x32_bf16 v[114:117], v[22:25], v[42:45], v[2:5]
	v_mfma_f32_16x16x32_bf16 v[122:125], v[30:33], v[42:45], v[6:9]
	v_mfma_f32_16x16x32_bf16 v[184:187], v[22:25], v[118:121], v[34:37]
	v_mfma_f32_16x16x32_bf16 v[118:121], v[30:33], v[118:121], v[50:53]
	v_mfma_f32_16x16x32_bf16 v[188:191], v[22:25], v[126:129], v[18:21]
	v_mfma_f32_16x16x32_bf16 v[126:129], v[30:33], v[126:129], v[26:29]
	s_setprio 2
	s_barrier
	v_mfma_f32_16x16x32_bf16 v[176:179], v[22:25], v[58:61], v[10:13]
	v_mfma_f32_16x16x32_bf16 v[180:183], v[30:33], v[58:61], v[14:17]
	s_setprio 0
	s_add_i32 s62, 0, 0x18000
	v_add_u32_e32 v2, s62, v140
	s_add_i32 s63, 0, 0x1c000
	ds_read_b128 v[192:195], v2
	ds_read_b128 v[196:199], v2 offset:1024
	ds_read_b128 v[200:203], v2 offset:2048
	ds_read_b128 v[204:207], v2 offset:3072
	v_add_u32_e32 v2, s63, v140
	ds_read_b128 v[208:211], v2
	ds_read_b128 v[212:215], v2 offset:1024
	ds_read_b128 v[216:219], v2 offset:2048
	ds_read_b128 v[220:223], v2 offset:3072
	s_mov_b32 m0, s49
	ds_read_b128 v[42:45], v141 offset:32768
	ds_read_b128 v[50:53], v141 offset:33792
	ds_read_b128 v[58:61], v141 offset:34816
	ds_read_b128 v[224:227], v141 offset:35840
	ds_read_b128 v[228:231], v141 offset:36864
	ds_read_b128 v[232:235], v141 offset:37888
	ds_read_b128 v[236:239], v141 offset:38912
	ds_read_b128 v[240:243], v141 offset:39936
	global_load_lds_dwordx4 v138, s[42:43]
	s_mov_b32 m0, s50
	s_nop 0
	global_load_lds_dwordx4 v132, s[42:43]
	s_waitcnt vmcnt(8)
	s_waitcnt lgkmcnt(0)
	s_barrier
	s_setprio 1
	s_waitcnt lgkmcnt(0)
	v_mfma_f32_16x16x32_bf16 v[2:5], v[192:195], v[42:45], v[66:69]
	v_mfma_f32_16x16x32_bf16 v[6:9], v[200:203], v[42:45], v[70:73]
	v_mfma_f32_16x16x32_bf16 v[10:13], v[192:195], v[58:61], v[74:77]
	v_mfma_f32_16x16x32_bf16 v[14:17], v[200:203], v[58:61], v[78:81]
	v_mfma_f32_16x16x32_bf16 v[18:21], v[192:195], v[228:231], v[82:85]
	v_mfma_f32_16x16x32_bf16 v[22:25], v[200:203], v[228:231], v[86:89]
	v_mfma_f32_16x16x32_bf16 v[26:29], v[192:195], v[236:239], v[90:93]
	v_mfma_f32_16x16x32_bf16 v[30:33], v[200:203], v[236:239], v[94:97]
	v_mfma_f32_16x16x32_bf16 v[2:5], v[196:199], v[50:53], v[2:5]
	v_mfma_f32_16x16x32_bf16 v[6:9], v[204:207], v[50:53], v[6:9]
	v_mfma_f32_16x16x32_bf16 v[10:13], v[196:199], v[224:227], v[10:13]
	v_mfma_f32_16x16x32_bf16 v[14:17], v[204:207], v[224:227], v[14:17]
	v_mfma_f32_16x16x32_bf16 v[18:21], v[196:199], v[232:235], v[18:21]
	v_mfma_f32_16x16x32_bf16 v[22:25], v[204:207], v[232:235], v[22:25]
	v_mfma_f32_16x16x32_bf16 v[26:29], v[196:199], v[240:243], v[26:29]
	v_mfma_f32_16x16x32_bf16 v[30:33], v[204:207], v[240:243], v[30:33]
	v_mfma_f32_16x16x32_bf16 v[34:37], v[208:211], v[42:45], v[98:101]
	v_mfma_f32_16x16x32_bf16 v[38:41], v[216:219], v[42:45], v[38:41]
	v_mfma_f32_16x16x32_bf16 v[34:37], v[212:215], v[50:53], v[34:37]
	v_mfma_f32_16x16x32_bf16 v[38:41], v[220:223], v[50:53], v[38:41]
	v_mfma_f32_16x16x32_bf16 v[42:45], v[208:211], v[58:61], v[102:105]
	v_mfma_f32_16x16x32_bf16 v[46:49], v[216:219], v[58:61], v[46:49]
	v_mfma_f32_16x16x32_bf16 v[50:53], v[208:211], v[228:231], v[106:109]
	v_mfma_f32_16x16x32_bf16 v[54:57], v[216:219], v[228:231], v[54:57]
	v_mfma_f32_16x16x32_bf16 v[58:61], v[208:211], v[236:239], v[110:113]
	v_mfma_f32_16x16x32_bf16 v[62:65], v[216:219], v[236:239], v[62:65]
	v_mfma_f32_16x16x32_bf16 v[42:45], v[212:215], v[224:227], v[42:45]
	v_mfma_f32_16x16x32_bf16 v[46:49], v[220:223], v[224:227], v[46:49]
	v_mfma_f32_16x16x32_bf16 v[50:53], v[212:215], v[232:235], v[50:53]
	v_mfma_f32_16x16x32_bf16 v[54:57], v[220:223], v[232:235], v[54:57]
	s_setprio 2
	s_barrier
	v_mfma_f32_16x16x32_bf16 v[58:61], v[212:215], v[240:243], v[58:61]
	v_mfma_f32_16x16x32_bf16 v[62:65], v[220:223], v[240:243], v[62:65]
	s_setprio 0
	s_add_i32 s62, s62, s46
	v_lshl_add_u64 v[66:67], v[136:137], 0, s[12:13]
	s_mov_b32 m0, s62
	ds_read_b128 v[102:105], v141 offset:49152
	ds_read_b128 v[106:109], v141 offset:50176
	ds_read_b128 v[110:113], v141 offset:51200
	ds_read_b128 v[224:227], v141 offset:52224
	ds_read_b128 v[228:231], v141 offset:53248
	ds_read_b128 v[232:235], v141 offset:54272
	ds_read_b128 v[236:239], v141 offset:55296
	ds_read_b128 v[240:243], v141 offset:56320
	global_load_lds_dwordx4 v[66:67], off
	v_lshl_add_u64 v[66:67], v[244:245], 0, s[12:13]
	s_add_i32 m0, s62, 0x2000
	s_add_i32 s62, s63, s46
	global_load_lds_dwordx4 v[66:67], off
	s_mov_b32 m0, s62
	v_lshl_add_u64 v[66:67], v[246:247], 0, s[12:13]
	global_load_lds_dwordx4 v130, s[44:45]
	s_add_i32 m0, s62, 0x2000
	s_nop 0
	global_load_lds_dwordx4 v134, s[44:45]
	s_mov_b32 m0, s54
	s_nop 0
	global_load_lds_dwordx4 v[66:67], off
	v_lshl_add_u64 v[66:67], v[248:249], 0, s[12:13]
	s_mov_b32 m0, s55
	s_nop 0
	global_load_lds_dwordx4 v[66:67], off
	s_waitcnt vmcnt(8)
	s_waitcnt lgkmcnt(0)
	s_barrier
	s_setprio 1
	s_waitcnt lgkmcnt(0)
	v_mfma_f32_16x16x32_bf16 v[66:69], v[192:195], v[102:105], v[142:145]
	v_mfma_f32_16x16x32_bf16 v[70:73], v[200:203], v[102:105], v[148:151]
	v_mfma_f32_16x16x32_bf16 v[74:77], v[192:195], v[110:113], v[152:155]
	v_mfma_f32_16x16x32_bf16 v[78:81], v[200:203], v[110:113], v[156:159]
	v_mfma_f32_16x16x32_bf16 v[82:85], v[192:195], v[228:231], v[160:163]
	v_mfma_f32_16x16x32_bf16 v[86:89], v[200:203], v[228:231], v[164:167]
	v_mfma_f32_16x16x32_bf16 v[90:93], v[192:195], v[236:239], v[168:171]
	v_mfma_f32_16x16x32_bf16 v[94:97], v[200:203], v[236:239], v[172:175]
	v_mfma_f32_16x16x32_bf16 v[66:69], v[196:199], v[106:109], v[66:69]
	v_mfma_f32_16x16x32_bf16 v[70:73], v[204:207], v[106:109], v[70:73]
	v_mfma_f32_16x16x32_bf16 v[74:77], v[196:199], v[224:227], v[74:77]
	v_mfma_f32_16x16x32_bf16 v[78:81], v[204:207], v[224:227], v[78:81]
	v_mfma_f32_16x16x32_bf16 v[82:85], v[196:199], v[232:235], v[82:85]
	v_mfma_f32_16x16x32_bf16 v[86:89], v[204:207], v[232:235], v[86:89]
	v_mfma_f32_16x16x32_bf16 v[90:93], v[196:199], v[240:243], v[90:93]
	v_mfma_f32_16x16x32_bf16 v[94:97], v[204:207], v[240:243], v[94:97]
	v_mfma_f32_16x16x32_bf16 v[98:101], v[208:211], v[102:105], v[114:117]
	v_mfma_f32_16x16x32_bf16 v[102:105], v[216:219], v[102:105], v[122:125]
	v_mfma_f32_16x16x32_bf16 v[98:101], v[212:215], v[106:109], v[98:101]
	v_mfma_f32_16x16x32_bf16 v[102:105], v[220:223], v[106:109], v[102:105]
	v_mfma_f32_16x16x32_bf16 v[106:109], v[208:211], v[110:113], v[176:179]
	v_mfma_f32_16x16x32_bf16 v[110:113], v[216:219], v[110:113], v[180:183]
	v_mfma_f32_16x16x32_bf16 v[114:117], v[208:211], v[228:231], v[184:187]
	v_mfma_f32_16x16x32_bf16 v[118:121], v[216:219], v[228:231], v[118:121]
	v_mfma_f32_16x16x32_bf16 v[122:125], v[208:211], v[236:239], v[188:191]
	v_mfma_f32_16x16x32_bf16 v[126:129], v[216:219], v[236:239], v[126:129]
	v_mfma_f32_16x16x32_bf16 v[106:109], v[212:215], v[224:227], v[106:109]
	v_mfma_f32_16x16x32_bf16 v[110:113], v[220:223], v[224:227], v[110:113]
	v_mfma_f32_16x16x32_bf16 v[114:117], v[212:215], v[232:235], v[114:117]
	v_mfma_f32_16x16x32_bf16 v[118:121], v[220:223], v[232:235], v[118:121]
	s_setprio 2
	s_barrier
	v_mfma_f32_16x16x32_bf16 v[122:125], v[212:215], v[240:243], v[122:125]
	v_mfma_f32_16x16x32_bf16 v[126:129], v[220:223], v[240:243], v[126:129]
	s_setprio 0
	s_add_i32 s27, s27, 2
	s_cmp_ge_i32 s27, s15
	s_cbranch_scc0 .LBB0_495
	v_mov_b32_e32 v136, v130
	s_branch .LBB0_498

.LBB0_499:
	v_add_u32_e32 v133, s58, v140
	ds_read_b128 v[142:145], v133
	ds_read_b128 v[148:151], v133 offset:1024
	ds_read_b128 v[152:155], v133 offset:2048
	ds_read_b128 v[156:159], v133 offset:3072
	v_add_u32_e32 v133, s59, v140
	ds_read_b128 v[160:163], v133
	ds_read_b128 v[164:167], v133 offset:1024
	ds_read_b128 v[168:171], v133 offset:2048
	ds_read_b128 v[172:175], v133 offset:3072
	s_add_u32 s38, s36, 0xfff80080
	s_addc_u32 s39, s37, -1
	s_cmp_eq_u32 s42, 4
	s_cselect_b32 s41, s31, s39
	s_cselect_b32 s40, s30, s38
	s_cselect_b32 s39, s35, s27
	s_cselect_b32 s38, s34, s15
	s_mov_b32 m0, s56
	v_add_u32_e32 v141, 0, v1
	ds_read_b128 v[176:179], v141
	ds_read_b128 v[180:183], v141 offset:1024
	ds_read_b128 v[184:187], v141 offset:2048
	ds_read_b128 v[188:191], v141 offset:3072
	ds_read_b128 v[192:195], v141 offset:4096
	ds_read_b128 v[196:199], v141 offset:5120
	ds_read_b128 v[200:203], v141 offset:6144
	ds_read_b128 v[204:207], v141 offset:7168
	global_load_lds_dwordx4 v130, s[36:37]
	s_mov_b32 m0, s57
	v_mov_b32_e32 v133, v131
	global_load_lds_dwordx4 v132, s[36:37]
	s_waitcnt vmcnt(8)
	s_waitcnt lgkmcnt(0)
	s_barrier
	s_setprio 1
	s_waitcnt lgkmcnt(0)
	v_mfma_f32_16x16x32_bf16 v[2:5], v[142:145], v[176:179], v[2:5]
	v_mfma_f32_16x16x32_bf16 v[2:5], v[148:151], v[180:183], v[2:5]
	v_mfma_f32_16x16x32_bf16 v[6:9], v[156:159], v[180:183], v[6:9]
	v_mfma_f32_16x16x32_bf16 v[6:9], v[152:155], v[176:179], v[6:9]
	v_mfma_f32_16x16x32_bf16 v[14:17], v[152:155], v[184:187], v[14:17]
	v_mfma_f32_16x16x32_bf16 v[14:17], v[156:159], v[188:191], v[14:17]
	v_mfma_f32_16x16x32_bf16 v[10:13], v[148:151], v[188:191], v[10:13]
	v_mfma_f32_16x16x32_bf16 v[10:13], v[142:145], v[184:187], v[10:13]
	v_mfma_f32_16x16x32_bf16 v[18:21], v[142:145], v[192:195], v[18:21]
	v_mfma_f32_16x16x32_bf16 v[18:21], v[148:151], v[196:199], v[18:21]
	v_mfma_f32_16x16x32_bf16 v[22:25], v[156:159], v[196:199], v[22:25]
	v_mfma_f32_16x16x32_bf16 v[22:25], v[152:155], v[192:195], v[22:25]
	v_mfma_f32_16x16x32_bf16 v[30:33], v[152:155], v[200:203], v[30:33]
	v_mfma_f32_16x16x32_bf16 v[30:33], v[156:159], v[204:207], v[30:33]
	v_mfma_f32_16x16x32_bf16 v[26:29], v[148:151], v[204:207], v[26:29]
	v_mfma_f32_16x16x32_bf16 v[26:29], v[142:145], v[200:203], v[26:29]
	v_mfma_f32_16x16x32_bf16 v[34:37], v[160:163], v[176:179], v[34:37]
	v_mfma_f32_16x16x32_bf16 v[34:37], v[164:167], v[180:183], v[34:37]
	v_mfma_f32_16x16x32_bf16 v[38:41], v[172:175], v[180:183], v[38:41]
	v_mfma_f32_16x16x32_bf16 v[38:41], v[168:171], v[176:179], v[38:41]
	v_mfma_f32_16x16x32_bf16 v[46:49], v[168:171], v[184:187], v[46:49]
	v_mfma_f32_16x16x32_bf16 v[46:49], v[172:175], v[188:191], v[46:49]
	v_mfma_f32_16x16x32_bf16 v[42:45], v[164:167], v[188:191], v[42:45]
	v_mfma_f32_16x16x32_bf16 v[42:45], v[160:163], v[184:187], v[42:45]
	v_mfma_f32_16x16x32_bf16 v[50:53], v[160:163], v[192:195], v[50:53]
	v_mfma_f32_16x16x32_bf16 v[50:53], v[164:167], v[196:199], v[50:53]
	v_mfma_f32_16x16x32_bf16 v[54:57], v[172:175], v[196:199], v[54:57]
	v_mfma_f32_16x16x32_bf16 v[54:57], v[168:171], v[192:195], v[54:57]
	v_mfma_f32_16x16x32_bf16 v[62:65], v[168:171], v[200:203], v[62:65]
	v_mfma_f32_16x16x32_bf16 v[62:65], v[172:175], v[204:207], v[62:65]
	s_setprio 2
	s_barrier
	v_mfma_f32_16x16x32_bf16 v[58:61], v[164:167], v[204:207], v[58:61]
	v_mfma_f32_16x16x32_bf16 v[58:61], v[160:163], v[200:203], v[58:61]
	s_setprio 0
	s_add_i32 s43, s58, s46
	s_mov_b32 m0, s43
	ds_read_b128 v[176:179], v141 offset:16384
	ds_read_b128 v[180:183], v141 offset:17408
	ds_read_b128 v[184:187], v141 offset:18432
	ds_read_b128 v[188:191], v141 offset:19456
	ds_read_b128 v[192:195], v141 offset:20480
	ds_read_b128 v[196:199], v141 offset:21504
	ds_read_b128 v[200:203], v141 offset:22528
	ds_read_b128 v[204:207], v141 offset:23552
	global_load_lds_dwordx4 v136, s[38:39]
	s_add_i32 m0, s43, 0x2000
	s_add_u32 s44, s38, 0x400000
	s_addc_u32 s45, s39, 0
	s_add_i32 s43, s59, s46
	global_load_lds_dwordx4 v134, s[38:39]
	s_mov_b32 m0, s43
	v_mov_b32_e32 v137, v131
	global_load_lds_dwordx4 v136, s[44:45]
	s_add_i32 m0, s43, 0x2000
	v_mov_b32_e32 v135, v131
	global_load_lds_dwordx4 v134, s[44:45]
	s_mov_b32 m0, s47
	v_lshl_add_u64 v[138:139], s[38:39], 0, v[136:137]
	global_load_lds_dwordx4 v130, s[40:41]
	s_mov_b32 m0, s48
	v_lshl_add_u64 v[208:209], s[38:39], 0, v[134:135]
	global_load_lds_dwordx4 v132, s[40:41]
	s_waitcnt vmcnt(8)
	s_waitcnt lgkmcnt(0)
	v_lshl_add_u64 v[210:211], s[40:41], 0, v[130:131]
	v_lshl_add_u64 v[212:213], s[40:41], 0, v[132:133]
	s_barrier
	s_setprio 1
	s_waitcnt lgkmcnt(0)
	v_mfma_f32_16x16x32_bf16 v[66:69], v[142:145], v[176:179], v[66:69]
	v_mfma_f32_16x16x32_bf16 v[66:69], v[148:151], v[180:183], v[66:69]
	v_mfma_f32_16x16x32_bf16 v[70:73], v[156:159], v[180:183], v[70:73]
	v_mfma_f32_16x16x32_bf16 v[70:73], v[152:155], v[176:179], v[70:73]
	v_mfma_f32_16x16x32_bf16 v[78:81], v[152:155], v[184:187], v[78:81]
	v_mfma_f32_16x16x32_bf16 v[78:81], v[156:159], v[188:191], v[78:81]
	v_mfma_f32_16x16x32_bf16 v[74:77], v[148:151], v[188:191], v[74:77]
	v_mfma_f32_16x16x32_bf16 v[74:77], v[142:145], v[184:187], v[74:77]
	v_mfma_f32_16x16x32_bf16 v[82:85], v[142:145], v[192:195], v[82:85]
	v_mfma_f32_16x16x32_bf16 v[82:85], v[148:151], v[196:199], v[82:85]
	v_mfma_f32_16x16x32_bf16 v[86:89], v[156:159], v[196:199], v[86:89]
	v_mfma_f32_16x16x32_bf16 v[86:89], v[152:155], v[192:195], v[86:89]
	v_mfma_f32_16x16x32_bf16 v[94:97], v[152:155], v[200:203], v[94:97]
	v_mfma_f32_16x16x32_bf16 v[94:97], v[156:159], v[204:207], v[94:97]
	v_mfma_f32_16x16x32_bf16 v[90:93], v[148:151], v[204:207], v[90:93]
	v_mfma_f32_16x16x32_bf16 v[90:93], v[142:145], v[200:203], v[90:93]
	v_mfma_f32_16x16x32_bf16 v[98:101], v[160:163], v[176:179], v[98:101]
	v_mfma_f32_16x16x32_bf16 v[98:101], v[164:167], v[180:183], v[98:101]
	v_mfma_f32_16x16x32_bf16 v[102:105], v[172:175], v[180:183], v[102:105]
	v_mfma_f32_16x16x32_bf16 v[102:105], v[168:171], v[176:179], v[102:105]
	v_mfma_f32_16x16x32_bf16 v[110:113], v[168:171], v[184:187], v[110:113]
	v_mfma_f32_16x16x32_bf16 v[110:113], v[172:175], v[188:191], v[110:113]
	v_mfma_f32_16x16x32_bf16 v[106:109], v[164:167], v[188:191], v[106:109]
	v_mfma_f32_16x16x32_bf16 v[106:109], v[160:163], v[184:187], v[106:109]
	v_mfma_f32_16x16x32_bf16 v[114:117], v[160:163], v[192:195], v[114:117]
	v_mfma_f32_16x16x32_bf16 v[114:117], v[164:167], v[196:199], v[114:117]
	v_mfma_f32_16x16x32_bf16 v[118:121], v[172:175], v[196:199], v[118:121]
	v_mfma_f32_16x16x32_bf16 v[118:121], v[168:171], v[192:195], v[118:121]
	v_mfma_f32_16x16x32_bf16 v[126:129], v[168:171], v[200:203], v[126:129]
	v_mfma_f32_16x16x32_bf16 v[126:129], v[172:175], v[204:207], v[126:129]
	s_setprio 2
	s_barrier
	v_mfma_f32_16x16x32_bf16 v[122:125], v[164:167], v[204:207], v[122:125]
	v_mfma_f32_16x16x32_bf16 v[122:125], v[160:163], v[200:203], v[122:125]
	s_setprio 0
	s_add_i32 s43, 0, 0x18000
	v_add_u32_e32 v135, s43, v140
	s_add_i32 s44, 0, 0x1c000
	ds_read_b128 v[142:145], v135
	ds_read_b128 v[148:151], v135 offset:1024
	ds_read_b128 v[152:155], v135 offset:2048
	ds_read_b128 v[156:159], v135 offset:3072
	v_add_u32_e32 v135, s44, v140
	ds_read_b128 v[160:163], v135
	ds_read_b128 v[164:167], v135 offset:1024
	ds_read_b128 v[168:171], v135 offset:2048
	ds_read_b128 v[172:175], v135 offset:3072
	s_add_u32 s40, s40, 0x80000
	s_addc_u32 s41, s41, 0
	s_mov_b32 m0, s49
	ds_read_b128 v[176:179], v141 offset:32768
	ds_read_b128 v[180:183], v141 offset:33792
	ds_read_b128 v[184:187], v141 offset:34816
	ds_read_b128 v[188:191], v141 offset:35840
	ds_read_b128 v[192:195], v141 offset:36864
	ds_read_b128 v[196:199], v141 offset:37888
	ds_read_b128 v[200:203], v141 offset:38912
	ds_read_b128 v[204:207], v141 offset:39936
	global_load_lds_dwordx4 v130, s[40:41]
	s_mov_b32 m0, s50
	s_nop 0
	global_load_lds_dwordx4 v132, s[40:41]
	s_waitcnt vmcnt(8)
	s_waitcnt lgkmcnt(0)
	s_barrier
	s_setprio 1
	s_waitcnt lgkmcnt(0)
	v_mfma_f32_16x16x32_bf16 v[2:5], v[142:145], v[176:179], v[2:5]
	v_mfma_f32_16x16x32_bf16 v[2:5], v[148:151], v[180:183], v[2:5]
	v_mfma_f32_16x16x32_bf16 v[6:9], v[156:159], v[180:183], v[6:9]
	v_mfma_f32_16x16x32_bf16 v[6:9], v[152:155], v[176:179], v[6:9]
	v_mfma_f32_16x16x32_bf16 v[14:17], v[152:155], v[184:187], v[14:17]
	v_mfma_f32_16x16x32_bf16 v[14:17], v[156:159], v[188:191], v[14:17]
	v_mfma_f32_16x16x32_bf16 v[10:13], v[148:151], v[188:191], v[10:13]
	v_mfma_f32_16x16x32_bf16 v[10:13], v[142:145], v[184:187], v[10:13]
	v_mfma_f32_16x16x32_bf16 v[18:21], v[142:145], v[192:195], v[18:21]
	v_mfma_f32_16x16x32_bf16 v[18:21], v[148:151], v[196:199], v[18:21]
	v_mfma_f32_16x16x32_bf16 v[22:25], v[156:159], v[196:199], v[22:25]
	v_mfma_f32_16x16x32_bf16 v[22:25], v[152:155], v[192:195], v[22:25]
	v_mfma_f32_16x16x32_bf16 v[30:33], v[152:155], v[200:203], v[30:33]
	v_mfma_f32_16x16x32_bf16 v[30:33], v[156:159], v[204:207], v[30:33]
	v_mfma_f32_16x16x32_bf16 v[26:29], v[148:151], v[204:207], v[26:29]
	v_mfma_f32_16x16x32_bf16 v[26:29], v[142:145], v[200:203], v[26:29]
	v_mfma_f32_16x16x32_bf16 v[34:37], v[160:163], v[176:179], v[34:37]
	v_mfma_f32_16x16x32_bf16 v[34:37], v[164:167], v[180:183], v[34:37]
	v_mfma_f32_16x16x32_bf16 v[38:41], v[172:175], v[180:183], v[38:41]
	v_mfma_f32_16x16x32_bf16 v[38:41], v[168:171], v[176:179], v[38:41]
	v_mfma_f32_16x16x32_bf16 v[46:49], v[168:171], v[184:187], v[46:49]
	v_mfma_f32_16x16x32_bf16 v[46:49], v[172:175], v[188:191], v[46:49]
	v_mfma_f32_16x16x32_bf16 v[42:45], v[164:167], v[188:191], v[42:45]
	v_mfma_f32_16x16x32_bf16 v[42:45], v[160:163], v[184:187], v[42:45]
	v_mfma_f32_16x16x32_bf16 v[50:53], v[160:163], v[192:195], v[50:53]
	v_mfma_f32_16x16x32_bf16 v[50:53], v[164:167], v[196:199], v[50:53]
	v_mfma_f32_16x16x32_bf16 v[54:57], v[172:175], v[196:199], v[54:57]
	v_mfma_f32_16x16x32_bf16 v[54:57], v[168:171], v[192:195], v[54:57]
	v_mfma_f32_16x16x32_bf16 v[62:65], v[168:171], v[200:203], v[62:65]
	v_mfma_f32_16x16x32_bf16 v[62:65], v[172:175], v[204:207], v[62:65]
	s_setprio 2
	s_barrier
	v_mfma_f32_16x16x32_bf16 v[58:61], v[164:167], v[204:207], v[58:61]
	v_mfma_f32_16x16x32_bf16 v[58:61], v[160:163], v[200:203], v[58:61]
	s_setprio 0
	s_add_i32 s40, s43, s46
	v_lshl_add_u64 v[138:139], v[138:139], 0, s[6:7]
	s_mov_b32 m0, s40
	ds_read_b128 v[176:179], v141 offset:49152
	ds_read_b128 v[180:183], v141 offset:50176
	ds_read_b128 v[184:187], v141 offset:51200
	ds_read_b128 v[188:191], v141 offset:52224
	ds_read_b128 v[192:195], v141 offset:53248
	ds_read_b128 v[196:199], v141 offset:54272
	ds_read_b128 v[200:203], v141 offset:55296
	ds_read_b128 v[204:207], v141 offset:56320
	global_load_lds_dwordx4 v[138:139], off
	s_add_i32 m0, s40, 0x2000
	s_add_u32 s38, s38, 0x400080
	v_lshl_add_u64 v[138:139], v[208:209], 0, s[6:7]
	s_addc_u32 s39, s39, 0
	s_add_i32 s40, s44, s46
	global_load_lds_dwordx4 v[138:139], off
	s_mov_b32 m0, s40
	v_lshl_add_u64 v[138:139], v[210:211], 0, s[6:7]
	global_load_lds_dwordx4 v136, s[38:39]
	s_add_i32 m0, s40, 0x2000
	s_nop 0
	global_load_lds_dwordx4 v134, s[38:39]
	s_mov_b32 m0, s54
	s_nop 0
	global_load_lds_dwordx4 v[138:139], off
	v_lshl_add_u64 v[138:139], v[212:213], 0, s[6:7]
	s_mov_b32 m0, s55
	s_nop 0
	global_load_lds_dwordx4 v[138:139], off
	s_waitcnt vmcnt(8)
	s_waitcnt lgkmcnt(0)
	s_barrier
	s_setprio 1
	s_waitcnt lgkmcnt(0)
	v_mfma_f32_16x16x32_bf16 v[66:69], v[142:145], v[176:179], v[66:69]
	v_mfma_f32_16x16x32_bf16 v[66:69], v[148:151], v[180:183], v[66:69]
	v_mfma_f32_16x16x32_bf16 v[70:73], v[156:159], v[180:183], v[70:73]
	v_mfma_f32_16x16x32_bf16 v[70:73], v[152:155], v[176:179], v[70:73]
	v_mfma_f32_16x16x32_bf16 v[78:81], v[152:155], v[184:187], v[78:81]
	v_mfma_f32_16x16x32_bf16 v[78:81], v[156:159], v[188:191], v[78:81]
	v_mfma_f32_16x16x32_bf16 v[74:77], v[148:151], v[188:191], v[74:77]
	v_mfma_f32_16x16x32_bf16 v[74:77], v[142:145], v[184:187], v[74:77]
	v_mfma_f32_16x16x32_bf16 v[82:85], v[142:145], v[192:195], v[82:85]
	v_mfma_f32_16x16x32_bf16 v[82:85], v[148:151], v[196:199], v[82:85]
	v_mfma_f32_16x16x32_bf16 v[86:89], v[156:159], v[196:199], v[86:89]
	v_mfma_f32_16x16x32_bf16 v[86:89], v[152:155], v[192:195], v[86:89]
	v_mfma_f32_16x16x32_bf16 v[94:97], v[152:155], v[200:203], v[94:97]
	v_mfma_f32_16x16x32_bf16 v[94:97], v[156:159], v[204:207], v[94:97]
	v_mfma_f32_16x16x32_bf16 v[90:93], v[148:151], v[204:207], v[90:93]
	v_mfma_f32_16x16x32_bf16 v[90:93], v[142:145], v[200:203], v[90:93]
	v_mfma_f32_16x16x32_bf16 v[98:101], v[160:163], v[176:179], v[98:101]
	v_mfma_f32_16x16x32_bf16 v[98:101], v[164:167], v[180:183], v[98:101]
	v_mfma_f32_16x16x32_bf16 v[102:105], v[172:175], v[180:183], v[102:105]
	v_mfma_f32_16x16x32_bf16 v[102:105], v[168:171], v[176:179], v[102:105]
	v_mfma_f32_16x16x32_bf16 v[110:113], v[168:171], v[184:187], v[110:113]
	v_mfma_f32_16x16x32_bf16 v[110:113], v[172:175], v[188:191], v[110:113]
	v_mfma_f32_16x16x32_bf16 v[106:109], v[164:167], v[188:191], v[106:109]
	v_mfma_f32_16x16x32_bf16 v[106:109], v[160:163], v[184:187], v[106:109]
	v_mfma_f32_16x16x32_bf16 v[114:117], v[160:163], v[192:195], v[114:117]
	v_mfma_f32_16x16x32_bf16 v[114:117], v[164:167], v[196:199], v[114:117]
	v_mfma_f32_16x16x32_bf16 v[118:121], v[172:175], v[196:199], v[118:121]
	v_mfma_f32_16x16x32_bf16 v[118:121], v[168:171], v[192:195], v[118:121]
	v_mfma_f32_16x16x32_bf16 v[126:129], v[168:171], v[200:203], v[126:129]
	v_mfma_f32_16x16x32_bf16 v[126:129], v[172:175], v[204:207], v[126:129]
	s_setprio 2
	s_barrier
	v_mfma_f32_16x16x32_bf16 v[122:125], v[164:167], v[204:207], v[122:125]
	v_mfma_f32_16x16x32_bf16 v[122:125], v[160:163], v[200:203], v[122:125]
	s_setprio 0
	s_add_i32 s42, s42, 2
	s_add_u32 s36, s36, 0x100
	s_addc_u32 s37, s37, 0
	s_add_u32 s15, s15, 0x100
	s_addc_u32 s27, s27, 0
	s_cmp_gt_u32 s42, 5
	s_cbranch_scc0 .LBB0_499
	s_and_b64 vcc, exec, s[8:9]
	s_cbranch_vccz .LBB0_502
	s_barrier

.LBB0_528:
	s_add_i32 s53, 0, 0x10000
	s_add_i32 s72, 0, 0x14000
	v_add_u32_e32 v16, s53, v147
	v_add_u32_e32 v32, s72, v147
	ds_read_b128 v[4:7], v16
	ds_read_b128 v[8:11], v16 offset:1024
	ds_read_b128 v[12:15], v16 offset:2048
	ds_read_b128 v[16:19], v16 offset:3072
	ds_read_b128 v[20:23], v32
	ds_read_b128 v[24:27], v32 offset:1024
	ds_read_b128 v[28:31], v32 offset:2048
	ds_read_b128 v[32:35], v32 offset:3072
	v_add_u32_e32 v231, 0, v146
	ds_read_b128 v[36:39], v231
	ds_read_b128 v[40:43], v231 offset:1024
	ds_read_b128 v[44:47], v231 offset:2048
	ds_read_b128 v[48:51], v231 offset:3072
	ds_read_b128 v[52:55], v231 offset:4096
	ds_read_b128 v[56:59], v231 offset:5120
	ds_read_b128 v[60:63], v231 offset:6144
	ds_read_b128 v[64:67], v231 offset:7168
	s_waitcnt vmcnt(8)
	s_waitcnt lgkmcnt(0)
	s_barrier
	s_setprio 1
	s_waitcnt lgkmcnt(0)
	v_mfma_f32_16x16x32_f16 v[68:71], v[4:7], v[36:39], 0
	v_mfma_f32_16x16x32_f16 v[68:71], v[8:11], v[40:43], v[68:71]
	v_mfma_f32_16x16x32_f16 v[72:75], v[12:15], v[36:39], 0
	v_mfma_f32_16x16x32_f16 v[72:75], v[16:19], v[40:43], v[72:75]
	v_mfma_f32_16x16x32_f16 v[80:83], v[12:15], v[44:47], 0
	v_mfma_f32_16x16x32_f16 v[80:83], v[16:19], v[48:51], v[80:83]
	v_mfma_f32_16x16x32_f16 v[76:79], v[4:7], v[44:47], 0
	v_mfma_f32_16x16x32_f16 v[76:79], v[8:11], v[48:51], v[76:79]
	v_mfma_f32_16x16x32_f16 v[84:87], v[4:7], v[52:55], 0
	v_mfma_f32_16x16x32_f16 v[84:87], v[8:11], v[56:59], v[84:87]
	v_mfma_f32_16x16x32_f16 v[88:91], v[12:15], v[52:55], 0
	v_mfma_f32_16x16x32_f16 v[88:91], v[16:19], v[56:59], v[88:91]
	v_mfma_f32_16x16x32_f16 v[96:99], v[12:15], v[60:63], 0
	v_mfma_f32_16x16x32_f16 v[96:99], v[16:19], v[64:67], v[96:99]
	v_mfma_f32_16x16x32_f16 v[92:95], v[4:7], v[60:63], 0
	v_mfma_f32_16x16x32_f16 v[92:95], v[8:11], v[64:67], v[92:95]
	v_mfma_f32_16x16x32_f16 v[100:103], v[20:23], v[36:39], 0
	v_mfma_f32_16x16x32_f16 v[36:39], v[28:31], v[36:39], 0
	v_mfma_f32_16x16x32_f16 v[104:107], v[20:23], v[44:47], 0
	v_mfma_f32_16x16x32_f16 v[44:47], v[28:31], v[44:47], 0
	v_mfma_f32_16x16x32_f16 v[108:111], v[20:23], v[52:55], 0
	v_mfma_f32_16x16x32_f16 v[52:55], v[28:31], v[52:55], 0
	v_mfma_f32_16x16x32_f16 v[112:115], v[20:23], v[60:63], 0
	v_mfma_f32_16x16x32_f16 v[60:63], v[28:31], v[60:63], 0
	v_mfma_f32_16x16x32_f16 v[100:103], v[24:27], v[40:43], v[100:103]
	v_mfma_f32_16x16x32_f16 v[40:43], v[32:35], v[40:43], v[36:39]
	v_mfma_f32_16x16x32_f16 v[104:107], v[24:27], v[48:51], v[104:107]
	v_mfma_f32_16x16x32_f16 v[48:51], v[32:35], v[48:51], v[44:47]
	v_mfma_f32_16x16x32_f16 v[108:111], v[24:27], v[56:59], v[108:111]
	v_mfma_f32_16x16x32_f16 v[56:59], v[32:35], v[56:59], v[52:55]
	s_setprio 2
	s_barrier
	v_mfma_f32_16x16x32_f16 v[112:115], v[24:27], v[64:67], v[112:115]
	v_mfma_f32_16x16x32_f16 v[64:67], v[32:35], v[64:67], v[60:63]
	s_setprio 0
	v_lshl_add_u64 v[136:137], s[6:7], 0, v[2:3]
	s_add_i32 s53, s53, s38
	v_mov_b32_e32 v135, v3
	v_lshl_add_u64 v[140:141], v[136:137], 0, s[74:75]
	s_mov_b32 m0, s53
	v_lshl_add_u64 v[144:145], s[6:7], 0, v[134:135]
	ds_read_b128 v[36:39], v231 offset:16384
	ds_read_b128 v[44:47], v231 offset:17408
	ds_read_b128 v[52:55], v231 offset:18432
	ds_read_b128 v[60:63], v231 offset:19456
	ds_read_b128 v[116:119], v231 offset:20480
	ds_read_b128 v[120:123], v231 offset:21504
	ds_read_b128 v[124:127], v231 offset:22528
	ds_read_b128 v[128:131], v231 offset:23552
	global_load_lds_dwordx4 v[140:141], off
	v_lshl_add_u64 v[140:141], v[144:145], 0, s[74:75]
	s_add_i32 m0, s53, 0x2000
	s_add_i32 s53, s72, s38
	global_load_lds_dwordx4 v[140:141], off
	s_mov_b32 m0, s53
	v_mov_b32_e32 v139, v3
	global_load_lds_dwordx4 v2, s[16:17]
	s_add_i32 m0, s53, 0x2000
	v_lshl_add_u64 v[248:249], s[8:9], 0, v[138:139]
	v_mov_b32_e32 v133, v3
	global_load_lds_dwordx4 v134, s[16:17]
	v_lshl_add_u64 v[140:141], v[248:249], 0, s[74:75]
	s_mov_b32 m0, s58
	v_lshl_add_u64 v[250:251], s[8:9], 0, v[132:133]
	global_load_lds_dwordx4 v[140:141], off
	v_lshl_add_u64 v[140:141], v[250:251], 0, s[74:75]
	s_mov_b32 m0, s59
	s_nop 0
	global_load_lds_dwordx4 v[140:141], off
	s_waitcnt vmcnt(8)
	s_waitcnt lgkmcnt(0)
	s_barrier
	s_setprio 1
	s_waitcnt lgkmcnt(0)
	v_mfma_f32_16x16x32_f16 v[140:143], v[4:7], v[36:39], 0
	v_mfma_f32_16x16x32_f16 v[148:151], v[12:15], v[36:39], 0
	v_mfma_f32_16x16x32_f16 v[152:155], v[4:7], v[52:55], 0
	v_mfma_f32_16x16x32_f16 v[156:159], v[12:15], v[52:55], 0
	v_mfma_f32_16x16x32_f16 v[160:163], v[4:7], v[116:119], 0
	v_mfma_f32_16x16x32_f16 v[164:167], v[12:15], v[116:119], 0
	v_mfma_f32_16x16x32_f16 v[4:7], v[4:7], v[124:127], 0
	v_mfma_f32_16x16x32_f16 v[12:15], v[12:15], v[124:127], 0
	v_mfma_f32_16x16x32_f16 v[140:143], v[8:11], v[44:47], v[140:143]
	v_mfma_f32_16x16x32_f16 v[148:151], v[16:19], v[44:47], v[148:151]
	v_mfma_f32_16x16x32_f16 v[152:155], v[8:11], v[60:63], v[152:155]
	v_mfma_f32_16x16x32_f16 v[156:159], v[16:19], v[60:63], v[156:159]
	v_mfma_f32_16x16x32_f16 v[160:163], v[8:11], v[120:123], v[160:163]
	v_mfma_f32_16x16x32_f16 v[164:167], v[16:19], v[120:123], v[164:167]
	v_mfma_f32_16x16x32_f16 v[168:171], v[8:11], v[128:131], v[4:7]
	v_mfma_f32_16x16x32_f16 v[172:175], v[16:19], v[128:131], v[12:15]
	v_mfma_f32_16x16x32_f16 v[4:7], v[20:23], v[36:39], 0
	v_mfma_f32_16x16x32_f16 v[8:11], v[28:31], v[36:39], 0
	v_mfma_f32_16x16x32_f16 v[12:15], v[20:23], v[52:55], 0
	v_mfma_f32_16x16x32_f16 v[16:19], v[28:31], v[52:55], 0
	v_mfma_f32_16x16x32_f16 v[36:39], v[20:23], v[116:119], 0
	v_mfma_f32_16x16x32_f16 v[52:55], v[28:31], v[116:119], 0
	v_mfma_f32_16x16x32_f16 v[20:23], v[20:23], v[124:127], 0
	v_mfma_f32_16x16x32_f16 v[28:31], v[28:31], v[124:127], 0
	v_mfma_f32_16x16x32_f16 v[116:119], v[24:27], v[44:47], v[4:7]
	v_mfma_f32_16x16x32_f16 v[124:127], v[32:35], v[44:47], v[8:11]
	v_mfma_f32_16x16x32_f16 v[184:187], v[24:27], v[120:123], v[36:39]
	v_mfma_f32_16x16x32_f16 v[120:123], v[32:35], v[120:123], v[52:55]
	v_mfma_f32_16x16x32_f16 v[188:191], v[24:27], v[128:131], v[20:23]
	v_mfma_f32_16x16x32_f16 v[128:131], v[32:35], v[128:131], v[28:31]
	s_setprio 2
	s_barrier
	v_mfma_f32_16x16x32_f16 v[176:179], v[24:27], v[60:63], v[12:15]
	v_mfma_f32_16x16x32_f16 v[180:183], v[32:35], v[60:63], v[16:19]
	s_setprio 0
	s_add_i32 s53, 0, 0x18000
	v_add_u32_e32 v4, s53, v147
	s_add_i32 s72, 0, 0x1c000
	ds_read_b128 v[192:195], v4
	ds_read_b128 v[196:199], v4 offset:1024
	ds_read_b128 v[200:203], v4 offset:2048
	ds_read_b128 v[204:207], v4 offset:3072
	v_add_u32_e32 v4, s72, v147
	ds_read_b128 v[208:211], v4
	ds_read_b128 v[212:215], v4 offset:1024
	ds_read_b128 v[216:219], v4 offset:2048
	ds_read_b128 v[220:223], v4 offset:3072
	s_mov_b32 m0, s60
	ds_read_b128 v[44:47], v231 offset:32768
	ds_read_b128 v[52:55], v231 offset:33792
	ds_read_b128 v[60:63], v231 offset:34816
	ds_read_b128 v[224:227], v231 offset:35840
	ds_read_b128 v[232:235], v231 offset:36864
	ds_read_b128 v[236:239], v231 offset:37888
	ds_read_b128 v[240:243], v231 offset:38912
	ds_read_b128 v[244:247], v231 offset:39936
	global_load_lds_dwordx4 v138, s[26:27]
	s_mov_b32 m0, s61
	s_nop 0
	global_load_lds_dwordx4 v132, s[26:27]
	s_waitcnt vmcnt(8)
	s_waitcnt lgkmcnt(0)
	s_barrier
	s_setprio 1
	s_waitcnt lgkmcnt(0)
	v_mfma_f32_16x16x32_f16 v[4:7], v[192:195], v[44:47], v[68:71]
	v_mfma_f32_16x16x32_f16 v[8:11], v[200:203], v[44:47], v[72:75]
	v_mfma_f32_16x16x32_f16 v[12:15], v[192:195], v[60:63], v[76:79]
	v_mfma_f32_16x16x32_f16 v[16:19], v[200:203], v[60:63], v[80:83]
	v_mfma_f32_16x16x32_f16 v[20:23], v[192:195], v[232:235], v[84:87]
	v_mfma_f32_16x16x32_f16 v[24:27], v[200:203], v[232:235], v[88:91]
	v_mfma_f32_16x16x32_f16 v[28:31], v[192:195], v[240:243], v[92:95]
	v_mfma_f32_16x16x32_f16 v[32:35], v[200:203], v[240:243], v[96:99]
	v_mfma_f32_16x16x32_f16 v[4:7], v[196:199], v[52:55], v[4:7]
	v_mfma_f32_16x16x32_f16 v[8:11], v[204:207], v[52:55], v[8:11]
	v_mfma_f32_16x16x32_f16 v[12:15], v[196:199], v[224:227], v[12:15]
	v_mfma_f32_16x16x32_f16 v[16:19], v[204:207], v[224:227], v[16:19]
	v_mfma_f32_16x16x32_f16 v[20:23], v[196:199], v[236:239], v[20:23]
	v_mfma_f32_16x16x32_f16 v[24:27], v[204:207], v[236:239], v[24:27]
	v_mfma_f32_16x16x32_f16 v[28:31], v[196:199], v[244:247], v[28:31]
	v_mfma_f32_16x16x32_f16 v[32:35], v[204:207], v[244:247], v[32:35]
	v_mfma_f32_16x16x32_f16 v[36:39], v[208:211], v[44:47], v[100:103]
	v_mfma_f32_16x16x32_f16 v[40:43], v[216:219], v[44:47], v[40:43]
	v_mfma_f32_16x16x32_f16 v[36:39], v[212:215], v[52:55], v[36:39]
	v_mfma_f32_16x16x32_f16 v[40:43], v[220:223], v[52:55], v[40:43]
	v_mfma_f32_16x16x32_f16 v[44:47], v[208:211], v[60:63], v[104:107]
	v_mfma_f32_16x16x32_f16 v[48:51], v[216:219], v[60:63], v[48:51]
	v_mfma_f32_16x16x32_f16 v[52:55], v[208:211], v[232:235], v[108:111]
	v_mfma_f32_16x16x32_f16 v[56:59], v[216:219], v[232:235], v[56:59]
	v_mfma_f32_16x16x32_f16 v[60:63], v[208:211], v[240:243], v[112:115]
	v_mfma_f32_16x16x32_f16 v[64:67], v[216:219], v[240:243], v[64:67]
	v_mfma_f32_16x16x32_f16 v[44:47], v[212:215], v[224:227], v[44:47]
	v_mfma_f32_16x16x32_f16 v[48:51], v[220:223], v[224:227], v[48:51]
	v_mfma_f32_16x16x32_f16 v[52:55], v[212:215], v[236:239], v[52:55]
	v_mfma_f32_16x16x32_f16 v[56:59], v[220:223], v[236:239], v[56:59]
	s_setprio 2
	s_barrier
	v_mfma_f32_16x16x32_f16 v[60:63], v[212:215], v[244:247], v[60:63]
	v_mfma_f32_16x16x32_f16 v[64:67], v[220:223], v[244:247], v[64:67]
	s_setprio 0
	s_add_i32 s53, s53, s38
	v_lshl_add_u64 v[68:69], v[136:137], 0, s[24:25]
	s_mov_b32 m0, s53
	ds_read_b128 v[104:107], v231 offset:49152
	ds_read_b128 v[108:111], v231 offset:50176
	ds_read_b128 v[112:115], v231 offset:51200
	ds_read_b128 v[224:227], v231 offset:52224
	ds_read_b128 v[232:235], v231 offset:53248
	ds_read_b128 v[236:239], v231 offset:54272
	ds_read_b128 v[240:243], v231 offset:55296
	ds_read_b128 v[244:247], v231 offset:56320
	global_load_lds_dwordx4 v[68:69], off
	v_lshl_add_u64 v[68:69], v[144:145], 0, s[24:25]
	s_add_i32 m0, s53, 0x2000
	s_add_i32 s53, s72, s38
	global_load_lds_dwordx4 v[68:69], off
	s_mov_b32 m0, s53
	v_lshl_add_u64 v[68:69], v[248:249], 0, s[24:25]
	global_load_lds_dwordx4 v2, s[28:29]
	s_add_i32 m0, s53, 0x2000
	s_nop 0
	global_load_lds_dwordx4 v134, s[28:29]
	s_mov_b32 m0, s64
	s_nop 0
	global_load_lds_dwordx4 v[68:69], off
	v_lshl_add_u64 v[68:69], v[250:251], 0, s[24:25]
	s_mov_b32 m0, s65
	s_nop 0
	global_load_lds_dwordx4 v[68:69], off
	s_waitcnt vmcnt(8)
	s_waitcnt lgkmcnt(0)
	s_barrier
	s_setprio 1
	s_waitcnt lgkmcnt(0)
	v_mfma_f32_16x16x32_f16 v[68:71], v[192:195], v[104:107], v[140:143]
	v_mfma_f32_16x16x32_f16 v[72:75], v[200:203], v[104:107], v[148:151]
	v_mfma_f32_16x16x32_f16 v[76:79], v[192:195], v[112:115], v[152:155]
	v_mfma_f32_16x16x32_f16 v[80:83], v[200:203], v[112:115], v[156:159]
	v_mfma_f32_16x16x32_f16 v[84:87], v[192:195], v[232:235], v[160:163]
	v_mfma_f32_16x16x32_f16 v[88:91], v[200:203], v[232:235], v[164:167]
	v_mfma_f32_16x16x32_f16 v[92:95], v[192:195], v[240:243], v[168:171]
	v_mfma_f32_16x16x32_f16 v[96:99], v[200:203], v[240:243], v[172:175]
	v_mfma_f32_16x16x32_f16 v[68:71], v[196:199], v[108:111], v[68:71]
	v_mfma_f32_16x16x32_f16 v[72:75], v[204:207], v[108:111], v[72:75]
	v_mfma_f32_16x16x32_f16 v[76:79], v[196:199], v[224:227], v[76:79]
	v_mfma_f32_16x16x32_f16 v[80:83], v[204:207], v[224:227], v[80:83]
	v_mfma_f32_16x16x32_f16 v[84:87], v[196:199], v[236:239], v[84:87]
	v_mfma_f32_16x16x32_f16 v[88:91], v[204:207], v[236:239], v[88:91]
	v_mfma_f32_16x16x32_f16 v[92:95], v[196:199], v[244:247], v[92:95]
	v_mfma_f32_16x16x32_f16 v[96:99], v[204:207], v[244:247], v[96:99]
	v_mfma_f32_16x16x32_f16 v[100:103], v[208:211], v[104:107], v[116:119]
	v_mfma_f32_16x16x32_f16 v[104:107], v[216:219], v[104:107], v[124:127]
	v_mfma_f32_16x16x32_f16 v[100:103], v[212:215], v[108:111], v[100:103]
	v_mfma_f32_16x16x32_f16 v[104:107], v[220:223], v[108:111], v[104:107]
	v_mfma_f32_16x16x32_f16 v[108:111], v[208:211], v[112:115], v[176:179]
	v_mfma_f32_16x16x32_f16 v[112:115], v[216:219], v[112:115], v[180:183]
	v_mfma_f32_16x16x32_f16 v[116:119], v[208:211], v[232:235], v[184:187]
	v_mfma_f32_16x16x32_f16 v[120:123], v[216:219], v[232:235], v[120:123]
	v_mfma_f32_16x16x32_f16 v[124:127], v[208:211], v[240:243], v[188:191]
	v_mfma_f32_16x16x32_f16 v[128:131], v[216:219], v[240:243], v[128:131]
	v_mfma_f32_16x16x32_f16 v[108:111], v[212:215], v[224:227], v[108:111]
	v_mfma_f32_16x16x32_f16 v[112:115], v[220:223], v[224:227], v[112:115]
	v_mfma_f32_16x16x32_f16 v[116:119], v[212:215], v[236:239], v[116:119]
	v_mfma_f32_16x16x32_f16 v[120:123], v[220:223], v[236:239], v[120:123]
	s_setprio 2
	s_barrier
	v_mfma_f32_16x16x32_f16 v[124:127], v[212:215], v[244:247], v[124:127]
	v_mfma_f32_16x16x32_f16 v[128:131], v[220:223], v[244:247], v[128:131]
	s_setprio 0
	s_add_i32 s41, s41, 2
	s_cmp_ge_i32 s41, s40
	s_cbranch_scc0 .LBB0_528
	v_mov_b32_e32 v136, v2
	s_branch .LBB0_531

.LBB0_532:
	s_add_u32 s6, s8, 0xfff80080
	s_addc_u32 s7, s9, -1
	s_add_i32 s29, 0, 0x10000
	s_cmp_eq_u32 s28, 28
	s_cselect_b32 s17, s13, s7
	s_cselect_b32 s16, s12, s6
	s_cselect_b32 s7, s15, s27
	s_cselect_b32 s6, s14, s26
	s_add_i32 s53, 0, 0x14000
	ds_read_b128 v[138:141], v240
	ds_read_b128 v[142:145], v240 offset:1024
	ds_read_b128 v[148:151], v240 offset:2048
	ds_read_b128 v[152:155], v240 offset:3072
	ds_read_b128 v[156:159], v240 offset:16384
	ds_read_b128 v[160:163], v240 offset:17408
	ds_read_b128 v[164:167], v240 offset:18432
	ds_read_b128 v[168:171], v240 offset:19456
	s_mov_b32 m0, s66
	ds_read_b128 v[172:175], v146
	ds_read_b128 v[176:179], v146 offset:1024
	ds_read_b128 v[180:183], v146 offset:2048
	ds_read_b128 v[184:187], v146 offset:3072
	ds_read_b128 v[188:191], v146 offset:4096
	ds_read_b128 v[192:195], v146 offset:5120
	ds_read_b128 v[196:199], v146 offset:6144
	ds_read_b128 v[200:203], v146 offset:7168
	global_load_lds_dwordx4 v2, s[8:9]
	s_mov_b32 m0, s67
	v_mov_b32_e32 v133, v3
	global_load_lds_dwordx4 v132, s[8:9]
	s_waitcnt vmcnt(8)
	s_waitcnt lgkmcnt(0)
	s_barrier
	s_setprio 1
	s_waitcnt lgkmcnt(0)
	v_mfma_f32_16x16x32_f16 v[4:7], v[138:141], v[172:175], v[4:7]
	v_mfma_f32_16x16x32_f16 v[4:7], v[142:145], v[176:179], v[4:7]
	v_mfma_f32_16x16x32_f16 v[8:11], v[152:155], v[176:179], v[8:11]
	v_mfma_f32_16x16x32_f16 v[8:11], v[148:151], v[172:175], v[8:11]
	v_mfma_f32_16x16x32_f16 v[16:19], v[148:151], v[180:183], v[16:19]
	v_mfma_f32_16x16x32_f16 v[16:19], v[152:155], v[184:187], v[16:19]
	v_mfma_f32_16x16x32_f16 v[12:15], v[142:145], v[184:187], v[12:15]
	v_mfma_f32_16x16x32_f16 v[12:15], v[138:141], v[180:183], v[12:15]
	v_mfma_f32_16x16x32_f16 v[20:23], v[138:141], v[188:191], v[20:23]
	v_mfma_f32_16x16x32_f16 v[20:23], v[142:145], v[192:195], v[20:23]
	v_mfma_f32_16x16x32_f16 v[24:27], v[152:155], v[192:195], v[24:27]
	v_mfma_f32_16x16x32_f16 v[24:27], v[148:151], v[188:191], v[24:27]
	v_mfma_f32_16x16x32_f16 v[32:35], v[148:151], v[196:199], v[32:35]
	v_mfma_f32_16x16x32_f16 v[32:35], v[152:155], v[200:203], v[32:35]
	v_mfma_f32_16x16x32_f16 v[28:31], v[142:145], v[200:203], v[28:31]
	v_mfma_f32_16x16x32_f16 v[28:31], v[138:141], v[196:199], v[28:31]
	v_mfma_f32_16x16x32_f16 v[36:39], v[156:159], v[172:175], v[36:39]
	v_mfma_f32_16x16x32_f16 v[36:39], v[160:163], v[176:179], v[36:39]
	v_mfma_f32_16x16x32_f16 v[40:43], v[168:171], v[176:179], v[40:43]
	v_mfma_f32_16x16x32_f16 v[40:43], v[164:167], v[172:175], v[40:43]
	v_mfma_f32_16x16x32_f16 v[48:51], v[164:167], v[180:183], v[48:51]
	v_mfma_f32_16x16x32_f16 v[48:51], v[168:171], v[184:187], v[48:51]
	v_mfma_f32_16x16x32_f16 v[44:47], v[160:163], v[184:187], v[44:47]
	v_mfma_f32_16x16x32_f16 v[44:47], v[156:159], v[180:183], v[44:47]
	v_mfma_f32_16x16x32_f16 v[52:55], v[156:159], v[188:191], v[52:55]
	v_mfma_f32_16x16x32_f16 v[52:55], v[160:163], v[192:195], v[52:55]
	v_mfma_f32_16x16x32_f16 v[56:59], v[168:171], v[192:195], v[56:59]
	v_mfma_f32_16x16x32_f16 v[56:59], v[164:167], v[188:191], v[56:59]
	v_mfma_f32_16x16x32_f16 v[64:67], v[164:167], v[196:199], v[64:67]
	v_mfma_f32_16x16x32_f16 v[64:67], v[168:171], v[200:203], v[64:67]
	s_setprio 2
	s_barrier
	v_mfma_f32_16x16x32_f16 v[60:63], v[160:163], v[200:203], v[60:63]
	v_mfma_f32_16x16x32_f16 v[60:63], v[156:159], v[196:199], v[60:63]
	s_setprio 0
	s_add_i32 s29, s29, s38
	s_mov_b32 m0, s29
	ds_read_b128 v[172:175], v146 offset:16384
	ds_read_b128 v[176:179], v146 offset:17408
	ds_read_b128 v[180:183], v146 offset:18432
	ds_read_b128 v[184:187], v146 offset:19456
	ds_read_b128 v[188:191], v146 offset:20480
	ds_read_b128 v[192:195], v146 offset:21504
	ds_read_b128 v[196:199], v146 offset:22528
	ds_read_b128 v[200:203], v146 offset:23552
	global_load_lds_dwordx4 v136, s[6:7]
	s_add_i32 m0, s29, 0x2000
	s_add_u32 s40, s6, 0x80000
	s_addc_u32 s41, s7, 0
	s_add_i32 s29, s53, s38
	global_load_lds_dwordx4 v134, s[6:7]
	s_mov_b32 m0, s29
	v_mov_b32_e32 v137, v3
	global_load_lds_dwordx4 v136, s[40:41]
	s_add_i32 m0, s29, 0x2000
	v_mov_b32_e32 v135, v3
	global_load_lds_dwordx4 v134, s[40:41]
	s_mov_b32 m0, s58
	s_nop 0
	global_load_lds_dwordx4 v2, s[16:17]
	s_mov_b32 m0, s59
	s_nop 0
	global_load_lds_dwordx4 v132, s[16:17]
	s_waitcnt vmcnt(8)
	s_waitcnt lgkmcnt(0)
	s_add_u32 s88, s6, s86
	s_addc_u32 s89, s7, s87
	s_add_u32 s90, s16, s86
	s_addc_u32 s91, s17, s87
	s_barrier
	s_setprio 1
	s_waitcnt lgkmcnt(0)
	v_mfma_f32_16x16x32_f16 v[68:71], v[138:141], v[172:175], v[68:71]
	v_mfma_f32_16x16x32_f16 v[68:71], v[142:145], v[176:179], v[68:71]
	v_mfma_f32_16x16x32_f16 v[72:75], v[152:155], v[176:179], v[72:75]
	v_mfma_f32_16x16x32_f16 v[72:75], v[148:151], v[172:175], v[72:75]
	v_mfma_f32_16x16x32_f16 v[80:83], v[148:151], v[180:183], v[80:83]
	v_mfma_f32_16x16x32_f16 v[80:83], v[152:155], v[184:187], v[80:83]
	v_mfma_f32_16x16x32_f16 v[76:79], v[142:145], v[184:187], v[76:79]
	v_mfma_f32_16x16x32_f16 v[76:79], v[138:141], v[180:183], v[76:79]
	v_mfma_f32_16x16x32_f16 v[84:87], v[138:141], v[188:191], v[84:87]
	v_mfma_f32_16x16x32_f16 v[84:87], v[142:145], v[192:195], v[84:87]
	v_mfma_f32_16x16x32_f16 v[88:91], v[152:155], v[192:195], v[88:91]
	v_mfma_f32_16x16x32_f16 v[88:91], v[148:151], v[188:191], v[88:91]
	v_mfma_f32_16x16x32_f16 v[96:99], v[148:151], v[196:199], v[96:99]
	v_mfma_f32_16x16x32_f16 v[96:99], v[152:155], v[200:203], v[96:99]
	v_mfma_f32_16x16x32_f16 v[92:95], v[142:145], v[200:203], v[92:95]
	v_mfma_f32_16x16x32_f16 v[92:95], v[138:141], v[196:199], v[92:95]
	v_mfma_f32_16x16x32_f16 v[100:103], v[156:159], v[172:175], v[100:103]
	v_mfma_f32_16x16x32_f16 v[100:103], v[160:163], v[176:179], v[100:103]
	v_mfma_f32_16x16x32_f16 v[104:107], v[168:171], v[176:179], v[104:107]
	v_mfma_f32_16x16x32_f16 v[104:107], v[164:167], v[172:175], v[104:107]
	v_mfma_f32_16x16x32_f16 v[112:115], v[164:167], v[180:183], v[112:115]
	v_mfma_f32_16x16x32_f16 v[112:115], v[168:171], v[184:187], v[112:115]
	v_mfma_f32_16x16x32_f16 v[108:111], v[160:163], v[184:187], v[108:111]
	v_mfma_f32_16x16x32_f16 v[108:111], v[156:159], v[180:183], v[108:111]
	v_mfma_f32_16x16x32_f16 v[116:119], v[156:159], v[188:191], v[116:119]
	v_mfma_f32_16x16x32_f16 v[116:119], v[160:163], v[192:195], v[116:119]
	v_mfma_f32_16x16x32_f16 v[120:123], v[168:171], v[192:195], v[120:123]
	v_mfma_f32_16x16x32_f16 v[120:123], v[164:167], v[188:191], v[120:123]
	v_mfma_f32_16x16x32_f16 v[128:131], v[164:167], v[196:199], v[128:131]
	v_mfma_f32_16x16x32_f16 v[128:131], v[168:171], v[200:203], v[128:131]
	s_setprio 2
	s_barrier
	v_mfma_f32_16x16x32_f16 v[124:127], v[160:163], v[200:203], v[124:127]
	v_mfma_f32_16x16x32_f16 v[124:127], v[156:159], v[196:199], v[124:127]
	s_setprio 0
	s_add_i32 s29, 0, 0x18000
	s_add_i32 s40, 0, 0x1c000
	ds_read_b128 v[138:141], v240 offset:32768
	ds_read_b128 v[142:145], v240 offset:33792
	ds_read_b128 v[148:151], v240 offset:34816
	ds_read_b128 v[152:155], v240 offset:35840
	ds_read_b128 v[156:159], v240 offset:49152
	ds_read_b128 v[160:163], v240 offset:50176
	ds_read_b128 v[164:167], v240 offset:51200
	ds_read_b128 v[168:171], v240 offset:52224
	s_add_u32 s16, s16, 0x80000
	s_addc_u32 s17, s17, 0
	s_mov_b32 m0, s60
	ds_read_b128 v[172:175], v146 offset:32768
	ds_read_b128 v[176:179], v146 offset:33792
	ds_read_b128 v[180:183], v146 offset:34816
	ds_read_b128 v[184:187], v146 offset:35840
	ds_read_b128 v[188:191], v146 offset:36864
	ds_read_b128 v[192:195], v146 offset:37888
	ds_read_b128 v[196:199], v146 offset:38912
	ds_read_b128 v[200:203], v146 offset:39936
	global_load_lds_dwordx4 v2, s[16:17]
	s_mov_b32 m0, s61
	s_nop 0
	global_load_lds_dwordx4 v132, s[16:17]
	s_waitcnt vmcnt(8)
	s_waitcnt lgkmcnt(0)
	s_barrier
	s_setprio 1
	s_waitcnt lgkmcnt(0)
	v_mfma_f32_16x16x32_f16 v[4:7], v[138:141], v[172:175], v[4:7]
	v_mfma_f32_16x16x32_f16 v[4:7], v[142:145], v[176:179], v[4:7]
	v_mfma_f32_16x16x32_f16 v[8:11], v[152:155], v[176:179], v[8:11]
	v_mfma_f32_16x16x32_f16 v[8:11], v[148:151], v[172:175], v[8:11]
	v_mfma_f32_16x16x32_f16 v[16:19], v[148:151], v[180:183], v[16:19]
	v_mfma_f32_16x16x32_f16 v[16:19], v[152:155], v[184:187], v[16:19]
	v_mfma_f32_16x16x32_f16 v[12:15], v[142:145], v[184:187], v[12:15]
	v_mfma_f32_16x16x32_f16 v[12:15], v[138:141], v[180:183], v[12:15]
	v_mfma_f32_16x16x32_f16 v[20:23], v[138:141], v[188:191], v[20:23]
	v_mfma_f32_16x16x32_f16 v[20:23], v[142:145], v[192:195], v[20:23]
	v_mfma_f32_16x16x32_f16 v[24:27], v[152:155], v[192:195], v[24:27]
	v_mfma_f32_16x16x32_f16 v[24:27], v[148:151], v[188:191], v[24:27]
	v_mfma_f32_16x16x32_f16 v[32:35], v[148:151], v[196:199], v[32:35]
	v_mfma_f32_16x16x32_f16 v[32:35], v[152:155], v[200:203], v[32:35]
	v_mfma_f32_16x16x32_f16 v[28:31], v[142:145], v[200:203], v[28:31]
	v_mfma_f32_16x16x32_f16 v[28:31], v[138:141], v[196:199], v[28:31]
	v_mfma_f32_16x16x32_f16 v[36:39], v[156:159], v[172:175], v[36:39]
	v_mfma_f32_16x16x32_f16 v[36:39], v[160:163], v[176:179], v[36:39]
	v_mfma_f32_16x16x32_f16 v[40:43], v[168:171], v[176:179], v[40:43]
	v_mfma_f32_16x16x32_f16 v[40:43], v[164:167], v[172:175], v[40:43]
	v_mfma_f32_16x16x32_f16 v[48:51], v[164:167], v[180:183], v[48:51]
	v_mfma_f32_16x16x32_f16 v[48:51], v[168:171], v[184:187], v[48:51]
	v_mfma_f32_16x16x32_f16 v[44:47], v[160:163], v[184:187], v[44:47]
	v_mfma_f32_16x16x32_f16 v[44:47], v[156:159], v[180:183], v[44:47]
	v_mfma_f32_16x16x32_f16 v[52:55], v[156:159], v[188:191], v[52:55]
	v_mfma_f32_16x16x32_f16 v[52:55], v[160:163], v[192:195], v[52:55]
	v_mfma_f32_16x16x32_f16 v[56:59], v[168:171], v[192:195], v[56:59]
	v_mfma_f32_16x16x32_f16 v[56:59], v[164:167], v[188:191], v[56:59]
	v_mfma_f32_16x16x32_f16 v[64:67], v[164:167], v[196:199], v[64:67]
	v_mfma_f32_16x16x32_f16 v[64:67], v[168:171], v[200:203], v[64:67]
	s_setprio 2
	s_barrier
	v_mfma_f32_16x16x32_f16 v[60:63], v[160:163], v[200:203], v[60:63]
	v_mfma_f32_16x16x32_f16 v[60:63], v[156:159], v[196:199], v[60:63]
	s_setprio 0
	s_add_i32 s16, s29, s38
	s_mov_b32 m0, s16
	ds_read_b128 v[172:175], v146 offset:49152
	ds_read_b128 v[176:179], v146 offset:50176
	ds_read_b128 v[180:183], v146 offset:51200
	ds_read_b128 v[184:187], v146 offset:52224
	ds_read_b128 v[188:191], v146 offset:53248
	ds_read_b128 v[192:195], v146 offset:54272
	ds_read_b128 v[196:199], v146 offset:55296
	ds_read_b128 v[200:203], v146 offset:56320
	global_load_lds_dwordx4 v136, s[88:89]
	s_add_i32 m0, s16, 0x2000
	s_add_u32 s6, s6, 0x80080
	s_addc_u32 s7, s7, 0
	s_add_i32 s16, s40, s38
	global_load_lds_dwordx4 v134, s[88:89]
	s_mov_b32 m0, s16
	s_nop 0
	global_load_lds_dwordx4 v136, s[6:7]
	s_add_i32 m0, s16, 0x2000
	s_nop 0
	global_load_lds_dwordx4 v134, s[6:7]
	s_mov_b32 m0, s64
	s_nop 0
	global_load_lds_dwordx4 v2, s[90:91]
	s_mov_b32 m0, s65
	s_nop 0
	global_load_lds_dwordx4 v132, s[90:91]
	s_waitcnt vmcnt(8)
	s_waitcnt lgkmcnt(0)
	s_barrier
	s_setprio 1
	s_waitcnt lgkmcnt(0)
	v_mfma_f32_16x16x32_f16 v[68:71], v[138:141], v[172:175], v[68:71]
	v_mfma_f32_16x16x32_f16 v[68:71], v[142:145], v[176:179], v[68:71]
	v_mfma_f32_16x16x32_f16 v[72:75], v[152:155], v[176:179], v[72:75]
	v_mfma_f32_16x16x32_f16 v[72:75], v[148:151], v[172:175], v[72:75]
	v_mfma_f32_16x16x32_f16 v[80:83], v[148:151], v[180:183], v[80:83]
	v_mfma_f32_16x16x32_f16 v[80:83], v[152:155], v[184:187], v[80:83]
	v_mfma_f32_16x16x32_f16 v[76:79], v[142:145], v[184:187], v[76:79]
	v_mfma_f32_16x16x32_f16 v[76:79], v[138:141], v[180:183], v[76:79]
	v_mfma_f32_16x16x32_f16 v[84:87], v[138:141], v[188:191], v[84:87]
	v_mfma_f32_16x16x32_f16 v[84:87], v[142:145], v[192:195], v[84:87]
	v_mfma_f32_16x16x32_f16 v[88:91], v[152:155], v[192:195], v[88:91]
	v_mfma_f32_16x16x32_f16 v[88:91], v[148:151], v[188:191], v[88:91]
	v_mfma_f32_16x16x32_f16 v[96:99], v[148:151], v[196:199], v[96:99]
	v_mfma_f32_16x16x32_f16 v[96:99], v[152:155], v[200:203], v[96:99]
	v_mfma_f32_16x16x32_f16 v[92:95], v[142:145], v[200:203], v[92:95]
	v_mfma_f32_16x16x32_f16 v[92:95], v[138:141], v[196:199], v[92:95]
	v_mfma_f32_16x16x32_f16 v[100:103], v[156:159], v[172:175], v[100:103]
	v_mfma_f32_16x16x32_f16 v[100:103], v[160:163], v[176:179], v[100:103]
	v_mfma_f32_16x16x32_f16 v[104:107], v[168:171], v[176:179], v[104:107]
	v_mfma_f32_16x16x32_f16 v[104:107], v[164:167], v[172:175], v[104:107]
	v_mfma_f32_16x16x32_f16 v[112:115], v[164:167], v[180:183], v[112:115]
	v_mfma_f32_16x16x32_f16 v[112:115], v[168:171], v[184:187], v[112:115]
	v_mfma_f32_16x16x32_f16 v[108:111], v[160:163], v[184:187], v[108:111]
	v_mfma_f32_16x16x32_f16 v[108:111], v[156:159], v[180:183], v[108:111]
	v_mfma_f32_16x16x32_f16 v[116:119], v[156:159], v[188:191], v[116:119]
	v_mfma_f32_16x16x32_f16 v[116:119], v[160:163], v[192:195], v[116:119]
	v_mfma_f32_16x16x32_f16 v[120:123], v[168:171], v[192:195], v[120:123]
	v_mfma_f32_16x16x32_f16 v[120:123], v[164:167], v[188:191], v[120:123]
	v_mfma_f32_16x16x32_f16 v[128:131], v[164:167], v[196:199], v[128:131]
	v_mfma_f32_16x16x32_f16 v[128:131], v[168:171], v[200:203], v[128:131]
	s_setprio 2
	s_barrier
	v_mfma_f32_16x16x32_f16 v[124:127], v[160:163], v[200:203], v[124:127]
	v_mfma_f32_16x16x32_f16 v[124:127], v[156:159], v[196:199], v[124:127]
	s_setprio 0
	s_add_i32 s28, s28, 2
	s_add_u32 s8, s8, 0x100
	s_addc_u32 s9, s9, 0
	s_add_u32 s26, s26, 0x100
	s_addc_u32 s27, s27, 0
	s_cmp_gt_u32 s28, 29
	s_cbranch_scc0 .LBB0_532
	s_and_b64 vcc, exec, s[50:51]
	s_cbranch_vccz .LBB0_535
	s_barrier

.LBB0_641:
	s_add_i32 s43, 0, 0x10000
	s_add_i32 s71, 0, 0x14000
	v_add_u32_e32 v16, s43, v232
	v_add_u32_e32 v32, s71, v232
	ds_read_b128 v[4:7], v16
	ds_read_b128 v[8:11], v16 offset:1024
	ds_read_b128 v[12:15], v16 offset:2048
	ds_read_b128 v[16:19], v16 offset:3072
	ds_read_b128 v[20:23], v32
	ds_read_b128 v[24:27], v32 offset:1024
	ds_read_b128 v[28:31], v32 offset:2048
	ds_read_b128 v[32:35], v32 offset:3072
	v_add_u32_e32 v233, 0, v231
	ds_read_b128 v[36:39], v233
	ds_read_b128 v[40:43], v233 offset:1024
	ds_read_b128 v[44:47], v233 offset:2048
	ds_read_b128 v[48:51], v233 offset:3072
	ds_read_b128 v[52:55], v233 offset:4096
	ds_read_b128 v[56:59], v233 offset:5120
	ds_read_b128 v[60:63], v233 offset:6144
	ds_read_b128 v[64:67], v233 offset:7168
	s_waitcnt vmcnt(8)
	s_waitcnt lgkmcnt(0)
	s_barrier
	s_setprio 1
	s_waitcnt lgkmcnt(0)
	v_mfma_f32_16x16x32_bf16 v[68:71], v[4:7], v[36:39], 0
	v_mfma_f32_16x16x32_bf16 v[68:71], v[8:11], v[40:43], v[68:71]
	v_mfma_f32_16x16x32_bf16 v[72:75], v[12:15], v[36:39], 0
	v_mfma_f32_16x16x32_bf16 v[72:75], v[16:19], v[40:43], v[72:75]
	v_mfma_f32_16x16x32_bf16 v[80:83], v[12:15], v[44:47], 0
	v_mfma_f32_16x16x32_bf16 v[80:83], v[16:19], v[48:51], v[80:83]
	v_mfma_f32_16x16x32_bf16 v[76:79], v[4:7], v[44:47], 0
	v_mfma_f32_16x16x32_bf16 v[76:79], v[8:11], v[48:51], v[76:79]
	v_mfma_f32_16x16x32_bf16 v[84:87], v[4:7], v[52:55], 0
	v_mfma_f32_16x16x32_bf16 v[84:87], v[8:11], v[56:59], v[84:87]
	v_mfma_f32_16x16x32_bf16 v[88:91], v[12:15], v[52:55], 0
	v_mfma_f32_16x16x32_bf16 v[88:91], v[16:19], v[56:59], v[88:91]
	v_mfma_f32_16x16x32_bf16 v[96:99], v[12:15], v[60:63], 0
	v_mfma_f32_16x16x32_bf16 v[96:99], v[16:19], v[64:67], v[96:99]
	v_mfma_f32_16x16x32_bf16 v[92:95], v[4:7], v[60:63], 0
	v_mfma_f32_16x16x32_bf16 v[92:95], v[8:11], v[64:67], v[92:95]
	v_mfma_f32_16x16x32_bf16 v[100:103], v[20:23], v[36:39], 0
	v_mfma_f32_16x16x32_bf16 v[36:39], v[28:31], v[36:39], 0
	v_mfma_f32_16x16x32_bf16 v[104:107], v[20:23], v[44:47], 0
	v_mfma_f32_16x16x32_bf16 v[44:47], v[28:31], v[44:47], 0
	v_mfma_f32_16x16x32_bf16 v[108:111], v[20:23], v[52:55], 0
	v_mfma_f32_16x16x32_bf16 v[52:55], v[28:31], v[52:55], 0
	v_mfma_f32_16x16x32_bf16 v[112:115], v[20:23], v[60:63], 0
	v_mfma_f32_16x16x32_bf16 v[60:63], v[28:31], v[60:63], 0
	v_mfma_f32_16x16x32_bf16 v[100:103], v[24:27], v[40:43], v[100:103]
	v_mfma_f32_16x16x32_bf16 v[40:43], v[32:35], v[40:43], v[36:39]
	v_mfma_f32_16x16x32_bf16 v[104:107], v[24:27], v[48:51], v[104:107]
	v_mfma_f32_16x16x32_bf16 v[48:51], v[32:35], v[48:51], v[44:47]
	v_mfma_f32_16x16x32_bf16 v[108:111], v[24:27], v[56:59], v[108:111]
	v_mfma_f32_16x16x32_bf16 v[56:59], v[32:35], v[56:59], v[52:55]
	s_setprio 2
	s_barrier
	v_mfma_f32_16x16x32_bf16 v[112:115], v[24:27], v[64:67], v[112:115]
	v_mfma_f32_16x16x32_bf16 v[64:67], v[32:35], v[64:67], v[60:63]
	s_setprio 0
	v_lshl_add_u64 v[186:187], s[8:9], 0, v[2:3]
	s_add_i32 s43, s43, s54
	v_mov_b32_e32 v191, v3
	v_lshl_add_u64 v[134:135], v[186:187], 0, s[80:81]
	s_mov_b32 m0, s43
	v_lshl_add_u64 v[246:247], s[8:9], 0, v[190:191]
	ds_read_b128 v[36:39], v233 offset:16384
	ds_read_b128 v[44:47], v233 offset:17408
	ds_read_b128 v[52:55], v233 offset:18432
	ds_read_b128 v[60:63], v233 offset:19456
	ds_read_b128 v[116:119], v233 offset:20480
	ds_read_b128 v[120:123], v233 offset:21504
	ds_read_b128 v[124:127], v233 offset:22528
	ds_read_b128 v[128:131], v233 offset:23552
	global_load_lds_dwordx4 v[134:135], off
	v_lshl_add_u64 v[134:135], v[246:247], 0, s[80:81]
	s_add_i32 m0, s43, 0x2000
	s_add_i32 s43, s71, s54
	global_load_lds_dwordx4 v[134:135], off
	s_mov_b32 m0, s43
	v_mov_b32_e32 v133, v3
	global_load_lds_dwordx4 v2, s[16:17]
	s_add_i32 m0, s43, 0x2000
	v_lshl_add_u64 v[248:249], s[6:7], 0, v[132:133]
	v_mov_b32_e32 v189, v3
	global_load_lds_dwordx4 v190, s[16:17]
	v_lshl_add_u64 v[134:135], v[248:249], 0, s[80:81]
	s_mov_b32 m0, s55
	v_lshl_add_u64 v[250:251], s[6:7], 0, v[188:189]
	global_load_lds_dwordx4 v[134:135], off
	v_lshl_add_u64 v[134:135], v[250:251], 0, s[80:81]
	s_mov_b32 m0, s56
	s_nop 0
	global_load_lds_dwordx4 v[134:135], off
	s_waitcnt vmcnt(8)
	s_waitcnt lgkmcnt(0)
	s_barrier
	s_setprio 1
	s_waitcnt lgkmcnt(0)
	v_mfma_f32_16x16x32_bf16 v[134:137], v[4:7], v[36:39], 0
	v_mfma_f32_16x16x32_bf16 v[138:141], v[12:15], v[36:39], 0
	v_mfma_f32_16x16x32_bf16 v[142:145], v[4:7], v[52:55], 0
	v_mfma_f32_16x16x32_bf16 v[146:149], v[12:15], v[52:55], 0
	v_mfma_f32_16x16x32_bf16 v[150:153], v[4:7], v[116:119], 0
	v_mfma_f32_16x16x32_bf16 v[154:157], v[12:15], v[116:119], 0
	v_mfma_f32_16x16x32_bf16 v[4:7], v[4:7], v[124:127], 0
	v_mfma_f32_16x16x32_bf16 v[12:15], v[12:15], v[124:127], 0
	v_mfma_f32_16x16x32_bf16 v[134:137], v[8:11], v[44:47], v[134:137]
	v_mfma_f32_16x16x32_bf16 v[138:141], v[16:19], v[44:47], v[138:141]
	v_mfma_f32_16x16x32_bf16 v[142:145], v[8:11], v[60:63], v[142:145]
	v_mfma_f32_16x16x32_bf16 v[146:149], v[16:19], v[60:63], v[146:149]
	v_mfma_f32_16x16x32_bf16 v[150:153], v[8:11], v[120:123], v[150:153]
	v_mfma_f32_16x16x32_bf16 v[154:157], v[16:19], v[120:123], v[154:157]
	v_mfma_f32_16x16x32_bf16 v[158:161], v[8:11], v[128:131], v[4:7]
	v_mfma_f32_16x16x32_bf16 v[162:165], v[16:19], v[128:131], v[12:15]
	v_mfma_f32_16x16x32_bf16 v[4:7], v[20:23], v[36:39], 0
	v_mfma_f32_16x16x32_bf16 v[8:11], v[28:31], v[36:39], 0
	v_mfma_f32_16x16x32_bf16 v[12:15], v[20:23], v[52:55], 0
	v_mfma_f32_16x16x32_bf16 v[16:19], v[28:31], v[52:55], 0
	v_mfma_f32_16x16x32_bf16 v[36:39], v[20:23], v[116:119], 0
	v_mfma_f32_16x16x32_bf16 v[52:55], v[28:31], v[116:119], 0
	v_mfma_f32_16x16x32_bf16 v[20:23], v[20:23], v[124:127], 0
	v_mfma_f32_16x16x32_bf16 v[28:31], v[28:31], v[124:127], 0
	v_mfma_f32_16x16x32_bf16 v[116:119], v[24:27], v[44:47], v[4:7]
	v_mfma_f32_16x16x32_bf16 v[124:127], v[32:35], v[44:47], v[8:11]
	v_mfma_f32_16x16x32_bf16 v[174:177], v[24:27], v[120:123], v[36:39]
	v_mfma_f32_16x16x32_bf16 v[120:123], v[32:35], v[120:123], v[52:55]
	v_mfma_f32_16x16x32_bf16 v[178:181], v[24:27], v[128:131], v[20:23]
	v_mfma_f32_16x16x32_bf16 v[128:131], v[32:35], v[128:131], v[28:31]
	s_setprio 2
	s_barrier
	v_mfma_f32_16x16x32_bf16 v[166:169], v[24:27], v[60:63], v[12:15]
	v_mfma_f32_16x16x32_bf16 v[170:173], v[32:35], v[60:63], v[16:19]
	s_setprio 0
	s_add_i32 s43, 0, 0x18000
	v_add_u32_e32 v4, s43, v232
	s_add_i32 s71, 0, 0x1c000
	ds_read_b128 v[182:185], v4
	ds_read_b128 v[192:195], v4 offset:1024
	ds_read_b128 v[196:199], v4 offset:2048
	ds_read_b128 v[200:203], v4 offset:3072
	v_add_u32_e32 v4, s71, v232
	ds_read_b128 v[204:207], v4
	ds_read_b128 v[208:211], v4 offset:1024
	ds_read_b128 v[212:215], v4 offset:2048
	ds_read_b128 v[216:219], v4 offset:3072
	s_mov_b32 m0, s57
	ds_read_b128 v[44:47], v233 offset:32768
	ds_read_b128 v[52:55], v233 offset:33792
	ds_read_b128 v[60:63], v233 offset:34816
	ds_read_b128 v[220:223], v233 offset:35840
	ds_read_b128 v[224:227], v233 offset:36864
	ds_read_b128 v[234:237], v233 offset:37888
	ds_read_b128 v[238:241], v233 offset:38912
	ds_read_b128 v[242:245], v233 offset:39936
	global_load_lds_dwordx4 v132, s[26:27]
	s_mov_b32 m0, s58
	s_nop 0
	global_load_lds_dwordx4 v188, s[26:27]
	s_waitcnt vmcnt(8)
	s_waitcnt lgkmcnt(0)
	s_barrier
	s_setprio 1
	s_waitcnt lgkmcnt(0)
	v_mfma_f32_16x16x32_bf16 v[4:7], v[182:185], v[44:47], v[68:71]
	v_mfma_f32_16x16x32_bf16 v[8:11], v[196:199], v[44:47], v[72:75]
	v_mfma_f32_16x16x32_bf16 v[12:15], v[182:185], v[60:63], v[76:79]
	v_mfma_f32_16x16x32_bf16 v[16:19], v[196:199], v[60:63], v[80:83]
	v_mfma_f32_16x16x32_bf16 v[20:23], v[182:185], v[224:227], v[84:87]
	v_mfma_f32_16x16x32_bf16 v[24:27], v[196:199], v[224:227], v[88:91]
	v_mfma_f32_16x16x32_bf16 v[28:31], v[182:185], v[238:241], v[92:95]
	v_mfma_f32_16x16x32_bf16 v[32:35], v[196:199], v[238:241], v[96:99]
	v_mfma_f32_16x16x32_bf16 v[4:7], v[192:195], v[52:55], v[4:7]
	v_mfma_f32_16x16x32_bf16 v[8:11], v[200:203], v[52:55], v[8:11]
	v_mfma_f32_16x16x32_bf16 v[12:15], v[192:195], v[220:223], v[12:15]
	v_mfma_f32_16x16x32_bf16 v[16:19], v[200:203], v[220:223], v[16:19]
	v_mfma_f32_16x16x32_bf16 v[20:23], v[192:195], v[234:237], v[20:23]
	v_mfma_f32_16x16x32_bf16 v[24:27], v[200:203], v[234:237], v[24:27]
	v_mfma_f32_16x16x32_bf16 v[28:31], v[192:195], v[242:245], v[28:31]
	v_mfma_f32_16x16x32_bf16 v[32:35], v[200:203], v[242:245], v[32:35]
	v_mfma_f32_16x16x32_bf16 v[36:39], v[204:207], v[44:47], v[100:103]
	v_mfma_f32_16x16x32_bf16 v[40:43], v[212:215], v[44:47], v[40:43]
	v_mfma_f32_16x16x32_bf16 v[36:39], v[208:211], v[52:55], v[36:39]
	v_mfma_f32_16x16x32_bf16 v[40:43], v[216:219], v[52:55], v[40:43]
	v_mfma_f32_16x16x32_bf16 v[44:47], v[204:207], v[60:63], v[104:107]
	v_mfma_f32_16x16x32_bf16 v[48:51], v[212:215], v[60:63], v[48:51]
	v_mfma_f32_16x16x32_bf16 v[52:55], v[204:207], v[224:227], v[108:111]
	v_mfma_f32_16x16x32_bf16 v[56:59], v[212:215], v[224:227], v[56:59]
	v_mfma_f32_16x16x32_bf16 v[60:63], v[204:207], v[238:241], v[112:115]
	v_mfma_f32_16x16x32_bf16 v[64:67], v[212:215], v[238:241], v[64:67]
	v_mfma_f32_16x16x32_bf16 v[44:47], v[208:211], v[220:223], v[44:47]
	v_mfma_f32_16x16x32_bf16 v[48:51], v[216:219], v[220:223], v[48:51]
	v_mfma_f32_16x16x32_bf16 v[52:55], v[208:211], v[234:237], v[52:55]
	v_mfma_f32_16x16x32_bf16 v[56:59], v[216:219], v[234:237], v[56:59]
	s_setprio 2
	s_barrier
	v_mfma_f32_16x16x32_bf16 v[60:63], v[208:211], v[242:245], v[60:63]
	v_mfma_f32_16x16x32_bf16 v[64:67], v[216:219], v[242:245], v[64:67]
	s_setprio 0
	s_add_i32 s43, s43, s54
	v_lshl_add_u64 v[68:69], v[186:187], 0, s[0:1]
	s_mov_b32 m0, s43
	ds_read_b128 v[104:107], v233 offset:49152
	ds_read_b128 v[108:111], v233 offset:50176
	ds_read_b128 v[112:115], v233 offset:51200
	ds_read_b128 v[220:223], v233 offset:52224
	ds_read_b128 v[224:227], v233 offset:53248
	ds_read_b128 v[234:237], v233 offset:54272
	ds_read_b128 v[238:241], v233 offset:55296
	ds_read_b128 v[242:245], v233 offset:56320
	global_load_lds_dwordx4 v[68:69], off
	v_lshl_add_u64 v[68:69], v[246:247], 0, s[0:1]
	s_add_i32 m0, s43, 0x2000
	s_add_i32 s43, s71, s54
	global_load_lds_dwordx4 v[68:69], off
	s_mov_b32 m0, s43
	v_lshl_add_u64 v[68:69], v[248:249], 0, s[0:1]
	global_load_lds_dwordx4 v2, s[28:29]
	s_add_i32 m0, s43, 0x2000
	s_nop 0
	global_load_lds_dwordx4 v190, s[28:29]
	s_mov_b32 m0, s62
	s_nop 0
	global_load_lds_dwordx4 v[68:69], off
	v_lshl_add_u64 v[68:69], v[250:251], 0, s[0:1]
	s_mov_b32 m0, s63
	s_nop 0
	global_load_lds_dwordx4 v[68:69], off
	s_waitcnt vmcnt(8)
	s_waitcnt lgkmcnt(0)
	s_barrier
	s_setprio 1
	s_waitcnt lgkmcnt(0)
	v_mfma_f32_16x16x32_bf16 v[68:71], v[182:185], v[104:107], v[134:137]
	v_mfma_f32_16x16x32_bf16 v[72:75], v[196:199], v[104:107], v[138:141]
	v_mfma_f32_16x16x32_bf16 v[76:79], v[182:185], v[112:115], v[142:145]
	v_mfma_f32_16x16x32_bf16 v[80:83], v[196:199], v[112:115], v[146:149]
	v_mfma_f32_16x16x32_bf16 v[84:87], v[182:185], v[224:227], v[150:153]
	v_mfma_f32_16x16x32_bf16 v[88:91], v[196:199], v[224:227], v[154:157]
	v_mfma_f32_16x16x32_bf16 v[92:95], v[182:185], v[238:241], v[158:161]
	v_mfma_f32_16x16x32_bf16 v[96:99], v[196:199], v[238:241], v[162:165]
	v_mfma_f32_16x16x32_bf16 v[68:71], v[192:195], v[108:111], v[68:71]
	v_mfma_f32_16x16x32_bf16 v[72:75], v[200:203], v[108:111], v[72:75]
	v_mfma_f32_16x16x32_bf16 v[76:79], v[192:195], v[220:223], v[76:79]
	v_mfma_f32_16x16x32_bf16 v[80:83], v[200:203], v[220:223], v[80:83]
	v_mfma_f32_16x16x32_bf16 v[84:87], v[192:195], v[234:237], v[84:87]
	v_mfma_f32_16x16x32_bf16 v[88:91], v[200:203], v[234:237], v[88:91]
	v_mfma_f32_16x16x32_bf16 v[92:95], v[192:195], v[242:245], v[92:95]
	v_mfma_f32_16x16x32_bf16 v[96:99], v[200:203], v[242:245], v[96:99]
	v_mfma_f32_16x16x32_bf16 v[100:103], v[204:207], v[104:107], v[116:119]
	v_mfma_f32_16x16x32_bf16 v[104:107], v[212:215], v[104:107], v[124:127]
	v_mfma_f32_16x16x32_bf16 v[100:103], v[208:211], v[108:111], v[100:103]
	v_mfma_f32_16x16x32_bf16 v[104:107], v[216:219], v[108:111], v[104:107]
	v_mfma_f32_16x16x32_bf16 v[108:111], v[204:207], v[112:115], v[166:169]
	v_mfma_f32_16x16x32_bf16 v[112:115], v[212:215], v[112:115], v[170:173]
	v_mfma_f32_16x16x32_bf16 v[116:119], v[204:207], v[224:227], v[174:177]
	v_mfma_f32_16x16x32_bf16 v[120:123], v[212:215], v[224:227], v[120:123]
	v_mfma_f32_16x16x32_bf16 v[124:127], v[204:207], v[238:241], v[178:181]
	v_mfma_f32_16x16x32_bf16 v[128:131], v[212:215], v[238:241], v[128:131]
	v_mfma_f32_16x16x32_bf16 v[108:111], v[208:211], v[220:223], v[108:111]
	v_mfma_f32_16x16x32_bf16 v[112:115], v[216:219], v[220:223], v[112:115]
	v_mfma_f32_16x16x32_bf16 v[116:119], v[208:211], v[234:237], v[116:119]
	v_mfma_f32_16x16x32_bf16 v[120:123], v[216:219], v[234:237], v[120:123]
	s_setprio 2
	s_barrier
	v_mfma_f32_16x16x32_bf16 v[124:127], v[208:211], v[242:245], v[124:127]
	v_mfma_f32_16x16x32_bf16 v[128:131], v[216:219], v[242:245], v[128:131]
	s_setprio 0
	s_add_i32 s42, s42, 2
	s_cmp_ge_i32 s42, s38
	s_cbranch_scc0 .LBB0_641
	v_mov_b32_e32 v192, v2
	s_branch .LBB0_644

.LBB0_649:
	s_or_b32 s38, s28, 1
	s_lshl_b64 s[42:43], s[38:39], 7
	s_sub_u32 s38, 0, s42
	s_subb_u32 s42, 0, s43
	s_add_u32 s38, s6, s38
	s_addc_u32 s43, s7, s42
	s_add_i32 s71, 0, 0x10000
	s_add_i32 s72, 0, 0x14000
	s_waitcnt lgkmcnt(0)
	ds_read_b128 v[132:135], v240
	ds_read_b128 v[136:139], v240 offset:1024
	ds_read_b128 v[140:143], v240 offset:2048
	ds_read_b128 v[144:147], v240 offset:3072
	ds_read_b128 v[148:151], v240 offset:16384
	ds_read_b128 v[152:155], v240 offset:17408
	ds_read_b128 v[156:159], v240 offset:18432
	ds_read_b128 v[160:163], v240 offset:19456
	s_add_u32 s42, s38, 0x160000
	s_mov_b32 m0, s64
	s_addc_u32 s43, s43, 0
	ds_read_b128 v[164:167], v231
	ds_read_b128 v[168:171], v231 offset:1024
	ds_read_b128 v[172:175], v231 offset:2048
	ds_read_b128 v[176:179], v231 offset:3072
	ds_read_b128 v[180:183], v231 offset:4096
	ds_read_b128 v[184:187], v231 offset:5120
	ds_read_b128 v[194:197], v231 offset:6144
	ds_read_b128 v[198:201], v231 offset:7168
	global_load_lds_dwordx4 v2, s[42:43]
	s_mov_b32 m0, s65
	v_mov_b32_e32 v189, v3
	global_load_lds_dwordx4 v188, s[42:43]
	s_waitcnt vmcnt(8)
	s_waitcnt lgkmcnt(0)
	s_barrier
	s_setprio 1
	s_waitcnt lgkmcnt(0)
	v_mfma_f32_16x16x32_bf16 v[4:7], v[132:135], v[164:167], v[4:7]
	v_mfma_f32_16x16x32_bf16 v[4:7], v[136:139], v[168:171], v[4:7]
	v_mfma_f32_16x16x32_bf16 v[8:11], v[144:147], v[168:171], v[8:11]
	v_mfma_f32_16x16x32_bf16 v[8:11], v[140:143], v[164:167], v[8:11]
	v_mfma_f32_16x16x32_bf16 v[16:19], v[140:143], v[172:175], v[16:19]
	v_mfma_f32_16x16x32_bf16 v[16:19], v[144:147], v[176:179], v[16:19]
	v_mfma_f32_16x16x32_bf16 v[12:15], v[136:139], v[176:179], v[12:15]
	v_mfma_f32_16x16x32_bf16 v[12:15], v[132:135], v[172:175], v[12:15]
	v_mfma_f32_16x16x32_bf16 v[20:23], v[132:135], v[180:183], v[20:23]
	v_mfma_f32_16x16x32_bf16 v[20:23], v[136:139], v[184:187], v[20:23]
	v_mfma_f32_16x16x32_bf16 v[24:27], v[144:147], v[184:187], v[24:27]
	v_mfma_f32_16x16x32_bf16 v[24:27], v[140:143], v[180:183], v[24:27]
	v_mfma_f32_16x16x32_bf16 v[32:35], v[140:143], v[194:197], v[32:35]
	v_mfma_f32_16x16x32_bf16 v[32:35], v[144:147], v[198:201], v[32:35]
	v_mfma_f32_16x16x32_bf16 v[28:31], v[136:139], v[198:201], v[28:31]
	v_mfma_f32_16x16x32_bf16 v[28:31], v[132:135], v[194:197], v[28:31]
	v_mfma_f32_16x16x32_bf16 v[36:39], v[148:151], v[164:167], v[36:39]
	v_mfma_f32_16x16x32_bf16 v[36:39], v[152:155], v[168:171], v[36:39]
	v_mfma_f32_16x16x32_bf16 v[40:43], v[160:163], v[168:171], v[40:43]
	v_mfma_f32_16x16x32_bf16 v[40:43], v[156:159], v[164:167], v[40:43]
	v_mfma_f32_16x16x32_bf16 v[48:51], v[156:159], v[172:175], v[48:51]
	v_mfma_f32_16x16x32_bf16 v[48:51], v[160:163], v[176:179], v[48:51]
	v_mfma_f32_16x16x32_bf16 v[44:47], v[152:155], v[176:179], v[44:47]
	v_mfma_f32_16x16x32_bf16 v[44:47], v[148:151], v[172:175], v[44:47]
	v_mfma_f32_16x16x32_bf16 v[52:55], v[148:151], v[180:183], v[52:55]
	v_mfma_f32_16x16x32_bf16 v[52:55], v[152:155], v[184:187], v[52:55]
	v_mfma_f32_16x16x32_bf16 v[56:59], v[160:163], v[184:187], v[56:59]
	v_mfma_f32_16x16x32_bf16 v[56:59], v[156:159], v[180:183], v[56:59]
	v_mfma_f32_16x16x32_bf16 v[64:67], v[156:159], v[194:197], v[64:67]
	v_mfma_f32_16x16x32_bf16 v[64:67], v[160:163], v[198:201], v[64:67]
	s_setprio 2
	s_barrier
	v_mfma_f32_16x16x32_bf16 v[60:63], v[152:155], v[198:201], v[60:63]
	v_mfma_f32_16x16x32_bf16 v[60:63], v[148:151], v[194:197], v[60:63]
	s_setprio 0
	s_add_i32 s38, s71, s54
	s_mov_b32 m0, s38
	ds_read_b128 v[164:167], v231 offset:16384
	ds_read_b128 v[168:171], v231 offset:17408
	ds_read_b128 v[172:175], v231 offset:18432
	ds_read_b128 v[176:179], v231 offset:19456
	ds_read_b128 v[180:183], v231 offset:20480
	ds_read_b128 v[184:187], v231 offset:21504
	ds_read_b128 v[194:197], v231 offset:22528
	ds_read_b128 v[198:201], v231 offset:23552
	global_load_lds_dwordx4 v192, s[16:17]
	s_add_i32 m0, s38, 0x2000
	s_add_u32 s42, s16, 0x160000
	s_addc_u32 s43, s17, 0
	s_add_i32 s38, s72, s54
	global_load_lds_dwordx4 v190, s[16:17]
	s_mov_b32 m0, s38
	v_mov_b32_e32 v193, v3
	global_load_lds_dwordx4 v192, s[42:43]
	s_add_i32 m0, s38, 0x2000
	v_mov_b32_e32 v191, v3
	global_load_lds_dwordx4 v190, s[42:43]
	s_mov_b32 m0, s55
	v_lshl_add_u64 v[202:203], s[16:17], 0, v[192:193]
	global_load_lds_dwordx4 v2, s[26:27]
	s_mov_b32 m0, s56
	v_lshl_add_u64 v[204:205], s[16:17], 0, v[190:191]
	global_load_lds_dwordx4 v188, s[26:27]
	s_waitcnt vmcnt(8)
	s_waitcnt lgkmcnt(0)
	v_lshl_add_u64 v[206:207], s[26:27], 0, v[2:3]
	v_lshl_add_u64 v[208:209], s[26:27], 0, v[188:189]
	s_barrier
	s_setprio 1
	s_waitcnt lgkmcnt(0)
	v_mfma_f32_16x16x32_bf16 v[68:71], v[132:135], v[164:167], v[68:71]
	v_mfma_f32_16x16x32_bf16 v[68:71], v[136:139], v[168:171], v[68:71]
	v_mfma_f32_16x16x32_bf16 v[72:75], v[144:147], v[168:171], v[72:75]
	v_mfma_f32_16x16x32_bf16 v[72:75], v[140:143], v[164:167], v[72:75]
	v_mfma_f32_16x16x32_bf16 v[80:83], v[140:143], v[172:175], v[80:83]
	v_mfma_f32_16x16x32_bf16 v[80:83], v[144:147], v[176:179], v[80:83]
	v_mfma_f32_16x16x32_bf16 v[76:79], v[136:139], v[176:179], v[76:79]
	v_mfma_f32_16x16x32_bf16 v[76:79], v[132:135], v[172:175], v[76:79]
	v_mfma_f32_16x16x32_bf16 v[84:87], v[132:135], v[180:183], v[84:87]
	v_mfma_f32_16x16x32_bf16 v[84:87], v[136:139], v[184:187], v[84:87]
	v_mfma_f32_16x16x32_bf16 v[88:91], v[144:147], v[184:187], v[88:91]
	v_mfma_f32_16x16x32_bf16 v[88:91], v[140:143], v[180:183], v[88:91]
	v_mfma_f32_16x16x32_bf16 v[96:99], v[140:143], v[194:197], v[96:99]
	v_mfma_f32_16x16x32_bf16 v[96:99], v[144:147], v[198:201], v[96:99]
	v_mfma_f32_16x16x32_bf16 v[92:95], v[136:139], v[198:201], v[92:95]
	v_mfma_f32_16x16x32_bf16 v[92:95], v[132:135], v[194:197], v[92:95]
	v_mfma_f32_16x16x32_bf16 v[100:103], v[148:151], v[164:167], v[100:103]
	v_mfma_f32_16x16x32_bf16 v[100:103], v[152:155], v[168:171], v[100:103]
	v_mfma_f32_16x16x32_bf16 v[104:107], v[160:163], v[168:171], v[104:107]
	v_mfma_f32_16x16x32_bf16 v[104:107], v[156:159], v[164:167], v[104:107]
	v_mfma_f32_16x16x32_bf16 v[112:115], v[156:159], v[172:175], v[112:115]
	v_mfma_f32_16x16x32_bf16 v[112:115], v[160:163], v[176:179], v[112:115]
	v_mfma_f32_16x16x32_bf16 v[108:111], v[152:155], v[176:179], v[108:111]
	v_mfma_f32_16x16x32_bf16 v[108:111], v[148:151], v[172:175], v[108:111]
	v_mfma_f32_16x16x32_bf16 v[116:119], v[148:151], v[180:183], v[116:119]
	v_mfma_f32_16x16x32_bf16 v[116:119], v[152:155], v[184:187], v[116:119]
	v_mfma_f32_16x16x32_bf16 v[120:123], v[160:163], v[184:187], v[120:123]
	v_mfma_f32_16x16x32_bf16 v[120:123], v[156:159], v[180:183], v[120:123]
	v_mfma_f32_16x16x32_bf16 v[128:131], v[156:159], v[194:197], v[128:131]
	v_mfma_f32_16x16x32_bf16 v[128:131], v[160:163], v[198:201], v[128:131]
	s_setprio 2
	s_barrier
	v_mfma_f32_16x16x32_bf16 v[124:127], v[152:155], v[198:201], v[124:127]
	v_mfma_f32_16x16x32_bf16 v[124:127], v[148:151], v[194:197], v[124:127]
	s_setprio 0
	s_add_i32 s38, 0, 0x18000
	s_add_i32 s42, 0, 0x1c000
	ds_read_b128 v[132:135], v240 offset:32768
	ds_read_b128 v[136:139], v240 offset:33792
	ds_read_b128 v[140:143], v240 offset:34816
	ds_read_b128 v[144:147], v240 offset:35840
	ds_read_b128 v[148:151], v240 offset:49152
	ds_read_b128 v[152:155], v240 offset:50176
	ds_read_b128 v[156:159], v240 offset:51200
	ds_read_b128 v[160:163], v240 offset:52224
	s_add_u32 s26, s26, 0x160000
	s_addc_u32 s27, s27, 0
	s_mov_b32 m0, s57
	ds_read_b128 v[164:167], v231 offset:32768
	ds_read_b128 v[168:171], v231 offset:33792
	ds_read_b128 v[172:175], v231 offset:34816
	ds_read_b128 v[176:179], v231 offset:35840
	ds_read_b128 v[180:183], v231 offset:36864
	ds_read_b128 v[184:187], v231 offset:37888
	ds_read_b128 v[194:197], v231 offset:38912
	ds_read_b128 v[198:201], v231 offset:39936
	global_load_lds_dwordx4 v2, s[26:27]
	s_mov_b32 m0, s58
	s_nop 0
	global_load_lds_dwordx4 v188, s[26:27]
	s_waitcnt vmcnt(8)
	s_waitcnt lgkmcnt(0)
	s_barrier
	s_setprio 1
	s_waitcnt lgkmcnt(0)
	v_mfma_f32_16x16x32_bf16 v[4:7], v[132:135], v[164:167], v[4:7]
	v_mfma_f32_16x16x32_bf16 v[4:7], v[136:139], v[168:171], v[4:7]
	v_mfma_f32_16x16x32_bf16 v[8:11], v[144:147], v[168:171], v[8:11]
	v_mfma_f32_16x16x32_bf16 v[8:11], v[140:143], v[164:167], v[8:11]
	v_mfma_f32_16x16x32_bf16 v[16:19], v[140:143], v[172:175], v[16:19]
	v_mfma_f32_16x16x32_bf16 v[16:19], v[144:147], v[176:179], v[16:19]
	v_mfma_f32_16x16x32_bf16 v[12:15], v[136:139], v[176:179], v[12:15]
	v_mfma_f32_16x16x32_bf16 v[12:15], v[132:135], v[172:175], v[12:15]
	v_mfma_f32_16x16x32_bf16 v[20:23], v[132:135], v[180:183], v[20:23]
	v_mfma_f32_16x16x32_bf16 v[20:23], v[136:139], v[184:187], v[20:23]
	v_mfma_f32_16x16x32_bf16 v[24:27], v[144:147], v[184:187], v[24:27]
	v_mfma_f32_16x16x32_bf16 v[24:27], v[140:143], v[180:183], v[24:27]
	v_mfma_f32_16x16x32_bf16 v[32:35], v[140:143], v[194:197], v[32:35]
	v_mfma_f32_16x16x32_bf16 v[32:35], v[144:147], v[198:201], v[32:35]
	v_mfma_f32_16x16x32_bf16 v[28:31], v[136:139], v[198:201], v[28:31]
	v_mfma_f32_16x16x32_bf16 v[28:31], v[132:135], v[194:197], v[28:31]
	v_mfma_f32_16x16x32_bf16 v[36:39], v[148:151], v[164:167], v[36:39]
	v_mfma_f32_16x16x32_bf16 v[36:39], v[152:155], v[168:171], v[36:39]
	v_mfma_f32_16x16x32_bf16 v[40:43], v[160:163], v[168:171], v[40:43]
	v_mfma_f32_16x16x32_bf16 v[40:43], v[156:159], v[164:167], v[40:43]
	v_mfma_f32_16x16x32_bf16 v[48:51], v[156:159], v[172:175], v[48:51]
	v_mfma_f32_16x16x32_bf16 v[48:51], v[160:163], v[176:179], v[48:51]
	v_mfma_f32_16x16x32_bf16 v[44:47], v[152:155], v[176:179], v[44:47]
	v_mfma_f32_16x16x32_bf16 v[44:47], v[148:151], v[172:175], v[44:47]
	v_mfma_f32_16x16x32_bf16 v[52:55], v[148:151], v[180:183], v[52:55]
	v_mfma_f32_16x16x32_bf16 v[52:55], v[152:155], v[184:187], v[52:55]
	v_mfma_f32_16x16x32_bf16 v[56:59], v[160:163], v[184:187], v[56:59]
	v_mfma_f32_16x16x32_bf16 v[56:59], v[156:159], v[180:183], v[56:59]
	v_mfma_f32_16x16x32_bf16 v[64:67], v[156:159], v[194:197], v[64:67]
	v_mfma_f32_16x16x32_bf16 v[64:67], v[160:163], v[198:201], v[64:67]
	s_setprio 2
	s_barrier
	v_mfma_f32_16x16x32_bf16 v[60:63], v[152:155], v[198:201], v[60:63]
	v_mfma_f32_16x16x32_bf16 v[60:63], v[148:151], v[194:197], v[60:63]
	s_setprio 0
	s_add_i32 s26, s38, s54
	v_lshl_add_u64 v[202:203], v[202:203], 0, s[4:5]
	s_mov_b32 m0, s26
	ds_read_b128 v[164:167], v231 offset:49152
	ds_read_b128 v[168:171], v231 offset:50176
	ds_read_b128 v[172:175], v231 offset:51200
	ds_read_b128 v[176:179], v231 offset:52224
	ds_read_b128 v[180:183], v231 offset:53248
	ds_read_b128 v[184:187], v231 offset:54272
	ds_read_b128 v[194:197], v231 offset:55296
	ds_read_b128 v[198:201], v231 offset:56320
	global_load_lds_dwordx4 v[202:203], off
	s_add_i32 m0, s26, 0x2000
	s_add_u32 s16, s16, 0x15ff80
	v_lshl_add_u64 v[202:203], v[204:205], 0, s[4:5]
	s_addc_u32 s17, s17, 0
	s_add_i32 s26, s42, s54
	global_load_lds_dwordx4 v[202:203], off
	s_mov_b32 m0, s26
	v_lshl_add_u64 v[202:203], v[206:207], 0, s[4:5]
	global_load_lds_dwordx4 v192, s[16:17]
	s_add_i32 m0, s26, 0x2000
	s_nop 0
	global_load_lds_dwordx4 v190, s[16:17]
	s_mov_b32 m0, s62
	s_nop 0
	global_load_lds_dwordx4 v[202:203], off
	v_lshl_add_u64 v[202:203], v[208:209], 0, s[4:5]
	s_mov_b32 m0, s63
	s_nop 0
	global_load_lds_dwordx4 v[202:203], off
	s_waitcnt vmcnt(8)
	s_waitcnt lgkmcnt(0)
	s_barrier
	s_setprio 1
	s_waitcnt lgkmcnt(0)
	v_mfma_f32_16x16x32_bf16 v[68:71], v[132:135], v[164:167], v[68:71]
	v_mfma_f32_16x16x32_bf16 v[68:71], v[136:139], v[168:171], v[68:71]
	v_mfma_f32_16x16x32_bf16 v[72:75], v[144:147], v[168:171], v[72:75]
	v_mfma_f32_16x16x32_bf16 v[72:75], v[140:143], v[164:167], v[72:75]
	v_mfma_f32_16x16x32_bf16 v[80:83], v[140:143], v[172:175], v[80:83]
	v_mfma_f32_16x16x32_bf16 v[80:83], v[144:147], v[176:179], v[80:83]
	v_mfma_f32_16x16x32_bf16 v[76:79], v[136:139], v[176:179], v[76:79]
	v_mfma_f32_16x16x32_bf16 v[76:79], v[132:135], v[172:175], v[76:79]
	v_mfma_f32_16x16x32_bf16 v[84:87], v[132:135], v[180:183], v[84:87]
	v_mfma_f32_16x16x32_bf16 v[84:87], v[136:139], v[184:187], v[84:87]
	v_mfma_f32_16x16x32_bf16 v[88:91], v[144:147], v[184:187], v[88:91]
	v_mfma_f32_16x16x32_bf16 v[88:91], v[140:143], v[180:183], v[88:91]
	v_mfma_f32_16x16x32_bf16 v[96:99], v[140:143], v[194:197], v[96:99]
	v_mfma_f32_16x16x32_bf16 v[96:99], v[144:147], v[198:201], v[96:99]
	v_mfma_f32_16x16x32_bf16 v[92:95], v[136:139], v[198:201], v[92:95]
	v_mfma_f32_16x16x32_bf16 v[92:95], v[132:135], v[194:197], v[92:95]
	v_mfma_f32_16x16x32_bf16 v[100:103], v[148:151], v[164:167], v[100:103]
	v_mfma_f32_16x16x32_bf16 v[100:103], v[152:155], v[168:171], v[100:103]
	v_mfma_f32_16x16x32_bf16 v[104:107], v[160:163], v[168:171], v[104:107]
	v_mfma_f32_16x16x32_bf16 v[104:107], v[156:159], v[164:167], v[104:107]
	v_mfma_f32_16x16x32_bf16 v[112:115], v[156:159], v[172:175], v[112:115]
	v_mfma_f32_16x16x32_bf16 v[112:115], v[160:163], v[176:179], v[112:115]
	v_mfma_f32_16x16x32_bf16 v[108:111], v[152:155], v[176:179], v[108:111]
	v_mfma_f32_16x16x32_bf16 v[108:111], v[148:151], v[172:175], v[108:111]
	v_mfma_f32_16x16x32_bf16 v[116:119], v[148:151], v[180:183], v[116:119]
	v_mfma_f32_16x16x32_bf16 v[116:119], v[152:155], v[184:187], v[116:119]
	v_mfma_f32_16x16x32_bf16 v[120:123], v[160:163], v[184:187], v[120:123]
	v_mfma_f32_16x16x32_bf16 v[120:123], v[156:159], v[180:183], v[120:123]
	v_mfma_f32_16x16x32_bf16 v[128:131], v[156:159], v[194:197], v[128:131]
	v_mfma_f32_16x16x32_bf16 v[128:131], v[160:163], v[198:201], v[128:131]
	s_setprio 2
	s_barrier
	v_mfma_f32_16x16x32_bf16 v[124:127], v[152:155], v[198:201], v[124:127]
	v_mfma_f32_16x16x32_bf16 v[124:127], v[148:151], v[194:197], v[124:127]
	s_setprio 0
	s_cmpk_gt_u32 s28, 0x55
	s_cbranch_scc1 .LBB0_651
	s_mov_b32 s28, s29
	s_branch .LBB0_645

.LBB0_749:
	s_add_i32 s47, 0, 0x10000
	s_add_i32 s49, 0, 0x14000
	v_add_u32_e32 v16, s47, v147
	v_add_u32_e32 v32, s49, v147
	ds_read_b128 v[4:7], v16
	ds_read_b128 v[8:11], v16 offset:1024
	ds_read_b128 v[12:15], v16 offset:2048
	ds_read_b128 v[16:19], v16 offset:3072
	ds_read_b128 v[20:23], v32
	ds_read_b128 v[24:27], v32 offset:1024
	ds_read_b128 v[28:31], v32 offset:2048
	ds_read_b128 v[32:35], v32 offset:3072
	v_add_u32_e32 v231, 0, v146
	ds_read_b128 v[36:39], v231
	ds_read_b128 v[40:43], v231 offset:1024
	ds_read_b128 v[44:47], v231 offset:2048
	ds_read_b128 v[48:51], v231 offset:3072
	ds_read_b128 v[52:55], v231 offset:4096
	ds_read_b128 v[56:59], v231 offset:5120
	ds_read_b128 v[60:63], v231 offset:6144
	ds_read_b128 v[64:67], v231 offset:7168
	s_waitcnt vmcnt(8)
	s_waitcnt lgkmcnt(0)
	s_barrier
	s_setprio 1
	s_waitcnt lgkmcnt(0)
	v_mfma_f32_16x16x32_f16 v[68:71], v[4:7], v[36:39], 0
	v_mfma_f32_16x16x32_f16 v[68:71], v[8:11], v[40:43], v[68:71]
	v_mfma_f32_16x16x32_f16 v[72:75], v[12:15], v[36:39], 0
	v_mfma_f32_16x16x32_f16 v[72:75], v[16:19], v[40:43], v[72:75]
	v_mfma_f32_16x16x32_f16 v[80:83], v[12:15], v[44:47], 0
	v_mfma_f32_16x16x32_f16 v[80:83], v[16:19], v[48:51], v[80:83]
	v_mfma_f32_16x16x32_f16 v[76:79], v[4:7], v[44:47], 0
	v_mfma_f32_16x16x32_f16 v[76:79], v[8:11], v[48:51], v[76:79]
	v_mfma_f32_16x16x32_f16 v[84:87], v[4:7], v[52:55], 0
	v_mfma_f32_16x16x32_f16 v[84:87], v[8:11], v[56:59], v[84:87]
	v_mfma_f32_16x16x32_f16 v[88:91], v[12:15], v[52:55], 0
	v_mfma_f32_16x16x32_f16 v[88:91], v[16:19], v[56:59], v[88:91]
	v_mfma_f32_16x16x32_f16 v[96:99], v[12:15], v[60:63], 0
	v_mfma_f32_16x16x32_f16 v[96:99], v[16:19], v[64:67], v[96:99]
	v_mfma_f32_16x16x32_f16 v[92:95], v[4:7], v[60:63], 0
	v_mfma_f32_16x16x32_f16 v[92:95], v[8:11], v[64:67], v[92:95]
	v_mfma_f32_16x16x32_f16 v[100:103], v[20:23], v[36:39], 0
	v_mfma_f32_16x16x32_f16 v[36:39], v[28:31], v[36:39], 0
	v_mfma_f32_16x16x32_f16 v[104:107], v[20:23], v[44:47], 0
	v_mfma_f32_16x16x32_f16 v[44:47], v[28:31], v[44:47], 0
	v_mfma_f32_16x16x32_f16 v[108:111], v[20:23], v[52:55], 0
	v_mfma_f32_16x16x32_f16 v[52:55], v[28:31], v[52:55], 0
	v_mfma_f32_16x16x32_f16 v[112:115], v[20:23], v[60:63], 0
	v_mfma_f32_16x16x32_f16 v[60:63], v[28:31], v[60:63], 0
	v_mfma_f32_16x16x32_f16 v[100:103], v[24:27], v[40:43], v[100:103]
	v_mfma_f32_16x16x32_f16 v[40:43], v[32:35], v[40:43], v[36:39]
	v_mfma_f32_16x16x32_f16 v[104:107], v[24:27], v[48:51], v[104:107]
	v_mfma_f32_16x16x32_f16 v[48:51], v[32:35], v[48:51], v[44:47]
	v_mfma_f32_16x16x32_f16 v[108:111], v[24:27], v[56:59], v[108:111]
	v_mfma_f32_16x16x32_f16 v[56:59], v[32:35], v[56:59], v[52:55]
	s_setprio 2
	s_barrier
	v_mfma_f32_16x16x32_f16 v[112:115], v[24:27], v[64:67], v[112:115]
	v_mfma_f32_16x16x32_f16 v[64:67], v[32:35], v[64:67], v[60:63]
	s_setprio 0
	v_lshl_add_u64 v[136:137], s[6:7], 0, v[2:3]
	s_add_i32 s47, s47, s62
	v_mov_b32_e32 v135, v3
	v_lshl_add_u64 v[140:141], v[136:137], 0, s[74:75]
	s_mov_b32 m0, s47
	v_lshl_add_u64 v[144:145], s[6:7], 0, v[134:135]
	ds_read_b128 v[36:39], v231 offset:16384
	ds_read_b128 v[44:47], v231 offset:17408
	ds_read_b128 v[52:55], v231 offset:18432
	ds_read_b128 v[60:63], v231 offset:19456
	ds_read_b128 v[116:119], v231 offset:20480
	ds_read_b128 v[120:123], v231 offset:21504
	ds_read_b128 v[124:127], v231 offset:22528
	ds_read_b128 v[128:131], v231 offset:23552
	global_load_lds_dwordx4 v[140:141], off
	v_lshl_add_u64 v[140:141], v[144:145], 0, s[74:75]
	s_add_i32 m0, s47, 0x2000
	s_add_i32 s47, s49, s62
	global_load_lds_dwordx4 v[140:141], off
	s_mov_b32 m0, s47
	v_mov_b32_e32 v139, v3
	global_load_lds_dwordx4 v2, s[16:17]
	s_add_i32 m0, s47, 0x2000
	v_lshl_add_u64 v[248:249], s[8:9], 0, v[138:139]
	v_mov_b32_e32 v133, v3
	global_load_lds_dwordx4 v134, s[16:17]
	v_lshl_add_u64 v[140:141], v[248:249], 0, s[74:75]
	s_mov_b32 m0, s63
	v_lshl_add_u64 v[250:251], s[8:9], 0, v[132:133]
	global_load_lds_dwordx4 v[140:141], off
	v_lshl_add_u64 v[140:141], v[250:251], 0, s[74:75]
	s_mov_b32 m0, s64
	s_nop 0
	global_load_lds_dwordx4 v[140:141], off
	s_waitcnt vmcnt(8)
	s_waitcnt lgkmcnt(0)
	s_barrier
	s_setprio 1
	s_waitcnt lgkmcnt(0)
	v_mfma_f32_16x16x32_f16 v[140:143], v[4:7], v[36:39], 0
	v_mfma_f32_16x16x32_f16 v[148:151], v[12:15], v[36:39], 0
	v_mfma_f32_16x16x32_f16 v[152:155], v[4:7], v[52:55], 0
	v_mfma_f32_16x16x32_f16 v[156:159], v[12:15], v[52:55], 0
	v_mfma_f32_16x16x32_f16 v[160:163], v[4:7], v[116:119], 0
	v_mfma_f32_16x16x32_f16 v[164:167], v[12:15], v[116:119], 0
	v_mfma_f32_16x16x32_f16 v[4:7], v[4:7], v[124:127], 0
	v_mfma_f32_16x16x32_f16 v[12:15], v[12:15], v[124:127], 0
	v_mfma_f32_16x16x32_f16 v[140:143], v[8:11], v[44:47], v[140:143]
	v_mfma_f32_16x16x32_f16 v[148:151], v[16:19], v[44:47], v[148:151]
	v_mfma_f32_16x16x32_f16 v[152:155], v[8:11], v[60:63], v[152:155]
	v_mfma_f32_16x16x32_f16 v[156:159], v[16:19], v[60:63], v[156:159]
	v_mfma_f32_16x16x32_f16 v[160:163], v[8:11], v[120:123], v[160:163]
	v_mfma_f32_16x16x32_f16 v[164:167], v[16:19], v[120:123], v[164:167]
	v_mfma_f32_16x16x32_f16 v[168:171], v[8:11], v[128:131], v[4:7]
	v_mfma_f32_16x16x32_f16 v[172:175], v[16:19], v[128:131], v[12:15]
	v_mfma_f32_16x16x32_f16 v[4:7], v[20:23], v[36:39], 0
	v_mfma_f32_16x16x32_f16 v[8:11], v[28:31], v[36:39], 0
	v_mfma_f32_16x16x32_f16 v[12:15], v[20:23], v[52:55], 0
	v_mfma_f32_16x16x32_f16 v[16:19], v[28:31], v[52:55], 0
	v_mfma_f32_16x16x32_f16 v[36:39], v[20:23], v[116:119], 0
	v_mfma_f32_16x16x32_f16 v[52:55], v[28:31], v[116:119], 0
	v_mfma_f32_16x16x32_f16 v[20:23], v[20:23], v[124:127], 0
	v_mfma_f32_16x16x32_f16 v[28:31], v[28:31], v[124:127], 0
	v_mfma_f32_16x16x32_f16 v[116:119], v[24:27], v[44:47], v[4:7]
	v_mfma_f32_16x16x32_f16 v[124:127], v[32:35], v[44:47], v[8:11]
	v_mfma_f32_16x16x32_f16 v[184:187], v[24:27], v[120:123], v[36:39]
	v_mfma_f32_16x16x32_f16 v[120:123], v[32:35], v[120:123], v[52:55]
	v_mfma_f32_16x16x32_f16 v[188:191], v[24:27], v[128:131], v[20:23]
	v_mfma_f32_16x16x32_f16 v[128:131], v[32:35], v[128:131], v[28:31]
	s_setprio 2
	s_barrier
	v_mfma_f32_16x16x32_f16 v[176:179], v[24:27], v[60:63], v[12:15]
	v_mfma_f32_16x16x32_f16 v[180:183], v[32:35], v[60:63], v[16:19]
	s_setprio 0
	s_add_i32 s47, 0, 0x18000
	v_add_u32_e32 v4, s47, v147
	s_add_i32 s49, 0, 0x1c000
	ds_read_b128 v[192:195], v4
	ds_read_b128 v[196:199], v4 offset:1024
	ds_read_b128 v[200:203], v4 offset:2048
	ds_read_b128 v[204:207], v4 offset:3072
	v_add_u32_e32 v4, s49, v147
	ds_read_b128 v[208:211], v4
	ds_read_b128 v[212:215], v4 offset:1024
	ds_read_b128 v[216:219], v4 offset:2048
	ds_read_b128 v[220:223], v4 offset:3072
	s_mov_b32 m0, s65
	ds_read_b128 v[44:47], v231 offset:32768
	ds_read_b128 v[52:55], v231 offset:33792
	ds_read_b128 v[60:63], v231 offset:34816
	ds_read_b128 v[224:227], v231 offset:35840
	ds_read_b128 v[232:235], v231 offset:36864
	ds_read_b128 v[236:239], v231 offset:37888
	ds_read_b128 v[240:243], v231 offset:38912
	ds_read_b128 v[244:247], v231 offset:39936
	global_load_lds_dwordx4 v138, s[26:27]
	s_mov_b32 m0, s66
	s_nop 0
	global_load_lds_dwordx4 v132, s[26:27]
	s_waitcnt vmcnt(8)
	s_waitcnt lgkmcnt(0)
	s_barrier
	s_setprio 1
	s_waitcnt lgkmcnt(0)
	v_mfma_f32_16x16x32_f16 v[4:7], v[192:195], v[44:47], v[68:71]
	v_mfma_f32_16x16x32_f16 v[8:11], v[200:203], v[44:47], v[72:75]
	v_mfma_f32_16x16x32_f16 v[12:15], v[192:195], v[60:63], v[76:79]
	v_mfma_f32_16x16x32_f16 v[16:19], v[200:203], v[60:63], v[80:83]
	v_mfma_f32_16x16x32_f16 v[20:23], v[192:195], v[232:235], v[84:87]
	v_mfma_f32_16x16x32_f16 v[24:27], v[200:203], v[232:235], v[88:91]
	v_mfma_f32_16x16x32_f16 v[28:31], v[192:195], v[240:243], v[92:95]
	v_mfma_f32_16x16x32_f16 v[32:35], v[200:203], v[240:243], v[96:99]
	v_mfma_f32_16x16x32_f16 v[4:7], v[196:199], v[52:55], v[4:7]
	v_mfma_f32_16x16x32_f16 v[8:11], v[204:207], v[52:55], v[8:11]
	v_mfma_f32_16x16x32_f16 v[12:15], v[196:199], v[224:227], v[12:15]
	v_mfma_f32_16x16x32_f16 v[16:19], v[204:207], v[224:227], v[16:19]
	v_mfma_f32_16x16x32_f16 v[20:23], v[196:199], v[236:239], v[20:23]
	v_mfma_f32_16x16x32_f16 v[24:27], v[204:207], v[236:239], v[24:27]
	v_mfma_f32_16x16x32_f16 v[28:31], v[196:199], v[244:247], v[28:31]
	v_mfma_f32_16x16x32_f16 v[32:35], v[204:207], v[244:247], v[32:35]
	v_mfma_f32_16x16x32_f16 v[36:39], v[208:211], v[44:47], v[100:103]
	v_mfma_f32_16x16x32_f16 v[40:43], v[216:219], v[44:47], v[40:43]
	v_mfma_f32_16x16x32_f16 v[36:39], v[212:215], v[52:55], v[36:39]
	v_mfma_f32_16x16x32_f16 v[40:43], v[220:223], v[52:55], v[40:43]
	v_mfma_f32_16x16x32_f16 v[44:47], v[208:211], v[60:63], v[104:107]
	v_mfma_f32_16x16x32_f16 v[48:51], v[216:219], v[60:63], v[48:51]
	v_mfma_f32_16x16x32_f16 v[52:55], v[208:211], v[232:235], v[108:111]
	v_mfma_f32_16x16x32_f16 v[56:59], v[216:219], v[232:235], v[56:59]
	v_mfma_f32_16x16x32_f16 v[60:63], v[208:211], v[240:243], v[112:115]
	v_mfma_f32_16x16x32_f16 v[64:67], v[216:219], v[240:243], v[64:67]
	v_mfma_f32_16x16x32_f16 v[44:47], v[212:215], v[224:227], v[44:47]
	v_mfma_f32_16x16x32_f16 v[48:51], v[220:223], v[224:227], v[48:51]
	v_mfma_f32_16x16x32_f16 v[52:55], v[212:215], v[236:239], v[52:55]
	v_mfma_f32_16x16x32_f16 v[56:59], v[220:223], v[236:239], v[56:59]
	s_setprio 2
	s_barrier
	v_mfma_f32_16x16x32_f16 v[60:63], v[212:215], v[244:247], v[60:63]
	v_mfma_f32_16x16x32_f16 v[64:67], v[220:223], v[244:247], v[64:67]
	s_setprio 0
	s_add_i32 s47, s47, s62
	v_lshl_add_u64 v[68:69], v[136:137], 0, s[24:25]
	s_mov_b32 m0, s47
	ds_read_b128 v[104:107], v231 offset:49152
	ds_read_b128 v[108:111], v231 offset:50176
	ds_read_b128 v[112:115], v231 offset:51200
	ds_read_b128 v[224:227], v231 offset:52224
	ds_read_b128 v[232:235], v231 offset:53248
	ds_read_b128 v[236:239], v231 offset:54272
	ds_read_b128 v[240:243], v231 offset:55296
	ds_read_b128 v[244:247], v231 offset:56320
	global_load_lds_dwordx4 v[68:69], off
	v_lshl_add_u64 v[68:69], v[144:145], 0, s[24:25]
	s_add_i32 m0, s47, 0x2000
	s_add_i32 s47, s49, s62
	global_load_lds_dwordx4 v[68:69], off
	s_mov_b32 m0, s47
	v_lshl_add_u64 v[68:69], v[248:249], 0, s[24:25]
	global_load_lds_dwordx4 v2, s[28:29]
	s_add_i32 m0, s47, 0x2000
	s_nop 0
	global_load_lds_dwordx4 v134, s[28:29]
	s_mov_b32 m0, s69
	s_nop 0
	global_load_lds_dwordx4 v[68:69], off
	v_lshl_add_u64 v[68:69], v[250:251], 0, s[24:25]
	s_mov_b32 m0, s70
	s_nop 0
	global_load_lds_dwordx4 v[68:69], off
	s_waitcnt vmcnt(8)
	s_waitcnt lgkmcnt(0)
	s_barrier
	s_setprio 1
	s_waitcnt lgkmcnt(0)
	v_mfma_f32_16x16x32_f16 v[68:71], v[192:195], v[104:107], v[140:143]
	v_mfma_f32_16x16x32_f16 v[72:75], v[200:203], v[104:107], v[148:151]
	v_mfma_f32_16x16x32_f16 v[76:79], v[192:195], v[112:115], v[152:155]
	v_mfma_f32_16x16x32_f16 v[80:83], v[200:203], v[112:115], v[156:159]
	v_mfma_f32_16x16x32_f16 v[84:87], v[192:195], v[232:235], v[160:163]
	v_mfma_f32_16x16x32_f16 v[88:91], v[200:203], v[232:235], v[164:167]
	v_mfma_f32_16x16x32_f16 v[92:95], v[192:195], v[240:243], v[168:171]
	v_mfma_f32_16x16x32_f16 v[96:99], v[200:203], v[240:243], v[172:175]
	v_mfma_f32_16x16x32_f16 v[68:71], v[196:199], v[108:111], v[68:71]
	v_mfma_f32_16x16x32_f16 v[72:75], v[204:207], v[108:111], v[72:75]
	v_mfma_f32_16x16x32_f16 v[76:79], v[196:199], v[224:227], v[76:79]
	v_mfma_f32_16x16x32_f16 v[80:83], v[204:207], v[224:227], v[80:83]
	v_mfma_f32_16x16x32_f16 v[84:87], v[196:199], v[236:239], v[84:87]
	v_mfma_f32_16x16x32_f16 v[88:91], v[204:207], v[236:239], v[88:91]
	v_mfma_f32_16x16x32_f16 v[92:95], v[196:199], v[244:247], v[92:95]
	v_mfma_f32_16x16x32_f16 v[96:99], v[204:207], v[244:247], v[96:99]
	v_mfma_f32_16x16x32_f16 v[100:103], v[208:211], v[104:107], v[116:119]
	v_mfma_f32_16x16x32_f16 v[104:107], v[216:219], v[104:107], v[124:127]
	v_mfma_f32_16x16x32_f16 v[100:103], v[212:215], v[108:111], v[100:103]
	v_mfma_f32_16x16x32_f16 v[104:107], v[220:223], v[108:111], v[104:107]
	v_mfma_f32_16x16x32_f16 v[108:111], v[208:211], v[112:115], v[176:179]
	v_mfma_f32_16x16x32_f16 v[112:115], v[216:219], v[112:115], v[180:183]
	v_mfma_f32_16x16x32_f16 v[116:119], v[208:211], v[232:235], v[184:187]
	v_mfma_f32_16x16x32_f16 v[120:123], v[216:219], v[232:235], v[120:123]
	v_mfma_f32_16x16x32_f16 v[124:127], v[208:211], v[240:243], v[188:191]
	v_mfma_f32_16x16x32_f16 v[128:131], v[216:219], v[240:243], v[128:131]
	v_mfma_f32_16x16x32_f16 v[108:111], v[212:215], v[224:227], v[108:111]
	v_mfma_f32_16x16x32_f16 v[112:115], v[220:223], v[224:227], v[112:115]
	v_mfma_f32_16x16x32_f16 v[116:119], v[212:215], v[236:239], v[116:119]
	v_mfma_f32_16x16x32_f16 v[120:123], v[220:223], v[236:239], v[120:123]
	s_setprio 2
	s_barrier
	v_mfma_f32_16x16x32_f16 v[124:127], v[212:215], v[244:247], v[124:127]
	v_mfma_f32_16x16x32_f16 v[128:131], v[220:223], v[244:247], v[128:131]
	s_setprio 0
	s_add_i32 s45, s45, 2
	s_cmp_ge_i32 s45, s44
	s_cbranch_scc0 .LBB0_749
	v_mov_b32_e32 v136, v2
	s_branch .LBB0_752

.LBB0_753:
	s_add_u32 s6, s8, 0xfff80080
	s_addc_u32 s7, s9, -1
	s_add_i32 s29, 0, 0x10000
	s_cmp_eq_u32 s28, 28
	s_cselect_b32 s17, s13, s7
	s_cselect_b32 s16, s12, s6
	v_add_u32_e32 v133, s29, v147
	s_cselect_b32 s7, s15, s27
	s_cselect_b32 s6, s14, s26
	s_add_i32 s47, 0, 0x14000
	ds_read_b128 v[138:141], v133
	ds_read_b128 v[142:145], v133 offset:1024
	ds_read_b128 v[148:151], v133 offset:2048
	ds_read_b128 v[152:155], v133 offset:3072
	v_add_u32_e32 v133, s47, v147
	ds_read_b128 v[156:159], v133
	ds_read_b128 v[160:163], v133 offset:1024
	ds_read_b128 v[164:167], v133 offset:2048
	ds_read_b128 v[168:171], v133 offset:3072
	s_mov_b32 m0, s71
	v_add_u32_e32 v212, 0, v146
	ds_read_b128 v[172:175], v212
	ds_read_b128 v[176:179], v212 offset:1024
	ds_read_b128 v[180:183], v212 offset:2048
	ds_read_b128 v[184:187], v212 offset:3072
	ds_read_b128 v[188:191], v212 offset:4096
	ds_read_b128 v[192:195], v212 offset:5120
	ds_read_b128 v[196:199], v212 offset:6144
	ds_read_b128 v[200:203], v212 offset:7168
	global_load_lds_dwordx4 v2, s[8:9]
	s_mov_b32 m0, s72
	v_mov_b32_e32 v133, v3
	global_load_lds_dwordx4 v132, s[8:9]
	s_waitcnt vmcnt(8)
	s_waitcnt lgkmcnt(0)
	s_barrier
	s_setprio 1
	s_waitcnt lgkmcnt(0)
	v_mfma_f32_16x16x32_f16 v[4:7], v[138:141], v[172:175], v[4:7]
	v_mfma_f32_16x16x32_f16 v[4:7], v[142:145], v[176:179], v[4:7]
	v_mfma_f32_16x16x32_f16 v[8:11], v[152:155], v[176:179], v[8:11]
	v_mfma_f32_16x16x32_f16 v[8:11], v[148:151], v[172:175], v[8:11]
	v_mfma_f32_16x16x32_f16 v[16:19], v[148:151], v[180:183], v[16:19]
	v_mfma_f32_16x16x32_f16 v[16:19], v[152:155], v[184:187], v[16:19]
	v_mfma_f32_16x16x32_f16 v[12:15], v[142:145], v[184:187], v[12:15]
	v_mfma_f32_16x16x32_f16 v[12:15], v[138:141], v[180:183], v[12:15]
	v_mfma_f32_16x16x32_f16 v[20:23], v[138:141], v[188:191], v[20:23]
	v_mfma_f32_16x16x32_f16 v[20:23], v[142:145], v[192:195], v[20:23]
	v_mfma_f32_16x16x32_f16 v[24:27], v[152:155], v[192:195], v[24:27]
	v_mfma_f32_16x16x32_f16 v[24:27], v[148:151], v[188:191], v[24:27]
	v_mfma_f32_16x16x32_f16 v[32:35], v[148:151], v[196:199], v[32:35]
	v_mfma_f32_16x16x32_f16 v[32:35], v[152:155], v[200:203], v[32:35]
	v_mfma_f32_16x16x32_f16 v[28:31], v[142:145], v[200:203], v[28:31]
	v_mfma_f32_16x16x32_f16 v[28:31], v[138:141], v[196:199], v[28:31]
	v_mfma_f32_16x16x32_f16 v[36:39], v[156:159], v[172:175], v[36:39]
	v_mfma_f32_16x16x32_f16 v[36:39], v[160:163], v[176:179], v[36:39]
	v_mfma_f32_16x16x32_f16 v[40:43], v[168:171], v[176:179], v[40:43]
	v_mfma_f32_16x16x32_f16 v[40:43], v[164:167], v[172:175], v[40:43]
	v_mfma_f32_16x16x32_f16 v[48:51], v[164:167], v[180:183], v[48:51]
	v_mfma_f32_16x16x32_f16 v[48:51], v[168:171], v[184:187], v[48:51]
	v_mfma_f32_16x16x32_f16 v[44:47], v[160:163], v[184:187], v[44:47]
	v_mfma_f32_16x16x32_f16 v[44:47], v[156:159], v[180:183], v[44:47]
	v_mfma_f32_16x16x32_f16 v[52:55], v[156:159], v[188:191], v[52:55]
	v_mfma_f32_16x16x32_f16 v[52:55], v[160:163], v[192:195], v[52:55]
	v_mfma_f32_16x16x32_f16 v[56:59], v[168:171], v[192:195], v[56:59]
	v_mfma_f32_16x16x32_f16 v[56:59], v[164:167], v[188:191], v[56:59]
	v_mfma_f32_16x16x32_f16 v[64:67], v[164:167], v[196:199], v[64:67]
	v_mfma_f32_16x16x32_f16 v[64:67], v[168:171], v[200:203], v[64:67]
	s_setprio 2
	s_barrier
	v_mfma_f32_16x16x32_f16 v[60:63], v[160:163], v[200:203], v[60:63]
	v_mfma_f32_16x16x32_f16 v[60:63], v[156:159], v[196:199], v[60:63]
	s_setprio 0
	s_add_i32 s29, s29, s62
	s_mov_b32 m0, s29
	ds_read_b128 v[172:175], v212 offset:16384
	ds_read_b128 v[176:179], v212 offset:17408
	ds_read_b128 v[180:183], v212 offset:18432
	ds_read_b128 v[184:187], v212 offset:19456
	ds_read_b128 v[188:191], v212 offset:20480
	ds_read_b128 v[192:195], v212 offset:21504
	ds_read_b128 v[196:199], v212 offset:22528
	ds_read_b128 v[200:203], v212 offset:23552
	global_load_lds_dwordx4 v136, s[6:7]
	s_add_i32 m0, s29, 0x2000
	s_add_u32 s44, s6, 0x80000
	s_addc_u32 s45, s7, 0
	s_add_i32 s29, s47, s62
	global_load_lds_dwordx4 v134, s[6:7]
	s_mov_b32 m0, s29
	v_mov_b32_e32 v137, v3
	global_load_lds_dwordx4 v136, s[44:45]
	s_add_i32 m0, s29, 0x2000
	v_mov_b32_e32 v135, v3
	global_load_lds_dwordx4 v134, s[44:45]
	s_mov_b32 m0, s63
	v_lshl_add_u64 v[204:205], s[6:7], 0, v[136:137]
	global_load_lds_dwordx4 v2, s[16:17]
	s_mov_b32 m0, s64
	v_lshl_add_u64 v[206:207], s[6:7], 0, v[134:135]
	global_load_lds_dwordx4 v132, s[16:17]
	s_waitcnt vmcnt(8)
	s_waitcnt lgkmcnt(0)
	v_lshl_add_u64 v[208:209], s[16:17], 0, v[2:3]
	v_lshl_add_u64 v[210:211], s[16:17], 0, v[132:133]
	s_barrier
	s_setprio 1
	s_waitcnt lgkmcnt(0)
	v_mfma_f32_16x16x32_f16 v[68:71], v[138:141], v[172:175], v[68:71]
	v_mfma_f32_16x16x32_f16 v[68:71], v[142:145], v[176:179], v[68:71]
	v_mfma_f32_16x16x32_f16 v[72:75], v[152:155], v[176:179], v[72:75]
	v_mfma_f32_16x16x32_f16 v[72:75], v[148:151], v[172:175], v[72:75]
	v_mfma_f32_16x16x32_f16 v[80:83], v[148:151], v[180:183], v[80:83]
	v_mfma_f32_16x16x32_f16 v[80:83], v[152:155], v[184:187], v[80:83]
	v_mfma_f32_16x16x32_f16 v[76:79], v[142:145], v[184:187], v[76:79]
	v_mfma_f32_16x16x32_f16 v[76:79], v[138:141], v[180:183], v[76:79]
	v_mfma_f32_16x16x32_f16 v[84:87], v[138:141], v[188:191], v[84:87]
	v_mfma_f32_16x16x32_f16 v[84:87], v[142:145], v[192:195], v[84:87]
	v_mfma_f32_16x16x32_f16 v[88:91], v[152:155], v[192:195], v[88:91]
	v_mfma_f32_16x16x32_f16 v[88:91], v[148:151], v[188:191], v[88:91]
	v_mfma_f32_16x16x32_f16 v[96:99], v[148:151], v[196:199], v[96:99]
	v_mfma_f32_16x16x32_f16 v[96:99], v[152:155], v[200:203], v[96:99]
	v_mfma_f32_16x16x32_f16 v[92:95], v[142:145], v[200:203], v[92:95]
	v_mfma_f32_16x16x32_f16 v[92:95], v[138:141], v[196:199], v[92:95]
	v_mfma_f32_16x16x32_f16 v[100:103], v[156:159], v[172:175], v[100:103]
	v_mfma_f32_16x16x32_f16 v[100:103], v[160:163], v[176:179], v[100:103]
	v_mfma_f32_16x16x32_f16 v[104:107], v[168:171], v[176:179], v[104:107]
	v_mfma_f32_16x16x32_f16 v[104:107], v[164:167], v[172:175], v[104:107]
	v_mfma_f32_16x16x32_f16 v[112:115], v[164:167], v[180:183], v[112:115]
	v_mfma_f32_16x16x32_f16 v[112:115], v[168:171], v[184:187], v[112:115]
	v_mfma_f32_16x16x32_f16 v[108:111], v[160:163], v[184:187], v[108:111]
	v_mfma_f32_16x16x32_f16 v[108:111], v[156:159], v[180:183], v[108:111]
	v_mfma_f32_16x16x32_f16 v[116:119], v[156:159], v[188:191], v[116:119]
	v_mfma_f32_16x16x32_f16 v[116:119], v[160:163], v[192:195], v[116:119]
	v_mfma_f32_16x16x32_f16 v[120:123], v[168:171], v[192:195], v[120:123]
	v_mfma_f32_16x16x32_f16 v[120:123], v[164:167], v[188:191], v[120:123]
	v_mfma_f32_16x16x32_f16 v[128:131], v[164:167], v[196:199], v[128:131]
	v_mfma_f32_16x16x32_f16 v[128:131], v[168:171], v[200:203], v[128:131]
	s_setprio 2
	s_barrier
	v_mfma_f32_16x16x32_f16 v[124:127], v[160:163], v[200:203], v[124:127]
	v_mfma_f32_16x16x32_f16 v[124:127], v[156:159], v[196:199], v[124:127]
	s_setprio 0
	s_add_i32 s29, 0, 0x18000
	v_add_u32_e32 v135, s29, v147
	s_add_i32 s44, 0, 0x1c000
	ds_read_b128 v[138:141], v135
	ds_read_b128 v[142:145], v135 offset:1024
	ds_read_b128 v[148:151], v135 offset:2048
	ds_read_b128 v[152:155], v135 offset:3072
	v_add_u32_e32 v135, s44, v147
	ds_read_b128 v[156:159], v135
	ds_read_b128 v[160:163], v135 offset:1024
	ds_read_b128 v[164:167], v135 offset:2048
	ds_read_b128 v[168:171], v135 offset:3072
	s_add_u32 s16, s16, 0x80000
	s_addc_u32 s17, s17, 0
	s_mov_b32 m0, s65
	ds_read_b128 v[172:175], v212 offset:32768
	ds_read_b128 v[176:179], v212 offset:33792
	ds_read_b128 v[180:183], v212 offset:34816
	ds_read_b128 v[184:187], v212 offset:35840
	ds_read_b128 v[188:191], v212 offset:36864
	ds_read_b128 v[192:195], v212 offset:37888
	ds_read_b128 v[196:199], v212 offset:38912
	ds_read_b128 v[200:203], v212 offset:39936
	global_load_lds_dwordx4 v2, s[16:17]
	s_mov_b32 m0, s66
	s_nop 0
	global_load_lds_dwordx4 v132, s[16:17]
	s_waitcnt vmcnt(8)
	s_waitcnt lgkmcnt(0)
	s_barrier
	s_setprio 1
	s_waitcnt lgkmcnt(0)
	v_mfma_f32_16x16x32_f16 v[4:7], v[138:141], v[172:175], v[4:7]
	v_mfma_f32_16x16x32_f16 v[4:7], v[142:145], v[176:179], v[4:7]
	v_mfma_f32_16x16x32_f16 v[8:11], v[152:155], v[176:179], v[8:11]
	v_mfma_f32_16x16x32_f16 v[8:11], v[148:151], v[172:175], v[8:11]
	v_mfma_f32_16x16x32_f16 v[16:19], v[148:151], v[180:183], v[16:19]
	v_mfma_f32_16x16x32_f16 v[16:19], v[152:155], v[184:187], v[16:19]
	v_mfma_f32_16x16x32_f16 v[12:15], v[142:145], v[184:187], v[12:15]
	v_mfma_f32_16x16x32_f16 v[12:15], v[138:141], v[180:183], v[12:15]
	v_mfma_f32_16x16x32_f16 v[20:23], v[138:141], v[188:191], v[20:23]
	v_mfma_f32_16x16x32_f16 v[20:23], v[142:145], v[192:195], v[20:23]
	v_mfma_f32_16x16x32_f16 v[24:27], v[152:155], v[192:195], v[24:27]
	v_mfma_f32_16x16x32_f16 v[24:27], v[148:151], v[188:191], v[24:27]
	v_mfma_f32_16x16x32_f16 v[32:35], v[148:151], v[196:199], v[32:35]
	v_mfma_f32_16x16x32_f16 v[32:35], v[152:155], v[200:203], v[32:35]
	v_mfma_f32_16x16x32_f16 v[28:31], v[142:145], v[200:203], v[28:31]
	v_mfma_f32_16x16x32_f16 v[28:31], v[138:141], v[196:199], v[28:31]
	v_mfma_f32_16x16x32_f16 v[36:39], v[156:159], v[172:175], v[36:39]
	v_mfma_f32_16x16x32_f16 v[36:39], v[160:163], v[176:179], v[36:39]
	v_mfma_f32_16x16x32_f16 v[40:43], v[168:171], v[176:179], v[40:43]
	v_mfma_f32_16x16x32_f16 v[40:43], v[164:167], v[172:175], v[40:43]
	v_mfma_f32_16x16x32_f16 v[48:51], v[164:167], v[180:183], v[48:51]
	v_mfma_f32_16x16x32_f16 v[48:51], v[168:171], v[184:187], v[48:51]
	v_mfma_f32_16x16x32_f16 v[44:47], v[160:163], v[184:187], v[44:47]
	v_mfma_f32_16x16x32_f16 v[44:47], v[156:159], v[180:183], v[44:47]
	v_mfma_f32_16x16x32_f16 v[52:55], v[156:159], v[188:191], v[52:55]
	v_mfma_f32_16x16x32_f16 v[52:55], v[160:163], v[192:195], v[52:55]
	v_mfma_f32_16x16x32_f16 v[56:59], v[168:171], v[192:195], v[56:59]
	v_mfma_f32_16x16x32_f16 v[56:59], v[164:167], v[188:191], v[56:59]
	v_mfma_f32_16x16x32_f16 v[64:67], v[164:167], v[196:199], v[64:67]
	v_mfma_f32_16x16x32_f16 v[64:67], v[168:171], v[200:203], v[64:67]
	s_setprio 2
	s_barrier
	v_mfma_f32_16x16x32_f16 v[60:63], v[160:163], v[200:203], v[60:63]
	v_mfma_f32_16x16x32_f16 v[60:63], v[156:159], v[196:199], v[60:63]
	s_setprio 0
	s_add_i32 s16, s29, s62
	v_lshl_add_u64 v[204:205], v[204:205], 0, s[86:87]
	s_mov_b32 m0, s16
	ds_read_b128 v[172:175], v212 offset:49152
	ds_read_b128 v[176:179], v212 offset:50176
	ds_read_b128 v[180:183], v212 offset:51200
	ds_read_b128 v[184:187], v212 offset:52224
	ds_read_b128 v[188:191], v212 offset:53248
	ds_read_b128 v[192:195], v212 offset:54272
	ds_read_b128 v[196:199], v212 offset:55296
	ds_read_b128 v[200:203], v212 offset:56320
	global_load_lds_dwordx4 v[204:205], off
	s_add_i32 m0, s16, 0x2000
	s_add_u32 s6, s6, 0x80080
	v_lshl_add_u64 v[204:205], v[206:207], 0, s[86:87]
	s_addc_u32 s7, s7, 0
	s_add_i32 s16, s44, s62
	global_load_lds_dwordx4 v[204:205], off
	s_mov_b32 m0, s16
	v_lshl_add_u64 v[204:205], v[208:209], 0, s[86:87]
	global_load_lds_dwordx4 v136, s[6:7]
	s_add_i32 m0, s16, 0x2000
	s_nop 0
	global_load_lds_dwordx4 v134, s[6:7]
	s_mov_b32 m0, s69
	s_nop 0
	global_load_lds_dwordx4 v[204:205], off
	v_lshl_add_u64 v[204:205], v[210:211], 0, s[86:87]
	s_mov_b32 m0, s70
	s_nop 0
	global_load_lds_dwordx4 v[204:205], off
	s_waitcnt vmcnt(8)
	s_waitcnt lgkmcnt(0)
	s_barrier
	s_setprio 1
	s_waitcnt lgkmcnt(0)
	v_mfma_f32_16x16x32_f16 v[68:71], v[138:141], v[172:175], v[68:71]
	v_mfma_f32_16x16x32_f16 v[68:71], v[142:145], v[176:179], v[68:71]
	v_mfma_f32_16x16x32_f16 v[72:75], v[152:155], v[176:179], v[72:75]
	v_mfma_f32_16x16x32_f16 v[72:75], v[148:151], v[172:175], v[72:75]
	v_mfma_f32_16x16x32_f16 v[80:83], v[148:151], v[180:183], v[80:83]
	v_mfma_f32_16x16x32_f16 v[80:83], v[152:155], v[184:187], v[80:83]
	v_mfma_f32_16x16x32_f16 v[76:79], v[142:145], v[184:187], v[76:79]
	v_mfma_f32_16x16x32_f16 v[76:79], v[138:141], v[180:183], v[76:79]
	v_mfma_f32_16x16x32_f16 v[84:87], v[138:141], v[188:191], v[84:87]
	v_mfma_f32_16x16x32_f16 v[84:87], v[142:145], v[192:195], v[84:87]
	v_mfma_f32_16x16x32_f16 v[88:91], v[152:155], v[192:195], v[88:91]
	v_mfma_f32_16x16x32_f16 v[88:91], v[148:151], v[188:191], v[88:91]
	v_mfma_f32_16x16x32_f16 v[96:99], v[148:151], v[196:199], v[96:99]
	v_mfma_f32_16x16x32_f16 v[96:99], v[152:155], v[200:203], v[96:99]
	v_mfma_f32_16x16x32_f16 v[92:95], v[142:145], v[200:203], v[92:95]
	v_mfma_f32_16x16x32_f16 v[92:95], v[138:141], v[196:199], v[92:95]
	v_mfma_f32_16x16x32_f16 v[100:103], v[156:159], v[172:175], v[100:103]
	v_mfma_f32_16x16x32_f16 v[100:103], v[160:163], v[176:179], v[100:103]
	v_mfma_f32_16x16x32_f16 v[104:107], v[168:171], v[176:179], v[104:107]
	v_mfma_f32_16x16x32_f16 v[104:107], v[164:167], v[172:175], v[104:107]
	v_mfma_f32_16x16x32_f16 v[112:115], v[164:167], v[180:183], v[112:115]
	v_mfma_f32_16x16x32_f16 v[112:115], v[168:171], v[184:187], v[112:115]
	v_mfma_f32_16x16x32_f16 v[108:111], v[160:163], v[184:187], v[108:111]
	v_mfma_f32_16x16x32_f16 v[108:111], v[156:159], v[180:183], v[108:111]
	v_mfma_f32_16x16x32_f16 v[116:119], v[156:159], v[188:191], v[116:119]
	v_mfma_f32_16x16x32_f16 v[116:119], v[160:163], v[192:195], v[116:119]
	v_mfma_f32_16x16x32_f16 v[120:123], v[168:171], v[192:195], v[120:123]
	v_mfma_f32_16x16x32_f16 v[120:123], v[164:167], v[188:191], v[120:123]
	v_mfma_f32_16x16x32_f16 v[128:131], v[164:167], v[196:199], v[128:131]
	v_mfma_f32_16x16x32_f16 v[128:131], v[168:171], v[200:203], v[128:131]
	s_setprio 2
	s_barrier
	v_mfma_f32_16x16x32_f16 v[124:127], v[160:163], v[200:203], v[124:127]
	v_mfma_f32_16x16x32_f16 v[124:127], v[156:159], v[196:199], v[124:127]
	s_setprio 0
	s_add_i32 s28, s28, 2
	s_add_u32 s8, s8, 0x100
	s_addc_u32 s9, s9, 0
	s_add_u32 s26, s26, 0x100
	s_addc_u32 s27, s27, 0
	s_cmp_gt_u32 s28, 29
	s_cbranch_scc0 .LBB0_753
	s_and_b64 vcc, exec, s[52:53]
	s_cbranch_vccz .LBB0_756
	s_barrier

.LBB0_1175:
	s_add_i32 s61, 0, 0x10000
	s_add_i32 s79, 0, 0x14000
	v_add_u32_e32 v16, s61, v209
	v_add_u32_e32 v32, s79, v209
	ds_read_b128 v[4:7], v16
	ds_read_b128 v[8:11], v16 offset:1024
	ds_read_b128 v[12:15], v16 offset:2048
	ds_read_b128 v[16:19], v16 offset:3072
	ds_read_b128 v[20:23], v32
	ds_read_b128 v[24:27], v32 offset:1024
	ds_read_b128 v[28:31], v32 offset:2048
	ds_read_b128 v[32:35], v32 offset:3072
	v_add_u32_e32 v231, 0, v208
	ds_read_b128 v[36:39], v231
	ds_read_b128 v[40:43], v231 offset:1024
	ds_read_b128 v[44:47], v231 offset:2048
	ds_read_b128 v[48:51], v231 offset:3072
	ds_read_b128 v[52:55], v231 offset:4096
	ds_read_b128 v[56:59], v231 offset:5120
	ds_read_b128 v[60:63], v231 offset:6144
	ds_read_b128 v[64:67], v231 offset:7168
	s_waitcnt vmcnt(8)
	s_waitcnt lgkmcnt(0)
	s_barrier
	s_setprio 1
	s_waitcnt lgkmcnt(0)
	v_mfma_f32_16x16x32_bf16 v[68:71], v[4:7], v[36:39], 0
	v_mfma_f32_16x16x32_bf16 v[68:71], v[8:11], v[40:43], v[68:71]
	v_mfma_f32_16x16x32_bf16 v[72:75], v[12:15], v[36:39], 0
	v_mfma_f32_16x16x32_bf16 v[72:75], v[16:19], v[40:43], v[72:75]
	v_mfma_f32_16x16x32_bf16 v[80:83], v[12:15], v[44:47], 0
	v_mfma_f32_16x16x32_bf16 v[80:83], v[16:19], v[48:51], v[80:83]
	v_mfma_f32_16x16x32_bf16 v[76:79], v[4:7], v[44:47], 0
	v_mfma_f32_16x16x32_bf16 v[76:79], v[8:11], v[48:51], v[76:79]
	v_mfma_f32_16x16x32_bf16 v[84:87], v[4:7], v[52:55], 0
	v_mfma_f32_16x16x32_bf16 v[84:87], v[8:11], v[56:59], v[84:87]
	v_mfma_f32_16x16x32_bf16 v[88:91], v[12:15], v[52:55], 0
	v_mfma_f32_16x16x32_bf16 v[88:91], v[16:19], v[56:59], v[88:91]
	v_mfma_f32_16x16x32_bf16 v[96:99], v[12:15], v[60:63], 0
	v_mfma_f32_16x16x32_bf16 v[96:99], v[16:19], v[64:67], v[96:99]
	v_mfma_f32_16x16x32_bf16 v[92:95], v[4:7], v[60:63], 0
	v_mfma_f32_16x16x32_bf16 v[92:95], v[8:11], v[64:67], v[92:95]
	v_mfma_f32_16x16x32_bf16 v[100:103], v[20:23], v[36:39], 0
	v_mfma_f32_16x16x32_bf16 v[36:39], v[28:31], v[36:39], 0
	v_mfma_f32_16x16x32_bf16 v[104:107], v[20:23], v[44:47], 0
	v_mfma_f32_16x16x32_bf16 v[44:47], v[28:31], v[44:47], 0
	v_mfma_f32_16x16x32_bf16 v[108:111], v[20:23], v[52:55], 0
	v_mfma_f32_16x16x32_bf16 v[52:55], v[28:31], v[52:55], 0
	v_mfma_f32_16x16x32_bf16 v[112:115], v[20:23], v[60:63], 0
	v_mfma_f32_16x16x32_bf16 v[60:63], v[28:31], v[60:63], 0
	v_mfma_f32_16x16x32_bf16 v[100:103], v[24:27], v[40:43], v[100:103]
	v_mfma_f32_16x16x32_bf16 v[40:43], v[32:35], v[40:43], v[36:39]
	v_mfma_f32_16x16x32_bf16 v[104:107], v[24:27], v[48:51], v[104:107]
	v_mfma_f32_16x16x32_bf16 v[48:51], v[32:35], v[48:51], v[44:47]
	v_mfma_f32_16x16x32_bf16 v[108:111], v[24:27], v[56:59], v[108:111]
	v_mfma_f32_16x16x32_bf16 v[56:59], v[32:35], v[56:59], v[52:55]
	s_setprio 2
	s_barrier
	v_mfma_f32_16x16x32_bf16 v[112:115], v[24:27], v[64:67], v[112:115]
	v_mfma_f32_16x16x32_bf16 v[64:67], v[32:35], v[64:67], v[60:63]
	s_setprio 0
	v_lshl_add_u64 v[186:187], s[12:13], 0, v[2:3]
	s_add_i32 s61, s61, s36
	v_mov_b32_e32 v191, v3
	v_lshl_add_u64 v[134:135], v[186:187], 0, s[74:75]
	s_mov_b32 m0, s61
	v_lshl_add_u64 v[226:227], s[12:13], 0, v[190:191]
	ds_read_b128 v[36:39], v231 offset:16384
	ds_read_b128 v[44:47], v231 offset:17408
	ds_read_b128 v[52:55], v231 offset:18432
	ds_read_b128 v[60:63], v231 offset:19456
	ds_read_b128 v[116:119], v231 offset:20480
	ds_read_b128 v[120:123], v231 offset:21504
	ds_read_b128 v[124:127], v231 offset:22528
	ds_read_b128 v[128:131], v231 offset:23552
	global_load_lds_dwordx4 v[134:135], off
	v_lshl_add_u64 v[134:135], v[226:227], 0, s[74:75]
	s_add_i32 m0, s61, 0x2000
	s_add_i32 s61, s79, s36
	global_load_lds_dwordx4 v[134:135], off
	s_mov_b32 m0, s61
	v_mov_b32_e32 v133, v3
	global_load_lds_dwordx4 v2, s[16:17]
	s_add_i32 m0, s61, 0x2000
	v_lshl_add_u64 v[248:249], s[6:7], 0, v[132:133]
	v_mov_b32_e32 v189, v3
	global_load_lds_dwordx4 v190, s[16:17]
	v_lshl_add_u64 v[134:135], v[248:249], 0, s[74:75]
	s_mov_b32 m0, s37
	v_lshl_add_u64 v[250:251], s[6:7], 0, v[188:189]
	global_load_lds_dwordx4 v[134:135], off
	v_lshl_add_u64 v[134:135], v[250:251], 0, s[74:75]
	s_mov_b32 m0, s66
	s_nop 0
	global_load_lds_dwordx4 v[134:135], off
	s_waitcnt vmcnt(8)
	s_waitcnt lgkmcnt(0)
	s_barrier
	s_setprio 1
	s_waitcnt lgkmcnt(0)
	v_mfma_f32_16x16x32_bf16 v[134:137], v[4:7], v[36:39], 0
	v_mfma_f32_16x16x32_bf16 v[138:141], v[12:15], v[36:39], 0
	v_mfma_f32_16x16x32_bf16 v[142:145], v[4:7], v[52:55], 0
	v_mfma_f32_16x16x32_bf16 v[146:149], v[12:15], v[52:55], 0
	v_mfma_f32_16x16x32_bf16 v[150:153], v[4:7], v[116:119], 0
	v_mfma_f32_16x16x32_bf16 v[154:157], v[12:15], v[116:119], 0
	v_mfma_f32_16x16x32_bf16 v[4:7], v[4:7], v[124:127], 0
	v_mfma_f32_16x16x32_bf16 v[12:15], v[12:15], v[124:127], 0
	v_mfma_f32_16x16x32_bf16 v[134:137], v[8:11], v[44:47], v[134:137]
	v_mfma_f32_16x16x32_bf16 v[138:141], v[16:19], v[44:47], v[138:141]
	v_mfma_f32_16x16x32_bf16 v[142:145], v[8:11], v[60:63], v[142:145]
	v_mfma_f32_16x16x32_bf16 v[146:149], v[16:19], v[60:63], v[146:149]
	v_mfma_f32_16x16x32_bf16 v[150:153], v[8:11], v[120:123], v[150:153]
	v_mfma_f32_16x16x32_bf16 v[154:157], v[16:19], v[120:123], v[154:157]
	v_mfma_f32_16x16x32_bf16 v[158:161], v[8:11], v[128:131], v[4:7]
	v_mfma_f32_16x16x32_bf16 v[162:165], v[16:19], v[128:131], v[12:15]
	v_mfma_f32_16x16x32_bf16 v[4:7], v[20:23], v[36:39], 0
	v_mfma_f32_16x16x32_bf16 v[8:11], v[28:31], v[36:39], 0
	v_mfma_f32_16x16x32_bf16 v[12:15], v[20:23], v[52:55], 0
	v_mfma_f32_16x16x32_bf16 v[16:19], v[28:31], v[52:55], 0
	v_mfma_f32_16x16x32_bf16 v[36:39], v[20:23], v[116:119], 0
	v_mfma_f32_16x16x32_bf16 v[52:55], v[28:31], v[116:119], 0
	v_mfma_f32_16x16x32_bf16 v[20:23], v[20:23], v[124:127], 0
	v_mfma_f32_16x16x32_bf16 v[28:31], v[28:31], v[124:127], 0
	v_mfma_f32_16x16x32_bf16 v[116:119], v[24:27], v[44:47], v[4:7]
	v_mfma_f32_16x16x32_bf16 v[124:127], v[32:35], v[44:47], v[8:11]
	v_mfma_f32_16x16x32_bf16 v[174:177], v[24:27], v[120:123], v[36:39]
	v_mfma_f32_16x16x32_bf16 v[120:123], v[32:35], v[120:123], v[52:55]
	v_mfma_f32_16x16x32_bf16 v[178:181], v[24:27], v[128:131], v[20:23]
	v_mfma_f32_16x16x32_bf16 v[128:131], v[32:35], v[128:131], v[28:31]
	s_setprio 2
	s_barrier
	v_mfma_f32_16x16x32_bf16 v[166:169], v[24:27], v[60:63], v[12:15]
	v_mfma_f32_16x16x32_bf16 v[170:173], v[32:35], v[60:63], v[16:19]
	s_setprio 0
	s_add_i32 s61, 0, 0x18000
	v_add_u32_e32 v4, s61, v209
	s_add_i32 s79, 0, 0x1c000
	ds_read_b128 v[182:185], v4
	ds_read_b128 v[192:195], v4 offset:1024
	ds_read_b128 v[196:199], v4 offset:2048
	ds_read_b128 v[200:203], v4 offset:3072
	v_add_u32_e32 v4, s79, v209
	ds_read_b128 v[204:207], v4
	ds_read_b128 v[210:213], v4 offset:1024
	ds_read_b128 v[214:217], v4 offset:2048
	ds_read_b128 v[218:221], v4 offset:3072
	s_mov_b32 m0, s67
	ds_read_b128 v[44:47], v231 offset:32768
	ds_read_b128 v[52:55], v231 offset:33792
	ds_read_b128 v[60:63], v231 offset:34816
	ds_read_b128 v[222:225], v231 offset:35840
	ds_read_b128 v[232:235], v231 offset:36864
	ds_read_b128 v[236:239], v231 offset:37888
	ds_read_b128 v[240:243], v231 offset:38912
	ds_read_b128 v[244:247], v231 offset:39936
	global_load_lds_dwordx4 v132, s[26:27]
	s_mov_b32 m0, s68
	s_nop 0
	global_load_lds_dwordx4 v188, s[26:27]
	s_waitcnt vmcnt(8)
	s_waitcnt lgkmcnt(0)
	s_barrier
	s_setprio 1
	s_waitcnt lgkmcnt(0)
	v_mfma_f32_16x16x32_bf16 v[4:7], v[182:185], v[44:47], v[68:71]
	v_mfma_f32_16x16x32_bf16 v[8:11], v[196:199], v[44:47], v[72:75]
	v_mfma_f32_16x16x32_bf16 v[12:15], v[182:185], v[60:63], v[76:79]
	v_mfma_f32_16x16x32_bf16 v[16:19], v[196:199], v[60:63], v[80:83]
	v_mfma_f32_16x16x32_bf16 v[20:23], v[182:185], v[232:235], v[84:87]
	v_mfma_f32_16x16x32_bf16 v[24:27], v[196:199], v[232:235], v[88:91]
	v_mfma_f32_16x16x32_bf16 v[28:31], v[182:185], v[240:243], v[92:95]
	v_mfma_f32_16x16x32_bf16 v[32:35], v[196:199], v[240:243], v[96:99]
	v_mfma_f32_16x16x32_bf16 v[4:7], v[192:195], v[52:55], v[4:7]
	v_mfma_f32_16x16x32_bf16 v[8:11], v[200:203], v[52:55], v[8:11]
	v_mfma_f32_16x16x32_bf16 v[12:15], v[192:195], v[222:225], v[12:15]
	v_mfma_f32_16x16x32_bf16 v[16:19], v[200:203], v[222:225], v[16:19]
	v_mfma_f32_16x16x32_bf16 v[20:23], v[192:195], v[236:239], v[20:23]
	v_mfma_f32_16x16x32_bf16 v[24:27], v[200:203], v[236:239], v[24:27]
	v_mfma_f32_16x16x32_bf16 v[28:31], v[192:195], v[244:247], v[28:31]
	v_mfma_f32_16x16x32_bf16 v[32:35], v[200:203], v[244:247], v[32:35]
	v_mfma_f32_16x16x32_bf16 v[36:39], v[204:207], v[44:47], v[100:103]
	v_mfma_f32_16x16x32_bf16 v[40:43], v[214:217], v[44:47], v[40:43]
	v_mfma_f32_16x16x32_bf16 v[36:39], v[210:213], v[52:55], v[36:39]
	v_mfma_f32_16x16x32_bf16 v[40:43], v[218:221], v[52:55], v[40:43]
	v_mfma_f32_16x16x32_bf16 v[44:47], v[204:207], v[60:63], v[104:107]
	v_mfma_f32_16x16x32_bf16 v[48:51], v[214:217], v[60:63], v[48:51]
	v_mfma_f32_16x16x32_bf16 v[52:55], v[204:207], v[232:235], v[108:111]
	v_mfma_f32_16x16x32_bf16 v[56:59], v[214:217], v[232:235], v[56:59]
	v_mfma_f32_16x16x32_bf16 v[60:63], v[204:207], v[240:243], v[112:115]
	v_mfma_f32_16x16x32_bf16 v[64:67], v[214:217], v[240:243], v[64:67]
	v_mfma_f32_16x16x32_bf16 v[44:47], v[210:213], v[222:225], v[44:47]
	v_mfma_f32_16x16x32_bf16 v[48:51], v[218:221], v[222:225], v[48:51]
	v_mfma_f32_16x16x32_bf16 v[52:55], v[210:213], v[236:239], v[52:55]
	v_mfma_f32_16x16x32_bf16 v[56:59], v[218:221], v[236:239], v[56:59]
	s_setprio 2
	s_barrier
	v_mfma_f32_16x16x32_bf16 v[60:63], v[210:213], v[244:247], v[60:63]
	v_mfma_f32_16x16x32_bf16 v[64:67], v[218:221], v[244:247], v[64:67]
	s_setprio 0
	s_add_i32 s61, s61, s36
	v_lshl_add_u64 v[68:69], v[186:187], 0, s[24:25]
	s_mov_b32 m0, s61
	ds_read_b128 v[104:107], v231 offset:49152
	ds_read_b128 v[108:111], v231 offset:50176
	ds_read_b128 v[112:115], v231 offset:51200
	ds_read_b128 v[222:225], v231 offset:52224
	ds_read_b128 v[232:235], v231 offset:53248
	ds_read_b128 v[236:239], v231 offset:54272
	ds_read_b128 v[240:243], v231 offset:55296
	ds_read_b128 v[244:247], v231 offset:56320
	global_load_lds_dwordx4 v[68:69], off
	v_lshl_add_u64 v[68:69], v[226:227], 0, s[24:25]
	s_add_i32 m0, s61, 0x2000
	s_add_i32 s61, s79, s36
	global_load_lds_dwordx4 v[68:69], off
	s_mov_b32 m0, s61
	v_lshl_add_u64 v[68:69], v[248:249], 0, s[24:25]
	global_load_lds_dwordx4 v2, s[28:29]
	s_add_i32 m0, s61, 0x2000
	s_nop 0
	global_load_lds_dwordx4 v190, s[28:29]
	s_mov_b32 m0, s71
	s_nop 0
	global_load_lds_dwordx4 v[68:69], off
	v_lshl_add_u64 v[68:69], v[250:251], 0, s[24:25]
	s_mov_b32 m0, s72
	s_nop 0
	global_load_lds_dwordx4 v[68:69], off
	s_waitcnt vmcnt(8)
	s_waitcnt lgkmcnt(0)
	s_barrier
	s_setprio 1
	s_waitcnt lgkmcnt(0)
	v_mfma_f32_16x16x32_bf16 v[68:71], v[182:185], v[104:107], v[134:137]
	v_mfma_f32_16x16x32_bf16 v[72:75], v[196:199], v[104:107], v[138:141]
	v_mfma_f32_16x16x32_bf16 v[76:79], v[182:185], v[112:115], v[142:145]
	v_mfma_f32_16x16x32_bf16 v[80:83], v[196:199], v[112:115], v[146:149]
	v_mfma_f32_16x16x32_bf16 v[84:87], v[182:185], v[232:235], v[150:153]
	v_mfma_f32_16x16x32_bf16 v[88:91], v[196:199], v[232:235], v[154:157]
	v_mfma_f32_16x16x32_bf16 v[92:95], v[182:185], v[240:243], v[158:161]
	v_mfma_f32_16x16x32_bf16 v[96:99], v[196:199], v[240:243], v[162:165]
	v_mfma_f32_16x16x32_bf16 v[68:71], v[192:195], v[108:111], v[68:71]
	v_mfma_f32_16x16x32_bf16 v[72:75], v[200:203], v[108:111], v[72:75]
	v_mfma_f32_16x16x32_bf16 v[76:79], v[192:195], v[222:225], v[76:79]
	v_mfma_f32_16x16x32_bf16 v[80:83], v[200:203], v[222:225], v[80:83]
	v_mfma_f32_16x16x32_bf16 v[84:87], v[192:195], v[236:239], v[84:87]
	v_mfma_f32_16x16x32_bf16 v[88:91], v[200:203], v[236:239], v[88:91]
	v_mfma_f32_16x16x32_bf16 v[92:95], v[192:195], v[244:247], v[92:95]
	v_mfma_f32_16x16x32_bf16 v[96:99], v[200:203], v[244:247], v[96:99]
	v_mfma_f32_16x16x32_bf16 v[100:103], v[204:207], v[104:107], v[116:119]
	v_mfma_f32_16x16x32_bf16 v[104:107], v[214:217], v[104:107], v[124:127]
	v_mfma_f32_16x16x32_bf16 v[100:103], v[210:213], v[108:111], v[100:103]
	v_mfma_f32_16x16x32_bf16 v[104:107], v[218:221], v[108:111], v[104:107]
	v_mfma_f32_16x16x32_bf16 v[108:111], v[204:207], v[112:115], v[166:169]
	v_mfma_f32_16x16x32_bf16 v[112:115], v[214:217], v[112:115], v[170:173]
	v_mfma_f32_16x16x32_bf16 v[116:119], v[204:207], v[232:235], v[174:177]
	v_mfma_f32_16x16x32_bf16 v[120:123], v[214:217], v[232:235], v[120:123]
	v_mfma_f32_16x16x32_bf16 v[124:127], v[204:207], v[240:243], v[178:181]
	v_mfma_f32_16x16x32_bf16 v[128:131], v[214:217], v[240:243], v[128:131]
	v_mfma_f32_16x16x32_bf16 v[108:111], v[210:213], v[222:225], v[108:111]
	v_mfma_f32_16x16x32_bf16 v[112:115], v[218:221], v[222:225], v[112:115]
	v_mfma_f32_16x16x32_bf16 v[116:119], v[210:213], v[236:239], v[116:119]
	v_mfma_f32_16x16x32_bf16 v[120:123], v[218:221], v[236:239], v[120:123]
	s_setprio 2
	s_barrier
	v_mfma_f32_16x16x32_bf16 v[124:127], v[210:213], v[244:247], v[124:127]
	v_mfma_f32_16x16x32_bf16 v[128:131], v[218:221], v[244:247], v[128:131]
	s_setprio 0
	s_add_i32 s43, s43, 2
	s_cmp_ge_i32 s43, s42
	s_cbranch_scc0 .LBB0_1175
.LBB0_1176:
	s_add_i32 s12, 0, 0x10000
	s_add_i32 s13, 0, 0x14000
	v_mov_b32_e32 v192, v2
	v_mov_b32_e32 v2, v132
	v_add_u32_e32 v144, s12, v209
	v_add_u32_e32 v160, s13, v209
	ds_read_b128 v[132:135], v144
	ds_read_b128 v[136:139], v144 offset:1024
	ds_read_b128 v[140:143], v144 offset:2048
	ds_read_b128 v[144:147], v144 offset:3072
	ds_read_b128 v[148:151], v160
	ds_read_b128 v[152:155], v160 offset:1024
	ds_read_b128 v[156:159], v160 offset:2048
	ds_read_b128 v[160:163], v160 offset:3072
	s_add_u32 s6, s6, 0x80180
	s_mov_b32 m0, s73
	v_add_u32_e32 v212, 0, v208
	s_addc_u32 s7, s7, 0
	ds_read_b128 v[164:167], v212
	ds_read_b128 v[168:171], v212 offset:1024
	ds_read_b128 v[172:175], v212 offset:2048
	ds_read_b128 v[176:179], v212 offset:3072
	ds_read_b128 v[180:183], v212 offset:4096
	ds_read_b128 v[184:187], v212 offset:5120
	ds_read_b128 v[194:197], v212 offset:6144
	ds_read_b128 v[198:201], v212 offset:7168
	global_load_lds_dwordx4 v2, s[6:7]
	s_mov_b32 m0, s76
	v_mov_b32_e32 v189, v3
	global_load_lds_dwordx4 v188, s[6:7]
	s_waitcnt vmcnt(8)
	s_waitcnt lgkmcnt(0)
	s_barrier
	s_setprio 1
	s_waitcnt lgkmcnt(0)
	v_mfma_f32_16x16x32_bf16 v[4:7], v[132:135], v[164:167], v[4:7]
	v_mfma_f32_16x16x32_bf16 v[4:7], v[136:139], v[168:171], v[4:7]
	v_mfma_f32_16x16x32_bf16 v[8:11], v[144:147], v[168:171], v[8:11]
	v_mfma_f32_16x16x32_bf16 v[8:11], v[140:143], v[164:167], v[8:11]
	v_mfma_f32_16x16x32_bf16 v[16:19], v[140:143], v[172:175], v[16:19]
	v_mfma_f32_16x16x32_bf16 v[16:19], v[144:147], v[176:179], v[16:19]
	v_mfma_f32_16x16x32_bf16 v[12:15], v[136:139], v[176:179], v[12:15]
	v_mfma_f32_16x16x32_bf16 v[12:15], v[132:135], v[172:175], v[12:15]
	v_mfma_f32_16x16x32_bf16 v[20:23], v[132:135], v[180:183], v[20:23]
	v_mfma_f32_16x16x32_bf16 v[20:23], v[136:139], v[184:187], v[20:23]
	v_mfma_f32_16x16x32_bf16 v[24:27], v[144:147], v[184:187], v[24:27]
	v_mfma_f32_16x16x32_bf16 v[24:27], v[140:143], v[180:183], v[24:27]
	v_mfma_f32_16x16x32_bf16 v[32:35], v[140:143], v[194:197], v[32:35]
	v_mfma_f32_16x16x32_bf16 v[32:35], v[144:147], v[198:201], v[32:35]
	v_mfma_f32_16x16x32_bf16 v[28:31], v[136:139], v[198:201], v[28:31]
	v_mfma_f32_16x16x32_bf16 v[28:31], v[132:135], v[194:197], v[28:31]
	v_mfma_f32_16x16x32_bf16 v[36:39], v[148:151], v[164:167], v[36:39]
	v_mfma_f32_16x16x32_bf16 v[36:39], v[152:155], v[168:171], v[36:39]
	v_mfma_f32_16x16x32_bf16 v[40:43], v[160:163], v[168:171], v[40:43]
	v_mfma_f32_16x16x32_bf16 v[40:43], v[156:159], v[164:167], v[40:43]
	v_mfma_f32_16x16x32_bf16 v[48:51], v[156:159], v[172:175], v[48:51]
	v_mfma_f32_16x16x32_bf16 v[48:51], v[160:163], v[176:179], v[48:51]
	v_mfma_f32_16x16x32_bf16 v[44:47], v[152:155], v[176:179], v[44:47]
	v_mfma_f32_16x16x32_bf16 v[44:47], v[148:151], v[172:175], v[44:47]
	v_mfma_f32_16x16x32_bf16 v[52:55], v[148:151], v[180:183], v[52:55]
	v_mfma_f32_16x16x32_bf16 v[52:55], v[152:155], v[184:187], v[52:55]
	v_mfma_f32_16x16x32_bf16 v[56:59], v[160:163], v[184:187], v[56:59]
	v_mfma_f32_16x16x32_bf16 v[56:59], v[156:159], v[180:183], v[56:59]
	v_mfma_f32_16x16x32_bf16 v[64:67], v[156:159], v[194:197], v[64:67]
	v_mfma_f32_16x16x32_bf16 v[64:67], v[160:163], v[198:201], v[64:67]
	s_setprio 2
	s_barrier
	v_mfma_f32_16x16x32_bf16 v[60:63], v[152:155], v[198:201], v[60:63]
	v_mfma_f32_16x16x32_bf16 v[60:63], v[148:151], v[194:197], v[60:63]
	s_setprio 0
	s_add_i32 s6, s12, s36
	s_mov_b32 m0, s6
	ds_read_b128 v[164:167], v212 offset:16384
	ds_read_b128 v[168:171], v212 offset:17408
	ds_read_b128 v[172:175], v212 offset:18432
	ds_read_b128 v[176:179], v212 offset:19456
	ds_read_b128 v[180:183], v212 offset:20480
	ds_read_b128 v[184:187], v212 offset:21504
	ds_read_b128 v[194:197], v212 offset:22528
	ds_read_b128 v[198:201], v212 offset:23552
	global_load_lds_dwordx4 v192, s[14:15]
	s_add_i32 m0, s6, 0x2000
	s_add_u32 s6, s14, 0x10000
	s_addc_u32 s7, s15, 0
	s_add_i32 s12, s13, s36
	global_load_lds_dwordx4 v190, s[14:15]
	s_mov_b32 m0, s12
	v_mov_b32_e32 v193, v3
	global_load_lds_dwordx4 v192, s[6:7]
	s_add_i32 m0, s12, 0x2000
	v_mov_b32_e32 v191, v3
	global_load_lds_dwordx4 v190, s[6:7]
	s_mov_b32 m0, s37
	v_lshl_add_u64 v[202:203], s[14:15], 0, v[192:193]
	global_load_lds_dwordx4 v2, s[10:11]
	s_mov_b32 m0, s66
	v_lshl_add_u64 v[204:205], s[14:15], 0, v[190:191]
	global_load_lds_dwordx4 v188, s[10:11]
	s_waitcnt vmcnt(8)
	s_waitcnt lgkmcnt(0)
	v_lshl_add_u64 v[206:207], s[10:11], 0, v[2:3]
	v_lshl_add_u64 v[210:211], s[10:11], 0, v[188:189]
	s_barrier
	s_setprio 1
	s_waitcnt lgkmcnt(0)
	v_mfma_f32_16x16x32_bf16 v[68:71], v[132:135], v[164:167], v[68:71]
	v_mfma_f32_16x16x32_bf16 v[68:71], v[136:139], v[168:171], v[68:71]
	v_mfma_f32_16x16x32_bf16 v[72:75], v[144:147], v[168:171], v[72:75]
	v_mfma_f32_16x16x32_bf16 v[72:75], v[140:143], v[164:167], v[72:75]
	v_mfma_f32_16x16x32_bf16 v[80:83], v[140:143], v[172:175], v[80:83]
	v_mfma_f32_16x16x32_bf16 v[80:83], v[144:147], v[176:179], v[80:83]
	v_mfma_f32_16x16x32_bf16 v[76:79], v[136:139], v[176:179], v[76:79]
	v_mfma_f32_16x16x32_bf16 v[76:79], v[132:135], v[172:175], v[76:79]
	v_mfma_f32_16x16x32_bf16 v[84:87], v[132:135], v[180:183], v[84:87]
	v_mfma_f32_16x16x32_bf16 v[84:87], v[136:139], v[184:187], v[84:87]
	v_mfma_f32_16x16x32_bf16 v[88:91], v[144:147], v[184:187], v[88:91]
	v_mfma_f32_16x16x32_bf16 v[88:91], v[140:143], v[180:183], v[88:91]
	v_mfma_f32_16x16x32_bf16 v[96:99], v[140:143], v[194:197], v[96:99]
	v_mfma_f32_16x16x32_bf16 v[96:99], v[144:147], v[198:201], v[96:99]
	v_mfma_f32_16x16x32_bf16 v[92:95], v[136:139], v[198:201], v[92:95]
	v_mfma_f32_16x16x32_bf16 v[92:95], v[132:135], v[194:197], v[92:95]
	v_mfma_f32_16x16x32_bf16 v[100:103], v[148:151], v[164:167], v[100:103]
	v_mfma_f32_16x16x32_bf16 v[100:103], v[152:155], v[168:171], v[100:103]
	v_mfma_f32_16x16x32_bf16 v[104:107], v[160:163], v[168:171], v[104:107]
	v_mfma_f32_16x16x32_bf16 v[104:107], v[156:159], v[164:167], v[104:107]
	v_mfma_f32_16x16x32_bf16 v[112:115], v[156:159], v[172:175], v[112:115]
	v_mfma_f32_16x16x32_bf16 v[112:115], v[160:163], v[176:179], v[112:115]
	v_mfma_f32_16x16x32_bf16 v[108:111], v[152:155], v[176:179], v[108:111]
	v_mfma_f32_16x16x32_bf16 v[108:111], v[148:151], v[172:175], v[108:111]
	v_mfma_f32_16x16x32_bf16 v[116:119], v[148:151], v[180:183], v[116:119]
	v_mfma_f32_16x16x32_bf16 v[116:119], v[152:155], v[184:187], v[116:119]
	v_mfma_f32_16x16x32_bf16 v[120:123], v[160:163], v[184:187], v[120:123]
	v_mfma_f32_16x16x32_bf16 v[120:123], v[156:159], v[180:183], v[120:123]
	v_mfma_f32_16x16x32_bf16 v[128:131], v[156:159], v[194:197], v[128:131]
	v_mfma_f32_16x16x32_bf16 v[128:131], v[160:163], v[198:201], v[128:131]
	s_setprio 2
	s_barrier
	v_mfma_f32_16x16x32_bf16 v[124:127], v[152:155], v[198:201], v[124:127]
	v_mfma_f32_16x16x32_bf16 v[124:127], v[148:151], v[194:197], v[124:127]
	s_setprio 0
	s_add_i32 s12, 0, 0x18000
	s_add_i32 s13, 0, 0x1c000
	v_add_u32_e32 v144, s12, v209
	v_add_u32_e32 v160, s13, v209
	ds_read_b128 v[132:135], v144
	ds_read_b128 v[136:139], v144 offset:1024
	ds_read_b128 v[140:143], v144 offset:2048
	ds_read_b128 v[144:147], v144 offset:3072
	ds_read_b128 v[148:151], v160
	ds_read_b128 v[152:155], v160 offset:1024
	ds_read_b128 v[156:159], v160 offset:2048
	ds_read_b128 v[160:163], v160 offset:3072
	s_add_u32 s6, s10, 0x80000
	s_addc_u32 s7, s11, 0
	s_mov_b32 m0, s67
	ds_read_b128 v[164:167], v212 offset:32768
	ds_read_b128 v[168:171], v212 offset:33792
	ds_read_b128 v[172:175], v212 offset:34816
	ds_read_b128 v[176:179], v212 offset:35840
	ds_read_b128 v[180:183], v212 offset:36864
	ds_read_b128 v[184:187], v212 offset:37888
	ds_read_b128 v[194:197], v212 offset:38912
	ds_read_b128 v[198:201], v212 offset:39936
	global_load_lds_dwordx4 v2, s[6:7]
	s_mov_b32 m0, s68
	s_nop 0
	global_load_lds_dwordx4 v188, s[6:7]
	s_waitcnt vmcnt(8)
	s_waitcnt lgkmcnt(0)
	s_barrier
	s_setprio 1
	s_waitcnt lgkmcnt(0)
	v_mfma_f32_16x16x32_bf16 v[4:7], v[132:135], v[164:167], v[4:7]
	v_mfma_f32_16x16x32_bf16 v[4:7], v[136:139], v[168:171], v[4:7]
	v_mfma_f32_16x16x32_bf16 v[8:11], v[144:147], v[168:171], v[8:11]
	v_mfma_f32_16x16x32_bf16 v[8:11], v[140:143], v[164:167], v[8:11]
	v_mfma_f32_16x16x32_bf16 v[16:19], v[140:143], v[172:175], v[16:19]
	v_mfma_f32_16x16x32_bf16 v[16:19], v[144:147], v[176:179], v[16:19]
	v_mfma_f32_16x16x32_bf16 v[12:15], v[136:139], v[176:179], v[12:15]
	v_mfma_f32_16x16x32_bf16 v[12:15], v[132:135], v[172:175], v[12:15]
	v_mfma_f32_16x16x32_bf16 v[20:23], v[132:135], v[180:183], v[20:23]
	v_mfma_f32_16x16x32_bf16 v[20:23], v[136:139], v[184:187], v[20:23]
	v_mfma_f32_16x16x32_bf16 v[24:27], v[144:147], v[184:187], v[24:27]
	v_mfma_f32_16x16x32_bf16 v[24:27], v[140:143], v[180:183], v[24:27]
	v_mfma_f32_16x16x32_bf16 v[32:35], v[140:143], v[194:197], v[32:35]
	v_mfma_f32_16x16x32_bf16 v[32:35], v[144:147], v[198:201], v[32:35]
	v_mfma_f32_16x16x32_bf16 v[28:31], v[136:139], v[198:201], v[28:31]
	v_mfma_f32_16x16x32_bf16 v[28:31], v[132:135], v[194:197], v[28:31]
	v_mfma_f32_16x16x32_bf16 v[36:39], v[148:151], v[164:167], v[36:39]
	v_mfma_f32_16x16x32_bf16 v[36:39], v[152:155], v[168:171], v[36:39]
	v_mfma_f32_16x16x32_bf16 v[40:43], v[160:163], v[168:171], v[40:43]
	v_mfma_f32_16x16x32_bf16 v[40:43], v[156:159], v[164:167], v[40:43]
	v_mfma_f32_16x16x32_bf16 v[48:51], v[156:159], v[172:175], v[48:51]
	v_mfma_f32_16x16x32_bf16 v[48:51], v[160:163], v[176:179], v[48:51]
	v_mfma_f32_16x16x32_bf16 v[44:47], v[152:155], v[176:179], v[44:47]
	v_mfma_f32_16x16x32_bf16 v[44:47], v[148:151], v[172:175], v[44:47]
	v_mfma_f32_16x16x32_bf16 v[52:55], v[148:151], v[180:183], v[52:55]
	v_mfma_f32_16x16x32_bf16 v[52:55], v[152:155], v[184:187], v[52:55]
	v_mfma_f32_16x16x32_bf16 v[56:59], v[160:163], v[184:187], v[56:59]
	v_mfma_f32_16x16x32_bf16 v[56:59], v[156:159], v[180:183], v[56:59]
	v_mfma_f32_16x16x32_bf16 v[64:67], v[156:159], v[194:197], v[64:67]
	v_mfma_f32_16x16x32_bf16 v[64:67], v[160:163], v[198:201], v[64:67]
	s_setprio 2
	s_barrier
	v_mfma_f32_16x16x32_bf16 v[60:63], v[152:155], v[198:201], v[60:63]
	v_mfma_f32_16x16x32_bf16 v[60:63], v[148:151], v[194:197], v[60:63]
	s_setprio 0
	s_add_i32 s6, s12, s36
	v_lshl_add_u64 v[202:203], v[202:203], 0, s[86:87]
	s_mov_b32 m0, s6
	ds_read_b128 v[164:167], v212 offset:49152
	ds_read_b128 v[168:171], v212 offset:50176
	ds_read_b128 v[172:175], v212 offset:51200
	ds_read_b128 v[176:179], v212 offset:52224
	ds_read_b128 v[180:183], v212 offset:53248
	ds_read_b128 v[184:187], v212 offset:54272
	ds_read_b128 v[194:197], v212 offset:55296
	ds_read_b128 v[198:201], v212 offset:56320
	global_load_lds_dwordx4 v[202:203], off
	s_add_i32 m0, s6, 0x2000
	s_add_u32 s6, s14, 0x10080
	v_lshl_add_u64 v[202:203], v[204:205], 0, s[86:87]
	s_addc_u32 s7, s15, 0
	s_add_i32 s12, s13, s36
	global_load_lds_dwordx4 v[202:203], off
	s_mov_b32 m0, s12
	v_lshl_add_u64 v[202:203], v[206:207], 0, s[86:87]
	global_load_lds_dwordx4 v192, s[6:7]
	s_add_i32 m0, s12, 0x2000
	s_nop 0
	global_load_lds_dwordx4 v190, s[6:7]
	s_mov_b32 m0, s71
	s_nop 0
	global_load_lds_dwordx4 v[202:203], off
	v_lshl_add_u64 v[202:203], v[210:211], 0, s[86:87]
	s_mov_b32 m0, s72
	s_nop 0
	global_load_lds_dwordx4 v[202:203], off
	s_waitcnt vmcnt(8)
	s_waitcnt lgkmcnt(0)
	s_barrier
	s_setprio 1
	s_waitcnt lgkmcnt(0)
	v_mfma_f32_16x16x32_bf16 v[68:71], v[132:135], v[164:167], v[68:71]
	v_mfma_f32_16x16x32_bf16 v[68:71], v[136:139], v[168:171], v[68:71]
	v_mfma_f32_16x16x32_bf16 v[72:75], v[144:147], v[168:171], v[72:75]
	v_mfma_f32_16x16x32_bf16 v[72:75], v[140:143], v[164:167], v[72:75]
	v_mfma_f32_16x16x32_bf16 v[80:83], v[140:143], v[172:175], v[80:83]
	v_mfma_f32_16x16x32_bf16 v[80:83], v[144:147], v[176:179], v[80:83]
	v_mfma_f32_16x16x32_bf16 v[76:79], v[136:139], v[176:179], v[76:79]
	v_mfma_f32_16x16x32_bf16 v[76:79], v[132:135], v[172:175], v[76:79]
	v_mfma_f32_16x16x32_bf16 v[84:87], v[132:135], v[180:183], v[84:87]
	v_mfma_f32_16x16x32_bf16 v[84:87], v[136:139], v[184:187], v[84:87]
	v_mfma_f32_16x16x32_bf16 v[88:91], v[144:147], v[184:187], v[88:91]
	v_mfma_f32_16x16x32_bf16 v[88:91], v[140:143], v[180:183], v[88:91]
	v_mfma_f32_16x16x32_bf16 v[96:99], v[140:143], v[194:197], v[96:99]
	v_mfma_f32_16x16x32_bf16 v[96:99], v[144:147], v[198:201], v[96:99]
	v_mfma_f32_16x16x32_bf16 v[92:95], v[136:139], v[198:201], v[92:95]
	v_mfma_f32_16x16x32_bf16 v[92:95], v[132:135], v[194:197], v[92:95]
	v_mfma_f32_16x16x32_bf16 v[100:103], v[148:151], v[164:167], v[100:103]
	v_mfma_f32_16x16x32_bf16 v[100:103], v[152:155], v[168:171], v[100:103]
	v_mfma_f32_16x16x32_bf16 v[104:107], v[160:163], v[168:171], v[104:107]
	v_mfma_f32_16x16x32_bf16 v[104:107], v[156:159], v[164:167], v[104:107]
	v_mfma_f32_16x16x32_bf16 v[112:115], v[156:159], v[172:175], v[112:115]
	v_mfma_f32_16x16x32_bf16 v[112:115], v[160:163], v[176:179], v[112:115]
	v_mfma_f32_16x16x32_bf16 v[108:111], v[152:155], v[176:179], v[108:111]
	v_mfma_f32_16x16x32_bf16 v[108:111], v[148:151], v[172:175], v[108:111]
	v_mfma_f32_16x16x32_bf16 v[116:119], v[148:151], v[180:183], v[116:119]
	v_mfma_f32_16x16x32_bf16 v[116:119], v[152:155], v[184:187], v[116:119]
	v_mfma_f32_16x16x32_bf16 v[120:123], v[160:163], v[184:187], v[120:123]
	v_mfma_f32_16x16x32_bf16 v[120:123], v[156:159], v[180:183], v[120:123]
	v_mfma_f32_16x16x32_bf16 v[128:131], v[156:159], v[194:197], v[128:131]
	v_mfma_f32_16x16x32_bf16 v[128:131], v[160:163], v[198:201], v[128:131]
	s_setprio 2
	s_barrier
	v_mfma_f32_16x16x32_bf16 v[124:127], v[152:155], v[198:201], v[124:127]
	v_mfma_f32_16x16x32_bf16 v[124:127], v[148:151], v[194:197], v[124:127]
	s_setprio 0
	s_and_b64 vcc, exec, s[58:59]
	s_cbranch_vccz .LBB0_1178
	s_barrier

.LBB0_1625:
	s_add_i32 s51, 0, 0x10000
	s_add_i32 s72, 0, 0x14000
	v_add_u32_e32 v16, s51, v232
	v_add_u32_e32 v32, s72, v232
	ds_read_b128 v[4:7], v16
	ds_read_b128 v[8:11], v16 offset:1024
	ds_read_b128 v[12:15], v16 offset:2048
	ds_read_b128 v[16:19], v16 offset:3072
	ds_read_b128 v[20:23], v32
	ds_read_b128 v[24:27], v32 offset:1024
	ds_read_b128 v[28:31], v32 offset:2048
	ds_read_b128 v[32:35], v32 offset:3072
	v_add_u32_e32 v233, 0, v231
	ds_read_b128 v[36:39], v233
	ds_read_b128 v[40:43], v233 offset:1024
	ds_read_b128 v[44:47], v233 offset:2048
	ds_read_b128 v[48:51], v233 offset:3072
	ds_read_b128 v[52:55], v233 offset:4096
	ds_read_b128 v[56:59], v233 offset:5120
	ds_read_b128 v[60:63], v233 offset:6144
	ds_read_b128 v[64:67], v233 offset:7168
	s_waitcnt vmcnt(8)
	s_waitcnt lgkmcnt(0)
	s_barrier
	s_setprio 1
	s_waitcnt lgkmcnt(0)
	v_mfma_f32_16x16x32_bf16 v[68:71], v[4:7], v[36:39], 0
	v_mfma_f32_16x16x32_bf16 v[68:71], v[8:11], v[40:43], v[68:71]
	v_mfma_f32_16x16x32_bf16 v[72:75], v[12:15], v[36:39], 0
	v_mfma_f32_16x16x32_bf16 v[72:75], v[16:19], v[40:43], v[72:75]
	v_mfma_f32_16x16x32_bf16 v[80:83], v[12:15], v[44:47], 0
	v_mfma_f32_16x16x32_bf16 v[80:83], v[16:19], v[48:51], v[80:83]
	v_mfma_f32_16x16x32_bf16 v[76:79], v[4:7], v[44:47], 0
	v_mfma_f32_16x16x32_bf16 v[76:79], v[8:11], v[48:51], v[76:79]
	v_mfma_f32_16x16x32_bf16 v[84:87], v[4:7], v[52:55], 0
	v_mfma_f32_16x16x32_bf16 v[84:87], v[8:11], v[56:59], v[84:87]
	v_mfma_f32_16x16x32_bf16 v[88:91], v[12:15], v[52:55], 0
	v_mfma_f32_16x16x32_bf16 v[88:91], v[16:19], v[56:59], v[88:91]
	v_mfma_f32_16x16x32_bf16 v[96:99], v[12:15], v[60:63], 0
	v_mfma_f32_16x16x32_bf16 v[96:99], v[16:19], v[64:67], v[96:99]
	v_mfma_f32_16x16x32_bf16 v[92:95], v[4:7], v[60:63], 0
	v_mfma_f32_16x16x32_bf16 v[92:95], v[8:11], v[64:67], v[92:95]
	v_mfma_f32_16x16x32_bf16 v[100:103], v[20:23], v[36:39], 0
	v_mfma_f32_16x16x32_bf16 v[36:39], v[28:31], v[36:39], 0
	v_mfma_f32_16x16x32_bf16 v[104:107], v[20:23], v[44:47], 0
	v_mfma_f32_16x16x32_bf16 v[44:47], v[28:31], v[44:47], 0
	v_mfma_f32_16x16x32_bf16 v[108:111], v[20:23], v[52:55], 0
	v_mfma_f32_16x16x32_bf16 v[52:55], v[28:31], v[52:55], 0
	v_mfma_f32_16x16x32_bf16 v[112:115], v[20:23], v[60:63], 0
	v_mfma_f32_16x16x32_bf16 v[60:63], v[28:31], v[60:63], 0
	v_mfma_f32_16x16x32_bf16 v[100:103], v[24:27], v[40:43], v[100:103]
	v_mfma_f32_16x16x32_bf16 v[40:43], v[32:35], v[40:43], v[36:39]
	v_mfma_f32_16x16x32_bf16 v[104:107], v[24:27], v[48:51], v[104:107]
	v_mfma_f32_16x16x32_bf16 v[48:51], v[32:35], v[48:51], v[44:47]
	v_mfma_f32_16x16x32_bf16 v[108:111], v[24:27], v[56:59], v[108:111]
	v_mfma_f32_16x16x32_bf16 v[56:59], v[32:35], v[56:59], v[52:55]
	s_setprio 2
	s_barrier
	v_mfma_f32_16x16x32_bf16 v[112:115], v[24:27], v[64:67], v[112:115]
	v_mfma_f32_16x16x32_bf16 v[64:67], v[32:35], v[64:67], v[60:63]
	s_setprio 0
	v_lshl_add_u64 v[186:187], s[12:13], 0, v[2:3]
	s_add_i32 s51, s51, s56
	v_mov_b32_e32 v191, v3
	v_lshl_add_u64 v[134:135], v[186:187], 0, s[74:75]
	s_mov_b32 m0, s51
	v_lshl_add_u64 v[246:247], s[12:13], 0, v[190:191]
	ds_read_b128 v[36:39], v233 offset:16384
	ds_read_b128 v[44:47], v233 offset:17408
	ds_read_b128 v[52:55], v233 offset:18432
	ds_read_b128 v[60:63], v233 offset:19456
	ds_read_b128 v[116:119], v233 offset:20480
	ds_read_b128 v[120:123], v233 offset:21504
	ds_read_b128 v[124:127], v233 offset:22528
	ds_read_b128 v[128:131], v233 offset:23552
	global_load_lds_dwordx4 v[134:135], off
	v_lshl_add_u64 v[134:135], v[246:247], 0, s[74:75]
	s_add_i32 m0, s51, 0x2000
	s_add_i32 s51, s72, s56
	global_load_lds_dwordx4 v[134:135], off
	s_mov_b32 m0, s51
	v_mov_b32_e32 v133, v3
	global_load_lds_dwordx4 v2, s[16:17]
	s_add_i32 m0, s51, 0x2000
	v_lshl_add_u64 v[248:249], s[14:15], 0, v[132:133]
	v_mov_b32_e32 v189, v3
	global_load_lds_dwordx4 v190, s[16:17]
	v_lshl_add_u64 v[134:135], v[248:249], 0, s[74:75]
	s_mov_b32 m0, s57
	v_lshl_add_u64 v[250:251], s[14:15], 0, v[188:189]
	global_load_lds_dwordx4 v[134:135], off
	v_lshl_add_u64 v[134:135], v[250:251], 0, s[74:75]
	s_mov_b32 m0, s58
	s_nop 0
	global_load_lds_dwordx4 v[134:135], off
	s_waitcnt vmcnt(8)
	s_waitcnt lgkmcnt(0)
	s_barrier
	s_setprio 1
	s_waitcnt lgkmcnt(0)
	v_mfma_f32_16x16x32_bf16 v[134:137], v[4:7], v[36:39], 0
	v_mfma_f32_16x16x32_bf16 v[138:141], v[12:15], v[36:39], 0
	v_mfma_f32_16x16x32_bf16 v[142:145], v[4:7], v[52:55], 0
	v_mfma_f32_16x16x32_bf16 v[146:149], v[12:15], v[52:55], 0
	v_mfma_f32_16x16x32_bf16 v[150:153], v[4:7], v[116:119], 0
	v_mfma_f32_16x16x32_bf16 v[154:157], v[12:15], v[116:119], 0
	v_mfma_f32_16x16x32_bf16 v[4:7], v[4:7], v[124:127], 0
	v_mfma_f32_16x16x32_bf16 v[12:15], v[12:15], v[124:127], 0
	v_mfma_f32_16x16x32_bf16 v[134:137], v[8:11], v[44:47], v[134:137]
	v_mfma_f32_16x16x32_bf16 v[138:141], v[16:19], v[44:47], v[138:141]
	v_mfma_f32_16x16x32_bf16 v[142:145], v[8:11], v[60:63], v[142:145]
	v_mfma_f32_16x16x32_bf16 v[146:149], v[16:19], v[60:63], v[146:149]
	v_mfma_f32_16x16x32_bf16 v[150:153], v[8:11], v[120:123], v[150:153]
	v_mfma_f32_16x16x32_bf16 v[154:157], v[16:19], v[120:123], v[154:157]
	v_mfma_f32_16x16x32_bf16 v[158:161], v[8:11], v[128:131], v[4:7]
	v_mfma_f32_16x16x32_bf16 v[162:165], v[16:19], v[128:131], v[12:15]
	v_mfma_f32_16x16x32_bf16 v[4:7], v[20:23], v[36:39], 0
	v_mfma_f32_16x16x32_bf16 v[8:11], v[28:31], v[36:39], 0
	v_mfma_f32_16x16x32_bf16 v[12:15], v[20:23], v[52:55], 0
	v_mfma_f32_16x16x32_bf16 v[16:19], v[28:31], v[52:55], 0
	v_mfma_f32_16x16x32_bf16 v[36:39], v[20:23], v[116:119], 0
	v_mfma_f32_16x16x32_bf16 v[52:55], v[28:31], v[116:119], 0
	v_mfma_f32_16x16x32_bf16 v[20:23], v[20:23], v[124:127], 0
	v_mfma_f32_16x16x32_bf16 v[28:31], v[28:31], v[124:127], 0
	v_mfma_f32_16x16x32_bf16 v[116:119], v[24:27], v[44:47], v[4:7]
	v_mfma_f32_16x16x32_bf16 v[124:127], v[32:35], v[44:47], v[8:11]
	v_mfma_f32_16x16x32_bf16 v[174:177], v[24:27], v[120:123], v[36:39]
	v_mfma_f32_16x16x32_bf16 v[120:123], v[32:35], v[120:123], v[52:55]
	v_mfma_f32_16x16x32_bf16 v[178:181], v[24:27], v[128:131], v[20:23]
	v_mfma_f32_16x16x32_bf16 v[128:131], v[32:35], v[128:131], v[28:31]
	s_setprio 2
	s_barrier
	v_mfma_f32_16x16x32_bf16 v[166:169], v[24:27], v[60:63], v[12:15]
	v_mfma_f32_16x16x32_bf16 v[170:173], v[32:35], v[60:63], v[16:19]
	s_setprio 0
	s_add_i32 s51, 0, 0x18000
	v_add_u32_e32 v4, s51, v232
	s_add_i32 s72, 0, 0x1c000
	ds_read_b128 v[182:185], v4
	ds_read_b128 v[192:195], v4 offset:1024
	ds_read_b128 v[196:199], v4 offset:2048
	ds_read_b128 v[200:203], v4 offset:3072
	v_add_u32_e32 v4, s72, v232
	ds_read_b128 v[204:207], v4
	ds_read_b128 v[208:211], v4 offset:1024
	ds_read_b128 v[212:215], v4 offset:2048
	ds_read_b128 v[216:219], v4 offset:3072
	s_mov_b32 m0, s59
	ds_read_b128 v[44:47], v233 offset:32768
	ds_read_b128 v[52:55], v233 offset:33792
	ds_read_b128 v[60:63], v233 offset:34816
	ds_read_b128 v[220:223], v233 offset:35840
	ds_read_b128 v[224:227], v233 offset:36864
	ds_read_b128 v[234:237], v233 offset:37888
	ds_read_b128 v[238:241], v233 offset:38912
	ds_read_b128 v[242:245], v233 offset:39936
	global_load_lds_dwordx4 v132, s[26:27]
	s_mov_b32 m0, s60
	s_nop 0
	global_load_lds_dwordx4 v188, s[26:27]
	s_waitcnt vmcnt(8)
	s_waitcnt lgkmcnt(0)
	s_barrier
	s_setprio 1
	s_waitcnt lgkmcnt(0)
	v_mfma_f32_16x16x32_bf16 v[4:7], v[182:185], v[44:47], v[68:71]
	v_mfma_f32_16x16x32_bf16 v[8:11], v[196:199], v[44:47], v[72:75]
	v_mfma_f32_16x16x32_bf16 v[12:15], v[182:185], v[60:63], v[76:79]
	v_mfma_f32_16x16x32_bf16 v[16:19], v[196:199], v[60:63], v[80:83]
	v_mfma_f32_16x16x32_bf16 v[20:23], v[182:185], v[224:227], v[84:87]
	v_mfma_f32_16x16x32_bf16 v[24:27], v[196:199], v[224:227], v[88:91]
	v_mfma_f32_16x16x32_bf16 v[28:31], v[182:185], v[238:241], v[92:95]
	v_mfma_f32_16x16x32_bf16 v[32:35], v[196:199], v[238:241], v[96:99]
	v_mfma_f32_16x16x32_bf16 v[4:7], v[192:195], v[52:55], v[4:7]
	v_mfma_f32_16x16x32_bf16 v[8:11], v[200:203], v[52:55], v[8:11]
	v_mfma_f32_16x16x32_bf16 v[12:15], v[192:195], v[220:223], v[12:15]
	v_mfma_f32_16x16x32_bf16 v[16:19], v[200:203], v[220:223], v[16:19]
	v_mfma_f32_16x16x32_bf16 v[20:23], v[192:195], v[234:237], v[20:23]
	v_mfma_f32_16x16x32_bf16 v[24:27], v[200:203], v[234:237], v[24:27]
	v_mfma_f32_16x16x32_bf16 v[28:31], v[192:195], v[242:245], v[28:31]
	v_mfma_f32_16x16x32_bf16 v[32:35], v[200:203], v[242:245], v[32:35]
	v_mfma_f32_16x16x32_bf16 v[36:39], v[204:207], v[44:47], v[100:103]
	v_mfma_f32_16x16x32_bf16 v[40:43], v[212:215], v[44:47], v[40:43]
	v_mfma_f32_16x16x32_bf16 v[36:39], v[208:211], v[52:55], v[36:39]
	v_mfma_f32_16x16x32_bf16 v[40:43], v[216:219], v[52:55], v[40:43]
	v_mfma_f32_16x16x32_bf16 v[44:47], v[204:207], v[60:63], v[104:107]
	v_mfma_f32_16x16x32_bf16 v[48:51], v[212:215], v[60:63], v[48:51]
	v_mfma_f32_16x16x32_bf16 v[52:55], v[204:207], v[224:227], v[108:111]
	v_mfma_f32_16x16x32_bf16 v[56:59], v[212:215], v[224:227], v[56:59]
	v_mfma_f32_16x16x32_bf16 v[60:63], v[204:207], v[238:241], v[112:115]
	v_mfma_f32_16x16x32_bf16 v[64:67], v[212:215], v[238:241], v[64:67]
	v_mfma_f32_16x16x32_bf16 v[44:47], v[208:211], v[220:223], v[44:47]
	v_mfma_f32_16x16x32_bf16 v[48:51], v[216:219], v[220:223], v[48:51]
	v_mfma_f32_16x16x32_bf16 v[52:55], v[208:211], v[234:237], v[52:55]
	v_mfma_f32_16x16x32_bf16 v[56:59], v[216:219], v[234:237], v[56:59]
	s_setprio 2
	s_barrier
	v_mfma_f32_16x16x32_bf16 v[60:63], v[208:211], v[242:245], v[60:63]
	v_mfma_f32_16x16x32_bf16 v[64:67], v[216:219], v[242:245], v[64:67]
	s_setprio 0
	s_add_i32 s51, s51, s56
	v_lshl_add_u64 v[68:69], v[186:187], 0, s[24:25]
	s_mov_b32 m0, s51
	ds_read_b128 v[104:107], v233 offset:49152
	ds_read_b128 v[108:111], v233 offset:50176
	ds_read_b128 v[112:115], v233 offset:51200
	ds_read_b128 v[220:223], v233 offset:52224
	ds_read_b128 v[224:227], v233 offset:53248
	ds_read_b128 v[234:237], v233 offset:54272
	ds_read_b128 v[238:241], v233 offset:55296
	ds_read_b128 v[242:245], v233 offset:56320
	global_load_lds_dwordx4 v[68:69], off
	v_lshl_add_u64 v[68:69], v[246:247], 0, s[24:25]
	s_add_i32 m0, s51, 0x2000
	s_add_i32 s51, s72, s56
	global_load_lds_dwordx4 v[68:69], off
	s_mov_b32 m0, s51
	v_lshl_add_u64 v[68:69], v[248:249], 0, s[24:25]
	global_load_lds_dwordx4 v2, s[28:29]
	s_add_i32 m0, s51, 0x2000
	s_nop 0
	global_load_lds_dwordx4 v190, s[28:29]
	s_mov_b32 m0, s64
	s_nop 0
	global_load_lds_dwordx4 v[68:69], off
	v_lshl_add_u64 v[68:69], v[250:251], 0, s[24:25]
	s_mov_b32 m0, s65
	s_nop 0
	global_load_lds_dwordx4 v[68:69], off
	s_waitcnt vmcnt(8)
	s_waitcnt lgkmcnt(0)
	s_barrier
	s_setprio 1
	s_waitcnt lgkmcnt(0)
	v_mfma_f32_16x16x32_bf16 v[68:71], v[182:185], v[104:107], v[134:137]
	v_mfma_f32_16x16x32_bf16 v[72:75], v[196:199], v[104:107], v[138:141]
	v_mfma_f32_16x16x32_bf16 v[76:79], v[182:185], v[112:115], v[142:145]
	v_mfma_f32_16x16x32_bf16 v[80:83], v[196:199], v[112:115], v[146:149]
	v_mfma_f32_16x16x32_bf16 v[84:87], v[182:185], v[224:227], v[150:153]
	v_mfma_f32_16x16x32_bf16 v[88:91], v[196:199], v[224:227], v[154:157]
	v_mfma_f32_16x16x32_bf16 v[92:95], v[182:185], v[238:241], v[158:161]
	v_mfma_f32_16x16x32_bf16 v[96:99], v[196:199], v[238:241], v[162:165]
	v_mfma_f32_16x16x32_bf16 v[68:71], v[192:195], v[108:111], v[68:71]
	v_mfma_f32_16x16x32_bf16 v[72:75], v[200:203], v[108:111], v[72:75]
	v_mfma_f32_16x16x32_bf16 v[76:79], v[192:195], v[220:223], v[76:79]
	v_mfma_f32_16x16x32_bf16 v[80:83], v[200:203], v[220:223], v[80:83]
	v_mfma_f32_16x16x32_bf16 v[84:87], v[192:195], v[234:237], v[84:87]
	v_mfma_f32_16x16x32_bf16 v[88:91], v[200:203], v[234:237], v[88:91]
	v_mfma_f32_16x16x32_bf16 v[92:95], v[192:195], v[242:245], v[92:95]
	v_mfma_f32_16x16x32_bf16 v[96:99], v[200:203], v[242:245], v[96:99]
	v_mfma_f32_16x16x32_bf16 v[100:103], v[204:207], v[104:107], v[116:119]
	v_mfma_f32_16x16x32_bf16 v[104:107], v[212:215], v[104:107], v[124:127]
	v_mfma_f32_16x16x32_bf16 v[100:103], v[208:211], v[108:111], v[100:103]
	v_mfma_f32_16x16x32_bf16 v[104:107], v[216:219], v[108:111], v[104:107]
	v_mfma_f32_16x16x32_bf16 v[108:111], v[204:207], v[112:115], v[166:169]
	v_mfma_f32_16x16x32_bf16 v[112:115], v[212:215], v[112:115], v[170:173]
	v_mfma_f32_16x16x32_bf16 v[116:119], v[204:207], v[224:227], v[174:177]
	v_mfma_f32_16x16x32_bf16 v[120:123], v[212:215], v[224:227], v[120:123]
	v_mfma_f32_16x16x32_bf16 v[124:127], v[204:207], v[238:241], v[178:181]
	v_mfma_f32_16x16x32_bf16 v[128:131], v[212:215], v[238:241], v[128:131]
	v_mfma_f32_16x16x32_bf16 v[108:111], v[208:211], v[220:223], v[108:111]
	v_mfma_f32_16x16x32_bf16 v[112:115], v[216:219], v[220:223], v[112:115]
	v_mfma_f32_16x16x32_bf16 v[116:119], v[208:211], v[234:237], v[116:119]
	v_mfma_f32_16x16x32_bf16 v[120:123], v[216:219], v[234:237], v[120:123]
	s_setprio 2
	s_barrier
	v_mfma_f32_16x16x32_bf16 v[124:127], v[208:211], v[242:245], v[124:127]
	v_mfma_f32_16x16x32_bf16 v[128:131], v[216:219], v[242:245], v[128:131]
	s_setprio 0
	s_add_i32 s43, s43, 2
	s_cmp_ge_i32 s43, s42
	s_cbranch_scc0 .LBB0_1625
	v_mov_b32_e32 v192, v2
	s_branch .LBB0_1628

.LBB0_1629:
	s_add_u32 s12, s14, 0xfff80080
	s_addc_u32 s13, s15, -1
	s_add_i32 s29, 0, 0x10000
	s_cmp_eq_u32 s28, 28
	s_cselect_b32 s17, s9, s13
	s_cselect_b32 s16, s8, s12
	s_cselect_b32 s13, s11, s27
	s_cselect_b32 s12, s10, s26
	s_add_i32 s51, 0, 0x14000
	v_add_u32_e32 v144, s29, v232
	v_add_u32_e32 v160, s51, v232
	s_waitcnt lgkmcnt(0)
	ds_read_b128 v[132:135], v144
	ds_read_b128 v[136:139], v144 offset:1024
	ds_read_b128 v[140:143], v144 offset:2048
	ds_read_b128 v[144:147], v144 offset:3072
	ds_read_b128 v[148:151], v160
	ds_read_b128 v[152:155], v160 offset:1024
	ds_read_b128 v[156:159], v160 offset:2048
	ds_read_b128 v[160:163], v160 offset:3072
	s_mov_b32 m0, s66
	v_add_u32_e32 v210, 0, v231
	ds_read_b128 v[164:167], v210
	ds_read_b128 v[168:171], v210 offset:1024
	ds_read_b128 v[172:175], v210 offset:2048
	ds_read_b128 v[176:179], v210 offset:3072
	ds_read_b128 v[180:183], v210 offset:4096
	ds_read_b128 v[184:187], v210 offset:5120
	ds_read_b128 v[194:197], v210 offset:6144
	ds_read_b128 v[198:201], v210 offset:7168
	global_load_lds_dwordx4 v2, s[14:15]
	s_mov_b32 m0, s67
	v_mov_b32_e32 v189, v3
	global_load_lds_dwordx4 v188, s[14:15]
	s_waitcnt vmcnt(8)
	s_waitcnt lgkmcnt(0)
	s_barrier
	s_setprio 1
	s_waitcnt lgkmcnt(0)
	v_mfma_f32_16x16x32_bf16 v[4:7], v[132:135], v[164:167], v[4:7]
	v_mfma_f32_16x16x32_bf16 v[4:7], v[136:139], v[168:171], v[4:7]
	v_mfma_f32_16x16x32_bf16 v[8:11], v[144:147], v[168:171], v[8:11]
	v_mfma_f32_16x16x32_bf16 v[8:11], v[140:143], v[164:167], v[8:11]
	v_mfma_f32_16x16x32_bf16 v[16:19], v[140:143], v[172:175], v[16:19]
	v_mfma_f32_16x16x32_bf16 v[16:19], v[144:147], v[176:179], v[16:19]
	v_mfma_f32_16x16x32_bf16 v[12:15], v[136:139], v[176:179], v[12:15]
	v_mfma_f32_16x16x32_bf16 v[12:15], v[132:135], v[172:175], v[12:15]
	v_mfma_f32_16x16x32_bf16 v[20:23], v[132:135], v[180:183], v[20:23]
	v_mfma_f32_16x16x32_bf16 v[20:23], v[136:139], v[184:187], v[20:23]
	v_mfma_f32_16x16x32_bf16 v[24:27], v[144:147], v[184:187], v[24:27]
	v_mfma_f32_16x16x32_bf16 v[24:27], v[140:143], v[180:183], v[24:27]
	v_mfma_f32_16x16x32_bf16 v[32:35], v[140:143], v[194:197], v[32:35]
	v_mfma_f32_16x16x32_bf16 v[32:35], v[144:147], v[198:201], v[32:35]
	v_mfma_f32_16x16x32_bf16 v[28:31], v[136:139], v[198:201], v[28:31]
	v_mfma_f32_16x16x32_bf16 v[28:31], v[132:135], v[194:197], v[28:31]
	v_mfma_f32_16x16x32_bf16 v[36:39], v[148:151], v[164:167], v[36:39]
	v_mfma_f32_16x16x32_bf16 v[36:39], v[152:155], v[168:171], v[36:39]
	v_mfma_f32_16x16x32_bf16 v[40:43], v[160:163], v[168:171], v[40:43]
	v_mfma_f32_16x16x32_bf16 v[40:43], v[156:159], v[164:167], v[40:43]
	v_mfma_f32_16x16x32_bf16 v[48:51], v[156:159], v[172:175], v[48:51]
	v_mfma_f32_16x16x32_bf16 v[48:51], v[160:163], v[176:179], v[48:51]
	v_mfma_f32_16x16x32_bf16 v[44:47], v[152:155], v[176:179], v[44:47]
	v_mfma_f32_16x16x32_bf16 v[44:47], v[148:151], v[172:175], v[44:47]
	v_mfma_f32_16x16x32_bf16 v[52:55], v[148:151], v[180:183], v[52:55]
	v_mfma_f32_16x16x32_bf16 v[52:55], v[152:155], v[184:187], v[52:55]
	v_mfma_f32_16x16x32_bf16 v[56:59], v[160:163], v[184:187], v[56:59]
	v_mfma_f32_16x16x32_bf16 v[56:59], v[156:159], v[180:183], v[56:59]
	v_mfma_f32_16x16x32_bf16 v[64:67], v[156:159], v[194:197], v[64:67]
	v_mfma_f32_16x16x32_bf16 v[64:67], v[160:163], v[198:201], v[64:67]
	s_setprio 2
	s_barrier
	v_mfma_f32_16x16x32_bf16 v[60:63], v[152:155], v[198:201], v[60:63]
	v_mfma_f32_16x16x32_bf16 v[60:63], v[148:151], v[194:197], v[60:63]
	s_setprio 0
	s_add_i32 s29, s29, s56
	s_mov_b32 m0, s29
	ds_read_b128 v[164:167], v210 offset:16384
	ds_read_b128 v[168:171], v210 offset:17408
	ds_read_b128 v[172:175], v210 offset:18432
	ds_read_b128 v[176:179], v210 offset:19456
	ds_read_b128 v[180:183], v210 offset:20480
	ds_read_b128 v[184:187], v210 offset:21504
	ds_read_b128 v[194:197], v210 offset:22528
	ds_read_b128 v[198:201], v210 offset:23552
	global_load_lds_dwordx4 v192, s[12:13]
	s_add_i32 m0, s29, 0x2000
	s_add_u32 s42, s12, 0x80000
	s_addc_u32 s43, s13, 0
	s_add_i32 s29, s51, s56
	global_load_lds_dwordx4 v190, s[12:13]
	s_mov_b32 m0, s29
	v_mov_b32_e32 v193, v3
	global_load_lds_dwordx4 v192, s[42:43]
	s_add_i32 m0, s29, 0x2000
	v_mov_b32_e32 v191, v3
	global_load_lds_dwordx4 v190, s[42:43]
	s_mov_b32 m0, s57
	v_lshl_add_u64 v[202:203], s[12:13], 0, v[192:193]
	global_load_lds_dwordx4 v2, s[16:17]
	s_mov_b32 m0, s58
	v_lshl_add_u64 v[204:205], s[12:13], 0, v[190:191]
	global_load_lds_dwordx4 v188, s[16:17]
	s_waitcnt vmcnt(8)
	s_waitcnt lgkmcnt(0)
	v_lshl_add_u64 v[206:207], s[16:17], 0, v[2:3]
	v_lshl_add_u64 v[208:209], s[16:17], 0, v[188:189]
	s_barrier
	s_setprio 1
	s_waitcnt lgkmcnt(0)
	v_mfma_f32_16x16x32_bf16 v[68:71], v[132:135], v[164:167], v[68:71]
	v_mfma_f32_16x16x32_bf16 v[68:71], v[136:139], v[168:171], v[68:71]
	v_mfma_f32_16x16x32_bf16 v[72:75], v[144:147], v[168:171], v[72:75]
	v_mfma_f32_16x16x32_bf16 v[72:75], v[140:143], v[164:167], v[72:75]
	v_mfma_f32_16x16x32_bf16 v[80:83], v[140:143], v[172:175], v[80:83]
	v_mfma_f32_16x16x32_bf16 v[80:83], v[144:147], v[176:179], v[80:83]
	v_mfma_f32_16x16x32_bf16 v[76:79], v[136:139], v[176:179], v[76:79]
	v_mfma_f32_16x16x32_bf16 v[76:79], v[132:135], v[172:175], v[76:79]
	v_mfma_f32_16x16x32_bf16 v[84:87], v[132:135], v[180:183], v[84:87]
	v_mfma_f32_16x16x32_bf16 v[84:87], v[136:139], v[184:187], v[84:87]
	v_mfma_f32_16x16x32_bf16 v[88:91], v[144:147], v[184:187], v[88:91]
	v_mfma_f32_16x16x32_bf16 v[88:91], v[140:143], v[180:183], v[88:91]
	v_mfma_f32_16x16x32_bf16 v[96:99], v[140:143], v[194:197], v[96:99]
	v_mfma_f32_16x16x32_bf16 v[96:99], v[144:147], v[198:201], v[96:99]
	v_mfma_f32_16x16x32_bf16 v[92:95], v[136:139], v[198:201], v[92:95]
	v_mfma_f32_16x16x32_bf16 v[92:95], v[132:135], v[194:197], v[92:95]
	v_mfma_f32_16x16x32_bf16 v[100:103], v[148:151], v[164:167], v[100:103]
	v_mfma_f32_16x16x32_bf16 v[100:103], v[152:155], v[168:171], v[100:103]
	v_mfma_f32_16x16x32_bf16 v[104:107], v[160:163], v[168:171], v[104:107]
	v_mfma_f32_16x16x32_bf16 v[104:107], v[156:159], v[164:167], v[104:107]
	v_mfma_f32_16x16x32_bf16 v[112:115], v[156:159], v[172:175], v[112:115]
	v_mfma_f32_16x16x32_bf16 v[112:115], v[160:163], v[176:179], v[112:115]
	v_mfma_f32_16x16x32_bf16 v[108:111], v[152:155], v[176:179], v[108:111]
	v_mfma_f32_16x16x32_bf16 v[108:111], v[148:151], v[172:175], v[108:111]
	v_mfma_f32_16x16x32_bf16 v[116:119], v[148:151], v[180:183], v[116:119]
	v_mfma_f32_16x16x32_bf16 v[116:119], v[152:155], v[184:187], v[116:119]
	v_mfma_f32_16x16x32_bf16 v[120:123], v[160:163], v[184:187], v[120:123]
	v_mfma_f32_16x16x32_bf16 v[120:123], v[156:159], v[180:183], v[120:123]
	v_mfma_f32_16x16x32_bf16 v[128:131], v[156:159], v[194:197], v[128:131]
	v_mfma_f32_16x16x32_bf16 v[128:131], v[160:163], v[198:201], v[128:131]
	s_setprio 2
	s_barrier
	v_mfma_f32_16x16x32_bf16 v[124:127], v[152:155], v[198:201], v[124:127]
	v_mfma_f32_16x16x32_bf16 v[124:127], v[148:151], v[194:197], v[124:127]
	s_setprio 0
	s_add_i32 s29, 0, 0x18000
	s_add_i32 s42, 0, 0x1c000
	v_add_u32_e32 v144, s29, v232
	v_add_u32_e32 v160, s42, v232
	ds_read_b128 v[132:135], v144
	ds_read_b128 v[136:139], v144 offset:1024
	ds_read_b128 v[140:143], v144 offset:2048
	ds_read_b128 v[144:147], v144 offset:3072
	ds_read_b128 v[148:151], v160
	ds_read_b128 v[152:155], v160 offset:1024
	ds_read_b128 v[156:159], v160 offset:2048
	ds_read_b128 v[160:163], v160 offset:3072
	s_add_u32 s16, s16, 0x80000
	s_addc_u32 s17, s17, 0
	s_mov_b32 m0, s59
	ds_read_b128 v[164:167], v210 offset:32768
	ds_read_b128 v[168:171], v210 offset:33792
	ds_read_b128 v[172:175], v210 offset:34816
	ds_read_b128 v[176:179], v210 offset:35840
	ds_read_b128 v[180:183], v210 offset:36864
	ds_read_b128 v[184:187], v210 offset:37888
	ds_read_b128 v[194:197], v210 offset:38912
	ds_read_b128 v[198:201], v210 offset:39936
	global_load_lds_dwordx4 v2, s[16:17]
	s_mov_b32 m0, s60
	s_nop 0
	global_load_lds_dwordx4 v188, s[16:17]
	s_waitcnt vmcnt(8)
	s_waitcnt lgkmcnt(0)
	s_barrier
	s_setprio 1
	s_waitcnt lgkmcnt(0)
	v_mfma_f32_16x16x32_bf16 v[4:7], v[132:135], v[164:167], v[4:7]
	v_mfma_f32_16x16x32_bf16 v[4:7], v[136:139], v[168:171], v[4:7]
	v_mfma_f32_16x16x32_bf16 v[8:11], v[144:147], v[168:171], v[8:11]
	v_mfma_f32_16x16x32_bf16 v[8:11], v[140:143], v[164:167], v[8:11]
	v_mfma_f32_16x16x32_bf16 v[16:19], v[140:143], v[172:175], v[16:19]
	v_mfma_f32_16x16x32_bf16 v[16:19], v[144:147], v[176:179], v[16:19]
	v_mfma_f32_16x16x32_bf16 v[12:15], v[136:139], v[176:179], v[12:15]
	v_mfma_f32_16x16x32_bf16 v[12:15], v[132:135], v[172:175], v[12:15]
	v_mfma_f32_16x16x32_bf16 v[20:23], v[132:135], v[180:183], v[20:23]
	v_mfma_f32_16x16x32_bf16 v[20:23], v[136:139], v[184:187], v[20:23]
	v_mfma_f32_16x16x32_bf16 v[24:27], v[144:147], v[184:187], v[24:27]
	v_mfma_f32_16x16x32_bf16 v[24:27], v[140:143], v[180:183], v[24:27]
	v_mfma_f32_16x16x32_bf16 v[32:35], v[140:143], v[194:197], v[32:35]
	v_mfma_f32_16x16x32_bf16 v[32:35], v[144:147], v[198:201], v[32:35]
	v_mfma_f32_16x16x32_bf16 v[28:31], v[136:139], v[198:201], v[28:31]
	v_mfma_f32_16x16x32_bf16 v[28:31], v[132:135], v[194:197], v[28:31]
	v_mfma_f32_16x16x32_bf16 v[36:39], v[148:151], v[164:167], v[36:39]
	v_mfma_f32_16x16x32_bf16 v[36:39], v[152:155], v[168:171], v[36:39]
	v_mfma_f32_16x16x32_bf16 v[40:43], v[160:163], v[168:171], v[40:43]
	v_mfma_f32_16x16x32_bf16 v[40:43], v[156:159], v[164:167], v[40:43]
	v_mfma_f32_16x16x32_bf16 v[48:51], v[156:159], v[172:175], v[48:51]
	v_mfma_f32_16x16x32_bf16 v[48:51], v[160:163], v[176:179], v[48:51]
	v_mfma_f32_16x16x32_bf16 v[44:47], v[152:155], v[176:179], v[44:47]
	v_mfma_f32_16x16x32_bf16 v[44:47], v[148:151], v[172:175], v[44:47]
	v_mfma_f32_16x16x32_bf16 v[52:55], v[148:151], v[180:183], v[52:55]
	v_mfma_f32_16x16x32_bf16 v[52:55], v[152:155], v[184:187], v[52:55]
	v_mfma_f32_16x16x32_bf16 v[56:59], v[160:163], v[184:187], v[56:59]
	v_mfma_f32_16x16x32_bf16 v[56:59], v[156:159], v[180:183], v[56:59]
	v_mfma_f32_16x16x32_bf16 v[64:67], v[156:159], v[194:197], v[64:67]
	v_mfma_f32_16x16x32_bf16 v[64:67], v[160:163], v[198:201], v[64:67]
	s_setprio 2
	s_barrier
	v_mfma_f32_16x16x32_bf16 v[60:63], v[152:155], v[198:201], v[60:63]
	v_mfma_f32_16x16x32_bf16 v[60:63], v[148:151], v[194:197], v[60:63]
	s_setprio 0
	s_add_i32 s16, s29, s56
	v_lshl_add_u64 v[202:203], v[202:203], 0, s[86:87]
	s_mov_b32 m0, s16
	ds_read_b128 v[164:167], v210 offset:49152
	ds_read_b128 v[168:171], v210 offset:50176
	ds_read_b128 v[172:175], v210 offset:51200
	ds_read_b128 v[176:179], v210 offset:52224
	ds_read_b128 v[180:183], v210 offset:53248
	ds_read_b128 v[184:187], v210 offset:54272
	ds_read_b128 v[194:197], v210 offset:55296
	ds_read_b128 v[198:201], v210 offset:56320
	global_load_lds_dwordx4 v[202:203], off
	s_add_i32 m0, s16, 0x2000
	s_add_u32 s12, s12, 0x80080
	v_lshl_add_u64 v[202:203], v[204:205], 0, s[86:87]
	s_addc_u32 s13, s13, 0
	s_add_i32 s16, s42, s56
	global_load_lds_dwordx4 v[202:203], off
	s_mov_b32 m0, s16
	v_lshl_add_u64 v[202:203], v[206:207], 0, s[86:87]
	global_load_lds_dwordx4 v192, s[12:13]
	s_add_i32 m0, s16, 0x2000
	s_nop 0
	global_load_lds_dwordx4 v190, s[12:13]
	s_mov_b32 m0, s64
	s_nop 0
	global_load_lds_dwordx4 v[202:203], off
	v_lshl_add_u64 v[202:203], v[208:209], 0, s[86:87]
	s_mov_b32 m0, s65
	s_nop 0
	global_load_lds_dwordx4 v[202:203], off
	s_waitcnt vmcnt(8)
	s_waitcnt lgkmcnt(0)
	s_barrier
	s_setprio 1
	s_waitcnt lgkmcnt(0)
	v_mfma_f32_16x16x32_bf16 v[68:71], v[132:135], v[164:167], v[68:71]
	v_mfma_f32_16x16x32_bf16 v[68:71], v[136:139], v[168:171], v[68:71]
	v_mfma_f32_16x16x32_bf16 v[72:75], v[144:147], v[168:171], v[72:75]
	v_mfma_f32_16x16x32_bf16 v[72:75], v[140:143], v[164:167], v[72:75]
	v_mfma_f32_16x16x32_bf16 v[80:83], v[140:143], v[172:175], v[80:83]
	v_mfma_f32_16x16x32_bf16 v[80:83], v[144:147], v[176:179], v[80:83]
	v_mfma_f32_16x16x32_bf16 v[76:79], v[136:139], v[176:179], v[76:79]
	v_mfma_f32_16x16x32_bf16 v[76:79], v[132:135], v[172:175], v[76:79]
	v_mfma_f32_16x16x32_bf16 v[84:87], v[132:135], v[180:183], v[84:87]
	v_mfma_f32_16x16x32_bf16 v[84:87], v[136:139], v[184:187], v[84:87]
	v_mfma_f32_16x16x32_bf16 v[88:91], v[144:147], v[184:187], v[88:91]
	v_mfma_f32_16x16x32_bf16 v[88:91], v[140:143], v[180:183], v[88:91]
	v_mfma_f32_16x16x32_bf16 v[96:99], v[140:143], v[194:197], v[96:99]
	v_mfma_f32_16x16x32_bf16 v[96:99], v[144:147], v[198:201], v[96:99]
	v_mfma_f32_16x16x32_bf16 v[92:95], v[136:139], v[198:201], v[92:95]
	v_mfma_f32_16x16x32_bf16 v[92:95], v[132:135], v[194:197], v[92:95]
	v_mfma_f32_16x16x32_bf16 v[100:103], v[148:151], v[164:167], v[100:103]
	v_mfma_f32_16x16x32_bf16 v[100:103], v[152:155], v[168:171], v[100:103]
	v_mfma_f32_16x16x32_bf16 v[104:107], v[160:163], v[168:171], v[104:107]
	v_mfma_f32_16x16x32_bf16 v[104:107], v[156:159], v[164:167], v[104:107]
	v_mfma_f32_16x16x32_bf16 v[112:115], v[156:159], v[172:175], v[112:115]
	v_mfma_f32_16x16x32_bf16 v[112:115], v[160:163], v[176:179], v[112:115]
	v_mfma_f32_16x16x32_bf16 v[108:111], v[152:155], v[176:179], v[108:111]
	v_mfma_f32_16x16x32_bf16 v[108:111], v[148:151], v[172:175], v[108:111]
	v_mfma_f32_16x16x32_bf16 v[116:119], v[148:151], v[180:183], v[116:119]
	v_mfma_f32_16x16x32_bf16 v[116:119], v[152:155], v[184:187], v[116:119]
	v_mfma_f32_16x16x32_bf16 v[120:123], v[160:163], v[184:187], v[120:123]
	v_mfma_f32_16x16x32_bf16 v[120:123], v[156:159], v[180:183], v[120:123]
	v_mfma_f32_16x16x32_bf16 v[128:131], v[156:159], v[194:197], v[128:131]
	v_mfma_f32_16x16x32_bf16 v[128:131], v[160:163], v[198:201], v[128:131]
	s_setprio 2
	s_barrier
	v_mfma_f32_16x16x32_bf16 v[124:127], v[152:155], v[198:201], v[124:127]
	v_mfma_f32_16x16x32_bf16 v[124:127], v[148:151], v[194:197], v[124:127]
	s_setprio 0
	s_add_i32 s28, s28, 2
	s_add_u32 s14, s14, 0x100
	s_addc_u32 s15, s15, 0
	s_add_u32 s26, s26, 0x100
	s_addc_u32 s27, s27, 0
	s_cmp_gt_u32 s28, 29
	s_cbranch_scc0 .LBB0_1629
	s_and_b64 vcc, exec, s[48:49]
	s_cbranch_vccz .LBB0_1632
	s_barrier

.LBB0_2065:
	s_add_i32 s51, 0, 0x10000
	s_add_i32 s71, 0, 0x14000
	v_add_u32_e32 v16, s51, v232
	v_add_u32_e32 v32, s71, v232
	ds_read_b128 v[4:7], v16
	ds_read_b128 v[8:11], v16 offset:1024
	ds_read_b128 v[12:15], v16 offset:2048
	ds_read_b128 v[16:19], v16 offset:3072
	ds_read_b128 v[20:23], v32
	ds_read_b128 v[24:27], v32 offset:1024
	ds_read_b128 v[28:31], v32 offset:2048
	ds_read_b128 v[32:35], v32 offset:3072
	v_add_u32_e32 v233, 0, v231
	ds_read_b128 v[36:39], v233
	ds_read_b128 v[40:43], v233 offset:1024
	ds_read_b128 v[44:47], v233 offset:2048
	ds_read_b128 v[48:51], v233 offset:3072
	ds_read_b128 v[52:55], v233 offset:4096
	ds_read_b128 v[56:59], v233 offset:5120
	ds_read_b128 v[60:63], v233 offset:6144
	ds_read_b128 v[64:67], v233 offset:7168
	s_waitcnt vmcnt(8)
	s_waitcnt lgkmcnt(0)
	s_barrier
	s_setprio 1
	s_waitcnt lgkmcnt(0)
	v_mfma_f32_16x16x32_bf16 v[68:71], v[4:7], v[36:39], 0
	v_mfma_f32_16x16x32_bf16 v[68:71], v[8:11], v[40:43], v[68:71]
	v_mfma_f32_16x16x32_bf16 v[72:75], v[12:15], v[36:39], 0
	v_mfma_f32_16x16x32_bf16 v[72:75], v[16:19], v[40:43], v[72:75]
	v_mfma_f32_16x16x32_bf16 v[80:83], v[12:15], v[44:47], 0
	v_mfma_f32_16x16x32_bf16 v[80:83], v[16:19], v[48:51], v[80:83]
	v_mfma_f32_16x16x32_bf16 v[76:79], v[4:7], v[44:47], 0
	v_mfma_f32_16x16x32_bf16 v[76:79], v[8:11], v[48:51], v[76:79]
	v_mfma_f32_16x16x32_bf16 v[84:87], v[4:7], v[52:55], 0
	v_mfma_f32_16x16x32_bf16 v[84:87], v[8:11], v[56:59], v[84:87]
	v_mfma_f32_16x16x32_bf16 v[88:91], v[12:15], v[52:55], 0
	v_mfma_f32_16x16x32_bf16 v[88:91], v[16:19], v[56:59], v[88:91]
	v_mfma_f32_16x16x32_bf16 v[96:99], v[12:15], v[60:63], 0
	v_mfma_f32_16x16x32_bf16 v[96:99], v[16:19], v[64:67], v[96:99]
	v_mfma_f32_16x16x32_bf16 v[92:95], v[4:7], v[60:63], 0
	v_mfma_f32_16x16x32_bf16 v[92:95], v[8:11], v[64:67], v[92:95]
	v_mfma_f32_16x16x32_bf16 v[100:103], v[20:23], v[36:39], 0
	v_mfma_f32_16x16x32_bf16 v[36:39], v[28:31], v[36:39], 0
	v_mfma_f32_16x16x32_bf16 v[104:107], v[20:23], v[44:47], 0
	v_mfma_f32_16x16x32_bf16 v[44:47], v[28:31], v[44:47], 0
	v_mfma_f32_16x16x32_bf16 v[108:111], v[20:23], v[52:55], 0
	v_mfma_f32_16x16x32_bf16 v[52:55], v[28:31], v[52:55], 0
	v_mfma_f32_16x16x32_bf16 v[112:115], v[20:23], v[60:63], 0
	v_mfma_f32_16x16x32_bf16 v[60:63], v[28:31], v[60:63], 0
	v_mfma_f32_16x16x32_bf16 v[100:103], v[24:27], v[40:43], v[100:103]
	v_mfma_f32_16x16x32_bf16 v[40:43], v[32:35], v[40:43], v[36:39]
	v_mfma_f32_16x16x32_bf16 v[104:107], v[24:27], v[48:51], v[104:107]
	v_mfma_f32_16x16x32_bf16 v[48:51], v[32:35], v[48:51], v[44:47]
	v_mfma_f32_16x16x32_bf16 v[108:111], v[24:27], v[56:59], v[108:111]
	v_mfma_f32_16x16x32_bf16 v[56:59], v[32:35], v[56:59], v[52:55]
	s_setprio 2
	s_barrier
	v_mfma_f32_16x16x32_bf16 v[112:115], v[24:27], v[64:67], v[112:115]
	v_mfma_f32_16x16x32_bf16 v[64:67], v[32:35], v[64:67], v[60:63]
	s_setprio 0
	v_lshl_add_u64 v[186:187], s[12:13], 0, v[2:3]
	s_add_i32 s51, s51, s38
	v_mov_b32_e32 v191, v3
	v_lshl_add_u64 v[134:135], v[186:187], 0, s[74:75]
	s_mov_b32 m0, s51
	v_lshl_add_u64 v[246:247], s[12:13], 0, v[190:191]
	ds_read_b128 v[36:39], v233 offset:16384
	ds_read_b128 v[44:47], v233 offset:17408
	ds_read_b128 v[52:55], v233 offset:18432
	ds_read_b128 v[60:63], v233 offset:19456
	ds_read_b128 v[116:119], v233 offset:20480
	ds_read_b128 v[120:123], v233 offset:21504
	ds_read_b128 v[124:127], v233 offset:22528
	ds_read_b128 v[128:131], v233 offset:23552
	global_load_lds_dwordx4 v[134:135], off
	v_lshl_add_u64 v[134:135], v[246:247], 0, s[74:75]
	s_add_i32 m0, s51, 0x2000
	s_add_i32 s51, s71, s38
	global_load_lds_dwordx4 v[134:135], off
	s_mov_b32 m0, s51
	v_mov_b32_e32 v133, v3
	global_load_lds_dwordx4 v2, s[16:17]
	s_add_i32 m0, s51, 0x2000
	v_lshl_add_u64 v[248:249], s[14:15], 0, v[132:133]
	v_mov_b32_e32 v189, v3
	global_load_lds_dwordx4 v190, s[16:17]
	v_lshl_add_u64 v[134:135], v[248:249], 0, s[74:75]
	s_mov_b32 m0, s56
	v_lshl_add_u64 v[250:251], s[14:15], 0, v[188:189]
	global_load_lds_dwordx4 v[134:135], off
	v_lshl_add_u64 v[134:135], v[250:251], 0, s[74:75]
	s_mov_b32 m0, s57
	s_nop 0
	global_load_lds_dwordx4 v[134:135], off
	s_waitcnt vmcnt(8)
	s_waitcnt lgkmcnt(0)
	s_barrier
	s_setprio 1
	s_waitcnt lgkmcnt(0)
	v_mfma_f32_16x16x32_bf16 v[134:137], v[4:7], v[36:39], 0
	v_mfma_f32_16x16x32_bf16 v[138:141], v[12:15], v[36:39], 0
	v_mfma_f32_16x16x32_bf16 v[142:145], v[4:7], v[52:55], 0
	v_mfma_f32_16x16x32_bf16 v[146:149], v[12:15], v[52:55], 0
	v_mfma_f32_16x16x32_bf16 v[150:153], v[4:7], v[116:119], 0
	v_mfma_f32_16x16x32_bf16 v[154:157], v[12:15], v[116:119], 0
	v_mfma_f32_16x16x32_bf16 v[4:7], v[4:7], v[124:127], 0
	v_mfma_f32_16x16x32_bf16 v[12:15], v[12:15], v[124:127], 0
	v_mfma_f32_16x16x32_bf16 v[134:137], v[8:11], v[44:47], v[134:137]
	v_mfma_f32_16x16x32_bf16 v[138:141], v[16:19], v[44:47], v[138:141]
	v_mfma_f32_16x16x32_bf16 v[142:145], v[8:11], v[60:63], v[142:145]
	v_mfma_f32_16x16x32_bf16 v[146:149], v[16:19], v[60:63], v[146:149]
	v_mfma_f32_16x16x32_bf16 v[150:153], v[8:11], v[120:123], v[150:153]
	v_mfma_f32_16x16x32_bf16 v[154:157], v[16:19], v[120:123], v[154:157]
	v_mfma_f32_16x16x32_bf16 v[158:161], v[8:11], v[128:131], v[4:7]
	v_mfma_f32_16x16x32_bf16 v[162:165], v[16:19], v[128:131], v[12:15]
	v_mfma_f32_16x16x32_bf16 v[4:7], v[20:23], v[36:39], 0
	v_mfma_f32_16x16x32_bf16 v[8:11], v[28:31], v[36:39], 0
	v_mfma_f32_16x16x32_bf16 v[12:15], v[20:23], v[52:55], 0
	v_mfma_f32_16x16x32_bf16 v[16:19], v[28:31], v[52:55], 0
	v_mfma_f32_16x16x32_bf16 v[36:39], v[20:23], v[116:119], 0
	v_mfma_f32_16x16x32_bf16 v[52:55], v[28:31], v[116:119], 0
	v_mfma_f32_16x16x32_bf16 v[20:23], v[20:23], v[124:127], 0
	v_mfma_f32_16x16x32_bf16 v[28:31], v[28:31], v[124:127], 0
	v_mfma_f32_16x16x32_bf16 v[116:119], v[24:27], v[44:47], v[4:7]
	v_mfma_f32_16x16x32_bf16 v[124:127], v[32:35], v[44:47], v[8:11]
	v_mfma_f32_16x16x32_bf16 v[174:177], v[24:27], v[120:123], v[36:39]
	v_mfma_f32_16x16x32_bf16 v[120:123], v[32:35], v[120:123], v[52:55]
	v_mfma_f32_16x16x32_bf16 v[178:181], v[24:27], v[128:131], v[20:23]
	v_mfma_f32_16x16x32_bf16 v[128:131], v[32:35], v[128:131], v[28:31]
	s_setprio 2
	s_barrier
	v_mfma_f32_16x16x32_bf16 v[166:169], v[24:27], v[60:63], v[12:15]
	v_mfma_f32_16x16x32_bf16 v[170:173], v[32:35], v[60:63], v[16:19]
	s_setprio 0
	s_add_i32 s51, 0, 0x18000
	v_add_u32_e32 v4, s51, v232
	s_add_i32 s71, 0, 0x1c000
	ds_read_b128 v[182:185], v4
	ds_read_b128 v[192:195], v4 offset:1024
	ds_read_b128 v[196:199], v4 offset:2048
	ds_read_b128 v[200:203], v4 offset:3072
	v_add_u32_e32 v4, s71, v232
	ds_read_b128 v[204:207], v4
	ds_read_b128 v[208:211], v4 offset:1024
	ds_read_b128 v[212:215], v4 offset:2048
	ds_read_b128 v[216:219], v4 offset:3072
	s_mov_b32 m0, s58
	ds_read_b128 v[44:47], v233 offset:32768
	ds_read_b128 v[52:55], v233 offset:33792
	ds_read_b128 v[60:63], v233 offset:34816
	ds_read_b128 v[220:223], v233 offset:35840
	ds_read_b128 v[224:227], v233 offset:36864
	ds_read_b128 v[234:237], v233 offset:37888
	ds_read_b128 v[238:241], v233 offset:38912
	ds_read_b128 v[242:245], v233 offset:39936
	global_load_lds_dwordx4 v132, s[26:27]
	s_mov_b32 m0, s59
	s_nop 0
	global_load_lds_dwordx4 v188, s[26:27]
	s_waitcnt vmcnt(8)
	s_waitcnt lgkmcnt(0)
	s_barrier
	s_setprio 1
	s_waitcnt lgkmcnt(0)
	v_mfma_f32_16x16x32_bf16 v[4:7], v[182:185], v[44:47], v[68:71]
	v_mfma_f32_16x16x32_bf16 v[8:11], v[196:199], v[44:47], v[72:75]
	v_mfma_f32_16x16x32_bf16 v[12:15], v[182:185], v[60:63], v[76:79]
	v_mfma_f32_16x16x32_bf16 v[16:19], v[196:199], v[60:63], v[80:83]
	v_mfma_f32_16x16x32_bf16 v[20:23], v[182:185], v[224:227], v[84:87]
	v_mfma_f32_16x16x32_bf16 v[24:27], v[196:199], v[224:227], v[88:91]
	v_mfma_f32_16x16x32_bf16 v[28:31], v[182:185], v[238:241], v[92:95]
	v_mfma_f32_16x16x32_bf16 v[32:35], v[196:199], v[238:241], v[96:99]
	v_mfma_f32_16x16x32_bf16 v[4:7], v[192:195], v[52:55], v[4:7]
	v_mfma_f32_16x16x32_bf16 v[8:11], v[200:203], v[52:55], v[8:11]
	v_mfma_f32_16x16x32_bf16 v[12:15], v[192:195], v[220:223], v[12:15]
	v_mfma_f32_16x16x32_bf16 v[16:19], v[200:203], v[220:223], v[16:19]
	v_mfma_f32_16x16x32_bf16 v[20:23], v[192:195], v[234:237], v[20:23]
	v_mfma_f32_16x16x32_bf16 v[24:27], v[200:203], v[234:237], v[24:27]
	v_mfma_f32_16x16x32_bf16 v[28:31], v[192:195], v[242:245], v[28:31]
	v_mfma_f32_16x16x32_bf16 v[32:35], v[200:203], v[242:245], v[32:35]
	v_mfma_f32_16x16x32_bf16 v[36:39], v[204:207], v[44:47], v[100:103]
	v_mfma_f32_16x16x32_bf16 v[40:43], v[212:215], v[44:47], v[40:43]
	v_mfma_f32_16x16x32_bf16 v[36:39], v[208:211], v[52:55], v[36:39]
	v_mfma_f32_16x16x32_bf16 v[40:43], v[216:219], v[52:55], v[40:43]
	v_mfma_f32_16x16x32_bf16 v[44:47], v[204:207], v[60:63], v[104:107]
	v_mfma_f32_16x16x32_bf16 v[48:51], v[212:215], v[60:63], v[48:51]
	v_mfma_f32_16x16x32_bf16 v[52:55], v[204:207], v[224:227], v[108:111]
	v_mfma_f32_16x16x32_bf16 v[56:59], v[212:215], v[224:227], v[56:59]
	v_mfma_f32_16x16x32_bf16 v[60:63], v[204:207], v[238:241], v[112:115]
	v_mfma_f32_16x16x32_bf16 v[64:67], v[212:215], v[238:241], v[64:67]
	v_mfma_f32_16x16x32_bf16 v[44:47], v[208:211], v[220:223], v[44:47]
	v_mfma_f32_16x16x32_bf16 v[48:51], v[216:219], v[220:223], v[48:51]
	v_mfma_f32_16x16x32_bf16 v[52:55], v[208:211], v[234:237], v[52:55]
	v_mfma_f32_16x16x32_bf16 v[56:59], v[216:219], v[234:237], v[56:59]
	s_setprio 2
	s_barrier
	v_mfma_f32_16x16x32_bf16 v[60:63], v[208:211], v[242:245], v[60:63]
	v_mfma_f32_16x16x32_bf16 v[64:67], v[216:219], v[242:245], v[64:67]
	s_setprio 0
	s_add_i32 s51, s51, s38
	v_lshl_add_u64 v[68:69], v[186:187], 0, s[24:25]
	s_mov_b32 m0, s51
	ds_read_b128 v[104:107], v233 offset:49152
	ds_read_b128 v[108:111], v233 offset:50176
	ds_read_b128 v[112:115], v233 offset:51200
	ds_read_b128 v[220:223], v233 offset:52224
	ds_read_b128 v[224:227], v233 offset:53248
	ds_read_b128 v[234:237], v233 offset:54272
	ds_read_b128 v[238:241], v233 offset:55296
	ds_read_b128 v[242:245], v233 offset:56320
	global_load_lds_dwordx4 v[68:69], off
	v_lshl_add_u64 v[68:69], v[246:247], 0, s[24:25]
	s_add_i32 m0, s51, 0x2000
	s_add_i32 s51, s71, s38
	global_load_lds_dwordx4 v[68:69], off
	s_mov_b32 m0, s51
	v_lshl_add_u64 v[68:69], v[248:249], 0, s[24:25]
	global_load_lds_dwordx4 v2, s[28:29]
	s_add_i32 m0, s51, 0x2000
	s_nop 0
	global_load_lds_dwordx4 v190, s[28:29]
	s_mov_b32 m0, s63
	s_nop 0
	global_load_lds_dwordx4 v[68:69], off
	v_lshl_add_u64 v[68:69], v[250:251], 0, s[24:25]
	s_mov_b32 m0, s64
	s_nop 0
	global_load_lds_dwordx4 v[68:69], off
	s_waitcnt vmcnt(8)
	s_waitcnt lgkmcnt(0)
	s_barrier
	s_setprio 1
	s_waitcnt lgkmcnt(0)
	v_mfma_f32_16x16x32_bf16 v[68:71], v[182:185], v[104:107], v[134:137]
	v_mfma_f32_16x16x32_bf16 v[72:75], v[196:199], v[104:107], v[138:141]
	v_mfma_f32_16x16x32_bf16 v[76:79], v[182:185], v[112:115], v[142:145]
	v_mfma_f32_16x16x32_bf16 v[80:83], v[196:199], v[112:115], v[146:149]
	v_mfma_f32_16x16x32_bf16 v[84:87], v[182:185], v[224:227], v[150:153]
	v_mfma_f32_16x16x32_bf16 v[88:91], v[196:199], v[224:227], v[154:157]
	v_mfma_f32_16x16x32_bf16 v[92:95], v[182:185], v[238:241], v[158:161]
	v_mfma_f32_16x16x32_bf16 v[96:99], v[196:199], v[238:241], v[162:165]
	v_mfma_f32_16x16x32_bf16 v[68:71], v[192:195], v[108:111], v[68:71]
	v_mfma_f32_16x16x32_bf16 v[72:75], v[200:203], v[108:111], v[72:75]
	v_mfma_f32_16x16x32_bf16 v[76:79], v[192:195], v[220:223], v[76:79]
	v_mfma_f32_16x16x32_bf16 v[80:83], v[200:203], v[220:223], v[80:83]
	v_mfma_f32_16x16x32_bf16 v[84:87], v[192:195], v[234:237], v[84:87]
	v_mfma_f32_16x16x32_bf16 v[88:91], v[200:203], v[234:237], v[88:91]
	v_mfma_f32_16x16x32_bf16 v[92:95], v[192:195], v[242:245], v[92:95]
	v_mfma_f32_16x16x32_bf16 v[96:99], v[200:203], v[242:245], v[96:99]
	v_mfma_f32_16x16x32_bf16 v[100:103], v[204:207], v[104:107], v[116:119]
	v_mfma_f32_16x16x32_bf16 v[104:107], v[212:215], v[104:107], v[124:127]
	v_mfma_f32_16x16x32_bf16 v[100:103], v[208:211], v[108:111], v[100:103]
	v_mfma_f32_16x16x32_bf16 v[104:107], v[216:219], v[108:111], v[104:107]
	v_mfma_f32_16x16x32_bf16 v[108:111], v[204:207], v[112:115], v[166:169]
	v_mfma_f32_16x16x32_bf16 v[112:115], v[212:215], v[112:115], v[170:173]
	v_mfma_f32_16x16x32_bf16 v[116:119], v[204:207], v[224:227], v[174:177]
	v_mfma_f32_16x16x32_bf16 v[120:123], v[212:215], v[224:227], v[120:123]
	v_mfma_f32_16x16x32_bf16 v[124:127], v[204:207], v[238:241], v[178:181]
	v_mfma_f32_16x16x32_bf16 v[128:131], v[212:215], v[238:241], v[128:131]
	v_mfma_f32_16x16x32_bf16 v[108:111], v[208:211], v[220:223], v[108:111]
	v_mfma_f32_16x16x32_bf16 v[112:115], v[216:219], v[220:223], v[112:115]
	v_mfma_f32_16x16x32_bf16 v[116:119], v[208:211], v[234:237], v[116:119]
	v_mfma_f32_16x16x32_bf16 v[120:123], v[216:219], v[234:237], v[120:123]
	s_setprio 2
	s_barrier
	v_mfma_f32_16x16x32_bf16 v[124:127], v[208:211], v[242:245], v[124:127]
	v_mfma_f32_16x16x32_bf16 v[128:131], v[216:219], v[242:245], v[128:131]
	s_setprio 0
	s_add_i32 s45, s45, 2
	s_cmp_ge_i32 s45, s44
	s_cbranch_scc0 .LBB0_2065
	v_mov_b32_e32 v192, v2
	s_branch .LBB0_2068

.LBB0_2069:
	s_add_u32 s12, s14, 0xfff80080
	s_addc_u32 s13, s15, -1
	s_add_i32 s29, 0, 0x10000
	s_cmp_eq_u32 s28, 4
	s_cselect_b32 s17, s9, s13
	s_cselect_b32 s16, s8, s12
	s_cselect_b32 s13, s11, s27
	s_cselect_b32 s12, s10, s26
	s_add_i32 s51, 0, 0x14000
	v_add_u32_e32 v144, s29, v232
	v_add_u32_e32 v160, s51, v232
	s_waitcnt lgkmcnt(0)
	ds_read_b128 v[132:135], v144
	ds_read_b128 v[136:139], v144 offset:1024
	ds_read_b128 v[140:143], v144 offset:2048
	ds_read_b128 v[144:147], v144 offset:3072
	ds_read_b128 v[148:151], v160
	ds_read_b128 v[152:155], v160 offset:1024
	ds_read_b128 v[156:159], v160 offset:2048
	ds_read_b128 v[160:163], v160 offset:3072
	s_mov_b32 m0, s65
	v_add_u32_e32 v210, 0, v231
	ds_read_b128 v[164:167], v210
	ds_read_b128 v[168:171], v210 offset:1024
	ds_read_b128 v[172:175], v210 offset:2048
	ds_read_b128 v[176:179], v210 offset:3072
	ds_read_b128 v[180:183], v210 offset:4096
	ds_read_b128 v[184:187], v210 offset:5120
	ds_read_b128 v[194:197], v210 offset:6144
	ds_read_b128 v[198:201], v210 offset:7168
	global_load_lds_dwordx4 v2, s[14:15]
	s_mov_b32 m0, s66
	v_mov_b32_e32 v189, v3
	global_load_lds_dwordx4 v188, s[14:15]
	s_waitcnt vmcnt(8)
	s_waitcnt lgkmcnt(0)
	s_barrier
	s_setprio 1
	s_waitcnt lgkmcnt(0)
	v_mfma_f32_16x16x32_bf16 v[4:7], v[132:135], v[164:167], v[4:7]
	v_mfma_f32_16x16x32_bf16 v[4:7], v[136:139], v[168:171], v[4:7]
	v_mfma_f32_16x16x32_bf16 v[8:11], v[144:147], v[168:171], v[8:11]
	v_mfma_f32_16x16x32_bf16 v[8:11], v[140:143], v[164:167], v[8:11]
	v_mfma_f32_16x16x32_bf16 v[16:19], v[140:143], v[172:175], v[16:19]
	v_mfma_f32_16x16x32_bf16 v[16:19], v[144:147], v[176:179], v[16:19]
	v_mfma_f32_16x16x32_bf16 v[12:15], v[136:139], v[176:179], v[12:15]
	v_mfma_f32_16x16x32_bf16 v[12:15], v[132:135], v[172:175], v[12:15]
	v_mfma_f32_16x16x32_bf16 v[20:23], v[132:135], v[180:183], v[20:23]
	v_mfma_f32_16x16x32_bf16 v[20:23], v[136:139], v[184:187], v[20:23]
	v_mfma_f32_16x16x32_bf16 v[24:27], v[144:147], v[184:187], v[24:27]
	v_mfma_f32_16x16x32_bf16 v[24:27], v[140:143], v[180:183], v[24:27]
	v_mfma_f32_16x16x32_bf16 v[32:35], v[140:143], v[194:197], v[32:35]
	v_mfma_f32_16x16x32_bf16 v[32:35], v[144:147], v[198:201], v[32:35]
	v_mfma_f32_16x16x32_bf16 v[28:31], v[136:139], v[198:201], v[28:31]
	v_mfma_f32_16x16x32_bf16 v[28:31], v[132:135], v[194:197], v[28:31]
	v_mfma_f32_16x16x32_bf16 v[36:39], v[148:151], v[164:167], v[36:39]
	v_mfma_f32_16x16x32_bf16 v[36:39], v[152:155], v[168:171], v[36:39]
	v_mfma_f32_16x16x32_bf16 v[40:43], v[160:163], v[168:171], v[40:43]
	v_mfma_f32_16x16x32_bf16 v[40:43], v[156:159], v[164:167], v[40:43]
	v_mfma_f32_16x16x32_bf16 v[48:51], v[156:159], v[172:175], v[48:51]
	v_mfma_f32_16x16x32_bf16 v[48:51], v[160:163], v[176:179], v[48:51]
	v_mfma_f32_16x16x32_bf16 v[44:47], v[152:155], v[176:179], v[44:47]
	v_mfma_f32_16x16x32_bf16 v[44:47], v[148:151], v[172:175], v[44:47]
	v_mfma_f32_16x16x32_bf16 v[52:55], v[148:151], v[180:183], v[52:55]
	v_mfma_f32_16x16x32_bf16 v[52:55], v[152:155], v[184:187], v[52:55]
	v_mfma_f32_16x16x32_bf16 v[56:59], v[160:163], v[184:187], v[56:59]
	v_mfma_f32_16x16x32_bf16 v[56:59], v[156:159], v[180:183], v[56:59]
	v_mfma_f32_16x16x32_bf16 v[64:67], v[156:159], v[194:197], v[64:67]
	v_mfma_f32_16x16x32_bf16 v[64:67], v[160:163], v[198:201], v[64:67]
	s_setprio 2
	s_barrier
	v_mfma_f32_16x16x32_bf16 v[60:63], v[152:155], v[198:201], v[60:63]
	v_mfma_f32_16x16x32_bf16 v[60:63], v[148:151], v[194:197], v[60:63]
	s_setprio 0
	s_add_i32 s29, s29, s38
	s_mov_b32 m0, s29
	ds_read_b128 v[164:167], v210 offset:16384
	ds_read_b128 v[168:171], v210 offset:17408
	ds_read_b128 v[172:175], v210 offset:18432
	ds_read_b128 v[176:179], v210 offset:19456
	ds_read_b128 v[180:183], v210 offset:20480
	ds_read_b128 v[184:187], v210 offset:21504
	ds_read_b128 v[194:197], v210 offset:22528
	ds_read_b128 v[198:201], v210 offset:23552
	global_load_lds_dwordx4 v192, s[12:13]
	s_add_i32 m0, s29, 0x2000
	s_add_u32 s44, s12, 0x20000
	s_addc_u32 s45, s13, 0
	s_add_i32 s29, s51, s38
	global_load_lds_dwordx4 v190, s[12:13]
	s_mov_b32 m0, s29
	v_mov_b32_e32 v193, v3
	global_load_lds_dwordx4 v192, s[44:45]
	s_add_i32 m0, s29, 0x2000
	v_mov_b32_e32 v191, v3
	global_load_lds_dwordx4 v190, s[44:45]
	s_mov_b32 m0, s56
	v_lshl_add_u64 v[202:203], s[12:13], 0, v[192:193]
	global_load_lds_dwordx4 v2, s[16:17]
	s_mov_b32 m0, s57
	v_lshl_add_u64 v[204:205], s[12:13], 0, v[190:191]
	global_load_lds_dwordx4 v188, s[16:17]
	s_waitcnt vmcnt(8)
	s_waitcnt lgkmcnt(0)
	v_lshl_add_u64 v[206:207], s[16:17], 0, v[2:3]
	v_lshl_add_u64 v[208:209], s[16:17], 0, v[188:189]
	s_barrier
	s_setprio 1
	s_waitcnt lgkmcnt(0)
	v_mfma_f32_16x16x32_bf16 v[68:71], v[132:135], v[164:167], v[68:71]
	v_mfma_f32_16x16x32_bf16 v[68:71], v[136:139], v[168:171], v[68:71]
	v_mfma_f32_16x16x32_bf16 v[72:75], v[144:147], v[168:171], v[72:75]
	v_mfma_f32_16x16x32_bf16 v[72:75], v[140:143], v[164:167], v[72:75]
	v_mfma_f32_16x16x32_bf16 v[80:83], v[140:143], v[172:175], v[80:83]
	v_mfma_f32_16x16x32_bf16 v[80:83], v[144:147], v[176:179], v[80:83]
	v_mfma_f32_16x16x32_bf16 v[76:79], v[136:139], v[176:179], v[76:79]
	v_mfma_f32_16x16x32_bf16 v[76:79], v[132:135], v[172:175], v[76:79]
	v_mfma_f32_16x16x32_bf16 v[84:87], v[132:135], v[180:183], v[84:87]
	v_mfma_f32_16x16x32_bf16 v[84:87], v[136:139], v[184:187], v[84:87]
	v_mfma_f32_16x16x32_bf16 v[88:91], v[144:147], v[184:187], v[88:91]
	v_mfma_f32_16x16x32_bf16 v[88:91], v[140:143], v[180:183], v[88:91]
	v_mfma_f32_16x16x32_bf16 v[96:99], v[140:143], v[194:197], v[96:99]
	v_mfma_f32_16x16x32_bf16 v[96:99], v[144:147], v[198:201], v[96:99]
	v_mfma_f32_16x16x32_bf16 v[92:95], v[136:139], v[198:201], v[92:95]
	v_mfma_f32_16x16x32_bf16 v[92:95], v[132:135], v[194:197], v[92:95]
	v_mfma_f32_16x16x32_bf16 v[100:103], v[148:151], v[164:167], v[100:103]
	v_mfma_f32_16x16x32_bf16 v[100:103], v[152:155], v[168:171], v[100:103]
	v_mfma_f32_16x16x32_bf16 v[104:107], v[160:163], v[168:171], v[104:107]
	v_mfma_f32_16x16x32_bf16 v[104:107], v[156:159], v[164:167], v[104:107]
	v_mfma_f32_16x16x32_bf16 v[112:115], v[156:159], v[172:175], v[112:115]
	v_mfma_f32_16x16x32_bf16 v[112:115], v[160:163], v[176:179], v[112:115]
	v_mfma_f32_16x16x32_bf16 v[108:111], v[152:155], v[176:179], v[108:111]
	v_mfma_f32_16x16x32_bf16 v[108:111], v[148:151], v[172:175], v[108:111]
	v_mfma_f32_16x16x32_bf16 v[116:119], v[148:151], v[180:183], v[116:119]
	v_mfma_f32_16x16x32_bf16 v[116:119], v[152:155], v[184:187], v[116:119]
	v_mfma_f32_16x16x32_bf16 v[120:123], v[160:163], v[184:187], v[120:123]
	v_mfma_f32_16x16x32_bf16 v[120:123], v[156:159], v[180:183], v[120:123]
	v_mfma_f32_16x16x32_bf16 v[128:131], v[156:159], v[194:197], v[128:131]
	v_mfma_f32_16x16x32_bf16 v[128:131], v[160:163], v[198:201], v[128:131]
	s_setprio 2
	s_barrier
	v_mfma_f32_16x16x32_bf16 v[124:127], v[152:155], v[198:201], v[124:127]
	v_mfma_f32_16x16x32_bf16 v[124:127], v[148:151], v[194:197], v[124:127]
	s_setprio 0
	s_add_i32 s29, 0, 0x18000
	s_add_i32 s44, 0, 0x1c000
	v_add_u32_e32 v144, s29, v232
	v_add_u32_e32 v160, s44, v232
	ds_read_b128 v[132:135], v144
	ds_read_b128 v[136:139], v144 offset:1024
	ds_read_b128 v[140:143], v144 offset:2048
	ds_read_b128 v[144:147], v144 offset:3072
	ds_read_b128 v[148:151], v160
	ds_read_b128 v[152:155], v160 offset:1024
	ds_read_b128 v[156:159], v160 offset:2048
	ds_read_b128 v[160:163], v160 offset:3072
	s_add_u32 s16, s16, 0x80000
	s_addc_u32 s17, s17, 0
	s_mov_b32 m0, s58
	ds_read_b128 v[164:167], v210 offset:32768
	ds_read_b128 v[168:171], v210 offset:33792
	ds_read_b128 v[172:175], v210 offset:34816
	ds_read_b128 v[176:179], v210 offset:35840
	ds_read_b128 v[180:183], v210 offset:36864
	ds_read_b128 v[184:187], v210 offset:37888
	ds_read_b128 v[194:197], v210 offset:38912
	ds_read_b128 v[198:201], v210 offset:39936
	global_load_lds_dwordx4 v2, s[16:17]
	s_mov_b32 m0, s59
	s_nop 0
	global_load_lds_dwordx4 v188, s[16:17]
	s_waitcnt vmcnt(8)
	s_waitcnt lgkmcnt(0)
	s_barrier
	s_setprio 1
	s_waitcnt lgkmcnt(0)
	v_mfma_f32_16x16x32_bf16 v[4:7], v[132:135], v[164:167], v[4:7]
	v_mfma_f32_16x16x32_bf16 v[4:7], v[136:139], v[168:171], v[4:7]
	v_mfma_f32_16x16x32_bf16 v[8:11], v[144:147], v[168:171], v[8:11]
	v_mfma_f32_16x16x32_bf16 v[8:11], v[140:143], v[164:167], v[8:11]
	v_mfma_f32_16x16x32_bf16 v[16:19], v[140:143], v[172:175], v[16:19]
	v_mfma_f32_16x16x32_bf16 v[16:19], v[144:147], v[176:179], v[16:19]
	v_mfma_f32_16x16x32_bf16 v[12:15], v[136:139], v[176:179], v[12:15]
	v_mfma_f32_16x16x32_bf16 v[12:15], v[132:135], v[172:175], v[12:15]
	v_mfma_f32_16x16x32_bf16 v[20:23], v[132:135], v[180:183], v[20:23]
	v_mfma_f32_16x16x32_bf16 v[20:23], v[136:139], v[184:187], v[20:23]
	v_mfma_f32_16x16x32_bf16 v[24:27], v[144:147], v[184:187], v[24:27]
	v_mfma_f32_16x16x32_bf16 v[24:27], v[140:143], v[180:183], v[24:27]
	v_mfma_f32_16x16x32_bf16 v[32:35], v[140:143], v[194:197], v[32:35]
	v_mfma_f32_16x16x32_bf16 v[32:35], v[144:147], v[198:201], v[32:35]
	v_mfma_f32_16x16x32_bf16 v[28:31], v[136:139], v[198:201], v[28:31]
	v_mfma_f32_16x16x32_bf16 v[28:31], v[132:135], v[194:197], v[28:31]
	v_mfma_f32_16x16x32_bf16 v[36:39], v[148:151], v[164:167], v[36:39]
	v_mfma_f32_16x16x32_bf16 v[36:39], v[152:155], v[168:171], v[36:39]
	v_mfma_f32_16x16x32_bf16 v[40:43], v[160:163], v[168:171], v[40:43]
	v_mfma_f32_16x16x32_bf16 v[40:43], v[156:159], v[164:167], v[40:43]
	v_mfma_f32_16x16x32_bf16 v[48:51], v[156:159], v[172:175], v[48:51]
	v_mfma_f32_16x16x32_bf16 v[48:51], v[160:163], v[176:179], v[48:51]
	v_mfma_f32_16x16x32_bf16 v[44:47], v[152:155], v[176:179], v[44:47]
	v_mfma_f32_16x16x32_bf16 v[44:47], v[148:151], v[172:175], v[44:47]
	v_mfma_f32_16x16x32_bf16 v[52:55], v[148:151], v[180:183], v[52:55]
	v_mfma_f32_16x16x32_bf16 v[52:55], v[152:155], v[184:187], v[52:55]
	v_mfma_f32_16x16x32_bf16 v[56:59], v[160:163], v[184:187], v[56:59]
	v_mfma_f32_16x16x32_bf16 v[56:59], v[156:159], v[180:183], v[56:59]
	v_mfma_f32_16x16x32_bf16 v[64:67], v[156:159], v[194:197], v[64:67]
	v_mfma_f32_16x16x32_bf16 v[64:67], v[160:163], v[198:201], v[64:67]
	s_setprio 2
	s_barrier
	v_mfma_f32_16x16x32_bf16 v[60:63], v[152:155], v[198:201], v[60:63]
	v_mfma_f32_16x16x32_bf16 v[60:63], v[148:151], v[194:197], v[60:63]
	s_setprio 0
	s_add_i32 s16, s29, s38
	v_lshl_add_u64 v[202:203], v[202:203], 0, s[86:87]
	s_mov_b32 m0, s16
	ds_read_b128 v[164:167], v210 offset:49152
	ds_read_b128 v[168:171], v210 offset:50176
	ds_read_b128 v[172:175], v210 offset:51200
	ds_read_b128 v[176:179], v210 offset:52224
	ds_read_b128 v[180:183], v210 offset:53248
	ds_read_b128 v[184:187], v210 offset:54272
	ds_read_b128 v[194:197], v210 offset:55296
	ds_read_b128 v[198:201], v210 offset:56320
	global_load_lds_dwordx4 v[202:203], off
	s_add_i32 m0, s16, 0x2000
	s_add_u32 s12, s12, 0x20080
	v_lshl_add_u64 v[202:203], v[204:205], 0, s[86:87]
	s_addc_u32 s13, s13, 0
	s_add_i32 s16, s44, s38
	global_load_lds_dwordx4 v[202:203], off
	s_mov_b32 m0, s16
	v_lshl_add_u64 v[202:203], v[206:207], 0, s[86:87]
	global_load_lds_dwordx4 v192, s[12:13]
	s_add_i32 m0, s16, 0x2000
	s_nop 0
	global_load_lds_dwordx4 v190, s[12:13]
	s_mov_b32 m0, s63
	s_nop 0
	global_load_lds_dwordx4 v[202:203], off
	v_lshl_add_u64 v[202:203], v[208:209], 0, s[86:87]
	s_mov_b32 m0, s64
	s_nop 0
	global_load_lds_dwordx4 v[202:203], off
	s_waitcnt vmcnt(8)
	s_waitcnt lgkmcnt(0)
	s_barrier
	s_setprio 1
	s_waitcnt lgkmcnt(0)
	v_mfma_f32_16x16x32_bf16 v[68:71], v[132:135], v[164:167], v[68:71]
	v_mfma_f32_16x16x32_bf16 v[68:71], v[136:139], v[168:171], v[68:71]
	v_mfma_f32_16x16x32_bf16 v[72:75], v[144:147], v[168:171], v[72:75]
	v_mfma_f32_16x16x32_bf16 v[72:75], v[140:143], v[164:167], v[72:75]
	v_mfma_f32_16x16x32_bf16 v[80:83], v[140:143], v[172:175], v[80:83]
	v_mfma_f32_16x16x32_bf16 v[80:83], v[144:147], v[176:179], v[80:83]
	v_mfma_f32_16x16x32_bf16 v[76:79], v[136:139], v[176:179], v[76:79]
	v_mfma_f32_16x16x32_bf16 v[76:79], v[132:135], v[172:175], v[76:79]
	v_mfma_f32_16x16x32_bf16 v[84:87], v[132:135], v[180:183], v[84:87]
	v_mfma_f32_16x16x32_bf16 v[84:87], v[136:139], v[184:187], v[84:87]
	v_mfma_f32_16x16x32_bf16 v[88:91], v[144:147], v[184:187], v[88:91]
	v_mfma_f32_16x16x32_bf16 v[88:91], v[140:143], v[180:183], v[88:91]
	v_mfma_f32_16x16x32_bf16 v[96:99], v[140:143], v[194:197], v[96:99]
	v_mfma_f32_16x16x32_bf16 v[96:99], v[144:147], v[198:201], v[96:99]
	v_mfma_f32_16x16x32_bf16 v[92:95], v[136:139], v[198:201], v[92:95]
	v_mfma_f32_16x16x32_bf16 v[92:95], v[132:135], v[194:197], v[92:95]
	v_mfma_f32_16x16x32_bf16 v[100:103], v[148:151], v[164:167], v[100:103]
	v_mfma_f32_16x16x32_bf16 v[100:103], v[152:155], v[168:171], v[100:103]
	v_mfma_f32_16x16x32_bf16 v[104:107], v[160:163], v[168:171], v[104:107]
	v_mfma_f32_16x16x32_bf16 v[104:107], v[156:159], v[164:167], v[104:107]
	v_mfma_f32_16x16x32_bf16 v[112:115], v[156:159], v[172:175], v[112:115]
	v_mfma_f32_16x16x32_bf16 v[112:115], v[160:163], v[176:179], v[112:115]
	v_mfma_f32_16x16x32_bf16 v[108:111], v[152:155], v[176:179], v[108:111]
	v_mfma_f32_16x16x32_bf16 v[108:111], v[148:151], v[172:175], v[108:111]
	v_mfma_f32_16x16x32_bf16 v[116:119], v[148:151], v[180:183], v[116:119]
	v_mfma_f32_16x16x32_bf16 v[116:119], v[152:155], v[184:187], v[116:119]
	v_mfma_f32_16x16x32_bf16 v[120:123], v[160:163], v[184:187], v[120:123]
	v_mfma_f32_16x16x32_bf16 v[120:123], v[156:159], v[180:183], v[120:123]
	v_mfma_f32_16x16x32_bf16 v[128:131], v[156:159], v[194:197], v[128:131]
	v_mfma_f32_16x16x32_bf16 v[128:131], v[160:163], v[198:201], v[128:131]
	s_setprio 2
	s_barrier
	v_mfma_f32_16x16x32_bf16 v[124:127], v[152:155], v[198:201], v[124:127]
	v_mfma_f32_16x16x32_bf16 v[124:127], v[148:151], v[194:197], v[124:127]
	s_setprio 0
	s_add_i32 s28, s28, 2
	s_add_u32 s14, s14, 0x100
	s_addc_u32 s15, s15, 0
	s_add_u32 s26, s26, 0x100
	s_addc_u32 s27, s27, 0
	s_cmp_gt_u32 s28, 5
	s_cbranch_scc0 .LBB0_2069
	s_and_b64 vcc, exec, s[48:49]
	s_cbranch_vccz .LBB0_2072
	s_barrier

.LBB0_2159:
	s_add_i32 s68, 0, 0x10000
	s_add_i32 s69, 0, 0x14000
	v_add_u32_e32 v16, s68, v143
	v_add_u32_e32 v32, s69, v143
	ds_read_b128 v[4:7], v16
	ds_read_b128 v[8:11], v16 offset:1024
	ds_read_b128 v[12:15], v16 offset:2048
	ds_read_b128 v[16:19], v16 offset:3072
	ds_read_b128 v[20:23], v32
	ds_read_b128 v[24:27], v32 offset:1024
	ds_read_b128 v[28:31], v32 offset:2048
	ds_read_b128 v[32:35], v32 offset:3072
	v_add_u32_e32 v231, 0, v142
	ds_read_b128 v[36:39], v231
	ds_read_b128 v[40:43], v231 offset:1024
	ds_read_b128 v[44:47], v231 offset:2048
	ds_read_b128 v[48:51], v231 offset:3072
	ds_read_b128 v[52:55], v231 offset:4096
	ds_read_b128 v[56:59], v231 offset:5120
	ds_read_b128 v[60:63], v231 offset:6144
	ds_read_b128 v[64:67], v231 offset:7168
	s_waitcnt vmcnt(8)
	s_waitcnt lgkmcnt(0)
	s_barrier
	s_setprio 1
	s_waitcnt lgkmcnt(0)
	v_mfma_f32_16x16x32_f16 v[68:71], v[4:7], v[36:39], 0
	v_mfma_f32_16x16x32_f16 v[72:75], v[12:15], v[36:39], 0
	v_mfma_f32_16x16x32_f16 v[76:79], v[4:7], v[44:47], 0
	v_mfma_f32_16x16x32_f16 v[80:83], v[12:15], v[44:47], 0
	v_mfma_f32_16x16x32_f16 v[84:87], v[4:7], v[52:55], 0
	v_mfma_f32_16x16x32_f16 v[88:91], v[12:15], v[52:55], 0
	v_mfma_f32_16x16x32_f16 v[92:95], v[4:7], v[60:63], 0
	v_mfma_f32_16x16x32_f16 v[96:99], v[12:15], v[60:63], 0
	v_mfma_f32_16x16x32_f16 v[68:71], v[8:11], v[40:43], v[68:71]
	v_mfma_f32_16x16x32_f16 v[72:75], v[16:19], v[40:43], v[72:75]
	v_mfma_f32_16x16x32_f16 v[76:79], v[8:11], v[48:51], v[76:79]
	v_mfma_f32_16x16x32_f16 v[80:83], v[16:19], v[48:51], v[80:83]
	v_mfma_f32_16x16x32_f16 v[84:87], v[8:11], v[56:59], v[84:87]
	v_mfma_f32_16x16x32_f16 v[88:91], v[16:19], v[56:59], v[88:91]
	v_mfma_f32_16x16x32_f16 v[92:95], v[8:11], v[64:67], v[92:95]
	v_mfma_f32_16x16x32_f16 v[100:103], v[16:19], v[64:67], v[96:99]
	v_mfma_f32_16x16x32_f16 v[96:99], v[20:23], v[36:39], 0
	v_mfma_f32_16x16x32_f16 v[36:39], v[28:31], v[36:39], 0
	v_mfma_f32_16x16x32_f16 v[104:107], v[20:23], v[44:47], 0
	v_mfma_f32_16x16x32_f16 v[44:47], v[28:31], v[44:47], 0
	v_mfma_f32_16x16x32_f16 v[108:111], v[20:23], v[52:55], 0
	v_mfma_f32_16x16x32_f16 v[52:55], v[28:31], v[52:55], 0
	v_mfma_f32_16x16x32_f16 v[112:115], v[20:23], v[60:63], 0
	v_mfma_f32_16x16x32_f16 v[60:63], v[28:31], v[60:63], 0
	v_mfma_f32_16x16x32_f16 v[116:119], v[24:27], v[40:43], v[96:99]
	v_mfma_f32_16x16x32_f16 v[36:39], v[32:35], v[40:43], v[36:39]
	v_mfma_f32_16x16x32_f16 v[40:43], v[24:27], v[48:51], v[104:107]
	v_mfma_f32_16x16x32_f16 v[44:47], v[32:35], v[48:51], v[44:47]
	v_mfma_f32_16x16x32_f16 v[48:51], v[24:27], v[56:59], v[108:111]
	v_mfma_f32_16x16x32_f16 v[52:55], v[32:35], v[56:59], v[52:55]
	s_setprio 2
	s_barrier
	v_mfma_f32_16x16x32_f16 v[56:59], v[24:27], v[64:67], v[112:115]
	v_mfma_f32_16x16x32_f16 v[60:63], v[32:35], v[64:67], v[60:63]
	s_setprio 0
	v_lshl_add_u64 v[138:139], s[8:9], 0, v[2:3]
	s_add_i32 s68, s68, s53
	v_mov_b32_e32 v135, v3
	v_lshl_add_u64 v[144:145], v[138:139], 0, s[74:75]
	s_mov_b32 m0, s68
	v_lshl_add_u64 v[192:193], s[8:9], 0, v[134:135]
	ds_read_b128 v[64:67], v231 offset:16384
	ds_read_b128 v[96:99], v231 offset:17408
	ds_read_b128 v[104:107], v231 offset:18432
	ds_read_b128 v[108:111], v231 offset:19456
	ds_read_b128 v[112:115], v231 offset:20480
	ds_read_b128 v[120:123], v231 offset:21504
	ds_read_b128 v[124:127], v231 offset:22528
	ds_read_b128 v[128:131], v231 offset:23552
	global_load_lds_dwordx4 v[144:145], off
	v_lshl_add_u64 v[144:145], v[192:193], 0, s[74:75]
	s_add_i32 m0, s68, 0x2000
	s_add_i32 s68, s69, s53
	global_load_lds_dwordx4 v[144:145], off
	s_mov_b32 m0, s68
	v_mov_b32_e32 v137, v3
	global_load_lds_dwordx4 v2, s[40:41]
	s_add_i32 m0, s68, 0x2000
	v_lshl_add_u64 v[248:249], s[6:7], 0, v[136:137]
	v_mov_b32_e32 v133, v3
	global_load_lds_dwordx4 v134, s[40:41]
	v_lshl_add_u64 v[144:145], v[248:249], 0, s[74:75]
	s_mov_b32 m0, s54
	v_lshl_add_u64 v[250:251], s[6:7], 0, v[132:133]
	global_load_lds_dwordx4 v[144:145], off
	v_lshl_add_u64 v[144:145], v[250:251], 0, s[74:75]
	s_mov_b32 m0, s55
	s_nop 0
	global_load_lds_dwordx4 v[144:145], off
	s_waitcnt vmcnt(8)
	s_waitcnt lgkmcnt(0)
	s_barrier
	s_setprio 1
	s_waitcnt lgkmcnt(0)
	v_mfma_f32_16x16x32_f16 v[144:147], v[4:7], v[64:67], 0
	v_mfma_f32_16x16x32_f16 v[148:151], v[12:15], v[64:67], 0
	v_mfma_f32_16x16x32_f16 v[152:155], v[4:7], v[104:107], 0
	v_mfma_f32_16x16x32_f16 v[156:159], v[12:15], v[104:107], 0
	v_mfma_f32_16x16x32_f16 v[160:163], v[4:7], v[112:115], 0
	v_mfma_f32_16x16x32_f16 v[164:167], v[12:15], v[112:115], 0
	v_mfma_f32_16x16x32_f16 v[4:7], v[4:7], v[124:127], 0
	v_mfma_f32_16x16x32_f16 v[12:15], v[12:15], v[124:127], 0
	v_mfma_f32_16x16x32_f16 v[144:147], v[8:11], v[96:99], v[144:147]
	v_mfma_f32_16x16x32_f16 v[152:155], v[8:11], v[108:111], v[152:155]
	v_mfma_f32_16x16x32_f16 v[160:163], v[8:11], v[120:123], v[160:163]
	v_mfma_f32_16x16x32_f16 v[4:7], v[8:11], v[128:131], v[4:7]
	v_mfma_f32_16x16x32_f16 v[8:11], v[16:19], v[128:131], v[12:15]
	v_mfma_f32_16x16x32_f16 v[148:151], v[16:19], v[96:99], v[148:151]
	v_mfma_f32_16x16x32_f16 v[156:159], v[16:19], v[108:111], v[156:159]
	v_mfma_f32_16x16x32_f16 v[164:167], v[16:19], v[120:123], v[164:167]
	v_mfma_f32_16x16x32_f16 v[12:15], v[20:23], v[64:67], 0
	v_mfma_f32_16x16x32_f16 v[16:19], v[28:31], v[64:67], 0
	v_mfma_f32_16x16x32_f16 v[64:67], v[20:23], v[104:107], 0
	v_mfma_f32_16x16x32_f16 v[104:107], v[28:31], v[104:107], 0
	v_mfma_f32_16x16x32_f16 v[168:171], v[20:23], v[112:115], 0
	v_mfma_f32_16x16x32_f16 v[112:115], v[28:31], v[112:115], 0
	v_mfma_f32_16x16x32_f16 v[20:23], v[20:23], v[124:127], 0
	v_mfma_f32_16x16x32_f16 v[28:31], v[28:31], v[124:127], 0
	v_mfma_f32_16x16x32_f16 v[12:15], v[24:27], v[96:99], v[12:15]
	v_mfma_f32_16x16x32_f16 v[172:175], v[32:35], v[96:99], v[16:19]
	v_mfma_f32_16x16x32_f16 v[176:179], v[24:27], v[108:111], v[64:67]
	v_mfma_f32_16x16x32_f16 v[180:183], v[32:35], v[108:111], v[104:107]
	v_mfma_f32_16x16x32_f16 v[168:171], v[24:27], v[120:123], v[168:171]
	v_mfma_f32_16x16x32_f16 v[184:187], v[32:35], v[120:123], v[112:115]
	s_setprio 2
	s_barrier
	v_mfma_f32_16x16x32_f16 v[188:191], v[24:27], v[128:131], v[20:23]
	v_mfma_f32_16x16x32_f16 v[196:199], v[32:35], v[128:131], v[28:31]
	s_setprio 0
	s_add_i32 s68, 0, 0x18000
	v_add_u32_e32 v24, s68, v143
	s_add_i32 s69, 0, 0x1c000
	ds_read_b128 v[16:19], v24
	ds_read_b128 v[20:23], v24 offset:1024
	ds_read_b128 v[28:31], v24 offset:2048
	ds_read_b128 v[200:203], v24 offset:3072
	v_add_u32_e32 v24, s69, v143
	ds_read_b128 v[204:207], v24
	ds_read_b128 v[208:211], v24 offset:1024
	ds_read_b128 v[212:215], v24 offset:2048
	ds_read_b128 v[216:219], v24 offset:3072
	s_mov_b32 m0, s56
	ds_read_b128 v[24:27], v231 offset:32768
	ds_read_b128 v[32:35], v231 offset:33792
	ds_read_b128 v[64:67], v231 offset:34816
	ds_read_b128 v[220:223], v231 offset:35840
	ds_read_b128 v[224:227], v231 offset:36864
	ds_read_b128 v[232:235], v231 offset:37888
	ds_read_b128 v[236:239], v231 offset:38912
	ds_read_b128 v[240:243], v231 offset:39936
	global_load_lds_dwordx4 v136, s[42:43]
	s_mov_b32 m0, s57
	s_nop 0
	global_load_lds_dwordx4 v132, s[42:43]
	s_waitcnt vmcnt(8)
	s_waitcnt lgkmcnt(0)
	s_barrier
	s_setprio 1
	s_waitcnt lgkmcnt(0)
	v_mfma_f32_16x16x32_f16 v[68:71], v[16:19], v[24:27], v[68:71]
	v_mfma_f32_16x16x32_f16 v[128:131], v[20:23], v[32:35], v[68:71]
	v_mfma_f32_16x16x32_f16 v[68:71], v[28:31], v[24:27], v[72:75]
	v_mfma_f32_16x16x32_f16 v[120:123], v[200:203], v[32:35], v[68:71]
	v_mfma_f32_16x16x32_f16 v[68:71], v[16:19], v[64:67], v[76:79]
	v_mfma_f32_16x16x32_f16 v[112:115], v[20:23], v[220:223], v[68:71]
	v_mfma_f32_16x16x32_f16 v[68:71], v[28:31], v[64:67], v[80:83]
	v_mfma_f32_16x16x32_f16 v[104:107], v[200:203], v[220:223], v[68:71]
	v_mfma_f32_16x16x32_f16 v[68:71], v[16:19], v[224:227], v[84:87]
	v_mfma_f32_16x16x32_f16 v[96:99], v[20:23], v[232:235], v[68:71]
	v_mfma_f32_16x16x32_f16 v[68:71], v[28:31], v[224:227], v[88:91]
	v_mfma_f32_16x16x32_f16 v[88:91], v[200:203], v[232:235], v[68:71]
	v_mfma_f32_16x16x32_f16 v[68:71], v[16:19], v[236:239], v[92:95]
	v_mfma_f32_16x16x32_f16 v[80:83], v[20:23], v[240:243], v[68:71]
	v_mfma_f32_16x16x32_f16 v[68:71], v[28:31], v[236:239], v[100:103]
	v_mfma_f32_16x16x32_f16 v[72:75], v[200:203], v[240:243], v[68:71]
	v_mfma_f32_16x16x32_f16 v[68:71], v[204:207], v[24:27], v[116:119]
	v_mfma_f32_16x16x32_f16 v[24:27], v[212:215], v[24:27], v[36:39]
	v_mfma_f32_16x16x32_f16 v[116:119], v[216:219], v[32:35], v[24:27]
	v_mfma_f32_16x16x32_f16 v[24:27], v[204:207], v[64:67], v[40:43]
	v_mfma_f32_16x16x32_f16 v[108:111], v[208:211], v[220:223], v[24:27]
	v_mfma_f32_16x16x32_f16 v[24:27], v[212:215], v[64:67], v[44:47]
	v_mfma_f32_16x16x32_f16 v[100:103], v[216:219], v[220:223], v[24:27]
	v_mfma_f32_16x16x32_f16 v[24:27], v[204:207], v[224:227], v[48:51]
	v_mfma_f32_16x16x32_f16 v[92:95], v[208:211], v[232:235], v[24:27]
	v_mfma_f32_16x16x32_f16 v[24:27], v[212:215], v[224:227], v[52:55]
	v_mfma_f32_16x16x32_f16 v[84:87], v[216:219], v[232:235], v[24:27]
	v_mfma_f32_16x16x32_f16 v[24:27], v[204:207], v[236:239], v[56:59]
	v_mfma_f32_16x16x32_f16 v[76:79], v[208:211], v[240:243], v[24:27]
	v_mfma_f32_16x16x32_f16 v[24:27], v[212:215], v[236:239], v[60:63]
	s_setprio 2
	s_barrier
	v_mfma_f32_16x16x32_f16 v[124:127], v[208:211], v[32:35], v[68:71]
	v_mfma_f32_16x16x32_f16 v[68:71], v[216:219], v[240:243], v[24:27]
	s_setprio 0
	s_add_i32 s68, s68, s53
	s_nop 2
	v_lshl_add_u64 v[24:25], v[138:139], 0, s[24:25]
	s_mov_b32 m0, s68
	ds_read_b128 v[36:39], v231 offset:49152
	ds_read_b128 v[44:47], v231 offset:50176
	ds_read_b128 v[220:223], v231 offset:51200
	ds_read_b128 v[224:227], v231 offset:52224
	ds_read_b128 v[232:235], v231 offset:53248
	ds_read_b128 v[236:239], v231 offset:54272
	ds_read_b128 v[240:243], v231 offset:55296
	ds_read_b128 v[244:247], v231 offset:56320
	global_load_lds_dwordx4 v[24:25], off
	v_lshl_add_u64 v[24:25], v[192:193], 0, s[24:25]
	s_add_i32 m0, s68, 0x2000
	s_add_i32 s68, s69, s53
	global_load_lds_dwordx4 v[24:25], off
	s_mov_b32 m0, s68
	v_lshl_add_u64 v[24:25], v[248:249], 0, s[24:25]
	global_load_lds_dwordx4 v2, s[44:45]
	s_add_i32 m0, s68, 0x2000
	s_nop 0
	global_load_lds_dwordx4 v134, s[44:45]
	s_mov_b32 m0, s59
	s_nop 0
	global_load_lds_dwordx4 v[24:25], off
	v_lshl_add_u64 v[24:25], v[250:251], 0, s[24:25]
	s_mov_b32 m0, s60
	s_nop 0
	global_load_lds_dwordx4 v[24:25], off
	s_waitcnt vmcnt(8)
	s_waitcnt lgkmcnt(0)
	s_barrier
	s_setprio 1
	s_waitcnt lgkmcnt(0)
	v_mfma_f32_16x16x32_f16 v[24:27], v[16:19], v[36:39], v[144:147]
	v_mfma_f32_16x16x32_f16 v[64:67], v[20:23], v[44:47], v[24:27]
	v_mfma_f32_16x16x32_f16 v[24:27], v[28:31], v[36:39], v[148:151]
	v_mfma_f32_16x16x32_f16 v[56:59], v[200:203], v[44:47], v[24:27]
	v_mfma_f32_16x16x32_f16 v[24:27], v[16:19], v[220:223], v[152:155]
	v_mfma_f32_16x16x32_f16 v[48:51], v[20:23], v[224:227], v[24:27]
	v_mfma_f32_16x16x32_f16 v[24:27], v[28:31], v[220:223], v[156:159]
	v_mfma_f32_16x16x32_f16 v[40:43], v[200:203], v[224:227], v[24:27]
	v_mfma_f32_16x16x32_f16 v[24:27], v[16:19], v[232:235], v[160:163]
	v_mfma_f32_16x16x32_f16 v[4:7], v[16:19], v[240:243], v[4:7]
	v_mfma_f32_16x16x32_f16 v[32:35], v[20:23], v[236:239], v[24:27]
	v_mfma_f32_16x16x32_f16 v[24:27], v[28:31], v[232:235], v[164:167]
	v_mfma_f32_16x16x32_f16 v[16:19], v[20:23], v[244:247], v[4:7]
	v_mfma_f32_16x16x32_f16 v[4:7], v[28:31], v[240:243], v[8:11]
	v_mfma_f32_16x16x32_f16 v[24:27], v[200:203], v[236:239], v[24:27]
	v_mfma_f32_16x16x32_f16 v[8:11], v[200:203], v[244:247], v[4:7]
	v_mfma_f32_16x16x32_f16 v[4:7], v[204:207], v[36:39], v[12:15]
	v_mfma_f32_16x16x32_f16 v[60:63], v[208:211], v[44:47], v[4:7]
	v_mfma_f32_16x16x32_f16 v[4:7], v[212:215], v[36:39], v[172:175]
	v_mfma_f32_16x16x32_f16 v[52:55], v[216:219], v[44:47], v[4:7]
	v_mfma_f32_16x16x32_f16 v[4:7], v[204:207], v[220:223], v[176:179]
	v_mfma_f32_16x16x32_f16 v[44:47], v[208:211], v[224:227], v[4:7]
	v_mfma_f32_16x16x32_f16 v[4:7], v[212:215], v[220:223], v[180:183]
	v_mfma_f32_16x16x32_f16 v[36:39], v[216:219], v[224:227], v[4:7]
	v_mfma_f32_16x16x32_f16 v[4:7], v[204:207], v[232:235], v[168:171]
	v_mfma_f32_16x16x32_f16 v[28:31], v[208:211], v[236:239], v[4:7]
	v_mfma_f32_16x16x32_f16 v[4:7], v[212:215], v[232:235], v[184:187]
	v_mfma_f32_16x16x32_f16 v[20:23], v[216:219], v[236:239], v[4:7]
	v_mfma_f32_16x16x32_f16 v[4:7], v[204:207], v[240:243], v[188:191]
	v_mfma_f32_16x16x32_f16 v[12:15], v[208:211], v[244:247], v[4:7]
	s_setprio 2
	s_barrier
	v_mfma_f32_16x16x32_f16 v[4:7], v[212:215], v[240:243], v[196:199]
	v_mfma_f32_16x16x32_f16 v[4:7], v[216:219], v[244:247], v[4:7]
	s_setprio 0
	s_add_i32 s67, s67, 2
	s_cmp_ge_i32 s67, s11
	s_cbranch_scc0 .LBB0_2159

.LBB0_2161:
	s_add_u32 s68, s6, s40
	s_addc_u32 s69, s7, s41
	s_add_u32 s42, s68, 0x200
	s_addc_u32 s43, s69, 0
	s_add_u32 s44, s8, s40
	s_addc_u32 s45, s9, s41
	s_add_u32 s67, s44, 0x200
	s_addc_u32 s70, s45, 0
	s_add_i32 s71, 0, 0x10000
	s_cmp_eq_u32 s11, 28
	s_cselect_b32 s45, s29, s43
	s_cselect_b32 s44, s28, s42
	v_add_u32_e32 v133, s71, v143
	s_cselect_b32 s43, s37, s70
	s_cselect_b32 s42, s36, s67
	s_add_i32 s67, 0, 0x14000
	ds_read_b128 v[144:147], v133
	ds_read_b128 v[148:151], v133 offset:1024
	ds_read_b128 v[152:155], v133 offset:2048
	ds_read_b128 v[156:159], v133 offset:3072
	v_add_u32_e32 v133, s67, v143
	ds_read_b128 v[160:163], v133
	ds_read_b128 v[164:167], v133 offset:1024
	ds_read_b128 v[168:171], v133 offset:2048
	ds_read_b128 v[172:175], v133 offset:3072
	v_lshl_add_u64 v[136:137], s[68:69], 0, v[2:3]
	s_mov_b32 m0, s61
	v_add_u32_e32 v216, 0, v142
	v_lshl_add_u64 v[136:137], v[136:137], 0, s[34:35]
	v_mov_b32_e32 v133, v3
	ds_read_b128 v[176:179], v216
	ds_read_b128 v[180:183], v216 offset:1024
	ds_read_b128 v[184:187], v216 offset:2048
	ds_read_b128 v[188:191], v216 offset:3072
	ds_read_b128 v[196:199], v216 offset:4096
	ds_read_b128 v[200:203], v216 offset:5120
	ds_read_b128 v[204:207], v216 offset:6144
	ds_read_b128 v[208:211], v216 offset:7168
	global_load_lds_dwordx4 v[136:137], off
	v_lshl_add_u64 v[136:137], s[68:69], 0, v[132:133]
	v_lshl_add_u64 v[136:137], v[136:137], 0, s[34:35]
	s_mov_b32 m0, s62
	s_nop 0
	global_load_lds_dwordx4 v[136:137], off
	s_waitcnt vmcnt(8)
	s_waitcnt lgkmcnt(0)
	s_barrier
	s_setprio 1
	s_waitcnt lgkmcnt(0)
	v_mfma_f32_16x16x32_f16 v[128:131], v[144:147], v[176:179], v[128:131]
	v_mfma_f32_16x16x32_f16 v[128:131], v[148:151], v[180:183], v[128:131]
	v_mfma_f32_16x16x32_f16 v[120:123], v[156:159], v[180:183], v[120:123]
	v_mfma_f32_16x16x32_f16 v[120:123], v[152:155], v[176:179], v[120:123]
	v_mfma_f32_16x16x32_f16 v[104:107], v[152:155], v[184:187], v[104:107]
	v_mfma_f32_16x16x32_f16 v[104:107], v[156:159], v[188:191], v[104:107]
	v_mfma_f32_16x16x32_f16 v[112:115], v[148:151], v[188:191], v[112:115]
	v_mfma_f32_16x16x32_f16 v[112:115], v[144:147], v[184:187], v[112:115]
	v_mfma_f32_16x16x32_f16 v[96:99], v[144:147], v[196:199], v[96:99]
	v_mfma_f32_16x16x32_f16 v[96:99], v[148:151], v[200:203], v[96:99]
	v_mfma_f32_16x16x32_f16 v[88:91], v[156:159], v[200:203], v[88:91]
	v_mfma_f32_16x16x32_f16 v[88:91], v[152:155], v[196:199], v[88:91]
	v_mfma_f32_16x16x32_f16 v[72:75], v[152:155], v[204:207], v[72:75]
	v_mfma_f32_16x16x32_f16 v[72:75], v[156:159], v[208:211], v[72:75]
	v_mfma_f32_16x16x32_f16 v[80:83], v[148:151], v[208:211], v[80:83]
	v_mfma_f32_16x16x32_f16 v[80:83], v[144:147], v[204:207], v[80:83]
	v_mfma_f32_16x16x32_f16 v[124:127], v[160:163], v[176:179], v[124:127]
	v_mfma_f32_16x16x32_f16 v[124:127], v[164:167], v[180:183], v[124:127]
	v_mfma_f32_16x16x32_f16 v[116:119], v[172:175], v[180:183], v[116:119]
	v_mfma_f32_16x16x32_f16 v[116:119], v[168:171], v[176:179], v[116:119]
	v_mfma_f32_16x16x32_f16 v[100:103], v[168:171], v[184:187], v[100:103]
	v_mfma_f32_16x16x32_f16 v[100:103], v[172:175], v[188:191], v[100:103]
	v_mfma_f32_16x16x32_f16 v[108:111], v[164:167], v[188:191], v[108:111]
	v_mfma_f32_16x16x32_f16 v[108:111], v[160:163], v[184:187], v[108:111]
	v_mfma_f32_16x16x32_f16 v[92:95], v[160:163], v[196:199], v[92:95]
	v_mfma_f32_16x16x32_f16 v[92:95], v[164:167], v[200:203], v[92:95]
	v_mfma_f32_16x16x32_f16 v[84:87], v[172:175], v[200:203], v[84:87]
	v_mfma_f32_16x16x32_f16 v[84:87], v[168:171], v[196:199], v[84:87]
	v_mfma_f32_16x16x32_f16 v[68:71], v[168:171], v[204:207], v[68:71]
	v_mfma_f32_16x16x32_f16 v[68:71], v[172:175], v[208:211], v[68:71]
	s_setprio 2
	s_barrier
	v_mfma_f32_16x16x32_f16 v[76:79], v[164:167], v[208:211], v[76:79]
	v_mfma_f32_16x16x32_f16 v[76:79], v[160:163], v[204:207], v[76:79]
	s_setprio 0
	s_add_i32 s68, s71, s53
	s_mov_b32 m0, s68
	ds_read_b128 v[176:179], v216 offset:16384
	ds_read_b128 v[180:183], v216 offset:17408
	ds_read_b128 v[184:187], v216 offset:18432
	ds_read_b128 v[188:191], v216 offset:19456
	ds_read_b128 v[196:199], v216 offset:20480
	ds_read_b128 v[200:203], v216 offset:21504
	ds_read_b128 v[204:207], v216 offset:22528
	ds_read_b128 v[208:211], v216 offset:23552
	global_load_lds_dwordx4 v138, s[42:43]
	s_add_i32 m0, s68, 0x2000
	s_add_u32 s68, s42, 0x80000
	s_addc_u32 s69, s43, 0
	s_add_i32 s67, s67, s53
	global_load_lds_dwordx4 v134, s[42:43]
	s_mov_b32 m0, s67
	v_mov_b32_e32 v139, v3
	global_load_lds_dwordx4 v138, s[68:69]
	s_add_i32 m0, s67, 0x2000
	v_mov_b32_e32 v135, v3
	global_load_lds_dwordx4 v134, s[68:69]
	s_mov_b32 m0, s54
	v_lshl_add_u64 v[136:137], s[42:43], 0, v[138:139]
	global_load_lds_dwordx4 v2, s[44:45]
	s_mov_b32 m0, s55
	v_lshl_add_u64 v[192:193], s[42:43], 0, v[134:135]
	global_load_lds_dwordx4 v132, s[44:45]
	s_waitcnt vmcnt(8)
	s_waitcnt lgkmcnt(0)
	v_lshl_add_u64 v[212:213], s[44:45], 0, v[2:3]
	v_lshl_add_u64 v[214:215], s[44:45], 0, v[132:133]
	s_barrier
	s_setprio 1
	s_waitcnt lgkmcnt(0)
	v_mfma_f32_16x16x32_f16 v[64:67], v[144:147], v[176:179], v[64:67]
	v_mfma_f32_16x16x32_f16 v[64:67], v[148:151], v[180:183], v[64:67]
	v_mfma_f32_16x16x32_f16 v[56:59], v[156:159], v[180:183], v[56:59]
	v_mfma_f32_16x16x32_f16 v[56:59], v[152:155], v[176:179], v[56:59]
	v_mfma_f32_16x16x32_f16 v[40:43], v[152:155], v[184:187], v[40:43]
	v_mfma_f32_16x16x32_f16 v[40:43], v[156:159], v[188:191], v[40:43]
	v_mfma_f32_16x16x32_f16 v[48:51], v[148:151], v[188:191], v[48:51]
	v_mfma_f32_16x16x32_f16 v[48:51], v[144:147], v[184:187], v[48:51]
	v_mfma_f32_16x16x32_f16 v[32:35], v[144:147], v[196:199], v[32:35]
	v_mfma_f32_16x16x32_f16 v[32:35], v[148:151], v[200:203], v[32:35]
	v_mfma_f32_16x16x32_f16 v[24:27], v[156:159], v[200:203], v[24:27]
	v_mfma_f32_16x16x32_f16 v[24:27], v[152:155], v[196:199], v[24:27]
	v_mfma_f32_16x16x32_f16 v[8:11], v[152:155], v[204:207], v[8:11]
	v_mfma_f32_16x16x32_f16 v[8:11], v[156:159], v[208:211], v[8:11]
	v_mfma_f32_16x16x32_f16 v[16:19], v[148:151], v[208:211], v[16:19]
	v_mfma_f32_16x16x32_f16 v[16:19], v[144:147], v[204:207], v[16:19]
	v_mfma_f32_16x16x32_f16 v[60:63], v[160:163], v[176:179], v[60:63]
	v_mfma_f32_16x16x32_f16 v[60:63], v[164:167], v[180:183], v[60:63]
	v_mfma_f32_16x16x32_f16 v[52:55], v[172:175], v[180:183], v[52:55]
	v_mfma_f32_16x16x32_f16 v[52:55], v[168:171], v[176:179], v[52:55]
	v_mfma_f32_16x16x32_f16 v[36:39], v[168:171], v[184:187], v[36:39]
	v_mfma_f32_16x16x32_f16 v[36:39], v[172:175], v[188:191], v[36:39]
	v_mfma_f32_16x16x32_f16 v[44:47], v[164:167], v[188:191], v[44:47]
	v_mfma_f32_16x16x32_f16 v[44:47], v[160:163], v[184:187], v[44:47]
	v_mfma_f32_16x16x32_f16 v[28:31], v[160:163], v[196:199], v[28:31]
	v_mfma_f32_16x16x32_f16 v[28:31], v[164:167], v[200:203], v[28:31]
	v_mfma_f32_16x16x32_f16 v[20:23], v[172:175], v[200:203], v[20:23]
	v_mfma_f32_16x16x32_f16 v[20:23], v[168:171], v[196:199], v[20:23]
	v_mfma_f32_16x16x32_f16 v[4:7], v[168:171], v[204:207], v[4:7]
	v_mfma_f32_16x16x32_f16 v[4:7], v[172:175], v[208:211], v[4:7]
	s_setprio 2
	s_barrier
	v_mfma_f32_16x16x32_f16 v[12:15], v[164:167], v[208:211], v[12:15]
	v_mfma_f32_16x16x32_f16 v[12:15], v[160:163], v[204:207], v[12:15]
	s_setprio 0
	s_add_i32 s67, 0, 0x18000
	v_add_u32_e32 v135, s67, v143
	s_add_i32 s68, 0, 0x1c000
	ds_read_b128 v[144:147], v135
	ds_read_b128 v[148:151], v135 offset:1024
	ds_read_b128 v[152:155], v135 offset:2048
	ds_read_b128 v[156:159], v135 offset:3072
	v_add_u32_e32 v135, s68, v143
	ds_read_b128 v[160:163], v135
	ds_read_b128 v[164:167], v135 offset:1024
	ds_read_b128 v[168:171], v135 offset:2048
	ds_read_b128 v[172:175], v135 offset:3072
	s_add_u32 s44, s44, 0x80000
	s_addc_u32 s45, s45, 0
	s_mov_b32 m0, s56
	ds_read_b128 v[176:179], v216 offset:32768
	ds_read_b128 v[180:183], v216 offset:33792
	ds_read_b128 v[184:187], v216 offset:34816
	ds_read_b128 v[188:191], v216 offset:35840
	ds_read_b128 v[196:199], v216 offset:36864
	ds_read_b128 v[200:203], v216 offset:37888
	ds_read_b128 v[204:207], v216 offset:38912
	ds_read_b128 v[208:211], v216 offset:39936
	global_load_lds_dwordx4 v2, s[44:45]
	s_mov_b32 m0, s57
	s_nop 0
	global_load_lds_dwordx4 v132, s[44:45]
	s_waitcnt vmcnt(8)
	s_waitcnt lgkmcnt(0)
	s_barrier
	s_setprio 1
	s_waitcnt lgkmcnt(0)
	v_mfma_f32_16x16x32_f16 v[128:131], v[144:147], v[176:179], v[128:131]
	v_mfma_f32_16x16x32_f16 v[128:131], v[148:151], v[180:183], v[128:131]
	v_mfma_f32_16x16x32_f16 v[120:123], v[156:159], v[180:183], v[120:123]
	v_mfma_f32_16x16x32_f16 v[120:123], v[152:155], v[176:179], v[120:123]
	v_mfma_f32_16x16x32_f16 v[104:107], v[152:155], v[184:187], v[104:107]
	v_mfma_f32_16x16x32_f16 v[104:107], v[156:159], v[188:191], v[104:107]
	v_mfma_f32_16x16x32_f16 v[112:115], v[148:151], v[188:191], v[112:115]
	v_mfma_f32_16x16x32_f16 v[112:115], v[144:147], v[184:187], v[112:115]
	v_mfma_f32_16x16x32_f16 v[96:99], v[144:147], v[196:199], v[96:99]
	v_mfma_f32_16x16x32_f16 v[96:99], v[148:151], v[200:203], v[96:99]
	v_mfma_f32_16x16x32_f16 v[88:91], v[156:159], v[200:203], v[88:91]
	v_mfma_f32_16x16x32_f16 v[88:91], v[152:155], v[196:199], v[88:91]
	v_mfma_f32_16x16x32_f16 v[72:75], v[152:155], v[204:207], v[72:75]
	v_mfma_f32_16x16x32_f16 v[72:75], v[156:159], v[208:211], v[72:75]
	v_mfma_f32_16x16x32_f16 v[80:83], v[148:151], v[208:211], v[80:83]
	v_mfma_f32_16x16x32_f16 v[80:83], v[144:147], v[204:207], v[80:83]
	v_mfma_f32_16x16x32_f16 v[124:127], v[160:163], v[176:179], v[124:127]
	v_mfma_f32_16x16x32_f16 v[124:127], v[164:167], v[180:183], v[124:127]
	v_mfma_f32_16x16x32_f16 v[116:119], v[172:175], v[180:183], v[116:119]
	v_mfma_f32_16x16x32_f16 v[116:119], v[168:171], v[176:179], v[116:119]
	v_mfma_f32_16x16x32_f16 v[100:103], v[168:171], v[184:187], v[100:103]
	v_mfma_f32_16x16x32_f16 v[100:103], v[172:175], v[188:191], v[100:103]
	v_mfma_f32_16x16x32_f16 v[108:111], v[164:167], v[188:191], v[108:111]
	v_mfma_f32_16x16x32_f16 v[108:111], v[160:163], v[184:187], v[108:111]
	v_mfma_f32_16x16x32_f16 v[92:95], v[160:163], v[196:199], v[92:95]
	v_mfma_f32_16x16x32_f16 v[92:95], v[164:167], v[200:203], v[92:95]
	v_mfma_f32_16x16x32_f16 v[84:87], v[172:175], v[200:203], v[84:87]
	v_mfma_f32_16x16x32_f16 v[84:87], v[168:171], v[196:199], v[84:87]
	v_mfma_f32_16x16x32_f16 v[68:71], v[168:171], v[204:207], v[68:71]
	v_mfma_f32_16x16x32_f16 v[68:71], v[172:175], v[208:211], v[68:71]
	s_setprio 2
	s_barrier
	v_mfma_f32_16x16x32_f16 v[76:79], v[164:167], v[208:211], v[76:79]
	v_mfma_f32_16x16x32_f16 v[76:79], v[160:163], v[204:207], v[76:79]
	s_setprio 0
	s_add_i32 s44, s67, s53
	v_lshl_add_u64 v[136:137], v[136:137], 0, s[86:87]
	s_mov_b32 m0, s44
	ds_read_b128 v[176:179], v216 offset:49152
	ds_read_b128 v[180:183], v216 offset:50176
	ds_read_b128 v[184:187], v216 offset:51200
	ds_read_b128 v[188:191], v216 offset:52224
	ds_read_b128 v[196:199], v216 offset:53248
	ds_read_b128 v[200:203], v216 offset:54272
	ds_read_b128 v[204:207], v216 offset:55296
	ds_read_b128 v[208:211], v216 offset:56320
	global_load_lds_dwordx4 v[136:137], off
	s_add_i32 m0, s44, 0x2000
	s_add_u32 s42, s42, 0x80080
	v_lshl_add_u64 v[136:137], v[192:193], 0, s[86:87]
	s_addc_u32 s43, s43, 0
	s_add_i32 s44, s68, s53
	global_load_lds_dwordx4 v[136:137], off
	s_mov_b32 m0, s44
	v_lshl_add_u64 v[136:137], v[212:213], 0, s[86:87]
	global_load_lds_dwordx4 v138, s[42:43]
	s_add_i32 m0, s44, 0x2000
	s_nop 0
	global_load_lds_dwordx4 v134, s[42:43]
	s_mov_b32 m0, s59
	s_nop 0
	global_load_lds_dwordx4 v[136:137], off
	v_lshl_add_u64 v[136:137], v[214:215], 0, s[86:87]
	s_mov_b32 m0, s60
	s_nop 0
	global_load_lds_dwordx4 v[136:137], off
	s_waitcnt vmcnt(8)
	s_waitcnt lgkmcnt(0)
	s_barrier
	s_setprio 1
	s_waitcnt lgkmcnt(0)
	v_mfma_f32_16x16x32_f16 v[64:67], v[144:147], v[176:179], v[64:67]
	v_mfma_f32_16x16x32_f16 v[64:67], v[148:151], v[180:183], v[64:67]
	v_mfma_f32_16x16x32_f16 v[56:59], v[156:159], v[180:183], v[56:59]
	v_mfma_f32_16x16x32_f16 v[56:59], v[152:155], v[176:179], v[56:59]
	v_mfma_f32_16x16x32_f16 v[40:43], v[152:155], v[184:187], v[40:43]
	v_mfma_f32_16x16x32_f16 v[40:43], v[156:159], v[188:191], v[40:43]
	v_mfma_f32_16x16x32_f16 v[48:51], v[148:151], v[188:191], v[48:51]
	v_mfma_f32_16x16x32_f16 v[48:51], v[144:147], v[184:187], v[48:51]
	v_mfma_f32_16x16x32_f16 v[32:35], v[144:147], v[196:199], v[32:35]
	v_mfma_f32_16x16x32_f16 v[32:35], v[148:151], v[200:203], v[32:35]
	v_mfma_f32_16x16x32_f16 v[24:27], v[156:159], v[200:203], v[24:27]
	v_mfma_f32_16x16x32_f16 v[24:27], v[152:155], v[196:199], v[24:27]
	v_mfma_f32_16x16x32_f16 v[8:11], v[152:155], v[204:207], v[8:11]
	v_mfma_f32_16x16x32_f16 v[8:11], v[156:159], v[208:211], v[8:11]
	v_mfma_f32_16x16x32_f16 v[16:19], v[148:151], v[208:211], v[16:19]
	v_mfma_f32_16x16x32_f16 v[16:19], v[144:147], v[204:207], v[16:19]
	v_mfma_f32_16x16x32_f16 v[60:63], v[160:163], v[176:179], v[60:63]
	v_mfma_f32_16x16x32_f16 v[60:63], v[164:167], v[180:183], v[60:63]
	v_mfma_f32_16x16x32_f16 v[52:55], v[172:175], v[180:183], v[52:55]
	v_mfma_f32_16x16x32_f16 v[52:55], v[168:171], v[176:179], v[52:55]
	v_mfma_f32_16x16x32_f16 v[36:39], v[168:171], v[184:187], v[36:39]
	v_mfma_f32_16x16x32_f16 v[36:39], v[172:175], v[188:191], v[36:39]
	v_mfma_f32_16x16x32_f16 v[44:47], v[164:167], v[188:191], v[44:47]
	v_mfma_f32_16x16x32_f16 v[44:47], v[160:163], v[184:187], v[44:47]
	v_mfma_f32_16x16x32_f16 v[28:31], v[160:163], v[196:199], v[28:31]
	v_mfma_f32_16x16x32_f16 v[28:31], v[164:167], v[200:203], v[28:31]
	v_mfma_f32_16x16x32_f16 v[20:23], v[172:175], v[200:203], v[20:23]
	v_mfma_f32_16x16x32_f16 v[20:23], v[168:171], v[196:199], v[20:23]
	v_mfma_f32_16x16x32_f16 v[4:7], v[168:171], v[204:207], v[4:7]
	v_mfma_f32_16x16x32_f16 v[4:7], v[172:175], v[208:211], v[4:7]
	s_setprio 2
	s_barrier
	v_mfma_f32_16x16x32_f16 v[12:15], v[164:167], v[208:211], v[12:15]
	v_mfma_f32_16x16x32_f16 v[12:15], v[160:163], v[204:207], v[12:15]
	s_setprio 0
	s_add_i32 s11, s11, 2
	s_add_u32 s40, s40, 0x100
	s_addc_u32 s41, s41, 0
	s_cmp_gt_u32 s11, 29
	s_cbranch_scc0 .LBB0_2161
	s_andn2_b64 vcc, exec, s[26:27]
	s_cbranch_vccnz .LBB0_2164
	s_add_u32 s6, s28, 0x80080
	s_addc_u32 s7, s29, 0
	s_mov_b32 m0, s61
	v_lshl_add_u64 v[144:145], s[6:7], 0, v[2:3]
	v_lshl_add_u64 v[136:137], s[6:7], 0, v[132:133]
	global_load_lds_dwordx4 v[144:145], off
	s_mov_b32 m0, s62
	s_mov_b32 s47, s65
	global_load_lds_dwordx4 v[136:137], off
	s_mov_b32 s64, s10
	s_mov_b64 s[8:9], s[14:15]
	s_mov_b64 s[6:7], s[12:13]
	s_mov_b32 s63, s66

.LBB0_2269:
	s_add_i32 s51, 0, 0x10000
	s_add_i32 s71, 0, 0x14000
	v_add_u32_e32 v16, s51, v232
	v_add_u32_e32 v32, s71, v232
	ds_read_b128 v[4:7], v16
	ds_read_b128 v[8:11], v16 offset:1024
	ds_read_b128 v[12:15], v16 offset:2048
	ds_read_b128 v[16:19], v16 offset:3072
	ds_read_b128 v[20:23], v32
	ds_read_b128 v[24:27], v32 offset:1024
	ds_read_b128 v[28:31], v32 offset:2048
	ds_read_b128 v[32:35], v32 offset:3072
	v_add_u32_e32 v233, 0, v231
	ds_read_b128 v[36:39], v233
	ds_read_b128 v[40:43], v233 offset:1024
	ds_read_b128 v[44:47], v233 offset:2048
	ds_read_b128 v[48:51], v233 offset:3072
	ds_read_b128 v[52:55], v233 offset:4096
	ds_read_b128 v[56:59], v233 offset:5120
	ds_read_b128 v[60:63], v233 offset:6144
	ds_read_b128 v[64:67], v233 offset:7168
	s_waitcnt vmcnt(8)
	s_waitcnt lgkmcnt(0)
	s_barrier
	s_setprio 1
	s_waitcnt lgkmcnt(0)
	v_mfma_f32_16x16x32_bf16 v[68:71], v[4:7], v[36:39], 0
	v_mfma_f32_16x16x32_bf16 v[68:71], v[8:11], v[40:43], v[68:71]
	v_mfma_f32_16x16x32_bf16 v[72:75], v[12:15], v[36:39], 0
	v_mfma_f32_16x16x32_bf16 v[72:75], v[16:19], v[40:43], v[72:75]
	v_mfma_f32_16x16x32_bf16 v[80:83], v[12:15], v[44:47], 0
	v_mfma_f32_16x16x32_bf16 v[80:83], v[16:19], v[48:51], v[80:83]
	v_mfma_f32_16x16x32_bf16 v[76:79], v[4:7], v[44:47], 0
	v_mfma_f32_16x16x32_bf16 v[76:79], v[8:11], v[48:51], v[76:79]
	v_mfma_f32_16x16x32_bf16 v[84:87], v[4:7], v[52:55], 0
	v_mfma_f32_16x16x32_bf16 v[84:87], v[8:11], v[56:59], v[84:87]
	v_mfma_f32_16x16x32_bf16 v[88:91], v[12:15], v[52:55], 0
	v_mfma_f32_16x16x32_bf16 v[88:91], v[16:19], v[56:59], v[88:91]
	v_mfma_f32_16x16x32_bf16 v[96:99], v[12:15], v[60:63], 0
	v_mfma_f32_16x16x32_bf16 v[96:99], v[16:19], v[64:67], v[96:99]
	v_mfma_f32_16x16x32_bf16 v[92:95], v[4:7], v[60:63], 0
	v_mfma_f32_16x16x32_bf16 v[92:95], v[8:11], v[64:67], v[92:95]
	v_mfma_f32_16x16x32_bf16 v[100:103], v[20:23], v[36:39], 0
	v_mfma_f32_16x16x32_bf16 v[36:39], v[28:31], v[36:39], 0
	v_mfma_f32_16x16x32_bf16 v[104:107], v[20:23], v[44:47], 0
	v_mfma_f32_16x16x32_bf16 v[44:47], v[28:31], v[44:47], 0
	v_mfma_f32_16x16x32_bf16 v[108:111], v[20:23], v[52:55], 0
	v_mfma_f32_16x16x32_bf16 v[52:55], v[28:31], v[52:55], 0
	v_mfma_f32_16x16x32_bf16 v[112:115], v[20:23], v[60:63], 0
	v_mfma_f32_16x16x32_bf16 v[60:63], v[28:31], v[60:63], 0
	v_mfma_f32_16x16x32_bf16 v[100:103], v[24:27], v[40:43], v[100:103]
	v_mfma_f32_16x16x32_bf16 v[40:43], v[32:35], v[40:43], v[36:39]
	v_mfma_f32_16x16x32_bf16 v[104:107], v[24:27], v[48:51], v[104:107]
	v_mfma_f32_16x16x32_bf16 v[48:51], v[32:35], v[48:51], v[44:47]
	v_mfma_f32_16x16x32_bf16 v[108:111], v[24:27], v[56:59], v[108:111]
	v_mfma_f32_16x16x32_bf16 v[56:59], v[32:35], v[56:59], v[52:55]
	s_setprio 2
	s_barrier
	v_mfma_f32_16x16x32_bf16 v[112:115], v[24:27], v[64:67], v[112:115]
	v_mfma_f32_16x16x32_bf16 v[64:67], v[32:35], v[64:67], v[60:63]
	s_setprio 0
	v_lshl_add_u64 v[186:187], s[12:13], 0, v[2:3]
	s_add_i32 s51, s51, s38
	v_mov_b32_e32 v191, v3
	v_lshl_add_u64 v[134:135], v[186:187], 0, s[74:75]
	s_mov_b32 m0, s51
	v_lshl_add_u64 v[246:247], s[12:13], 0, v[190:191]
	ds_read_b128 v[36:39], v233 offset:16384
	ds_read_b128 v[44:47], v233 offset:17408
	ds_read_b128 v[52:55], v233 offset:18432
	ds_read_b128 v[60:63], v233 offset:19456
	ds_read_b128 v[116:119], v233 offset:20480
	ds_read_b128 v[120:123], v233 offset:21504
	ds_read_b128 v[124:127], v233 offset:22528
	ds_read_b128 v[128:131], v233 offset:23552
	global_load_lds_dwordx4 v[134:135], off
	v_lshl_add_u64 v[134:135], v[246:247], 0, s[74:75]
	s_add_i32 m0, s51, 0x2000
	s_add_i32 s51, s71, s38
	global_load_lds_dwordx4 v[134:135], off
	s_mov_b32 m0, s51
	v_mov_b32_e32 v133, v3
	global_load_lds_dwordx4 v2, s[16:17]
	s_add_i32 m0, s51, 0x2000
	v_lshl_add_u64 v[248:249], s[14:15], 0, v[132:133]
	v_mov_b32_e32 v189, v3
	global_load_lds_dwordx4 v190, s[16:17]
	v_lshl_add_u64 v[134:135], v[248:249], 0, s[74:75]
	s_mov_b32 m0, s56
	v_lshl_add_u64 v[250:251], s[14:15], 0, v[188:189]
	global_load_lds_dwordx4 v[134:135], off
	v_lshl_add_u64 v[134:135], v[250:251], 0, s[74:75]
	s_mov_b32 m0, s57
	s_nop 0
	global_load_lds_dwordx4 v[134:135], off
	s_waitcnt vmcnt(8)
	s_waitcnt lgkmcnt(0)
	s_barrier
	s_setprio 1
	s_waitcnt lgkmcnt(0)
	v_mfma_f32_16x16x32_bf16 v[134:137], v[4:7], v[36:39], 0
	v_mfma_f32_16x16x32_bf16 v[138:141], v[12:15], v[36:39], 0
	v_mfma_f32_16x16x32_bf16 v[142:145], v[4:7], v[52:55], 0
	v_mfma_f32_16x16x32_bf16 v[146:149], v[12:15], v[52:55], 0
	v_mfma_f32_16x16x32_bf16 v[150:153], v[4:7], v[116:119], 0
	v_mfma_f32_16x16x32_bf16 v[154:157], v[12:15], v[116:119], 0
	v_mfma_f32_16x16x32_bf16 v[4:7], v[4:7], v[124:127], 0
	v_mfma_f32_16x16x32_bf16 v[12:15], v[12:15], v[124:127], 0
	v_mfma_f32_16x16x32_bf16 v[134:137], v[8:11], v[44:47], v[134:137]
	v_mfma_f32_16x16x32_bf16 v[138:141], v[16:19], v[44:47], v[138:141]
	v_mfma_f32_16x16x32_bf16 v[142:145], v[8:11], v[60:63], v[142:145]
	v_mfma_f32_16x16x32_bf16 v[146:149], v[16:19], v[60:63], v[146:149]
	v_mfma_f32_16x16x32_bf16 v[150:153], v[8:11], v[120:123], v[150:153]
	v_mfma_f32_16x16x32_bf16 v[154:157], v[16:19], v[120:123], v[154:157]
	v_mfma_f32_16x16x32_bf16 v[158:161], v[8:11], v[128:131], v[4:7]
	v_mfma_f32_16x16x32_bf16 v[162:165], v[16:19], v[128:131], v[12:15]
	v_mfma_f32_16x16x32_bf16 v[4:7], v[20:23], v[36:39], 0
	v_mfma_f32_16x16x32_bf16 v[8:11], v[28:31], v[36:39], 0
	v_mfma_f32_16x16x32_bf16 v[12:15], v[20:23], v[52:55], 0
	v_mfma_f32_16x16x32_bf16 v[16:19], v[28:31], v[52:55], 0
	v_mfma_f32_16x16x32_bf16 v[36:39], v[20:23], v[116:119], 0
	v_mfma_f32_16x16x32_bf16 v[52:55], v[28:31], v[116:119], 0
	v_mfma_f32_16x16x32_bf16 v[20:23], v[20:23], v[124:127], 0
	v_mfma_f32_16x16x32_bf16 v[28:31], v[28:31], v[124:127], 0
	v_mfma_f32_16x16x32_bf16 v[116:119], v[24:27], v[44:47], v[4:7]
	v_mfma_f32_16x16x32_bf16 v[124:127], v[32:35], v[44:47], v[8:11]
	v_mfma_f32_16x16x32_bf16 v[174:177], v[24:27], v[120:123], v[36:39]
	v_mfma_f32_16x16x32_bf16 v[120:123], v[32:35], v[120:123], v[52:55]
	v_mfma_f32_16x16x32_bf16 v[178:181], v[24:27], v[128:131], v[20:23]
	v_mfma_f32_16x16x32_bf16 v[128:131], v[32:35], v[128:131], v[28:31]
	s_setprio 2
	s_barrier
	v_mfma_f32_16x16x32_bf16 v[166:169], v[24:27], v[60:63], v[12:15]
	v_mfma_f32_16x16x32_bf16 v[170:173], v[32:35], v[60:63], v[16:19]
	s_setprio 0
	s_add_i32 s51, 0, 0x18000
	v_add_u32_e32 v4, s51, v232
	s_add_i32 s71, 0, 0x1c000
	ds_read_b128 v[182:185], v4
	ds_read_b128 v[192:195], v4 offset:1024
	ds_read_b128 v[196:199], v4 offset:2048
	ds_read_b128 v[200:203], v4 offset:3072
	v_add_u32_e32 v4, s71, v232
	ds_read_b128 v[204:207], v4
	ds_read_b128 v[208:211], v4 offset:1024
	ds_read_b128 v[212:215], v4 offset:2048
	ds_read_b128 v[216:219], v4 offset:3072
	s_mov_b32 m0, s58
	ds_read_b128 v[44:47], v233 offset:32768
	ds_read_b128 v[52:55], v233 offset:33792
	ds_read_b128 v[60:63], v233 offset:34816
	ds_read_b128 v[220:223], v233 offset:35840
	ds_read_b128 v[224:227], v233 offset:36864
	ds_read_b128 v[234:237], v233 offset:37888
	ds_read_b128 v[238:241], v233 offset:38912
	ds_read_b128 v[242:245], v233 offset:39936
	global_load_lds_dwordx4 v132, s[26:27]
	s_mov_b32 m0, s59
	s_nop 0
	global_load_lds_dwordx4 v188, s[26:27]
	s_waitcnt vmcnt(8)
	s_waitcnt lgkmcnt(0)
	s_barrier
	s_setprio 1
	s_waitcnt lgkmcnt(0)
	v_mfma_f32_16x16x32_bf16 v[4:7], v[182:185], v[44:47], v[68:71]
	v_mfma_f32_16x16x32_bf16 v[8:11], v[196:199], v[44:47], v[72:75]
	v_mfma_f32_16x16x32_bf16 v[12:15], v[182:185], v[60:63], v[76:79]
	v_mfma_f32_16x16x32_bf16 v[16:19], v[196:199], v[60:63], v[80:83]
	v_mfma_f32_16x16x32_bf16 v[20:23], v[182:185], v[224:227], v[84:87]
	v_mfma_f32_16x16x32_bf16 v[24:27], v[196:199], v[224:227], v[88:91]
	v_mfma_f32_16x16x32_bf16 v[28:31], v[182:185], v[238:241], v[92:95]
	v_mfma_f32_16x16x32_bf16 v[32:35], v[196:199], v[238:241], v[96:99]
	v_mfma_f32_16x16x32_bf16 v[4:7], v[192:195], v[52:55], v[4:7]
	v_mfma_f32_16x16x32_bf16 v[8:11], v[200:203], v[52:55], v[8:11]
	v_mfma_f32_16x16x32_bf16 v[12:15], v[192:195], v[220:223], v[12:15]
	v_mfma_f32_16x16x32_bf16 v[16:19], v[200:203], v[220:223], v[16:19]
	v_mfma_f32_16x16x32_bf16 v[20:23], v[192:195], v[234:237], v[20:23]
	v_mfma_f32_16x16x32_bf16 v[24:27], v[200:203], v[234:237], v[24:27]
	v_mfma_f32_16x16x32_bf16 v[28:31], v[192:195], v[242:245], v[28:31]
	v_mfma_f32_16x16x32_bf16 v[32:35], v[200:203], v[242:245], v[32:35]
	v_mfma_f32_16x16x32_bf16 v[36:39], v[204:207], v[44:47], v[100:103]
	v_mfma_f32_16x16x32_bf16 v[40:43], v[212:215], v[44:47], v[40:43]
	v_mfma_f32_16x16x32_bf16 v[36:39], v[208:211], v[52:55], v[36:39]
	v_mfma_f32_16x16x32_bf16 v[40:43], v[216:219], v[52:55], v[40:43]
	v_mfma_f32_16x16x32_bf16 v[44:47], v[204:207], v[60:63], v[104:107]
	v_mfma_f32_16x16x32_bf16 v[48:51], v[212:215], v[60:63], v[48:51]
	v_mfma_f32_16x16x32_bf16 v[52:55], v[204:207], v[224:227], v[108:111]
	v_mfma_f32_16x16x32_bf16 v[56:59], v[212:215], v[224:227], v[56:59]
	v_mfma_f32_16x16x32_bf16 v[60:63], v[204:207], v[238:241], v[112:115]
	v_mfma_f32_16x16x32_bf16 v[64:67], v[212:215], v[238:241], v[64:67]
	v_mfma_f32_16x16x32_bf16 v[44:47], v[208:211], v[220:223], v[44:47]
	v_mfma_f32_16x16x32_bf16 v[48:51], v[216:219], v[220:223], v[48:51]
	v_mfma_f32_16x16x32_bf16 v[52:55], v[208:211], v[234:237], v[52:55]
	v_mfma_f32_16x16x32_bf16 v[56:59], v[216:219], v[234:237], v[56:59]
	s_setprio 2
	s_barrier
	v_mfma_f32_16x16x32_bf16 v[60:63], v[208:211], v[242:245], v[60:63]
	v_mfma_f32_16x16x32_bf16 v[64:67], v[216:219], v[242:245], v[64:67]
	s_setprio 0
	s_add_i32 s51, s51, s38
	v_lshl_add_u64 v[68:69], v[186:187], 0, s[24:25]
	s_mov_b32 m0, s51
	ds_read_b128 v[104:107], v233 offset:49152
	ds_read_b128 v[108:111], v233 offset:50176
	ds_read_b128 v[112:115], v233 offset:51200
	ds_read_b128 v[220:223], v233 offset:52224
	ds_read_b128 v[224:227], v233 offset:53248
	ds_read_b128 v[234:237], v233 offset:54272
	ds_read_b128 v[238:241], v233 offset:55296
	ds_read_b128 v[242:245], v233 offset:56320
	global_load_lds_dwordx4 v[68:69], off
	v_lshl_add_u64 v[68:69], v[246:247], 0, s[24:25]
	s_add_i32 m0, s51, 0x2000
	s_add_i32 s51, s71, s38
	global_load_lds_dwordx4 v[68:69], off
	s_mov_b32 m0, s51
	v_lshl_add_u64 v[68:69], v[248:249], 0, s[24:25]
	global_load_lds_dwordx4 v2, s[28:29]
	s_add_i32 m0, s51, 0x2000
	s_nop 0
	global_load_lds_dwordx4 v190, s[28:29]
	s_mov_b32 m0, s63
	s_nop 0
	global_load_lds_dwordx4 v[68:69], off
	v_lshl_add_u64 v[68:69], v[250:251], 0, s[24:25]
	s_mov_b32 m0, s64
	s_nop 0
	global_load_lds_dwordx4 v[68:69], off
	s_waitcnt vmcnt(8)
	s_waitcnt lgkmcnt(0)
	s_barrier
	s_setprio 1
	s_waitcnt lgkmcnt(0)
	v_mfma_f32_16x16x32_bf16 v[68:71], v[182:185], v[104:107], v[134:137]
	v_mfma_f32_16x16x32_bf16 v[72:75], v[196:199], v[104:107], v[138:141]
	v_mfma_f32_16x16x32_bf16 v[76:79], v[182:185], v[112:115], v[142:145]
	v_mfma_f32_16x16x32_bf16 v[80:83], v[196:199], v[112:115], v[146:149]
	v_mfma_f32_16x16x32_bf16 v[84:87], v[182:185], v[224:227], v[150:153]
	v_mfma_f32_16x16x32_bf16 v[88:91], v[196:199], v[224:227], v[154:157]
	v_mfma_f32_16x16x32_bf16 v[92:95], v[182:185], v[238:241], v[158:161]
	v_mfma_f32_16x16x32_bf16 v[96:99], v[196:199], v[238:241], v[162:165]
	v_mfma_f32_16x16x32_bf16 v[68:71], v[192:195], v[108:111], v[68:71]
	v_mfma_f32_16x16x32_bf16 v[72:75], v[200:203], v[108:111], v[72:75]
	v_mfma_f32_16x16x32_bf16 v[76:79], v[192:195], v[220:223], v[76:79]
	v_mfma_f32_16x16x32_bf16 v[80:83], v[200:203], v[220:223], v[80:83]
	v_mfma_f32_16x16x32_bf16 v[84:87], v[192:195], v[234:237], v[84:87]
	v_mfma_f32_16x16x32_bf16 v[88:91], v[200:203], v[234:237], v[88:91]
	v_mfma_f32_16x16x32_bf16 v[92:95], v[192:195], v[242:245], v[92:95]
	v_mfma_f32_16x16x32_bf16 v[96:99], v[200:203], v[242:245], v[96:99]
	v_mfma_f32_16x16x32_bf16 v[100:103], v[204:207], v[104:107], v[116:119]
	v_mfma_f32_16x16x32_bf16 v[104:107], v[212:215], v[104:107], v[124:127]
	v_mfma_f32_16x16x32_bf16 v[100:103], v[208:211], v[108:111], v[100:103]
	v_mfma_f32_16x16x32_bf16 v[104:107], v[216:219], v[108:111], v[104:107]
	v_mfma_f32_16x16x32_bf16 v[108:111], v[204:207], v[112:115], v[166:169]
	v_mfma_f32_16x16x32_bf16 v[112:115], v[212:215], v[112:115], v[170:173]
	v_mfma_f32_16x16x32_bf16 v[116:119], v[204:207], v[224:227], v[174:177]
	v_mfma_f32_16x16x32_bf16 v[120:123], v[212:215], v[224:227], v[120:123]
	v_mfma_f32_16x16x32_bf16 v[124:127], v[204:207], v[238:241], v[178:181]
	v_mfma_f32_16x16x32_bf16 v[128:131], v[212:215], v[238:241], v[128:131]
	v_mfma_f32_16x16x32_bf16 v[108:111], v[208:211], v[220:223], v[108:111]
	v_mfma_f32_16x16x32_bf16 v[112:115], v[216:219], v[220:223], v[112:115]
	v_mfma_f32_16x16x32_bf16 v[116:119], v[208:211], v[234:237], v[116:119]
	v_mfma_f32_16x16x32_bf16 v[120:123], v[216:219], v[234:237], v[120:123]
	s_setprio 2
	s_barrier
	v_mfma_f32_16x16x32_bf16 v[124:127], v[208:211], v[242:245], v[124:127]
	v_mfma_f32_16x16x32_bf16 v[128:131], v[216:219], v[242:245], v[128:131]
	s_setprio 0
	s_add_i32 s41, s41, 2
	s_cmp_ge_i32 s41, s40
	s_cbranch_scc0 .LBB0_2269
	v_mov_b32_e32 v192, v2
	s_branch .LBB0_2272

.LBB0_2273:
	s_add_u32 s12, s14, 0xfffc0080
	s_addc_u32 s13, s15, -1
	s_add_i32 s29, 0, 0x10000
	s_cmp_eq_u32 s28, 12
	s_cselect_b32 s17, s9, s13
	s_cselect_b32 s16, s8, s12
	s_cselect_b32 s13, s11, s27
	s_cselect_b32 s12, s10, s26
	s_add_i32 s51, 0, 0x14000
	v_add_u32_e32 v144, s29, v232
	v_add_u32_e32 v160, s51, v232
	s_waitcnt lgkmcnt(0)
	ds_read_b128 v[132:135], v144
	ds_read_b128 v[136:139], v144 offset:1024
	ds_read_b128 v[140:143], v144 offset:2048
	ds_read_b128 v[144:147], v144 offset:3072
	ds_read_b128 v[148:151], v160
	ds_read_b128 v[152:155], v160 offset:1024
	ds_read_b128 v[156:159], v160 offset:2048
	ds_read_b128 v[160:163], v160 offset:3072
	s_mov_b32 m0, s65
	v_add_u32_e32 v210, 0, v231
	ds_read_b128 v[164:167], v210
	ds_read_b128 v[168:171], v210 offset:1024
	ds_read_b128 v[172:175], v210 offset:2048
	ds_read_b128 v[176:179], v210 offset:3072
	ds_read_b128 v[180:183], v210 offset:4096
	ds_read_b128 v[184:187], v210 offset:5120
	ds_read_b128 v[194:197], v210 offset:6144
	ds_read_b128 v[198:201], v210 offset:7168
	global_load_lds_dwordx4 v2, s[14:15]
	s_mov_b32 m0, s66
	v_mov_b32_e32 v189, v3
	global_load_lds_dwordx4 v188, s[14:15]
	s_waitcnt vmcnt(8)
	s_waitcnt lgkmcnt(0)
	s_barrier
	s_setprio 1
	s_waitcnt lgkmcnt(0)
	v_mfma_f32_16x16x32_bf16 v[4:7], v[132:135], v[164:167], v[4:7]
	v_mfma_f32_16x16x32_bf16 v[4:7], v[136:139], v[168:171], v[4:7]
	v_mfma_f32_16x16x32_bf16 v[8:11], v[144:147], v[168:171], v[8:11]
	v_mfma_f32_16x16x32_bf16 v[8:11], v[140:143], v[164:167], v[8:11]
	v_mfma_f32_16x16x32_bf16 v[16:19], v[140:143], v[172:175], v[16:19]
	v_mfma_f32_16x16x32_bf16 v[16:19], v[144:147], v[176:179], v[16:19]
	v_mfma_f32_16x16x32_bf16 v[12:15], v[136:139], v[176:179], v[12:15]
	v_mfma_f32_16x16x32_bf16 v[12:15], v[132:135], v[172:175], v[12:15]
	v_mfma_f32_16x16x32_bf16 v[20:23], v[132:135], v[180:183], v[20:23]
	v_mfma_f32_16x16x32_bf16 v[20:23], v[136:139], v[184:187], v[20:23]
	v_mfma_f32_16x16x32_bf16 v[24:27], v[144:147], v[184:187], v[24:27]
	v_mfma_f32_16x16x32_bf16 v[24:27], v[140:143], v[180:183], v[24:27]
	v_mfma_f32_16x16x32_bf16 v[32:35], v[140:143], v[194:197], v[32:35]
	v_mfma_f32_16x16x32_bf16 v[32:35], v[144:147], v[198:201], v[32:35]
	v_mfma_f32_16x16x32_bf16 v[28:31], v[136:139], v[198:201], v[28:31]
	v_mfma_f32_16x16x32_bf16 v[28:31], v[132:135], v[194:197], v[28:31]
	v_mfma_f32_16x16x32_bf16 v[36:39], v[148:151], v[164:167], v[36:39]
	v_mfma_f32_16x16x32_bf16 v[36:39], v[152:155], v[168:171], v[36:39]
	v_mfma_f32_16x16x32_bf16 v[40:43], v[160:163], v[168:171], v[40:43]
	v_mfma_f32_16x16x32_bf16 v[40:43], v[156:159], v[164:167], v[40:43]
	v_mfma_f32_16x16x32_bf16 v[48:51], v[156:159], v[172:175], v[48:51]
	v_mfma_f32_16x16x32_bf16 v[48:51], v[160:163], v[176:179], v[48:51]
	v_mfma_f32_16x16x32_bf16 v[44:47], v[152:155], v[176:179], v[44:47]
	v_mfma_f32_16x16x32_bf16 v[44:47], v[148:151], v[172:175], v[44:47]
	v_mfma_f32_16x16x32_bf16 v[52:55], v[148:151], v[180:183], v[52:55]
	v_mfma_f32_16x16x32_bf16 v[52:55], v[152:155], v[184:187], v[52:55]
	v_mfma_f32_16x16x32_bf16 v[56:59], v[160:163], v[184:187], v[56:59]
	v_mfma_f32_16x16x32_bf16 v[56:59], v[156:159], v[180:183], v[56:59]
	v_mfma_f32_16x16x32_bf16 v[64:67], v[156:159], v[194:197], v[64:67]
	v_mfma_f32_16x16x32_bf16 v[64:67], v[160:163], v[198:201], v[64:67]
	s_setprio 2
	s_barrier
	v_mfma_f32_16x16x32_bf16 v[60:63], v[152:155], v[198:201], v[60:63]
	v_mfma_f32_16x16x32_bf16 v[60:63], v[148:151], v[194:197], v[60:63]
	s_setprio 0
	s_add_i32 s29, s29, s38
	s_mov_b32 m0, s29
	ds_read_b128 v[164:167], v210 offset:16384
	ds_read_b128 v[168:171], v210 offset:17408
	ds_read_b128 v[172:175], v210 offset:18432
	ds_read_b128 v[176:179], v210 offset:19456
	ds_read_b128 v[180:183], v210 offset:20480
	ds_read_b128 v[184:187], v210 offset:21504
	ds_read_b128 v[194:197], v210 offset:22528
	ds_read_b128 v[198:201], v210 offset:23552
	global_load_lds_dwordx4 v192, s[12:13]
	s_add_i32 m0, s29, 0x2000
	s_add_u32 s40, s12, 0x100000
	s_addc_u32 s41, s13, 0
	s_add_i32 s29, s51, s38
	global_load_lds_dwordx4 v190, s[12:13]
	s_mov_b32 m0, s29
	v_mov_b32_e32 v193, v3
	global_load_lds_dwordx4 v192, s[40:41]
	s_add_i32 m0, s29, 0x2000
	v_mov_b32_e32 v191, v3
	global_load_lds_dwordx4 v190, s[40:41]
	s_mov_b32 m0, s56
	v_lshl_add_u64 v[202:203], s[12:13], 0, v[192:193]
	global_load_lds_dwordx4 v2, s[16:17]
	s_mov_b32 m0, s57
	v_lshl_add_u64 v[204:205], s[12:13], 0, v[190:191]
	global_load_lds_dwordx4 v188, s[16:17]
	s_waitcnt vmcnt(8)
	s_waitcnt lgkmcnt(0)
	v_lshl_add_u64 v[206:207], s[16:17], 0, v[2:3]
	v_lshl_add_u64 v[208:209], s[16:17], 0, v[188:189]
	s_barrier
	s_setprio 1
	s_waitcnt lgkmcnt(0)
	v_mfma_f32_16x16x32_bf16 v[68:71], v[132:135], v[164:167], v[68:71]
	v_mfma_f32_16x16x32_bf16 v[68:71], v[136:139], v[168:171], v[68:71]
	v_mfma_f32_16x16x32_bf16 v[72:75], v[144:147], v[168:171], v[72:75]
	v_mfma_f32_16x16x32_bf16 v[72:75], v[140:143], v[164:167], v[72:75]
	v_mfma_f32_16x16x32_bf16 v[80:83], v[140:143], v[172:175], v[80:83]
	v_mfma_f32_16x16x32_bf16 v[80:83], v[144:147], v[176:179], v[80:83]
	v_mfma_f32_16x16x32_bf16 v[76:79], v[136:139], v[176:179], v[76:79]
	v_mfma_f32_16x16x32_bf16 v[76:79], v[132:135], v[172:175], v[76:79]
	v_mfma_f32_16x16x32_bf16 v[84:87], v[132:135], v[180:183], v[84:87]
	v_mfma_f32_16x16x32_bf16 v[84:87], v[136:139], v[184:187], v[84:87]
	v_mfma_f32_16x16x32_bf16 v[88:91], v[144:147], v[184:187], v[88:91]
	v_mfma_f32_16x16x32_bf16 v[88:91], v[140:143], v[180:183], v[88:91]
	v_mfma_f32_16x16x32_bf16 v[96:99], v[140:143], v[194:197], v[96:99]
	v_mfma_f32_16x16x32_bf16 v[96:99], v[144:147], v[198:201], v[96:99]
	v_mfma_f32_16x16x32_bf16 v[92:95], v[136:139], v[198:201], v[92:95]
	v_mfma_f32_16x16x32_bf16 v[92:95], v[132:135], v[194:197], v[92:95]
	v_mfma_f32_16x16x32_bf16 v[100:103], v[148:151], v[164:167], v[100:103]
	v_mfma_f32_16x16x32_bf16 v[100:103], v[152:155], v[168:171], v[100:103]
	v_mfma_f32_16x16x32_bf16 v[104:107], v[160:163], v[168:171], v[104:107]
	v_mfma_f32_16x16x32_bf16 v[104:107], v[156:159], v[164:167], v[104:107]
	v_mfma_f32_16x16x32_bf16 v[112:115], v[156:159], v[172:175], v[112:115]
	v_mfma_f32_16x16x32_bf16 v[112:115], v[160:163], v[176:179], v[112:115]
	v_mfma_f32_16x16x32_bf16 v[108:111], v[152:155], v[176:179], v[108:111]
	v_mfma_f32_16x16x32_bf16 v[108:111], v[148:151], v[172:175], v[108:111]
	v_mfma_f32_16x16x32_bf16 v[116:119], v[148:151], v[180:183], v[116:119]
	v_mfma_f32_16x16x32_bf16 v[116:119], v[152:155], v[184:187], v[116:119]
	v_mfma_f32_16x16x32_bf16 v[120:123], v[160:163], v[184:187], v[120:123]
	v_mfma_f32_16x16x32_bf16 v[120:123], v[156:159], v[180:183], v[120:123]
	v_mfma_f32_16x16x32_bf16 v[128:131], v[156:159], v[194:197], v[128:131]
	v_mfma_f32_16x16x32_bf16 v[128:131], v[160:163], v[198:201], v[128:131]
	s_setprio 2
	s_barrier
	v_mfma_f32_16x16x32_bf16 v[124:127], v[152:155], v[198:201], v[124:127]
	v_mfma_f32_16x16x32_bf16 v[124:127], v[148:151], v[194:197], v[124:127]
	s_setprio 0
	s_add_i32 s29, 0, 0x18000
	s_add_i32 s40, 0, 0x1c000
	v_add_u32_e32 v144, s29, v232
	v_add_u32_e32 v160, s40, v232
	ds_read_b128 v[132:135], v144
	ds_read_b128 v[136:139], v144 offset:1024
	ds_read_b128 v[140:143], v144 offset:2048
	ds_read_b128 v[144:147], v144 offset:3072
	ds_read_b128 v[148:151], v160
	ds_read_b128 v[152:155], v160 offset:1024
	ds_read_b128 v[156:159], v160 offset:2048
	ds_read_b128 v[160:163], v160 offset:3072
	s_add_u32 s16, s16, 0x40000
	s_addc_u32 s17, s17, 0
	s_mov_b32 m0, s58
	ds_read_b128 v[164:167], v210 offset:32768
	ds_read_b128 v[168:171], v210 offset:33792
	ds_read_b128 v[172:175], v210 offset:34816
	ds_read_b128 v[176:179], v210 offset:35840
	ds_read_b128 v[180:183], v210 offset:36864
	ds_read_b128 v[184:187], v210 offset:37888
	ds_read_b128 v[194:197], v210 offset:38912
	ds_read_b128 v[198:201], v210 offset:39936
	global_load_lds_dwordx4 v2, s[16:17]
	s_mov_b32 m0, s59
	s_nop 0
	global_load_lds_dwordx4 v188, s[16:17]
	s_waitcnt vmcnt(8)
	s_waitcnt lgkmcnt(0)
	s_barrier
	s_setprio 1
	s_waitcnt lgkmcnt(0)
	v_mfma_f32_16x16x32_bf16 v[4:7], v[132:135], v[164:167], v[4:7]
	v_mfma_f32_16x16x32_bf16 v[4:7], v[136:139], v[168:171], v[4:7]
	v_mfma_f32_16x16x32_bf16 v[8:11], v[144:147], v[168:171], v[8:11]
	v_mfma_f32_16x16x32_bf16 v[8:11], v[140:143], v[164:167], v[8:11]
	v_mfma_f32_16x16x32_bf16 v[16:19], v[140:143], v[172:175], v[16:19]
	v_mfma_f32_16x16x32_bf16 v[16:19], v[144:147], v[176:179], v[16:19]
	v_mfma_f32_16x16x32_bf16 v[12:15], v[136:139], v[176:179], v[12:15]
	v_mfma_f32_16x16x32_bf16 v[12:15], v[132:135], v[172:175], v[12:15]
	v_mfma_f32_16x16x32_bf16 v[20:23], v[132:135], v[180:183], v[20:23]
	v_mfma_f32_16x16x32_bf16 v[20:23], v[136:139], v[184:187], v[20:23]
	v_mfma_f32_16x16x32_bf16 v[24:27], v[144:147], v[184:187], v[24:27]
	v_mfma_f32_16x16x32_bf16 v[24:27], v[140:143], v[180:183], v[24:27]
	v_mfma_f32_16x16x32_bf16 v[32:35], v[140:143], v[194:197], v[32:35]
	v_mfma_f32_16x16x32_bf16 v[32:35], v[144:147], v[198:201], v[32:35]
	v_mfma_f32_16x16x32_bf16 v[28:31], v[136:139], v[198:201], v[28:31]
	v_mfma_f32_16x16x32_bf16 v[28:31], v[132:135], v[194:197], v[28:31]
	v_mfma_f32_16x16x32_bf16 v[36:39], v[148:151], v[164:167], v[36:39]
	v_mfma_f32_16x16x32_bf16 v[36:39], v[152:155], v[168:171], v[36:39]
	v_mfma_f32_16x16x32_bf16 v[40:43], v[160:163], v[168:171], v[40:43]
	v_mfma_f32_16x16x32_bf16 v[40:43], v[156:159], v[164:167], v[40:43]
	v_mfma_f32_16x16x32_bf16 v[48:51], v[156:159], v[172:175], v[48:51]
	v_mfma_f32_16x16x32_bf16 v[48:51], v[160:163], v[176:179], v[48:51]
	v_mfma_f32_16x16x32_bf16 v[44:47], v[152:155], v[176:179], v[44:47]
	v_mfma_f32_16x16x32_bf16 v[44:47], v[148:151], v[172:175], v[44:47]
	v_mfma_f32_16x16x32_bf16 v[52:55], v[148:151], v[180:183], v[52:55]
	v_mfma_f32_16x16x32_bf16 v[52:55], v[152:155], v[184:187], v[52:55]
	v_mfma_f32_16x16x32_bf16 v[56:59], v[160:163], v[184:187], v[56:59]
	v_mfma_f32_16x16x32_bf16 v[56:59], v[156:159], v[180:183], v[56:59]
	v_mfma_f32_16x16x32_bf16 v[64:67], v[156:159], v[194:197], v[64:67]
	v_mfma_f32_16x16x32_bf16 v[64:67], v[160:163], v[198:201], v[64:67]
	s_setprio 2
	s_barrier
	v_mfma_f32_16x16x32_bf16 v[60:63], v[152:155], v[198:201], v[60:63]
	v_mfma_f32_16x16x32_bf16 v[60:63], v[148:151], v[194:197], v[60:63]
	s_setprio 0
	s_add_i32 s16, s29, s38
	v_lshl_add_u64 v[202:203], v[202:203], 0, s[86:87]
	s_mov_b32 m0, s16
	ds_read_b128 v[164:167], v210 offset:49152
	ds_read_b128 v[168:171], v210 offset:50176
	ds_read_b128 v[172:175], v210 offset:51200
	ds_read_b128 v[176:179], v210 offset:52224
	ds_read_b128 v[180:183], v210 offset:53248
	ds_read_b128 v[184:187], v210 offset:54272
	ds_read_b128 v[194:197], v210 offset:55296
	ds_read_b128 v[198:201], v210 offset:56320
	global_load_lds_dwordx4 v[202:203], off
	s_add_i32 m0, s16, 0x2000
	s_add_u32 s12, s12, 0x100080
	v_lshl_add_u64 v[202:203], v[204:205], 0, s[86:87]
	s_addc_u32 s13, s13, 0
	s_add_i32 s16, s40, s38
	global_load_lds_dwordx4 v[202:203], off
	s_mov_b32 m0, s16
	v_lshl_add_u64 v[202:203], v[206:207], 0, s[86:87]
	global_load_lds_dwordx4 v192, s[12:13]
	s_add_i32 m0, s16, 0x2000
	s_nop 0
	global_load_lds_dwordx4 v190, s[12:13]
	s_mov_b32 m0, s63
	s_nop 0
	global_load_lds_dwordx4 v[202:203], off
	v_lshl_add_u64 v[202:203], v[208:209], 0, s[86:87]
	s_mov_b32 m0, s64
	s_nop 0
	global_load_lds_dwordx4 v[202:203], off
	s_waitcnt vmcnt(8)
	s_waitcnt lgkmcnt(0)
	s_barrier
	s_setprio 1
	s_waitcnt lgkmcnt(0)
	v_mfma_f32_16x16x32_bf16 v[68:71], v[132:135], v[164:167], v[68:71]
	v_mfma_f32_16x16x32_bf16 v[68:71], v[136:139], v[168:171], v[68:71]
	v_mfma_f32_16x16x32_bf16 v[72:75], v[144:147], v[168:171], v[72:75]
	v_mfma_f32_16x16x32_bf16 v[72:75], v[140:143], v[164:167], v[72:75]
	v_mfma_f32_16x16x32_bf16 v[80:83], v[140:143], v[172:175], v[80:83]
	v_mfma_f32_16x16x32_bf16 v[80:83], v[144:147], v[176:179], v[80:83]
	v_mfma_f32_16x16x32_bf16 v[76:79], v[136:139], v[176:179], v[76:79]
	v_mfma_f32_16x16x32_bf16 v[76:79], v[132:135], v[172:175], v[76:79]
	v_mfma_f32_16x16x32_bf16 v[84:87], v[132:135], v[180:183], v[84:87]
	v_mfma_f32_16x16x32_bf16 v[84:87], v[136:139], v[184:187], v[84:87]
	v_mfma_f32_16x16x32_bf16 v[88:91], v[144:147], v[184:187], v[88:91]
	v_mfma_f32_16x16x32_bf16 v[88:91], v[140:143], v[180:183], v[88:91]
	v_mfma_f32_16x16x32_bf16 v[96:99], v[140:143], v[194:197], v[96:99]
	v_mfma_f32_16x16x32_bf16 v[96:99], v[144:147], v[198:201], v[96:99]
	v_mfma_f32_16x16x32_bf16 v[92:95], v[136:139], v[198:201], v[92:95]
	v_mfma_f32_16x16x32_bf16 v[92:95], v[132:135], v[194:197], v[92:95]
	v_mfma_f32_16x16x32_bf16 v[100:103], v[148:151], v[164:167], v[100:103]
	v_mfma_f32_16x16x32_bf16 v[100:103], v[152:155], v[168:171], v[100:103]
	v_mfma_f32_16x16x32_bf16 v[104:107], v[160:163], v[168:171], v[104:107]
	v_mfma_f32_16x16x32_bf16 v[104:107], v[156:159], v[164:167], v[104:107]
	v_mfma_f32_16x16x32_bf16 v[112:115], v[156:159], v[172:175], v[112:115]
	v_mfma_f32_16x16x32_bf16 v[112:115], v[160:163], v[176:179], v[112:115]
	v_mfma_f32_16x16x32_bf16 v[108:111], v[152:155], v[176:179], v[108:111]
	v_mfma_f32_16x16x32_bf16 v[108:111], v[148:151], v[172:175], v[108:111]
	v_mfma_f32_16x16x32_bf16 v[116:119], v[148:151], v[180:183], v[116:119]
	v_mfma_f32_16x16x32_bf16 v[116:119], v[152:155], v[184:187], v[116:119]
	v_mfma_f32_16x16x32_bf16 v[120:123], v[160:163], v[184:187], v[120:123]
	v_mfma_f32_16x16x32_bf16 v[120:123], v[156:159], v[180:183], v[120:123]
	v_mfma_f32_16x16x32_bf16 v[128:131], v[156:159], v[194:197], v[128:131]
	v_mfma_f32_16x16x32_bf16 v[128:131], v[160:163], v[198:201], v[128:131]
	s_setprio 2
	s_barrier
	v_mfma_f32_16x16x32_bf16 v[124:127], v[152:155], v[198:201], v[124:127]
	v_mfma_f32_16x16x32_bf16 v[124:127], v[148:151], v[194:197], v[124:127]
	s_setprio 0
	s_add_i32 s28, s28, 2
	s_add_u32 s14, s14, 0x100
	s_addc_u32 s15, s15, 0
	s_add_u32 s26, s26, 0x100
	s_addc_u32 s27, s27, 0
	s_cmp_gt_u32 s28, 13
	s_cbranch_scc0 .LBB0_2273
	s_and_b64 vcc, exec, s[48:49]
	s_cbranch_vccz .LBB0_2276
	s_barrier
